# flat_* memory ops converted to global_* in the SwiGLU / projection GEMM phases (1,2,3,8,10,12,15); waits unchanged
# speedup vs baseline: 1.0005x; 1.0005x over previous
.LBB0_306:
	v_cmp_gt_i64_e32 vcc, s[6:7], v[4:5]
	s_mov_b64 s[10:11], -1
	s_cbranch_vccnz .LBB0_305
	s_mov_b64 s[10:11], exec
	s_cbranch_execz .LBB0_304
	s_ashr_i32 s14, s6, 31
	s_lshr_b32 s14, s14, 29
	s_add_i32 s14, s6, s14
	s_ashr_i32 s15, s14, 3
	s_and_b32 s14, s14, -8
	s_sub_i32 s14, s6, s14
	s_cmp_lt_i32 s14, 0
	s_cselect_b32 s16, s12, 0x160
	s_mul_i32 s14, s16, s14
	s_add_i32 s14, s14, s15
	s_mul_hi_i32 s15, s14, 0x2e8ba2e9
	s_lshr_b32 s16, s15, 31
	s_ashr_i32 s15, s15, 5
	s_add_i32 s15, s15, s16
	s_lshl_b32 s16, s15, 3
	s_sub_i32 s17, 0x80, s16
	s_min_i32 s17, s17, 8
	s_abs_i32 s17, s17
	v_cvt_f32_u32_e32 v7, s17
	s_sub_i32 s18, 0, s17
	s_mulk_i32 s15, 0xb0
	s_sub_i32 s14, s14, s15
	v_rcp_iflag_f32_e32 v7, v7
	s_ashr_i32 s15, s14, 31
	s_abs_i32 s14, s14
	v_mul_f32_e32 v7, 0x4f7ffffe, v7
	v_cvt_u32_f32_e32 v7, v7
	s_nop 0
	v_readfirstlane_b32 s19, v7
	s_mul_i32 s18, s18, s19
	s_mul_hi_u32 s18, s19, s18
	s_add_i32 s19, s19, s18
	s_mul_hi_u32 s18, s14, s19
	s_mul_i32 s18, s18, s17
	s_sub_i32 s14, s14, s18
	s_sub_i32 s18, s14, s17
	s_cmp_ge_u32 s14, s17
	s_cselect_b32 s14, s18, s14
	s_sub_i32 s18, s14, s17
	s_cmp_ge_u32 s14, s17
	s_cselect_b32 s14, s18, s14
	s_xor_b32 s14, s14, s15
	s_sub_i32 s14, s14, s15
	s_add_i32 s14, s14, s16
	s_ashr_i32 s15, s14, 31
	s_lshl_b64 s[14:15], s[14:15], 14
	v_lshl_add_u64 v[22:23], v[2:3], 0, s[14:15]
	global_load_dwordx4 v[8:11], v[22:23], off
	global_load_dwordx4 v[14:17], v[22:23], off offset:16
	global_load_dwordx4 v[18:21], v[22:23], off offset:32
	s_nop 0
	global_load_dwordx4 v[22:25], v[22:23], off offset:48
	s_waitcnt vmcnt(0) lgkmcnt(0)
	v_mov_b32_e32 v26, v9
	v_mov_b32_e32 v27, v10
	v_mov_b32_e32 v28, v15
	v_mov_b32_e32 v29, v16
	v_mov_b32_e32 v9, v11
	v_mov_b32_e32 v15, v17
	v_mov_b32_e32 v10, v19
	v_mov_b32_e32 v16, v21
	v_pk_add_f32 v[8:9], v[26:27], v[8:9]
	v_pk_add_f32 v[14:15], v[28:29], v[14:15]
	v_pk_add_f32 v[10:11], v[18:19], v[10:11]
	v_pk_add_f32 v[16:17], v[20:21], v[16:17]
	v_pk_add_f32 v[8:9], v[8:9], v[8:9] op_sel:[0,1] op_sel_hi:[1,0]
	v_pk_add_f32 v[14:15], v[14:15], v[14:15] op_sel:[0,1] op_sel_hi:[1,0]
	v_mov_b32_e32 v11, v24
	v_mov_b32_e32 v17, v25
	v_mov_b32_e32 v9, v22
	v_mov_b32_e32 v15, v23
	v_pk_add_f32 v[10:11], v[10:11], v[16:17]
	v_pk_add_f32 v[8:9], v[8:9], v[14:15]
	s_nop 0
	v_pk_add_f32 v[8:9], v[8:9], v[10:11]
	s_nop 0
	v_add_f32_e32 v7, v8, v9
	v_fmamk_f32 v7, v7, 0x3a800000, v6
	v_mul_f32_e32 v8, 0x4b800000, v7
	v_cmp_gt_f32_e32 vcc, s13, v7
	s_nop 1
	v_cndmask_b32_e32 v7, v7, v8, vcc
	v_rsq_f32_e32 v7, v7
	s_nop 0
	v_mul_f32_e32 v8, 0x45800000, v7
	v_cndmask_b32_e32 v7, v7, v8, vcc
	ds_write_b32 v1, v7
	s_branch .LBB0_304

.LBB0_316:
	ds_read_b128 v[148:151], v158
	ds_read_b128 v[152:155], v159
	ds_read_b128 v[180:183], v160
	ds_read_b128 v[184:187], v161
	s_add_u32 s16, s56, 0xfffc0080
	s_addc_u32 s17, s57, -1
	s_cmp_eq_u32 vcc_lo, 12
	s_cselect_b32 s61, s19, s17
	s_cselect_b32 s60, s94, s16
	s_cselect_b32 s59, s15, s97
	s_cselect_b32 s58, s95, s96
	s_mov_b32 m0, s89
	v_lshl_add_u64 v[174:175], s[56:57], 0, v[142:143]
	ds_read_b128 v[188:191], v156
	ds_read_b128 v[192:195], v156 offset:1024
	ds_read_b128 v[196:199], v156 offset:2048
	ds_read_b128 v[200:203], v156 offset:3072
	ds_read_b128 v[204:207], v156 offset:4096
	ds_read_b128 v[208:211], v156 offset:5120
	ds_read_b128 v[212:215], v156 offset:6144
	ds_read_b128 v[216:219], v156 offset:7168
	global_load_lds_dwordx4 v[174:175], off
	v_lshl_add_u64 v[174:175], s[56:57], 0, v[140:141]
	s_mov_b32 m0, s90
	s_nop 0
	global_load_lds_dwordx4 v[174:175], off
	s_waitcnt lgkmcnt(8)
	s_barrier
	s_waitcnt lgkmcnt(0)
	s_setprio 1
	s_waitcnt lgkmcnt(0)
	v_mfma_f32_16x16x32_bf16 v[124:127], v[148:151], v[188:191], v[124:127]
	v_mfma_f32_16x16x32_bf16 v[120:123], v[180:183], v[188:191], v[120:123]
	v_mfma_f32_16x16x32_bf16 v[108:111], v[148:151], v[196:199], v[108:111]
	v_mfma_f32_16x16x32_bf16 v[104:107], v[180:183], v[196:199], v[104:107]
	v_mfma_f32_16x16x32_bf16 v[92:95], v[148:151], v[204:207], v[92:95]
	v_mfma_f32_16x16x32_bf16 v[88:91], v[180:183], v[204:207], v[88:91]
	v_mfma_f32_16x16x32_bf16 v[76:79], v[148:151], v[212:215], v[76:79]
	v_mfma_f32_16x16x32_bf16 v[72:75], v[180:183], v[212:215], v[72:75]
	v_mfma_f32_16x16x32_bf16 v[124:127], v[152:155], v[192:195], v[124:127]
	v_mfma_f32_16x16x32_bf16 v[120:123], v[184:187], v[192:195], v[120:123]
	v_mfma_f32_16x16x32_bf16 v[108:111], v[152:155], v[200:203], v[108:111]
	v_mfma_f32_16x16x32_bf16 v[104:107], v[184:187], v[200:203], v[104:107]
	v_mfma_f32_16x16x32_bf16 v[92:95], v[152:155], v[208:211], v[92:95]
	v_mfma_f32_16x16x32_bf16 v[88:91], v[184:187], v[208:211], v[88:91]
	v_mfma_f32_16x16x32_bf16 v[76:79], v[152:155], v[216:219], v[76:79]
	v_mfma_f32_16x16x32_bf16 v[72:75], v[184:187], v[216:219], v[72:75]
	s_setprio 0
	s_barrier
	s_mov_b32 m0, s68
	v_lshl_add_u64 v[174:175], s[58:59], 0, v[132:133]
	ds_read_b128 v[220:223], v162
	ds_read_b128 v[224:227], v163
	ds_read_b128 v[228:231], v164
	ds_read_b128 v[232:235], v165
	global_load_lds_dwordx4 v[174:175], off
	v_lshl_add_u64 v[236:237], s[58:59], 0, v[128:129]
	s_mov_b32 m0, s69
	s_nop 0
	global_load_lds_dwordx4 v[236:237], off
	s_barrier
	s_waitcnt lgkmcnt(0)
	s_setprio 1
	s_waitcnt lgkmcnt(0)
	v_mfma_f32_16x16x32_bf16 v[116:119], v[220:223], v[188:191], v[116:119]
	v_mfma_f32_16x16x32_bf16 v[112:115], v[228:231], v[188:191], v[112:115]
	v_mfma_f32_16x16x32_bf16 v[100:103], v[220:223], v[196:199], v[100:103]
	v_mfma_f32_16x16x32_bf16 v[96:99], v[228:231], v[196:199], v[96:99]
	v_mfma_f32_16x16x32_bf16 v[84:87], v[220:223], v[204:207], v[84:87]
	v_mfma_f32_16x16x32_bf16 v[80:83], v[228:231], v[204:207], v[80:83]
	v_mfma_f32_16x16x32_bf16 v[68:71], v[220:223], v[212:215], v[68:71]
	v_mfma_f32_16x16x32_bf16 v[64:67], v[228:231], v[212:215], v[64:67]
	v_mfma_f32_16x16x32_bf16 v[116:119], v[224:227], v[192:195], v[116:119]
	v_mfma_f32_16x16x32_bf16 v[112:115], v[232:235], v[192:195], v[112:115]
	v_mfma_f32_16x16x32_bf16 v[100:103], v[224:227], v[200:203], v[100:103]
	v_mfma_f32_16x16x32_bf16 v[96:99], v[232:235], v[200:203], v[96:99]
	v_mfma_f32_16x16x32_bf16 v[84:87], v[224:227], v[208:211], v[84:87]
	v_mfma_f32_16x16x32_bf16 v[80:83], v[232:235], v[208:211], v[80:83]
	v_mfma_f32_16x16x32_bf16 v[68:71], v[224:227], v[216:219], v[68:71]
	v_mfma_f32_16x16x32_bf16 v[64:67], v[232:235], v[216:219], v[64:67]
	s_setprio 0
	s_mov_b32 m0, s66
	v_lshl_add_u64 v[238:239], s[60:61], 0, v[134:135]
	s_barrier
	ds_read_b128 v[188:191], v156 offset:16384
	ds_read_b128 v[192:195], v156 offset:17408
	ds_read_b128 v[196:199], v156 offset:18432
	ds_read_b128 v[200:203], v156 offset:19456
	ds_read_b128 v[204:207], v156 offset:20480
	ds_read_b128 v[208:211], v156 offset:21504
	ds_read_b128 v[212:215], v156 offset:22528
	ds_read_b128 v[216:219], v156 offset:23552
	global_load_lds_dwordx4 v[238:239], off
	v_lshl_add_u64 v[240:241], s[60:61], 0, v[130:131]
	s_mov_b32 m0, s70
	s_nop 0
	global_load_lds_dwordx4 v[240:241], off
	s_barrier
	s_waitcnt lgkmcnt(0)
	s_setprio 1
	s_waitcnt lgkmcnt(0)
	v_mfma_f32_16x16x32_bf16 v[60:63], v[148:151], v[188:191], v[60:63]
	v_mfma_f32_16x16x32_bf16 v[56:59], v[180:183], v[188:191], v[56:59]
	v_mfma_f32_16x16x32_bf16 v[44:47], v[148:151], v[196:199], v[44:47]
	v_mfma_f32_16x16x32_bf16 v[40:43], v[180:183], v[196:199], v[40:43]
	v_mfma_f32_16x16x32_bf16 v[28:31], v[148:151], v[204:207], v[28:31]
	v_mfma_f32_16x16x32_bf16 v[24:27], v[180:183], v[204:207], v[24:27]
	v_mfma_f32_16x16x32_bf16 v[12:15], v[148:151], v[212:215], v[12:15]
	v_mfma_f32_16x16x32_bf16 v[8:11], v[180:183], v[212:215], v[8:11]
	v_mfma_f32_16x16x32_bf16 v[60:63], v[152:155], v[192:195], v[60:63]
	v_mfma_f32_16x16x32_bf16 v[56:59], v[184:187], v[192:195], v[56:59]
	v_mfma_f32_16x16x32_bf16 v[44:47], v[152:155], v[200:203], v[44:47]
	v_mfma_f32_16x16x32_bf16 v[40:43], v[184:187], v[200:203], v[40:43]
	v_mfma_f32_16x16x32_bf16 v[28:31], v[152:155], v[208:211], v[28:31]
	v_mfma_f32_16x16x32_bf16 v[24:27], v[184:187], v[208:211], v[24:27]
	v_mfma_f32_16x16x32_bf16 v[12:15], v[152:155], v[216:219], v[12:15]
	v_mfma_f32_16x16x32_bf16 v[8:11], v[184:187], v[216:219], v[8:11]
	s_setprio 0
	s_barrier
	s_add_u32 s16, s58, 0x40000
	s_addc_u32 s17, s59, 0
	s_mov_b32 m0, s71
	v_lshl_add_u64 v[148:149], s[16:17], 0, v[132:133]
	global_load_lds_dwordx4 v[148:149], off
	v_lshl_add_u64 v[148:149], s[16:17], 0, v[128:129]
	s_mov_b32 m0, s80
	s_nop 0
	global_load_lds_dwordx4 v[148:149], off
	s_waitcnt vmcnt(6)
	s_barrier
	s_setprio 1
	v_mfma_f32_16x16x32_bf16 v[52:55], v[220:223], v[188:191], v[52:55]
	v_mfma_f32_16x16x32_bf16 v[48:51], v[228:231], v[188:191], v[48:51]
	v_mfma_f32_16x16x32_bf16 v[36:39], v[220:223], v[196:199], v[36:39]
	v_mfma_f32_16x16x32_bf16 v[32:35], v[228:231], v[196:199], v[32:35]
	v_mfma_f32_16x16x32_bf16 v[20:23], v[220:223], v[204:207], v[20:23]
	v_mfma_f32_16x16x32_bf16 v[16:19], v[228:231], v[204:207], v[16:19]
	v_mfma_f32_16x16x32_bf16 v[4:7], v[220:223], v[212:215], v[4:7]
	v_mfma_f32_16x16x32_bf16 v[0:3], v[228:231], v[212:215], v[0:3]
	v_mfma_f32_16x16x32_bf16 v[52:55], v[224:227], v[192:195], v[52:55]
	v_mfma_f32_16x16x32_bf16 v[48:51], v[232:235], v[192:195], v[48:51]
	v_mfma_f32_16x16x32_bf16 v[36:39], v[224:227], v[200:203], v[36:39]
	v_mfma_f32_16x16x32_bf16 v[32:35], v[232:235], v[200:203], v[32:35]
	v_mfma_f32_16x16x32_bf16 v[20:23], v[224:227], v[208:211], v[20:23]
	v_mfma_f32_16x16x32_bf16 v[16:19], v[232:235], v[208:211], v[16:19]
	v_mfma_f32_16x16x32_bf16 v[4:7], v[224:227], v[216:219], v[4:7]
	v_mfma_f32_16x16x32_bf16 v[0:3], v[232:235], v[216:219], v[0:3]
	s_setprio 0
	s_barrier
	ds_read_b128 v[148:151], v166
	ds_read_b128 v[152:155], v167
	ds_read_b128 v[180:183], v168
	ds_read_b128 v[184:187], v169
	s_add_u32 s16, s60, 0x40000
	s_addc_u32 s17, s61, 0
	s_mov_b32 m0, s81
	v_lshl_add_u64 v[220:221], s[16:17], 0, v[134:135]
	ds_read_b128 v[188:191], v156 offset:32768
	ds_read_b128 v[192:195], v156 offset:33792
	ds_read_b128 v[196:199], v156 offset:34816
	ds_read_b128 v[200:203], v156 offset:35840
	ds_read_b128 v[204:207], v156 offset:36864
	ds_read_b128 v[208:211], v156 offset:37888
	ds_read_b128 v[212:215], v156 offset:38912
	ds_read_b128 v[216:219], v156 offset:39936
	global_load_lds_dwordx4 v[220:221], off
	v_lshl_add_u64 v[220:221], s[16:17], 0, v[130:131]
	s_mov_b32 m0, s82
	s_nop 0
	global_load_lds_dwordx4 v[220:221], off
	s_waitcnt lgkmcnt(8)
	s_barrier
	s_waitcnt lgkmcnt(0)
	s_setprio 1
	s_waitcnt lgkmcnt(0)
	v_mfma_f32_16x16x32_bf16 v[124:127], v[148:151], v[188:191], v[124:127]
	v_mfma_f32_16x16x32_bf16 v[120:123], v[180:183], v[188:191], v[120:123]
	v_mfma_f32_16x16x32_bf16 v[108:111], v[148:151], v[196:199], v[108:111]
	v_mfma_f32_16x16x32_bf16 v[104:107], v[180:183], v[196:199], v[104:107]
	v_mfma_f32_16x16x32_bf16 v[92:95], v[148:151], v[204:207], v[92:95]
	v_mfma_f32_16x16x32_bf16 v[88:91], v[180:183], v[204:207], v[88:91]
	v_mfma_f32_16x16x32_bf16 v[76:79], v[148:151], v[212:215], v[76:79]
	v_mfma_f32_16x16x32_bf16 v[72:75], v[180:183], v[212:215], v[72:75]
	v_mfma_f32_16x16x32_bf16 v[124:127], v[152:155], v[192:195], v[124:127]
	v_mfma_f32_16x16x32_bf16 v[120:123], v[184:187], v[192:195], v[120:123]
	v_mfma_f32_16x16x32_bf16 v[108:111], v[152:155], v[200:203], v[108:111]
	v_mfma_f32_16x16x32_bf16 v[104:107], v[184:187], v[200:203], v[104:107]
	v_mfma_f32_16x16x32_bf16 v[92:95], v[152:155], v[208:211], v[92:95]
	v_mfma_f32_16x16x32_bf16 v[88:91], v[184:187], v[208:211], v[88:91]
	v_mfma_f32_16x16x32_bf16 v[76:79], v[152:155], v[216:219], v[76:79]
	v_mfma_f32_16x16x32_bf16 v[72:75], v[184:187], v[216:219], v[72:75]
	s_setprio 0
	s_barrier
	s_mov_b32 m0, s83
	v_lshl_add_u64 v[174:175], v[174:175], 0, s[12:13]
	ds_read_b128 v[220:223], v170
	ds_read_b128 v[224:227], v171
	ds_read_b128 v[228:231], v172
	ds_read_b128 v[232:235], v173
	global_load_lds_dwordx4 v[174:175], off
	v_lshl_add_u64 v[174:175], v[236:237], 0, s[12:13]
	s_mov_b32 m0, s84
	s_nop 0
	global_load_lds_dwordx4 v[174:175], off
	s_barrier
	s_waitcnt lgkmcnt(0)
	s_setprio 1
	s_waitcnt lgkmcnt(0)
	v_mfma_f32_16x16x32_bf16 v[116:119], v[220:223], v[188:191], v[116:119]
	v_mfma_f32_16x16x32_bf16 v[112:115], v[228:231], v[188:191], v[112:115]
	v_mfma_f32_16x16x32_bf16 v[100:103], v[220:223], v[196:199], v[100:103]
	v_mfma_f32_16x16x32_bf16 v[96:99], v[228:231], v[196:199], v[96:99]
	v_mfma_f32_16x16x32_bf16 v[84:87], v[220:223], v[204:207], v[84:87]
	v_mfma_f32_16x16x32_bf16 v[80:83], v[228:231], v[204:207], v[80:83]
	v_mfma_f32_16x16x32_bf16 v[68:71], v[220:223], v[212:215], v[68:71]
	v_mfma_f32_16x16x32_bf16 v[64:67], v[228:231], v[212:215], v[64:67]
	v_mfma_f32_16x16x32_bf16 v[116:119], v[224:227], v[192:195], v[116:119]
	v_mfma_f32_16x16x32_bf16 v[112:115], v[232:235], v[192:195], v[112:115]
	v_mfma_f32_16x16x32_bf16 v[100:103], v[224:227], v[200:203], v[100:103]
	v_mfma_f32_16x16x32_bf16 v[96:99], v[232:235], v[200:203], v[96:99]
	v_mfma_f32_16x16x32_bf16 v[84:87], v[224:227], v[208:211], v[84:87]
	v_mfma_f32_16x16x32_bf16 v[80:83], v[232:235], v[208:211], v[80:83]
	v_mfma_f32_16x16x32_bf16 v[68:71], v[224:227], v[216:219], v[68:71]
	v_mfma_f32_16x16x32_bf16 v[64:67], v[232:235], v[216:219], v[64:67]
	s_setprio 0
	s_mov_b32 m0, s85
	v_lshl_add_u64 v[174:175], v[238:239], 0, s[12:13]
	s_barrier
	ds_read_b128 v[188:191], v156 offset:49152
	ds_read_b128 v[192:195], v156 offset:50176
	ds_read_b128 v[196:199], v156 offset:51200
	ds_read_b128 v[200:203], v156 offset:52224
	ds_read_b128 v[204:207], v156 offset:53248
	ds_read_b128 v[208:211], v156 offset:54272
	ds_read_b128 v[212:215], v156 offset:55296
	ds_read_b128 v[216:219], v156 offset:56320
	global_load_lds_dwordx4 v[174:175], off
	v_lshl_add_u64 v[174:175], v[240:241], 0, s[12:13]
	s_mov_b32 m0, s86
	s_nop 0
	global_load_lds_dwordx4 v[174:175], off
	s_barrier
	s_waitcnt lgkmcnt(0)
	s_setprio 1
	s_waitcnt lgkmcnt(0)
	v_mfma_f32_16x16x32_bf16 v[60:63], v[148:151], v[188:191], v[60:63]
	v_mfma_f32_16x16x32_bf16 v[56:59], v[180:183], v[188:191], v[56:59]
	v_mfma_f32_16x16x32_bf16 v[44:47], v[148:151], v[196:199], v[44:47]
	v_mfma_f32_16x16x32_bf16 v[40:43], v[180:183], v[196:199], v[40:43]
	v_mfma_f32_16x16x32_bf16 v[28:31], v[148:151], v[204:207], v[28:31]
	v_mfma_f32_16x16x32_bf16 v[24:27], v[180:183], v[204:207], v[24:27]
	v_mfma_f32_16x16x32_bf16 v[12:15], v[148:151], v[212:215], v[12:15]
	v_mfma_f32_16x16x32_bf16 v[8:11], v[180:183], v[212:215], v[8:11]
	v_mfma_f32_16x16x32_bf16 v[60:63], v[152:155], v[192:195], v[60:63]
	v_mfma_f32_16x16x32_bf16 v[56:59], v[184:187], v[192:195], v[56:59]
	v_mfma_f32_16x16x32_bf16 v[44:47], v[152:155], v[200:203], v[44:47]
	v_mfma_f32_16x16x32_bf16 v[40:43], v[184:187], v[200:203], v[40:43]
	v_mfma_f32_16x16x32_bf16 v[28:31], v[152:155], v[208:211], v[28:31]
	v_mfma_f32_16x16x32_bf16 v[24:27], v[184:187], v[208:211], v[24:27]
	v_mfma_f32_16x16x32_bf16 v[12:15], v[152:155], v[216:219], v[12:15]
	v_mfma_f32_16x16x32_bf16 v[8:11], v[184:187], v[216:219], v[8:11]
	s_setprio 0
	s_barrier
	s_add_u32 s16, s58, 0x40080
	s_addc_u32 s17, s59, 0
	s_mov_b32 m0, s87
	v_lshl_add_u64 v[148:149], s[16:17], 0, v[132:133]
	global_load_lds_dwordx4 v[148:149], off
	v_lshl_add_u64 v[148:149], s[16:17], 0, v[128:129]
	s_mov_b32 m0, s88
	s_nop 0
	global_load_lds_dwordx4 v[148:149], off
	s_waitcnt vmcnt(6)
	s_barrier
	s_setprio 1
	v_mfma_f32_16x16x32_bf16 v[52:55], v[220:223], v[188:191], v[52:55]
	v_mfma_f32_16x16x32_bf16 v[48:51], v[228:231], v[188:191], v[48:51]
	v_mfma_f32_16x16x32_bf16 v[36:39], v[220:223], v[196:199], v[36:39]
	v_mfma_f32_16x16x32_bf16 v[32:35], v[228:231], v[196:199], v[32:35]
	v_mfma_f32_16x16x32_bf16 v[20:23], v[220:223], v[204:207], v[20:23]
	v_mfma_f32_16x16x32_bf16 v[16:19], v[228:231], v[204:207], v[16:19]
	v_mfma_f32_16x16x32_bf16 v[4:7], v[220:223], v[212:215], v[4:7]
	v_mfma_f32_16x16x32_bf16 v[0:3], v[228:231], v[212:215], v[0:3]
	v_mfma_f32_16x16x32_bf16 v[52:55], v[224:227], v[192:195], v[52:55]
	v_mfma_f32_16x16x32_bf16 v[48:51], v[232:235], v[192:195], v[48:51]
	v_mfma_f32_16x16x32_bf16 v[36:39], v[224:227], v[200:203], v[36:39]
	v_mfma_f32_16x16x32_bf16 v[32:35], v[232:235], v[200:203], v[32:35]
	v_mfma_f32_16x16x32_bf16 v[20:23], v[224:227], v[208:211], v[20:23]
	v_mfma_f32_16x16x32_bf16 v[16:19], v[232:235], v[208:211], v[16:19]
	v_mfma_f32_16x16x32_bf16 v[4:7], v[224:227], v[216:219], v[4:7]
	v_mfma_f32_16x16x32_bf16 v[0:3], v[232:235], v[216:219], v[0:3]
	s_setprio 0
	s_add_i32 vcc_lo, vcc_lo, 2
	s_add_u32 s96, s96, 0x100
	s_addc_u32 s97, s97, 0
	s_add_u32 s56, s56, 0x100
	s_addc_u32 s57, s57, 0
	s_cmp_gt_u32 vcc_lo, 13
	s_barrier
	s_cbranch_scc0 .LBB0_316
	v_lshl_add_u32 v148, s39, 10, v157
	ds_read2_b32 v[154:155], v148 offset1:16
	ds_read2_b32 v[152:153], v148 offset0:32 offset1:48
	ds_read2_b32 v[150:151], v148 offset0:128 offset1:144
	ds_read2_b32 v[148:149], v148 offset0:160 offset1:176
	s_ashr_i32 s39, s38, 31
	s_waitcnt lgkmcnt(0)
	v_mul_f32_e32 v124, v124, v154
	v_mul_f32_e32 v174, 0xbfb8aa3b, v124
	v_exp_f32_e32 v174, v174
	v_mul_f32_e32 v116, v116, v154
	v_mul_f32_e32 v120, v120, v154
	v_mul_f32_e32 v112, v112, v154
	v_add_f32_e32 v174, 1.0, v174
	v_rcp_f32_e32 v174, v174
	v_mul_f32_e32 v117, v117, v154
	v_mul_f32_e32 v121, v121, v154
	v_mul_f32_e32 v113, v113, v154
	v_mul_f32_e32 v124, v124, v174
	v_mul_f32_e32 v116, v116, v124
	v_mul_f32_e32 v124, 0xbfb8aa3b, v120
	v_exp_f32_e32 v124, v124
	v_mul_f32_e32 v114, v114, v154
	v_mul_f32_e32 v115, v115, v154
	s_lshl_b64 s[38:39], s[38:39], 8
	v_add_f32_e32 v124, 1.0, v124
	v_rcp_f32_e32 v124, v124
	v_mul_f32_e32 v108, v108, v155
	v_mul_f32_e32 v100, v100, v155
	v_mul_f32_e32 v104, v104, v155
	v_mul_f32_e32 v120, v120, v124
	v_mul_f32_e32 v120, v112, v120
	v_mul_f32_e32 v112, v125, v154
	v_mul_f32_e32 v124, 0xbfb8aa3b, v112
	v_exp_f32_e32 v124, v124
	v_mul_f32_e32 v96, v96, v155
	v_mul_f32_e32 v101, v101, v155
	v_mul_f32_e32 v105, v105, v155
	v_add_f32_e32 v124, 1.0, v124
	v_rcp_f32_e32 v124, v124
	v_mul_f32_e32 v97, v97, v155
	v_mul_f32_e32 v102, v102, v155
	v_mul_f32_e32 v98, v98, v155
	v_mul_f32_e32 v112, v112, v124
	v_mul_f32_e32 v117, v117, v112
	v_mul_f32_e32 v112, 0xbfb8aa3b, v121
	v_exp_f32_e32 v112, v112
	v_mul_f32_e32 v103, v103, v155
	s_mov_b32 s15, 0x16000
	v_mul_f32_e32 v99, v99, v155
	v_add_f32_e32 v112, 1.0, v112
	v_rcp_f32_e32 v112, v112
	v_mul_f32_e32 v92, v92, v152
	v_mul_f32_e32 v84, v84, v152
	v_mul_f32_e32 v88, v88, v152
	v_mul_f32_e32 v112, v121, v112
	v_mul_f32_e32 v121, v113, v112
	v_mul_f32_e32 v112, v126, v154
	v_mul_f32_e32 v113, v118, v154
	v_mul_f32_e32 v118, v122, v154
	v_mul_f32_e32 v122, 0xbfb8aa3b, v112
	v_exp_f32_e32 v122, v122
	v_mul_f32_e32 v80, v80, v152
	v_mul_f32_e32 v85, v85, v152
	v_mul_f32_e32 v89, v89, v152
	v_add_f32_e32 v122, 1.0, v122
	v_rcp_f32_e32 v122, v122
	v_mul_f32_e32 v81, v81, v152
	v_mul_f32_e32 v86, v86, v152
	v_mul_f32_e32 v82, v82, v152
	v_mul_f32_e32 v112, v112, v122
	v_mul_f32_e32 v122, v113, v112
	v_mul_f32_e32 v112, 0xbfb8aa3b, v118
	v_exp_f32_e32 v112, v112
	v_mul_f32_e32 v113, v119, v154
	v_mul_f32_e32 v87, v87, v152
	v_mul_f32_e32 v83, v83, v152
	v_add_f32_e32 v112, 1.0, v112
	v_rcp_f32_e32 v112, v112
	v_mul_f32_e32 v76, v76, v153
	v_mul_f32_e32 v68, v68, v153
	v_mul_f32_e32 v72, v72, v153
	v_mul_f32_e32 v112, v118, v112
	v_mul_f32_e32 v118, v114, v112
	v_mul_f32_e32 v112, v127, v154
	v_mul_f32_e32 v119, 0xbfb8aa3b, v112
	v_exp_f32_e32 v119, v119
	v_mul_f32_e32 v114, v123, v154
	v_mul_f32_e32 v64, v64, v153
	v_mul_f32_e32 v69, v69, v153
	v_add_f32_e32 v119, 1.0, v119
	v_rcp_f32_e32 v119, v119
	v_mul_f32_e32 v73, v73, v153
	v_mul_f32_e32 v65, v65, v153
	v_mul_f32_e32 v70, v70, v153
	v_mul_f32_e32 v112, v112, v119
	v_mul_f32_e32 v119, v113, v112
	v_mul_f32_e32 v112, 0xbfb8aa3b, v114
	v_exp_f32_e32 v112, v112
	v_mul_f32_e32 v66, v66, v153
	v_mul_f32_e32 v71, v71, v153
	v_mul_f32_e32 v67, v67, v153
	v_add_f32_e32 v112, 1.0, v112
	v_rcp_f32_e32 v112, v112
	v_mul_f32_e32 v60, v60, v150
	v_mul_f32_e32 v52, v52, v150
	v_mul_f32_e32 v56, v56, v150
	v_mul_f32_e32 v112, v114, v112
	v_mul_f32_e32 v123, v115, v112
	v_lshl_add_u64 v[112:113], s[38:39], 0, v[138:139]
	v_cvt_pk_bf16_f32 v114, v116, v117
	v_cvt_pk_bf16_f32 v115, v122, v119
	v_cvt_pk_bf16_f32 v117, v118, v123
	v_mov_b64_e32 v[118:119], s[10:11]
	v_mad_u64_u32 v[118:119], s[38:39], v112, s91, v[118:119]
	s_lshl_b32 s38, s93, 7
	v_mad_i32_i24 v119, v113, s91, v119
	s_ashr_i32 s39, s38, 31
	v_lshl_add_u64 v[112:113], s[38:39], 1, v[118:119]
	v_lshl_add_u64 v[112:113], v[112:113], 0, s[6:7]
	v_lshl_add_u64 v[112:113], v[112:113], 0, v[136:137]
	v_cvt_pk_bf16_f32 v116, v120, v121
	s_waitcnt vmcnt(0)
	global_store_dwordx4 v[112:113], v[114:117], off
	v_mul_f32_e32 v48, v48, v150
	v_mul_f32_e32 v53, v53, v150
	v_mul_f32_e32 v114, 0xbfb8aa3b, v108
	v_exp_f32_e32 v114, v114
	v_mul_f32_e32 v57, v57, v150
	v_mul_f32_e32 v49, v49, v150
	v_mul_f32_e32 v54, v54, v150
	v_add_f32_e32 v114, 1.0, v114
	v_rcp_f32_e32 v114, v114
	v_mul_f32_e32 v50, v50, v150
	v_mul_f32_e32 v55, v55, v150
	v_mul_f32_e32 v51, v51, v150
	v_mul_f32_e32 v108, v108, v114
	v_mul_f32_e32 v100, v100, v108
	v_mul_f32_e32 v108, 0xbfb8aa3b, v104
	v_exp_f32_e32 v108, v108
	v_mul_f32_e32 v44, v44, v151
	v_mul_f32_e32 v36, v36, v151
	v_mul_f32_e32 v40, v40, v151
	v_add_f32_e32 v108, 1.0, v108
	v_rcp_f32_e32 v108, v108
	v_mul_f32_e32 v32, v32, v151
	v_mul_f32_e32 v37, v37, v151
	v_mul_f32_e32 v41, v41, v151
	v_mul_f32_e32 v104, v104, v108
	v_mul_f32_e32 v104, v96, v104
	v_mul_f32_e32 v96, v109, v155
	v_mul_f32_e32 v108, 0xbfb8aa3b, v96
	v_exp_f32_e32 v108, v108
	v_mul_f32_e32 v33, v33, v151
	v_mul_f32_e32 v38, v38, v151
	v_mul_f32_e32 v34, v34, v151
	v_add_f32_e32 v108, 1.0, v108
	v_rcp_f32_e32 v108, v108
	v_mul_f32_e32 v39, v39, v151
	v_mul_f32_e32 v35, v35, v151
	v_mul_f32_e32 v28, v28, v148
	v_mul_f32_e32 v96, v96, v108
	v_mul_f32_e32 v96, v101, v96
	v_mul_f32_e32 v101, 0xbfb8aa3b, v105
	v_exp_f32_e32 v101, v101
	v_cvt_pk_bf16_f32 v96, v100, v96
	v_add_co_u32_e32 v100, vcc, s15, v112
	v_add_f32_e32 v101, 1.0, v101
	v_rcp_f32_e32 v101, v101
	s_mov_b32 s15, 0x2c000
	v_mul_f32_e32 v20, v20, v148
	v_mul_f32_e32 v24, v24, v148
	v_mul_f32_e32 v101, v105, v101
	v_mul_f32_e32 v101, v97, v101
	v_mul_f32_e32 v97, v110, v155
	v_mul_f32_e32 v105, v106, v155
	v_mul_f32_e32 v106, 0xbfb8aa3b, v97
	v_exp_f32_e32 v106, v106
	v_mul_f32_e32 v16, v16, v148
	v_mul_f32_e32 v21, v21, v148
	v_mul_f32_e32 v25, v25, v148
	v_add_f32_e32 v106, 1.0, v106
	v_rcp_f32_e32 v106, v106
	v_mul_f32_e32 v17, v17, v148
	v_mul_f32_e32 v22, v22, v148
	v_mul_f32_e32 v18, v18, v148
	v_mul_f32_e32 v97, v97, v106
	v_mul_f32_e32 v97, v102, v97
	v_mul_f32_e32 v102, 0xbfb8aa3b, v105
	v_exp_f32_e32 v102, v102
	v_mul_f32_e32 v23, v23, v148
	v_mul_f32_e32 v19, v19, v148
	v_mul_f32_e32 v12, v12, v149
	v_add_f32_e32 v102, 1.0, v102
	v_rcp_f32_e32 v102, v102
	v_mul_f32_e32 v4, v4, v149
	v_mul_f32_e32 v8, v8, v149
	v_mul_f32_e32 v0, v0, v149
	v_mul_f32_e32 v102, v105, v102
	v_mul_f32_e32 v102, v98, v102
	v_mul_f32_e32 v98, v111, v155
	v_mul_f32_e32 v106, 0xbfb8aa3b, v98
	v_exp_f32_e32 v106, v106
	v_mul_f32_e32 v105, v107, v155
	v_mul_f32_e32 v5, v5, v149
	v_mul_f32_e32 v9, v9, v149
	v_add_f32_e32 v106, 1.0, v106
	v_rcp_f32_e32 v106, v106
	v_mul_f32_e32 v1, v1, v149
	v_mul_f32_e32 v6, v6, v149
	v_mul_f32_e32 v2, v2, v149
	v_mul_f32_e32 v98, v98, v106
	v_mul_f32_e32 v98, v103, v98
	v_mul_f32_e32 v103, 0xbfb8aa3b, v105
	v_exp_f32_e32 v103, v103
	v_cvt_pk_bf16_f32 v97, v97, v98
	v_cvt_pk_bf16_f32 v98, v104, v101
	v_addc_co_u32_e32 v101, vcc, 0, v113, vcc
	v_add_f32_e32 v103, 1.0, v103
	v_rcp_f32_e32 v103, v103
	v_mul_f32_e32 v7, v7, v149
	v_mul_f32_e32 v3, v3, v149
	s_mov_b32 s38, s18
	v_mul_f32_e32 v103, v105, v103
	v_mul_f32_e32 v99, v99, v103
	v_cvt_pk_bf16_f32 v99, v102, v99
	global_store_dwordx4 v[100:101], v[96:99], off
	s_mov_b32 s93, s14
	s_mov_b64 s[56:57], s[36:37]
	v_mul_f32_e32 v96, 0xbfb8aa3b, v92
	v_exp_f32_e32 v96, v96
	s_mov_b64 s[58:59], s[34:35]
	s_mov_b32 s39, s92
	v_add_f32_e32 v96, 1.0, v96
	v_rcp_f32_e32 v96, v96
	s_nop 0
	v_mul_f32_e32 v92, v92, v96
	v_mul_f32_e32 v84, v84, v92
	v_mul_f32_e32 v92, 0xbfb8aa3b, v88
	v_exp_f32_e32 v92, v92
	s_nop 0
	v_add_f32_e32 v92, 1.0, v92
	v_rcp_f32_e32 v92, v92
	s_nop 0
	v_mul_f32_e32 v88, v88, v92
	v_mul_f32_e32 v88, v80, v88
	v_mul_f32_e32 v80, v93, v152
	v_mul_f32_e32 v92, 0xbfb8aa3b, v80
	v_exp_f32_e32 v92, v92
	s_nop 0
	v_add_f32_e32 v92, 1.0, v92
	v_rcp_f32_e32 v92, v92
	s_nop 0
	v_mul_f32_e32 v80, v80, v92
	v_mul_f32_e32 v80, v85, v80
	v_mul_f32_e32 v85, 0xbfb8aa3b, v89
	v_exp_f32_e32 v85, v85
	v_cvt_pk_bf16_f32 v80, v84, v80
	v_add_co_u32_e32 v84, vcc, s15, v112
	v_add_f32_e32 v85, 1.0, v85
	v_rcp_f32_e32 v85, v85
	s_mov_b32 s15, 0x42000
	v_mul_f32_e32 v85, v89, v85
	v_mul_f32_e32 v85, v81, v85
	v_mul_f32_e32 v81, v94, v152
	v_mul_f32_e32 v89, v90, v152
	v_mul_f32_e32 v90, 0xbfb8aa3b, v81
	v_exp_f32_e32 v90, v90
	s_nop 0
	v_add_f32_e32 v90, 1.0, v90
	v_rcp_f32_e32 v90, v90
	s_nop 0
	v_mul_f32_e32 v81, v81, v90
	v_mul_f32_e32 v81, v86, v81
	v_mul_f32_e32 v86, 0xbfb8aa3b, v89
	v_exp_f32_e32 v86, v86
	s_nop 0
	v_add_f32_e32 v86, 1.0, v86
	v_rcp_f32_e32 v86, v86
	s_nop 0
	v_mul_f32_e32 v86, v89, v86
	v_mul_f32_e32 v86, v82, v86
	v_mul_f32_e32 v82, v95, v152
	v_mul_f32_e32 v90, 0xbfb8aa3b, v82
	v_exp_f32_e32 v90, v90
	v_mul_f32_e32 v89, v91, v152
	v_add_f32_e32 v90, 1.0, v90
	v_rcp_f32_e32 v90, v90
	s_nop 0
	v_mul_f32_e32 v82, v82, v90
	v_mul_f32_e32 v82, v87, v82
	v_mul_f32_e32 v87, 0xbfb8aa3b, v89
	v_exp_f32_e32 v87, v87
	v_cvt_pk_bf16_f32 v81, v81, v82
	v_cvt_pk_bf16_f32 v82, v88, v85
	v_addc_co_u32_e32 v85, vcc, 0, v113, vcc
	v_add_f32_e32 v87, 1.0, v87
	v_rcp_f32_e32 v87, v87
	s_nop 0
	v_mul_f32_e32 v87, v89, v87
	v_mul_f32_e32 v83, v83, v87
	v_cvt_pk_bf16_f32 v83, v86, v83
	global_store_dwordx4 v[84:85], v[80:83], off
	s_nop 1
	v_mul_f32_e32 v80, 0xbfb8aa3b, v76
	v_exp_f32_e32 v80, v80
	s_nop 0
	v_add_f32_e32 v80, 1.0, v80
	v_rcp_f32_e32 v80, v80
	s_nop 0
	v_mul_f32_e32 v76, v76, v80
	v_mul_f32_e32 v68, v68, v76
	v_mul_f32_e32 v76, 0xbfb8aa3b, v72
	v_exp_f32_e32 v76, v76
	s_nop 0
	v_add_f32_e32 v76, 1.0, v76
	v_rcp_f32_e32 v76, v76
	s_nop 0
	v_mul_f32_e32 v72, v72, v76
	v_mul_f32_e32 v72, v64, v72
	v_mul_f32_e32 v64, v77, v153
	v_mul_f32_e32 v76, 0xbfb8aa3b, v64
	v_exp_f32_e32 v76, v76
	s_nop 0
	v_add_f32_e32 v76, 1.0, v76
	v_rcp_f32_e32 v76, v76
	s_nop 0
	v_mul_f32_e32 v64, v64, v76
	v_mul_f32_e32 v64, v69, v64
	v_mul_f32_e32 v69, 0xbfb8aa3b, v73
	v_exp_f32_e32 v69, v69
	v_cvt_pk_bf16_f32 v64, v68, v64
	v_add_co_u32_e32 v68, vcc, s15, v112
	v_add_f32_e32 v69, 1.0, v69
	v_rcp_f32_e32 v69, v69
	s_mov_b32 s15, 0xb0000
	v_mul_f32_e32 v69, v73, v69
	v_mul_f32_e32 v69, v65, v69
	v_mul_f32_e32 v65, v78, v153
	v_mul_f32_e32 v73, v74, v153
	v_mul_f32_e32 v74, 0xbfb8aa3b, v65
	v_exp_f32_e32 v74, v74
	s_nop 0
	v_add_f32_e32 v74, 1.0, v74
	v_rcp_f32_e32 v74, v74
	s_nop 0
	v_mul_f32_e32 v65, v65, v74
	v_mul_f32_e32 v65, v70, v65
	v_mul_f32_e32 v70, 0xbfb8aa3b, v73
	v_exp_f32_e32 v70, v70
	s_nop 0
	v_add_f32_e32 v70, 1.0, v70
	v_rcp_f32_e32 v70, v70
	s_nop 0
	v_mul_f32_e32 v70, v73, v70
	v_mul_f32_e32 v70, v66, v70
	v_mul_f32_e32 v66, v79, v153
	v_mul_f32_e32 v74, 0xbfb8aa3b, v66
	v_exp_f32_e32 v74, v74
	v_mul_f32_e32 v73, v75, v153
	v_add_f32_e32 v74, 1.0, v74
	v_rcp_f32_e32 v74, v74
	s_nop 0
	v_mul_f32_e32 v66, v66, v74
	v_mul_f32_e32 v66, v71, v66
	v_mul_f32_e32 v71, 0xbfb8aa3b, v73
	v_exp_f32_e32 v71, v71
	v_cvt_pk_bf16_f32 v65, v65, v66
	v_cvt_pk_bf16_f32 v66, v72, v69
	v_addc_co_u32_e32 v69, vcc, 0, v113, vcc
	v_add_f32_e32 v71, 1.0, v71
	v_rcp_f32_e32 v71, v71
	s_nop 0
	v_mul_f32_e32 v71, v73, v71
	v_mul_f32_e32 v67, v67, v71
	v_cvt_pk_bf16_f32 v67, v70, v67
	global_store_dwordx4 v[68:69], v[64:67], off
	s_nop 1
	v_mul_f32_e32 v64, 0xbfb8aa3b, v60
	v_exp_f32_e32 v64, v64
	s_nop 0
	v_add_f32_e32 v64, 1.0, v64
	v_rcp_f32_e32 v64, v64
	s_nop 0
	v_mul_f32_e32 v60, v60, v64
	v_mul_f32_e32 v52, v52, v60
	v_mul_f32_e32 v60, 0xbfb8aa3b, v56
	v_exp_f32_e32 v60, v60
	s_nop 0
	v_add_f32_e32 v60, 1.0, v60
	v_rcp_f32_e32 v60, v60
	s_nop 0
	v_mul_f32_e32 v56, v56, v60
	v_mul_f32_e32 v56, v48, v56
	v_mul_f32_e32 v48, v61, v150
	v_mul_f32_e32 v60, 0xbfb8aa3b, v48
	v_exp_f32_e32 v60, v60
	s_nop 0
	v_add_f32_e32 v60, 1.0, v60
	v_rcp_f32_e32 v60, v60
	s_nop 0
	v_mul_f32_e32 v48, v48, v60
	v_mul_f32_e32 v48, v53, v48
	v_mul_f32_e32 v53, 0xbfb8aa3b, v57
	v_exp_f32_e32 v53, v53
	v_cvt_pk_bf16_f32 v48, v52, v48
	v_add_co_u32_e32 v52, vcc, s15, v112
	v_add_f32_e32 v53, 1.0, v53
	v_rcp_f32_e32 v53, v53
	s_mov_b32 s15, 0xc6000
	v_mul_f32_e32 v53, v57, v53
	v_mul_f32_e32 v53, v49, v53
	v_mul_f32_e32 v49, v62, v150
	v_mul_f32_e32 v57, v58, v150
	v_mul_f32_e32 v58, 0xbfb8aa3b, v49
	v_exp_f32_e32 v58, v58
	s_nop 0
	v_add_f32_e32 v58, 1.0, v58
	v_rcp_f32_e32 v58, v58
	s_nop 0
	v_mul_f32_e32 v49, v49, v58
	v_mul_f32_e32 v49, v54, v49
	v_mul_f32_e32 v54, 0xbfb8aa3b, v57
	v_exp_f32_e32 v54, v54
	s_nop 0
	v_add_f32_e32 v54, 1.0, v54
	v_rcp_f32_e32 v54, v54
	s_nop 0
	v_mul_f32_e32 v54, v57, v54
	v_mul_f32_e32 v54, v50, v54
	v_mul_f32_e32 v50, v63, v150
	v_mul_f32_e32 v58, 0xbfb8aa3b, v50
	v_exp_f32_e32 v58, v58
	v_mul_f32_e32 v57, v59, v150
	v_add_f32_e32 v58, 1.0, v58
	v_rcp_f32_e32 v58, v58
	s_nop 0
	v_mul_f32_e32 v50, v50, v58
	v_mul_f32_e32 v50, v55, v50
	v_mul_f32_e32 v55, 0xbfb8aa3b, v57
	v_exp_f32_e32 v55, v55
	v_cvt_pk_bf16_f32 v49, v49, v50
	v_cvt_pk_bf16_f32 v50, v56, v53
	v_addc_co_u32_e32 v53, vcc, 0, v113, vcc
	v_add_f32_e32 v55, 1.0, v55
	v_rcp_f32_e32 v55, v55
	s_nop 0
	v_mul_f32_e32 v55, v57, v55
	v_mul_f32_e32 v51, v51, v55
	v_cvt_pk_bf16_f32 v51, v54, v51
	global_store_dwordx4 v[52:53], v[48:51], off
	s_nop 1
	v_mul_f32_e32 v48, 0xbfb8aa3b, v44
	v_exp_f32_e32 v48, v48
	s_nop 0
	v_add_f32_e32 v48, 1.0, v48
	v_rcp_f32_e32 v48, v48
	s_nop 0
	v_mul_f32_e32 v44, v44, v48
	v_mul_f32_e32 v36, v36, v44
	v_mul_f32_e32 v44, 0xbfb8aa3b, v40
	v_exp_f32_e32 v44, v44
	s_nop 0
	v_add_f32_e32 v44, 1.0, v44
	v_rcp_f32_e32 v44, v44
	s_nop 0
	v_mul_f32_e32 v40, v40, v44
	v_mul_f32_e32 v40, v32, v40
	v_mul_f32_e32 v32, v45, v151
	v_mul_f32_e32 v44, 0xbfb8aa3b, v32
	v_exp_f32_e32 v44, v44
	s_nop 0
	v_add_f32_e32 v44, 1.0, v44
	v_rcp_f32_e32 v44, v44
	s_nop 0
	v_mul_f32_e32 v32, v32, v44
	v_mul_f32_e32 v32, v37, v32
	v_mul_f32_e32 v37, 0xbfb8aa3b, v41
	v_exp_f32_e32 v37, v37
	v_cvt_pk_bf16_f32 v32, v36, v32
	v_add_co_u32_e32 v36, vcc, s15, v112
	v_add_f32_e32 v37, 1.0, v37
	v_rcp_f32_e32 v37, v37
	s_mov_b32 s15, 0xdc000
	v_mul_f32_e32 v37, v41, v37
	v_mul_f32_e32 v37, v33, v37
	v_mul_f32_e32 v33, v46, v151
	v_mul_f32_e32 v41, v42, v151
	v_mul_f32_e32 v42, 0xbfb8aa3b, v33
	v_exp_f32_e32 v42, v42
	s_nop 0
	v_add_f32_e32 v42, 1.0, v42
	v_rcp_f32_e32 v42, v42
	s_nop 0
	v_mul_f32_e32 v33, v33, v42
	v_mul_f32_e32 v33, v38, v33
	v_mul_f32_e32 v38, 0xbfb8aa3b, v41
	v_exp_f32_e32 v38, v38
	s_nop 0
	v_add_f32_e32 v38, 1.0, v38
	v_rcp_f32_e32 v38, v38
	s_nop 0
	v_mul_f32_e32 v38, v41, v38
	v_mul_f32_e32 v38, v34, v38
	v_mul_f32_e32 v34, v47, v151
	v_mul_f32_e32 v42, 0xbfb8aa3b, v34
	v_exp_f32_e32 v42, v42
	v_mul_f32_e32 v41, v43, v151
	v_add_f32_e32 v42, 1.0, v42
	v_rcp_f32_e32 v42, v42
	s_nop 0
	v_mul_f32_e32 v34, v34, v42
	v_mul_f32_e32 v34, v39, v34
	v_mul_f32_e32 v39, 0xbfb8aa3b, v41
	v_exp_f32_e32 v39, v39
	v_cvt_pk_bf16_f32 v33, v33, v34
	v_cvt_pk_bf16_f32 v34, v40, v37
	v_addc_co_u32_e32 v37, vcc, 0, v113, vcc
	v_add_f32_e32 v39, 1.0, v39
	v_rcp_f32_e32 v39, v39
	s_nop 0
	v_mul_f32_e32 v39, v41, v39
	v_mul_f32_e32 v35, v35, v39
	v_cvt_pk_bf16_f32 v35, v38, v35
	global_store_dwordx4 v[36:37], v[32:35], off
	s_nop 1
	v_mul_f32_e32 v32, 0xbfb8aa3b, v28
	v_exp_f32_e32 v32, v32
	s_nop 0
	v_add_f32_e32 v32, 1.0, v32
	v_rcp_f32_e32 v32, v32
	s_nop 0
	v_mul_f32_e32 v28, v28, v32
	v_mul_f32_e32 v20, v20, v28
	v_mul_f32_e32 v28, 0xbfb8aa3b, v24
	v_exp_f32_e32 v28, v28
	s_nop 0
	v_add_f32_e32 v28, 1.0, v28
	v_rcp_f32_e32 v28, v28
	s_nop 0
	v_mul_f32_e32 v24, v24, v28
	v_mul_f32_e32 v24, v16, v24
	v_mul_f32_e32 v16, v29, v148
	v_mul_f32_e32 v28, 0xbfb8aa3b, v16
	v_exp_f32_e32 v28, v28
	s_nop 0
	v_add_f32_e32 v28, 1.0, v28
	v_rcp_f32_e32 v28, v28
	s_nop 0
	v_mul_f32_e32 v16, v16, v28
	v_mul_f32_e32 v16, v21, v16
	v_mul_f32_e32 v21, 0xbfb8aa3b, v25
	v_exp_f32_e32 v21, v21
	v_cvt_pk_bf16_f32 v16, v20, v16
	v_add_co_u32_e32 v20, vcc, s15, v112
	v_add_f32_e32 v21, 1.0, v21
	v_rcp_f32_e32 v21, v21
	s_nop 0
	v_mul_f32_e32 v21, v25, v21
	v_mul_f32_e32 v21, v17, v21
	v_mul_f32_e32 v17, v30, v148
	v_mul_f32_e32 v25, v26, v148
	v_mul_f32_e32 v26, 0xbfb8aa3b, v17
	v_exp_f32_e32 v26, v26
	s_nop 0
	v_add_f32_e32 v26, 1.0, v26
	v_rcp_f32_e32 v26, v26
	s_nop 0
	v_mul_f32_e32 v17, v17, v26
	v_mul_f32_e32 v17, v22, v17
	v_mul_f32_e32 v22, 0xbfb8aa3b, v25
	v_exp_f32_e32 v22, v22
	s_nop 0
	v_add_f32_e32 v22, 1.0, v22
	v_rcp_f32_e32 v22, v22
	s_nop 0
	v_mul_f32_e32 v22, v25, v22
	v_mul_f32_e32 v22, v18, v22
	v_mul_f32_e32 v18, v31, v148
	v_mul_f32_e32 v26, 0xbfb8aa3b, v18
	v_exp_f32_e32 v26, v26
	v_mul_f32_e32 v25, v27, v148
	v_add_f32_e32 v26, 1.0, v26
	v_rcp_f32_e32 v26, v26
	s_nop 0
	v_mul_f32_e32 v18, v18, v26
	v_mul_f32_e32 v18, v23, v18
	v_mul_f32_e32 v23, 0xbfb8aa3b, v25
	v_exp_f32_e32 v23, v23
	v_cvt_pk_bf16_f32 v17, v17, v18
	v_cvt_pk_bf16_f32 v18, v24, v21
	v_addc_co_u32_e32 v21, vcc, 0, v113, vcc
	v_add_f32_e32 v23, 1.0, v23
	v_rcp_f32_e32 v23, v23
	s_nop 0
	v_mul_f32_e32 v23, v25, v23
	v_mul_f32_e32 v19, v19, v23
	v_cvt_pk_bf16_f32 v19, v22, v19
	global_store_dwordx4 v[20:21], v[16:19], off
	s_nop 1
	v_mul_f32_e32 v16, 0xbfb8aa3b, v12
	v_exp_f32_e32 v16, v16
	s_nop 0
	v_add_f32_e32 v16, 1.0, v16
	v_rcp_f32_e32 v16, v16
	s_nop 0
	v_mul_f32_e32 v12, v12, v16
	v_mul_f32_e32 v4, v4, v12
	v_mul_f32_e32 v12, 0xbfb8aa3b, v8
	v_exp_f32_e32 v12, v12
	s_nop 0
	v_add_f32_e32 v12, 1.0, v12
	v_rcp_f32_e32 v12, v12
	s_nop 0
	v_mul_f32_e32 v8, v8, v12
	v_mul_f32_e32 v8, v0, v8
	v_mul_f32_e32 v0, v13, v149
	v_mul_f32_e32 v12, 0xbfb8aa3b, v0
	v_exp_f32_e32 v12, v12
	s_nop 0
	v_add_f32_e32 v12, 1.0, v12
	v_rcp_f32_e32 v12, v12
	s_nop 0
	v_mul_f32_e32 v0, v0, v12
	v_mul_f32_e32 v0, v5, v0
	v_mul_f32_e32 v5, 0xbfb8aa3b, v9
	v_exp_f32_e32 v5, v5
	v_cvt_pk_bf16_f32 v0, v4, v0
	v_add_co_u32_e32 v4, vcc, 0xf2000, v112
	v_add_f32_e32 v5, 1.0, v5
	v_rcp_f32_e32 v5, v5
	s_nop 0
	v_mul_f32_e32 v5, v9, v5
	v_mul_f32_e32 v5, v1, v5
	v_mul_f32_e32 v1, v14, v149
	v_mul_f32_e32 v9, v10, v149
	v_mul_f32_e32 v10, 0xbfb8aa3b, v1
	v_exp_f32_e32 v10, v10
	s_nop 0
	v_add_f32_e32 v10, 1.0, v10
	v_rcp_f32_e32 v10, v10
	s_nop 0
	v_mul_f32_e32 v1, v1, v10
	v_mul_f32_e32 v1, v6, v1
	v_mul_f32_e32 v6, 0xbfb8aa3b, v9
	v_exp_f32_e32 v6, v6
	s_nop 0
	v_add_f32_e32 v6, 1.0, v6
	v_rcp_f32_e32 v6, v6
	s_nop 0
	v_mul_f32_e32 v6, v9, v6
	v_mul_f32_e32 v6, v2, v6
	v_mul_f32_e32 v2, v15, v149
	v_mul_f32_e32 v10, 0xbfb8aa3b, v2
	v_exp_f32_e32 v10, v10
	v_mul_f32_e32 v9, v11, v149
	v_add_f32_e32 v10, 1.0, v10
	v_rcp_f32_e32 v10, v10
	s_nop 0
	v_mul_f32_e32 v2, v2, v10
	v_mul_f32_e32 v2, v7, v2
	v_mul_f32_e32 v7, 0xbfb8aa3b, v9
	v_exp_f32_e32 v7, v7
	v_cvt_pk_bf16_f32 v1, v1, v2
	v_cvt_pk_bf16_f32 v2, v8, v5
	v_addc_co_u32_e32 v5, vcc, 0, v113, vcc
	v_add_f32_e32 v7, 1.0, v7
	v_rcp_f32_e32 v7, v7
	s_and_b64 vcc, exec, s[8:9]
	v_mul_f32_e32 v7, v9, v7
	v_mul_f32_e32 v3, v3, v7
	v_cvt_pk_bf16_f32 v3, v6, v3
	global_store_dwordx4 v[4:5], v[0:3], off
	s_cbranch_vccz .LBB0_313
	v_readlane_b32 s2, v253, 0
	v_readlane_b32 s3, v253, 1
	s_load_dwordx4 s[92:95], s[2:3], 0xe0
	s_waitcnt vmcnt(0)
	s_cmpk_gt_u32 s33, 0xff
	v_readlane_b32 s90, v253, 56
	v_readlane_b32 s91, v253, 57
	s_cbranch_scc1 .LBB0_320
	s_barrier

.LBB0_410:
	s_or_b64 exec, exec, s[36:37]
	s_nop 4
	v_permlane16_swap_b32 v236, v232
	v_permlane16_swap_b32 v237, v233
	v_permlane16_swap_b32 v238, v234
	s_mov_b64 s[36:37], exec
	s_mov_b64 exec, 0xffffffff
	global_store_dword v[236:237], v238, off
	s_mov_b64 exec, s[36:37]
	s_mov_b64 s[18:19], 0xa0
	v_lshl_add_u64 v[50:51], v[166:167], 0, s[18:19]
	s_waitcnt lgkmcnt(0)
	v_lshlrev_b64 v[32:33], 12, v[50:51]
	v_lshl_add_u64 v[32:33], v[168:169], 0, v[32:33]
	global_load_dwordx4 v[52:55], v[32:33], off
	global_load_dwordx4 v[56:59], v[32:33], off offset:64
	global_load_dwordx4 v[60:63], v[32:33], off offset:512
	global_load_dwordx4 v[64:67], v[32:33], off offset:576
	s_mov_b64 s[18:19], 0xb0
	v_lshl_add_u64 v[48:49], v[166:167], 0, s[18:19]
	v_lshlrev_b64 v[32:33], 12, v[48:49]
	v_lshl_add_u64 v[32:33], v[168:169], 0, v[32:33]
	global_load_dwordx4 v[44:47], v[32:33], off
	global_load_dwordx4 v[40:43], v[32:33], off offset:64
	global_load_dwordx4 v[36:39], v[32:33], off offset:512
	s_nop 0
	global_load_dwordx4 v[32:35], v[32:33], off offset:576
	v_lshlrev_b64 v[68:69], 10, v[50:51]
	v_lshl_add_u64 v[68:69], v[68:69], 0, v[164:165]
	s_waitcnt vmcnt(0)
	s_waitcnt vmcnt(0)
	v_pk_fma_f32 v[30:31], v[30:31], 0.5, v[54:55] op_sel_hi:[1,0,1]
	v_lshlrev_b64 v[54:55], 1, v[68:69]
	v_pk_fma_f32 v[28:29], v[28:29], 0.5, v[52:53] op_sel_hi:[1,0,1]
	v_lshl_add_u64 v[52:53], v[68:69], 2, s[78:79]
	v_lshl_add_u64 v[68:69], s[0:1], 0, v[54:55]
	global_store_dwordx4 v[52:53], v[28:31], off
	v_cvt_pk_bf16_f32 v70, v28, v29
	v_cvt_pk_bf16_f32 v71, v30, v31
	s_nop 1
	v_mov_b32_e32 v240, v70
	v_mov_b32_e32 v241, v71
	v_lshl_add_u64 v[244:245], v[68:69], 0, v[246:247]
	v_mul_f32_e32 v68, v28, v28
	v_fmac_f32_e32 v68, v29, v29
	v_pk_fma_f32 v[26:27], v[26:27], 0.5, v[58:59] op_sel_hi:[1,0,1]
	v_pk_fma_f32 v[24:25], v[24:25], 0.5, v[56:57] op_sel_hi:[1,0,1]
	v_fmac_f32_e32 v68, v30, v30
	global_store_dwordx4 v[52:53], v[24:27], off offset:64
	v_cvt_pk_bf16_f32 v30, v24, v25
	v_or_b32_e32 v28, 32, v54
	v_mov_b32_e32 v29, v55
	v_mul_f32_e32 v24, v24, v24
	v_fmac_f32_e32 v24, v25, v25
	v_fmac_f32_e32 v24, v26, v26
	v_fmac_f32_e32 v68, v31, v31
	v_lshl_add_u64 v[28:29], s[0:1], 0, v[28:29]
	v_fmac_f32_e32 v24, v27, v27
	v_pk_fma_f32 v[22:23], v[22:23], 0.5, v[62:63] op_sel_hi:[1,0,1]
	v_pk_fma_f32 v[20:21], v[20:21], 0.5, v[60:61] op_sel_hi:[1,0,1]
	v_cvt_pk_bf16_f32 v31, v26, v27
	v_mov_b32_e32 v242, v30
	v_mov_b32_e32 v243, v31
	s_nop 1
	v_permlane16_swap_b32 v240, v242
	v_permlane16_swap_b32 v241, v243
	global_store_dwordx4 v[244:245], v[240:243], off
	v_add_f32_e32 v28, v68, v24
	global_store_dwordx4 v[52:53], v[20:23], off offset:512
	v_or_b32_e32 v24, 0x100, v54
	v_mov_b32_e32 v25, v55
	v_cvt_pk_bf16_f32 v26, v20, v21
	v_mul_f32_e32 v20, v20, v20
	v_lshl_add_u64 v[24:25], s[0:1], 0, v[24:25]
	v_fmac_f32_e32 v20, v21, v21
	v_pk_fma_f32 v[18:19], v[18:19], 0.5, v[66:67] op_sel_hi:[1,0,1]
	v_pk_fma_f32 v[16:17], v[16:17], 0.5, v[64:65] op_sel_hi:[1,0,1]
	v_cvt_pk_bf16_f32 v27, v22, v23
	s_nop 1
	v_mov_b32_e32 v240, v26
	v_mov_b32_e32 v241, v27
	v_lshl_add_u64 v[244:245], v[24:25], 0, v[246:247]
	v_fmac_f32_e32 v20, v22, v22
	global_store_dwordx4 v[52:53], v[16:19], off offset:576
	v_cvt_pk_bf16_f32 v22, v16, v17
	v_fmac_f32_e32 v20, v23, v23
	v_add_f32_e32 v24, v28, v20
	v_mul_f32_e32 v16, v16, v16
	v_fmac_f32_e32 v16, v17, v17
	v_fmac_f32_e32 v16, v18, v18
	v_fmac_f32_e32 v16, v19, v19
	v_add_f32_e32 v16, v24, v16
	ds_bpermute_b32 v17, v116, v16
	v_or_b32_e32 v54, 0x120, v54
	v_lshl_add_u64 v[20:21], s[0:1], 0, v[54:55]
	v_cvt_pk_bf16_f32 v23, v18, v19
	v_mov_b32_e32 v242, v22
	v_mov_b32_e32 v243, v23
	s_nop 1
	v_permlane16_swap_b32 v240, v242
	v_permlane16_swap_b32 v241, v243
	global_store_dwordx4 v[244:245], v[240:243], off
	s_waitcnt lgkmcnt(0)
	v_add_f32_e32 v16, v16, v17
	ds_bpermute_b32 v17, v117, v16
	s_and_saveexec_b64 s[36:37], s[8:9]
	s_cbranch_execz .LBB0_412
	v_lshlrev_b64 v[18:19], 6, v[50:51]
	v_lshl_add_u64 v[18:19], s[2:3], 0, v[18:19]
	v_lshl_add_u64 v[18:19], s[16:17], 2, v[18:19]
	s_lshl_b32 s6, s83, 2
	v_lshl_add_u64 v[18:19], v[18:19], 0, s[6:7]
	s_waitcnt lgkmcnt(0)
	v_add_f32_e32 v16, v16, v17
	global_store_dword v[18:19], v16, off
.LBB0_412:
	s_or_b64 exec, exec, s[36:37]
	s_waitcnt lgkmcnt(0)
	v_lshlrev_b64 v[16:17], 10, v[48:49]
	v_lshl_add_u64 v[16:17], v[16:17], 0, v[164:165]
	v_lshl_add_u64 v[18:19], v[16:17], 2, s[78:79]
	v_lshlrev_b64 v[16:17], 1, v[16:17]
	v_pk_fma_f32 v[14:15], v[14:15], 0.5, v[46:47] op_sel_hi:[1,0,1]
	v_pk_fma_f32 v[12:13], v[12:13], 0.5, v[44:45] op_sel_hi:[1,0,1]
	v_lshl_add_u64 v[20:21], s[0:1], 0, v[16:17]
	global_store_dwordx4 v[18:19], v[12:15], off
	v_cvt_pk_bf16_f32 v22, v12, v13
	v_cvt_pk_bf16_f32 v23, v14, v15
	s_nop 1
	v_mov_b32_e32 v240, v22
	v_mov_b32_e32 v241, v23
	v_lshl_add_u64 v[244:245], v[20:21], 0, v[246:247]
	v_mul_f32_e32 v20, v12, v12
	v_fmac_f32_e32 v20, v13, v13
	v_pk_fma_f32 v[10:11], v[10:11], 0.5, v[42:43] op_sel_hi:[1,0,1]
	v_pk_fma_f32 v[8:9], v[8:9], 0.5, v[40:41] op_sel_hi:[1,0,1]
	v_fmac_f32_e32 v20, v14, v14
	global_store_dwordx4 v[18:19], v[8:11], off offset:64
	v_or_b32_e32 v12, 32, v16
	v_mov_b32_e32 v13, v17
	v_cvt_pk_bf16_f32 v14, v8, v9
	v_mul_f32_e32 v8, v8, v8
	v_lshl_add_u64 v[12:13], s[0:1], 0, v[12:13]
	v_fmac_f32_e32 v8, v9, v9
	v_pk_fma_f32 v[6:7], v[6:7], 0.5, v[38:39] op_sel_hi:[1,0,1]
	v_pk_fma_f32 v[4:5], v[4:5], 0.5, v[36:37] op_sel_hi:[1,0,1]
	v_fmac_f32_e32 v20, v15, v15
	v_cvt_pk_bf16_f32 v15, v10, v11
	v_mov_b32_e32 v242, v14
	v_mov_b32_e32 v243, v15
	s_nop 1
	v_permlane16_swap_b32 v240, v242
	v_permlane16_swap_b32 v241, v243
	global_store_dwordx4 v[244:245], v[240:243], off
	v_fmac_f32_e32 v8, v10, v10
	global_store_dwordx4 v[18:19], v[4:7], off offset:512
	v_cvt_pk_bf16_f32 v10, v4, v5
	v_fmac_f32_e32 v8, v11, v11
	v_add_f32_e32 v11, v20, v8
	v_mul_f32_e32 v4, v4, v4
	v_fmac_f32_e32 v4, v5, v5
	v_fmac_f32_e32 v4, v6, v6
	v_fmac_f32_e32 v4, v7, v7
	v_add_f32_e32 v11, v11, v4
	v_pk_fma_f32 v[4:5], v[2:3], 0.5, v[34:35] op_sel_hi:[1,0,1]
	v_pk_fma_f32 v[2:3], v[0:1], 0.5, v[32:33] op_sel_hi:[1,0,1]
	v_or_b32_e32 v8, 0x100, v16
	v_mul_f32_e32 v0, v2, v2
	v_fmac_f32_e32 v0, v3, v3
	v_fmac_f32_e32 v0, v4, v4
	v_fmac_f32_e32 v0, v5, v5
	v_add_f32_e32 v0, v11, v0
	ds_bpermute_b32 v1, v116, v0
	v_mov_b32_e32 v9, v17
	v_or_b32_e32 v16, 0x120, v16
	v_lshl_add_u64 v[8:9], s[0:1], 0, v[8:9]
	v_cvt_pk_bf16_f32 v11, v6, v7
	s_waitcnt lgkmcnt(0)
	v_add_f32_e32 v0, v0, v1
	ds_bpermute_b32 v1, v117, v0
	v_lshl_add_u64 v[6:7], s[0:1], 0, v[16:17]
	s_nop 1
	v_mov_b32_e32 v240, v10
	v_mov_b32_e32 v241, v11
	v_lshl_add_u64 v[244:245], v[8:9], 0, v[246:247]
	global_store_dwordx4 v[18:19], v[2:5], off offset:576
	s_nop 1
	v_cvt_pk_bf16_f32 v2, v2, v3
	v_cvt_pk_bf16_f32 v3, v4, v5
	v_mov_b32_e32 v242, v2
	v_mov_b32_e32 v243, v3
	s_nop 1
	v_permlane16_swap_b32 v240, v242
	v_permlane16_swap_b32 v241, v243
	global_store_dwordx4 v[244:245], v[240:243], off
	s_and_saveexec_b64 s[36:37], s[8:9]
	s_cbranch_execz .LBB0_385
	v_lshlrev_b64 v[2:3], 6, v[48:49]
	v_lshl_add_u64 v[2:3], s[2:3], 0, v[2:3]
	v_lshl_add_u64 v[2:3], s[16:17], 2, v[2:3]
	s_lshl_b32 s6, s83, 2
	v_lshl_add_u64 v[2:3], v[2:3], 0, s[6:7]
	s_waitcnt lgkmcnt(0)
	v_add_f32_e32 v0, v0, v1
	global_store_dword v[2:3], v0, off
	s_branch .LBB0_385

.LBB0_420:
	s_add_u32 s2, s61, s0
	s_addc_u32 s3, s62, s1
	v_cmp_gt_i64_e64 s[6:7], s[2:3], 3
	s_mov_b64 s[2:3], -1
	s_and_b64 vcc, exec, s[6:7]
	s_cbranch_vccnz .LBB0_419
	s_and_saveexec_b64 s[2:3], s[8:9]
	s_cbranch_execz .LBB0_418
	s_add_i32 s5, s61, s0
	s_ashr_i32 s6, s5, 31
	s_lshr_b32 s6, s6, 29
	s_add_i32 s6, s5, s6
	s_ashr_i32 s7, s6, 3
	s_and_b32 s6, s6, -8
	s_sub_i32 s5, s5, s6
	s_min_i32 s5, s5, 4
	s_add_i32 s5, s5, s7
	s_ashr_i32 s6, s5, 31
	s_lshr_b32 s6, s6, 28
	s_add_i32 s6, s5, s6
	s_ashr_i32 s7, s6, 4
	s_lshl_b32 s7, s7, 3
	s_sub_i32 s10, 2, s7
	s_min_i32 s10, s10, 8
	s_abs_i32 s10, s10
	v_cvt_f32_u32_e32 v3, s10
	s_sub_i32 s11, 0, s10
	s_and_b32 s6, s6, -16
	s_sub_i32 s5, s5, s6
	v_rcp_iflag_f32_e32 v3, v3
	s_ashr_i32 s6, s5, 31
	s_abs_i32 s5, s5
	v_mul_f32_e32 v3, 0x4f7ffffe, v3
	v_cvt_u32_f32_e32 v3, v3
	s_nop 0
	v_readfirstlane_b32 s12, v3
	s_mul_i32 s11, s11, s12
	s_mul_hi_u32 s11, s12, s11
	s_add_i32 s12, s12, s11
	s_mul_hi_u32 s11, s5, s12
	s_mul_i32 s11, s11, s10
	s_sub_i32 s5, s5, s11
	s_sub_i32 s11, s5, s10
	s_cmp_ge_u32 s5, s10
	s_cselect_b32 s5, s11, s5
	s_sub_i32 s11, s5, s10
	s_cmp_ge_u32 s5, s10
	s_cselect_b32 s5, s11, s5
	s_xor_b32 s5, s5, s6
	s_sub_i32 s5, s5, s6
	s_add_i32 s6, s5, s7
	s_ashr_i32 s7, s6, 31
	s_lshl_b64 s[6:7], s[6:7], 14
	v_lshl_add_u64 v[16:17], v[154:155], 0, s[6:7]
	global_load_dwordx4 v[4:7], v[16:17], off
	global_load_dwordx4 v[8:11], v[16:17], off offset:16
	global_load_dwordx4 v[12:15], v[16:17], off offset:32
	s_nop 0
	global_load_dwordx4 v[16:19], v[16:17], off offset:48
	s_waitcnt vmcnt(0) lgkmcnt(0)
	v_mov_b32_e32 v20, v5
	v_mov_b32_e32 v21, v6
	v_mov_b32_e32 v22, v9
	v_mov_b32_e32 v23, v10
	v_mov_b32_e32 v5, v7
	v_mov_b32_e32 v9, v11
	v_mov_b32_e32 v6, v13
	v_mov_b32_e32 v10, v15
	v_pk_add_f32 v[4:5], v[20:21], v[4:5]
	v_pk_add_f32 v[8:9], v[22:23], v[8:9]
	v_pk_add_f32 v[6:7], v[12:13], v[6:7]
	v_pk_add_f32 v[10:11], v[14:15], v[10:11]
	v_pk_add_f32 v[4:5], v[4:5], v[4:5] op_sel:[0,1] op_sel_hi:[1,0]
	v_pk_add_f32 v[8:9], v[8:9], v[8:9] op_sel:[0,1] op_sel_hi:[1,0]
	v_mov_b32_e32 v7, v18
	v_mov_b32_e32 v11, v19
	v_mov_b32_e32 v5, v16
	v_mov_b32_e32 v9, v17
	v_pk_add_f32 v[6:7], v[6:7], v[10:11]
	v_pk_add_f32 v[4:5], v[4:5], v[8:9]
	s_nop 0
	v_pk_add_f32 v[4:5], v[4:5], v[6:7]
	s_nop 0
	v_add_f32_e32 v3, v4, v5
	v_fmamk_f32 v3, v3, 0x3a800000, v1
	v_mul_f32_e32 v4, 0x4b800000, v3
	v_cmp_gt_f32_e32 vcc, s4, v3
	s_nop 1
	v_cndmask_b32_e32 v3, v3, v4, vcc
	v_rsq_f32_e32 v3, v3
	s_nop 0
	v_mul_f32_e32 v4, 0x45800000, v3
	v_cndmask_b32_e32 v3, v3, v4, vcc
	ds_write_b32 v2, v3
	s_branch .LBB0_418

.LBB0_427:
	global_load_dwordx4 v[120:123], v[158:159], off offset:16
	global_load_dwordx4 v[124:127], v[158:159], off
	global_load_dwordx4 v[112:115], v[158:159], off offset:144
	global_load_dwordx4 v[116:119], v[158:159], off offset:128
	v_and_b32_e32 v169, 64, v205
	v_xor_b32_e32 v168, 16, v205
	v_add_u32_e32 v169, 64, v169
	v_cmp_lt_i32_e32 vcc, v168, v169
	v_mov_b32_e32 v208, v141
	v_mov_b32_e32 v209, v137
	v_cndmask_b32_e32 v168, v205, v168, vcc
	v_lshlrev_b32_e32 v206, 2, v168
	v_xor_b32_e32 v168, 32, v205
	v_cmp_lt_i32_e32 vcc, v168, v169
	v_mov_b32_e32 v169, v136
	v_pk_mul_f32 v[208:209], v[208:209], v[208:209]
	v_cndmask_b32_e32 v168, v205, v168, vcc
	v_lshlrev_b32_e32 v207, 2, v168
	v_mov_b32_e32 v168, v140
	v_pk_fma_f32 v[168:169], v[168:169], v[168:169], v[208:209]
	v_mov_b32_e32 v208, v142
	v_mov_b32_e32 v209, v138
	v_pk_fma_f32 v[168:169], v[208:209], v[208:209], v[168:169]
	v_mov_b32_e32 v208, v143
	v_mov_b32_e32 v209, v139
	v_mov_b32_e32 v210, v133
	v_mov_b32_e32 v211, v129
	v_pk_fma_f32 v[168:169], v[208:209], v[208:209], v[168:169]
	v_mov_b32_e32 v208, v132
	v_mov_b32_e32 v209, v128
	v_pk_mul_f32 v[210:211], v[210:211], v[210:211]
	v_add_f32_e32 v168, v168, v169
	v_pk_fma_f32 v[208:209], v[208:209], v[208:209], v[210:211]
	v_mov_b32_e32 v210, v134
	v_mov_b32_e32 v211, v130
	v_pk_fma_f32 v[208:209], v[210:211], v[210:211], v[208:209]
	v_mov_b32_e32 v210, v135
	v_mov_b32_e32 v211, v131
	v_pk_fma_f32 v[208:209], v[210:211], v[210:211], v[208:209]
	s_waitcnt vmcnt(0)
	ds_read2_b32 v[174:175], v166 offset1:16
	ds_read2_b32 v[172:173], v166 offset0:32 offset1:48
	ds_read2_b32 v[170:171], v166 offset0:128 offset1:144
	ds_read2_b32 v[166:167], v166 offset0:160 offset1:176
	v_add_f32_e32 v168, v168, v208
	v_add_f32_e32 v168, v168, v209
	ds_bpermute_b32 v169, v206, v168
	s_ashr_i32 s15, s14, 31
	s_lshl_b64 s[14:15], s[14:15], 17
	s_waitcnt lgkmcnt(0)
	v_add_f32_e32 v168, v168, v169
	ds_bpermute_b32 v169, v207, v168
	s_waitcnt lgkmcnt(0)
	v_add_f32_e32 v168, v168, v169
	v_mul_f32_e32 v168, v174, v168
	v_mul_f32_e32 v168, v174, v168
	v_fmamk_f32 v168, v168, 0x3c800000, v204
	v_cmp_gt_f32_e32 vcc, s96, v168
	v_mul_f32_e32 v169, 0x4b800000, v168
	s_nop 0
	v_cndmask_b32_e32 v168, v168, v169, vcc
	v_rsq_f32_e32 v168, v168
	s_nop 0
	v_mul_f32_e32 v169, 0x45800000, v168
	v_cndmask_b32_e32 v168, v168, v169, vcc
	v_mul_f32_e32 v174, v174, v168
	v_pk_mul_f32 v[140:141], v[140:141], v[174:175] op_sel_hi:[1,0]
	v_pk_mul_f32 v[142:143], v[142:143], v[174:175] op_sel_hi:[1,0]
	v_pk_mul_f32 v[136:137], v[136:137], v[174:175] op_sel_hi:[1,0]
	v_pk_mul_f32 v[138:139], v[138:139], v[174:175] op_sel_hi:[1,0]
	v_lshl_add_u64 v[168:169], v[160:161], 0, s[14:15]
	v_pk_mul_f32 v[128:129], v[128:129], v[174:175] op_sel_hi:[1,0]
	v_pk_mul_f32 v[130:131], v[130:131], v[174:175] op_sel_hi:[1,0]
	v_pk_mul_f32 v[132:133], v[132:133], v[174:175] op_sel_hi:[1,0]
	v_pk_mul_f32 v[134:135], v[134:135], v[174:175] op_sel_hi:[1,0]
	s_waitcnt vmcnt(0)
	v_pk_mul_f32 v[208:209], v[122:123], v[138:139]
	v_pk_mul_f32 v[142:143], v[126:127], v[142:143]
	v_pk_mul_f32 v[140:141], v[124:125], v[140:141]
	v_pk_mul_f32 v[138:139], v[120:121], v[136:137]
	v_cvt_pk_bf16_f32 v136, v140, v141
	v_cvt_pk_bf16_f32 v137, v142, v143
	v_pk_mul_f32 v[134:135], v[118:119], v[134:135]
	v_cvt_pk_bf16_f32 v138, v138, v139
	v_cvt_pk_bf16_f32 v139, v208, v209
	global_store_dwordx4 v[168:169], v[136:139], off
	v_pk_mul_f32 v[132:133], v[116:117], v[132:133]
	s_nop 0
	v_pk_mul_f32 v[136:137], v[114:115], v[130:131]
	v_pk_mul_f32 v[130:131], v[112:113], v[128:129]
	v_cvt_pk_bf16_f32 v128, v132, v133
	v_cvt_pk_bf16_f32 v129, v134, v135
	v_mov_b32_e32 v132, v101
	v_cvt_pk_bf16_f32 v130, v130, v131
	v_cvt_pk_bf16_f32 v131, v136, v137
	global_store_dwordx4 v[168:169], v[128:131], off offset:64
	v_mov_b32_e32 v133, v97
	v_pk_mul_f32 v[132:133], v[132:133], v[132:133]
	v_mov_b32_e32 v130, v109
	v_mov_b32_e32 v131, v105
	v_mov_b32_e32 v128, v108
	v_mov_b32_e32 v129, v104
	v_pk_mul_f32 v[130:131], v[130:131], v[130:131]
	s_nop 0
	v_pk_fma_f32 v[128:129], v[128:129], v[128:129], v[130:131]
	v_mov_b32_e32 v130, v110
	v_mov_b32_e32 v131, v106
	v_pk_fma_f32 v[128:129], v[130:131], v[130:131], v[128:129]
	v_mov_b32_e32 v130, v111
	v_mov_b32_e32 v131, v107
	v_pk_fma_f32 v[128:129], v[130:131], v[130:131], v[128:129]
	v_mov_b32_e32 v130, v100
	v_mov_b32_e32 v131, v96
	v_pk_fma_f32 v[130:131], v[130:131], v[130:131], v[132:133]
	v_mov_b32_e32 v132, v102
	v_mov_b32_e32 v133, v98
	v_pk_fma_f32 v[130:131], v[132:133], v[132:133], v[130:131]
	v_mov_b32_e32 v132, v103
	v_mov_b32_e32 v133, v99
	v_pk_fma_f32 v[130:131], v[132:133], v[132:133], v[130:131]
	v_add_f32_e32 v128, v128, v129
	v_add_f32_e32 v128, v128, v130
	v_add_f32_e32 v128, v128, v131
	ds_bpermute_b32 v129, v206, v128
	s_waitcnt lgkmcnt(0)
	v_add_f32_e32 v128, v128, v129
	ds_bpermute_b32 v129, v207, v128
	s_waitcnt lgkmcnt(0)
	v_add_f32_e32 v128, v128, v129
	v_mul_f32_e32 v128, v175, v128
	v_mul_f32_e32 v128, v175, v128
	v_fmamk_f32 v128, v128, 0x3c800000, v204
	v_cmp_gt_f32_e32 vcc, s96, v128
	v_mul_f32_e32 v129, 0x4b800000, v128
	s_nop 0
	v_cndmask_b32_e32 v128, v128, v129, vcc
	v_rsq_f32_e32 v128, v128
	s_nop 0
	v_mul_f32_e32 v129, 0x45800000, v128
	v_cndmask_b32_e32 v128, v128, v129, vcc
	v_mul_f32_e32 v128, v175, v128
	v_pk_mul_f32 v[108:109], v[108:109], v[128:129] op_sel_hi:[1,0]
	v_pk_mul_f32 v[104:105], v[104:105], v[128:129] op_sel_hi:[1,0]
	v_pk_mul_f32 v[108:109], v[124:125], v[108:109]
	v_pk_mul_f32 v[106:107], v[106:107], v[128:129] op_sel_hi:[1,0]
	v_pk_mul_f32 v[110:111], v[110:111], v[128:129] op_sel_hi:[1,0]
	v_pk_mul_f32 v[130:131], v[122:123], v[106:107]
	v_pk_mul_f32 v[106:107], v[120:121], v[104:105]
	v_cvt_pk_bf16_f32 v104, v108, v109
	v_add_co_u32_e32 v108, vcc, s83, v168
	v_pk_mul_f32 v[110:111], v[126:127], v[110:111]
	s_nop 0
	v_addc_co_u32_e32 v109, vcc, 0, v169, vcc
	v_cvt_pk_bf16_f32 v105, v110, v111
	v_pk_mul_f32 v[96:97], v[96:97], v[128:129] op_sel_hi:[1,0]
	v_pk_mul_f32 v[98:99], v[98:99], v[128:129] op_sel_hi:[1,0]
	v_cvt_pk_bf16_f32 v106, v106, v107
	v_cvt_pk_bf16_f32 v107, v130, v131
	global_store_dwordx4 v[108:109], v[104:107], off
	v_pk_mul_f32 v[100:101], v[100:101], v[128:129] op_sel_hi:[1,0]
	v_pk_mul_f32 v[102:103], v[102:103], v[128:129] op_sel_hi:[1,0]
	v_pk_mul_f32 v[104:105], v[114:115], v[98:99]
	v_pk_mul_f32 v[98:99], v[112:113], v[96:97]
	v_pk_mul_f32 v[102:103], v[118:119], v[102:103]
	v_cvt_pk_bf16_f32 v98, v98, v99
	v_cvt_pk_bf16_f32 v99, v104, v105
	v_pk_mul_f32 v[100:101], v[116:117], v[100:101]
	v_cvt_pk_bf16_f32 v97, v102, v103
	s_nop 0
	v_cvt_pk_bf16_f32 v96, v100, v101
	global_store_dwordx4 v[108:109], v[96:99], off offset:64
	v_mov_b32_e32 v100, v85
	v_mov_b32_e32 v101, v81
	v_mov_b32_e32 v98, v93
	v_mov_b32_e32 v99, v89
	v_mov_b32_e32 v96, v92
	v_mov_b32_e32 v97, v88
	v_pk_mul_f32 v[98:99], v[98:99], v[98:99]
	v_pk_mul_f32 v[100:101], v[100:101], v[100:101]
	v_pk_fma_f32 v[96:97], v[96:97], v[96:97], v[98:99]
	v_mov_b32_e32 v98, v94
	v_mov_b32_e32 v99, v90
	v_pk_fma_f32 v[96:97], v[98:99], v[98:99], v[96:97]
	v_mov_b32_e32 v98, v95
	v_mov_b32_e32 v99, v91
	v_pk_fma_f32 v[96:97], v[98:99], v[98:99], v[96:97]
	v_mov_b32_e32 v98, v84
	v_mov_b32_e32 v99, v80
	v_pk_fma_f32 v[98:99], v[98:99], v[98:99], v[100:101]
	v_mov_b32_e32 v100, v86
	v_mov_b32_e32 v101, v82
	v_pk_fma_f32 v[98:99], v[100:101], v[100:101], v[98:99]
	v_mov_b32_e32 v100, v87
	v_mov_b32_e32 v101, v83
	v_pk_fma_f32 v[98:99], v[100:101], v[100:101], v[98:99]
	v_add_f32_e32 v96, v96, v97
	v_add_f32_e32 v96, v96, v98
	v_add_f32_e32 v96, v96, v99
	ds_bpermute_b32 v97, v206, v96
	s_waitcnt lgkmcnt(0)
	v_add_f32_e32 v96, v96, v97
	ds_bpermute_b32 v97, v207, v96
	s_waitcnt lgkmcnt(0)
	v_add_f32_e32 v96, v96, v97
	v_mul_f32_e32 v96, v172, v96
	v_mul_f32_e32 v96, v172, v96
	v_fmamk_f32 v96, v96, 0x3c800000, v204
	v_cmp_gt_f32_e32 vcc, s96, v96
	v_mul_f32_e32 v97, 0x4b800000, v96
	s_nop 0
	v_cndmask_b32_e32 v96, v96, v97, vcc
	v_rsq_f32_e32 v96, v96
	s_nop 0
	v_mul_f32_e32 v97, 0x45800000, v96
	v_cndmask_b32_e32 v96, v96, v97, vcc
	v_mul_f32_e32 v96, v172, v96
	v_pk_mul_f32 v[92:93], v[92:93], v[96:97] op_sel_hi:[1,0]
	v_pk_mul_f32 v[88:89], v[88:89], v[96:97] op_sel_hi:[1,0]
	v_pk_mul_f32 v[92:93], v[124:125], v[92:93]
	v_pk_mul_f32 v[90:91], v[90:91], v[96:97] op_sel_hi:[1,0]
	v_pk_mul_f32 v[94:95], v[94:95], v[96:97] op_sel_hi:[1,0]
	v_pk_mul_f32 v[98:99], v[122:123], v[90:91]
	v_pk_mul_f32 v[90:91], v[120:121], v[88:89]
	v_cvt_pk_bf16_f32 v88, v92, v93
	v_add_co_u32_e32 v92, vcc, s86, v168
	v_pk_mul_f32 v[94:95], v[126:127], v[94:95]
	s_nop 0
	v_addc_co_u32_e32 v93, vcc, 0, v169, vcc
	v_cvt_pk_bf16_f32 v89, v94, v95
	v_pk_mul_f32 v[80:81], v[80:81], v[96:97] op_sel_hi:[1,0]
	v_pk_mul_f32 v[82:83], v[82:83], v[96:97] op_sel_hi:[1,0]
	v_cvt_pk_bf16_f32 v90, v90, v91
	v_cvt_pk_bf16_f32 v91, v98, v99
	global_store_dwordx4 v[92:93], v[88:91], off
	v_pk_mul_f32 v[84:85], v[84:85], v[96:97] op_sel_hi:[1,0]
	v_pk_mul_f32 v[86:87], v[86:87], v[96:97] op_sel_hi:[1,0]
	v_pk_mul_f32 v[88:89], v[114:115], v[82:83]
	v_pk_mul_f32 v[82:83], v[112:113], v[80:81]
	v_pk_mul_f32 v[86:87], v[118:119], v[86:87]
	v_cvt_pk_bf16_f32 v82, v82, v83
	v_cvt_pk_bf16_f32 v83, v88, v89
	v_pk_mul_f32 v[84:85], v[116:117], v[84:85]
	v_cvt_pk_bf16_f32 v81, v86, v87
	s_nop 0
	v_cvt_pk_bf16_f32 v80, v84, v85
	global_store_dwordx4 v[92:93], v[80:83], off offset:64
	v_mov_b32_e32 v84, v69
	v_mov_b32_e32 v85, v65
	v_mov_b32_e32 v82, v77
	v_mov_b32_e32 v83, v73
	v_mov_b32_e32 v80, v76
	v_mov_b32_e32 v81, v72
	v_pk_mul_f32 v[82:83], v[82:83], v[82:83]
	v_pk_mul_f32 v[84:85], v[84:85], v[84:85]
	v_pk_fma_f32 v[80:81], v[80:81], v[80:81], v[82:83]
	v_mov_b32_e32 v82, v78
	v_mov_b32_e32 v83, v74
	v_pk_fma_f32 v[80:81], v[82:83], v[82:83], v[80:81]
	v_mov_b32_e32 v82, v79
	v_mov_b32_e32 v83, v75
	v_pk_fma_f32 v[80:81], v[82:83], v[82:83], v[80:81]
	v_mov_b32_e32 v82, v68
	v_mov_b32_e32 v83, v64
	v_pk_fma_f32 v[82:83], v[82:83], v[82:83], v[84:85]
	v_mov_b32_e32 v84, v70
	v_mov_b32_e32 v85, v66
	v_pk_fma_f32 v[82:83], v[84:85], v[84:85], v[82:83]
	v_mov_b32_e32 v84, v71
	v_mov_b32_e32 v85, v67
	v_pk_fma_f32 v[82:83], v[84:85], v[84:85], v[82:83]
	v_add_f32_e32 v80, v80, v81
	v_add_f32_e32 v80, v80, v82
	v_add_f32_e32 v80, v80, v83
	ds_bpermute_b32 v81, v206, v80
	s_waitcnt lgkmcnt(0)
	v_add_f32_e32 v80, v80, v81
	ds_bpermute_b32 v81, v207, v80
	s_waitcnt lgkmcnt(0)
	v_add_f32_e32 v80, v80, v81
	v_mul_f32_e32 v80, v173, v80
	v_mul_f32_e32 v80, v173, v80
	v_fmamk_f32 v80, v80, 0x3c800000, v204
	v_cmp_gt_f32_e32 vcc, s96, v80
	v_mul_f32_e32 v81, 0x4b800000, v80
	s_nop 0
	v_cndmask_b32_e32 v80, v80, v81, vcc
	v_rsq_f32_e32 v80, v80
	s_nop 0
	v_mul_f32_e32 v81, 0x45800000, v80
	v_cndmask_b32_e32 v80, v80, v81, vcc
	v_mul_f32_e32 v80, v173, v80
	v_pk_mul_f32 v[76:77], v[76:77], v[80:81] op_sel_hi:[1,0]
	v_pk_mul_f32 v[72:73], v[72:73], v[80:81] op_sel_hi:[1,0]
	v_pk_mul_f32 v[76:77], v[124:125], v[76:77]
	v_pk_mul_f32 v[74:75], v[74:75], v[80:81] op_sel_hi:[1,0]
	v_pk_mul_f32 v[78:79], v[78:79], v[80:81] op_sel_hi:[1,0]
	v_pk_mul_f32 v[82:83], v[122:123], v[74:75]
	v_pk_mul_f32 v[74:75], v[120:121], v[72:73]
	v_cvt_pk_bf16_f32 v72, v76, v77
	v_add_co_u32_e32 v76, vcc, s87, v168
	v_pk_mul_f32 v[78:79], v[126:127], v[78:79]
	s_nop 0
	v_addc_co_u32_e32 v77, vcc, 0, v169, vcc
	v_cvt_pk_bf16_f32 v73, v78, v79
	v_pk_mul_f32 v[64:65], v[64:65], v[80:81] op_sel_hi:[1,0]
	v_pk_mul_f32 v[66:67], v[66:67], v[80:81] op_sel_hi:[1,0]
	v_cvt_pk_bf16_f32 v74, v74, v75
	v_cvt_pk_bf16_f32 v75, v82, v83
	global_store_dwordx4 v[76:77], v[72:75], off
	v_pk_mul_f32 v[68:69], v[68:69], v[80:81] op_sel_hi:[1,0]
	v_pk_mul_f32 v[70:71], v[70:71], v[80:81] op_sel_hi:[1,0]
	v_pk_mul_f32 v[72:73], v[114:115], v[66:67]
	v_pk_mul_f32 v[66:67], v[112:113], v[64:65]
	v_pk_mul_f32 v[70:71], v[118:119], v[70:71]
	v_cvt_pk_bf16_f32 v66, v66, v67
	v_cvt_pk_bf16_f32 v67, v72, v73
	v_pk_mul_f32 v[68:69], v[116:117], v[68:69]
	v_cvt_pk_bf16_f32 v65, v70, v71
	s_nop 0
	v_cvt_pk_bf16_f32 v64, v68, v69
	global_store_dwordx4 v[76:77], v[64:67], off offset:64
	v_mov_b32_e32 v68, v53
	v_mov_b32_e32 v69, v49
	v_mov_b32_e32 v66, v61
	v_mov_b32_e32 v67, v57
	v_mov_b32_e32 v64, v60
	v_mov_b32_e32 v65, v56
	v_pk_mul_f32 v[66:67], v[66:67], v[66:67]
	v_pk_mul_f32 v[68:69], v[68:69], v[68:69]
	v_pk_fma_f32 v[64:65], v[64:65], v[64:65], v[66:67]
	v_mov_b32_e32 v66, v62
	v_mov_b32_e32 v67, v58
	v_pk_fma_f32 v[64:65], v[66:67], v[66:67], v[64:65]
	v_mov_b32_e32 v66, v63
	v_mov_b32_e32 v67, v59
	v_pk_fma_f32 v[64:65], v[66:67], v[66:67], v[64:65]
	v_mov_b32_e32 v66, v52
	v_mov_b32_e32 v67, v48
	v_pk_fma_f32 v[66:67], v[66:67], v[66:67], v[68:69]
	v_mov_b32_e32 v68, v54
	v_mov_b32_e32 v69, v50
	v_pk_fma_f32 v[66:67], v[68:69], v[68:69], v[66:67]
	v_mov_b32_e32 v68, v55
	v_mov_b32_e32 v69, v51
	v_pk_fma_f32 v[66:67], v[68:69], v[68:69], v[66:67]
	v_add_f32_e32 v64, v64, v65
	v_add_f32_e32 v64, v64, v66
	v_add_f32_e32 v64, v64, v67
	ds_bpermute_b32 v65, v206, v64
	s_waitcnt lgkmcnt(0)
	v_add_f32_e32 v64, v64, v65
	ds_bpermute_b32 v65, v207, v64
	s_waitcnt lgkmcnt(0)
	v_add_f32_e32 v64, v64, v65
	v_mul_f32_e32 v64, v170, v64
	v_mul_f32_e32 v64, v170, v64
	v_fmamk_f32 v64, v64, 0x3c800000, v204
	v_cmp_gt_f32_e32 vcc, s96, v64
	v_mul_f32_e32 v65, 0x4b800000, v64
	s_nop 0
	v_cndmask_b32_e32 v64, v64, v65, vcc
	v_rsq_f32_e32 v64, v64
	s_nop 0
	v_mul_f32_e32 v65, 0x45800000, v64
	v_cndmask_b32_e32 v64, v64, v65, vcc
	v_mul_f32_e32 v64, v170, v64
	v_pk_mul_f32 v[60:61], v[60:61], v[64:65] op_sel_hi:[1,0]
	v_pk_mul_f32 v[56:57], v[56:57], v[64:65] op_sel_hi:[1,0]
	v_pk_mul_f32 v[60:61], v[124:125], v[60:61]
	v_pk_mul_f32 v[58:59], v[58:59], v[64:65] op_sel_hi:[1,0]
	v_pk_mul_f32 v[62:63], v[62:63], v[64:65] op_sel_hi:[1,0]
	v_pk_mul_f32 v[66:67], v[122:123], v[58:59]
	v_pk_mul_f32 v[58:59], v[120:121], v[56:57]
	v_cvt_pk_bf16_f32 v56, v60, v61
	v_add_co_u32_e32 v60, vcc, s81, v168
	v_pk_mul_f32 v[62:63], v[126:127], v[62:63]
	s_nop 0
	v_addc_co_u32_e32 v61, vcc, 0, v169, vcc
	v_cvt_pk_bf16_f32 v57, v62, v63
	v_pk_mul_f32 v[48:49], v[48:49], v[64:65] op_sel_hi:[1,0]
	v_pk_mul_f32 v[50:51], v[50:51], v[64:65] op_sel_hi:[1,0]
	v_cvt_pk_bf16_f32 v58, v58, v59
	v_cvt_pk_bf16_f32 v59, v66, v67
	global_store_dwordx4 v[60:61], v[56:59], off
	v_pk_mul_f32 v[52:53], v[52:53], v[64:65] op_sel_hi:[1,0]
	v_pk_mul_f32 v[54:55], v[54:55], v[64:65] op_sel_hi:[1,0]
	v_pk_mul_f32 v[56:57], v[114:115], v[50:51]
	v_pk_mul_f32 v[50:51], v[112:113], v[48:49]
	v_pk_mul_f32 v[54:55], v[118:119], v[54:55]
	v_cvt_pk_bf16_f32 v50, v50, v51
	v_cvt_pk_bf16_f32 v51, v56, v57
	v_pk_mul_f32 v[52:53], v[116:117], v[52:53]
	v_cvt_pk_bf16_f32 v49, v54, v55
	s_nop 0
	v_cvt_pk_bf16_f32 v48, v52, v53
	global_store_dwordx4 v[60:61], v[48:51], off offset:64
	v_mov_b32_e32 v52, v37
	v_mov_b32_e32 v53, v33
	v_mov_b32_e32 v50, v45
	v_mov_b32_e32 v51, v41
	v_mov_b32_e32 v48, v44
	v_mov_b32_e32 v49, v40
	v_pk_mul_f32 v[50:51], v[50:51], v[50:51]
	v_pk_mul_f32 v[52:53], v[52:53], v[52:53]
	v_pk_fma_f32 v[48:49], v[48:49], v[48:49], v[50:51]
	v_mov_b32_e32 v50, v46
	v_mov_b32_e32 v51, v42
	v_pk_fma_f32 v[48:49], v[50:51], v[50:51], v[48:49]
	v_mov_b32_e32 v50, v47
	v_mov_b32_e32 v51, v43
	v_pk_fma_f32 v[48:49], v[50:51], v[50:51], v[48:49]
	v_mov_b32_e32 v50, v36
	v_mov_b32_e32 v51, v32
	v_pk_fma_f32 v[50:51], v[50:51], v[50:51], v[52:53]
	v_mov_b32_e32 v52, v38
	v_mov_b32_e32 v53, v34
	v_pk_fma_f32 v[50:51], v[52:53], v[52:53], v[50:51]
	v_mov_b32_e32 v52, v39
	v_mov_b32_e32 v53, v35
	v_pk_fma_f32 v[50:51], v[52:53], v[52:53], v[50:51]
	v_add_f32_e32 v48, v48, v49
	v_add_f32_e32 v48, v48, v50
	v_add_f32_e32 v48, v48, v51
	ds_bpermute_b32 v49, v206, v48
	s_waitcnt lgkmcnt(0)
	v_add_f32_e32 v48, v48, v49
	ds_bpermute_b32 v49, v207, v48
	s_waitcnt lgkmcnt(0)
	v_add_f32_e32 v48, v48, v49
	v_mul_f32_e32 v48, v171, v48
	v_mul_f32_e32 v48, v171, v48
	v_fmamk_f32 v48, v48, 0x3c800000, v204
	v_cmp_gt_f32_e32 vcc, s96, v48
	v_mul_f32_e32 v49, 0x4b800000, v48
	s_nop 0
	v_cndmask_b32_e32 v48, v48, v49, vcc
	v_rsq_f32_e32 v48, v48
	s_nop 0
	v_mul_f32_e32 v49, 0x45800000, v48
	v_cndmask_b32_e32 v48, v48, v49, vcc
	v_mul_f32_e32 v48, v171, v48
	v_pk_mul_f32 v[44:45], v[44:45], v[48:49] op_sel_hi:[1,0]
	v_pk_mul_f32 v[40:41], v[40:41], v[48:49] op_sel_hi:[1,0]
	v_pk_mul_f32 v[44:45], v[124:125], v[44:45]
	v_pk_mul_f32 v[42:43], v[42:43], v[48:49] op_sel_hi:[1,0]
	v_pk_mul_f32 v[46:47], v[46:47], v[48:49] op_sel_hi:[1,0]
	v_pk_mul_f32 v[50:51], v[122:123], v[42:43]
	v_pk_mul_f32 v[42:43], v[120:121], v[40:41]
	v_cvt_pk_bf16_f32 v40, v44, v45
	v_add_co_u32_e32 v44, vcc, s82, v168
	v_pk_mul_f32 v[46:47], v[126:127], v[46:47]
	s_nop 0
	v_addc_co_u32_e32 v45, vcc, 0, v169, vcc
	v_cvt_pk_bf16_f32 v41, v46, v47
	v_pk_mul_f32 v[32:33], v[32:33], v[48:49] op_sel_hi:[1,0]
	v_pk_mul_f32 v[34:35], v[34:35], v[48:49] op_sel_hi:[1,0]
	v_cvt_pk_bf16_f32 v42, v42, v43
	v_cvt_pk_bf16_f32 v43, v50, v51
	global_store_dwordx4 v[44:45], v[40:43], off
	v_pk_mul_f32 v[36:37], v[36:37], v[48:49] op_sel_hi:[1,0]
	v_pk_mul_f32 v[38:39], v[38:39], v[48:49] op_sel_hi:[1,0]
	v_pk_mul_f32 v[40:41], v[114:115], v[34:35]
	v_pk_mul_f32 v[34:35], v[112:113], v[32:33]
	v_pk_mul_f32 v[38:39], v[118:119], v[38:39]
	v_cvt_pk_bf16_f32 v34, v34, v35
	v_cvt_pk_bf16_f32 v35, v40, v41
	v_pk_mul_f32 v[36:37], v[116:117], v[36:37]
	v_cvt_pk_bf16_f32 v33, v38, v39
	s_nop 0
	v_cvt_pk_bf16_f32 v32, v36, v37
	global_store_dwordx4 v[44:45], v[32:35], off offset:64
	v_mov_b32_e32 v36, v21
	v_mov_b32_e32 v37, v17
	v_mov_b32_e32 v34, v29
	v_mov_b32_e32 v35, v25
	v_mov_b32_e32 v32, v28
	v_mov_b32_e32 v33, v24
	v_pk_mul_f32 v[34:35], v[34:35], v[34:35]
	v_pk_mul_f32 v[36:37], v[36:37], v[36:37]
	v_pk_fma_f32 v[32:33], v[32:33], v[32:33], v[34:35]
	v_mov_b32_e32 v34, v30
	v_mov_b32_e32 v35, v26
	v_pk_fma_f32 v[32:33], v[34:35], v[34:35], v[32:33]
	v_mov_b32_e32 v34, v31
	v_mov_b32_e32 v35, v27
	v_pk_fma_f32 v[32:33], v[34:35], v[34:35], v[32:33]
	v_mov_b32_e32 v34, v20
	v_mov_b32_e32 v35, v16
	v_pk_fma_f32 v[34:35], v[34:35], v[34:35], v[36:37]
	v_mov_b32_e32 v36, v22
	v_mov_b32_e32 v37, v18
	v_pk_fma_f32 v[34:35], v[36:37], v[36:37], v[34:35]
	v_mov_b32_e32 v36, v23
	v_mov_b32_e32 v37, v19
	v_pk_fma_f32 v[34:35], v[36:37], v[36:37], v[34:35]
	v_add_f32_e32 v32, v32, v33
	v_add_f32_e32 v32, v32, v34
	v_add_f32_e32 v32, v32, v35
	ds_bpermute_b32 v33, v206, v32
	s_waitcnt lgkmcnt(0)
	v_add_f32_e32 v32, v32, v33
	ds_bpermute_b32 v33, v207, v32
	s_waitcnt lgkmcnt(0)
	v_add_f32_e32 v32, v32, v33
	v_mul_f32_e32 v32, v166, v32
	v_mul_f32_e32 v32, v166, v32
	v_fmamk_f32 v32, v32, 0x3c800000, v204
	v_cmp_gt_f32_e32 vcc, s96, v32
	v_mul_f32_e32 v33, 0x4b800000, v32
	s_nop 0
	v_cndmask_b32_e32 v32, v32, v33, vcc
	v_rsq_f32_e32 v32, v32
	s_nop 0
	v_mul_f32_e32 v33, 0x45800000, v32
	v_cndmask_b32_e32 v32, v32, v33, vcc
	v_mul_f32_e32 v32, v166, v32
	v_pk_mul_f32 v[28:29], v[28:29], v[32:33] op_sel_hi:[1,0]
	v_pk_mul_f32 v[24:25], v[24:25], v[32:33] op_sel_hi:[1,0]
	v_pk_mul_f32 v[28:29], v[124:125], v[28:29]
	v_pk_mul_f32 v[26:27], v[26:27], v[32:33] op_sel_hi:[1,0]
	v_pk_mul_f32 v[30:31], v[30:31], v[32:33] op_sel_hi:[1,0]
	v_pk_mul_f32 v[34:35], v[122:123], v[26:27]
	v_pk_mul_f32 v[26:27], v[120:121], v[24:25]
	v_cvt_pk_bf16_f32 v24, v28, v29
	v_add_co_u32_e32 v28, vcc, s84, v168
	v_pk_mul_f32 v[30:31], v[126:127], v[30:31]
	s_nop 0
	v_addc_co_u32_e32 v29, vcc, 0, v169, vcc
	v_cvt_pk_bf16_f32 v25, v30, v31
	v_pk_mul_f32 v[16:17], v[16:17], v[32:33] op_sel_hi:[1,0]
	v_pk_mul_f32 v[18:19], v[18:19], v[32:33] op_sel_hi:[1,0]
	v_cvt_pk_bf16_f32 v26, v26, v27
	v_cvt_pk_bf16_f32 v27, v34, v35
	global_store_dwordx4 v[28:29], v[24:27], off
	v_pk_mul_f32 v[20:21], v[20:21], v[32:33] op_sel_hi:[1,0]
	v_pk_mul_f32 v[22:23], v[22:23], v[32:33] op_sel_hi:[1,0]
	v_pk_mul_f32 v[24:25], v[114:115], v[18:19]
	v_pk_mul_f32 v[18:19], v[112:113], v[16:17]
	v_pk_mul_f32 v[22:23], v[118:119], v[22:23]
	v_cvt_pk_bf16_f32 v18, v18, v19
	v_cvt_pk_bf16_f32 v19, v24, v25
	v_pk_mul_f32 v[20:21], v[116:117], v[20:21]
	v_cvt_pk_bf16_f32 v17, v22, v23
	s_nop 0
	v_cvt_pk_bf16_f32 v16, v20, v21
	global_store_dwordx4 v[28:29], v[16:19], off offset:64
	v_mov_b32_e32 v20, v5
	v_mov_b32_e32 v21, v1
	v_mov_b32_e32 v18, v13
	v_mov_b32_e32 v19, v9
	v_mov_b32_e32 v16, v12
	v_mov_b32_e32 v17, v8
	v_pk_mul_f32 v[18:19], v[18:19], v[18:19]
	v_pk_mul_f32 v[20:21], v[20:21], v[20:21]
	v_pk_fma_f32 v[16:17], v[16:17], v[16:17], v[18:19]
	v_mov_b32_e32 v18, v14
	v_mov_b32_e32 v19, v10
	v_pk_fma_f32 v[16:17], v[18:19], v[18:19], v[16:17]
	v_mov_b32_e32 v18, v15
	v_mov_b32_e32 v19, v11
	v_pk_fma_f32 v[16:17], v[18:19], v[18:19], v[16:17]
	v_mov_b32_e32 v18, v4
	v_mov_b32_e32 v19, v0
	v_pk_fma_f32 v[18:19], v[18:19], v[18:19], v[20:21]
	v_mov_b32_e32 v20, v6
	v_mov_b32_e32 v21, v2
	v_pk_fma_f32 v[18:19], v[20:21], v[20:21], v[18:19]
	v_mov_b32_e32 v20, v7
	v_mov_b32_e32 v21, v3
	v_pk_fma_f32 v[18:19], v[20:21], v[20:21], v[18:19]
	v_add_f32_e32 v16, v16, v17
	v_add_f32_e32 v16, v16, v18
	v_add_f32_e32 v16, v16, v19
	ds_bpermute_b32 v17, v206, v16
	s_waitcnt lgkmcnt(0)
	v_add_f32_e32 v16, v16, v17
	ds_bpermute_b32 v17, v207, v16
	s_waitcnt lgkmcnt(0)
	v_add_f32_e32 v16, v16, v17
	v_mul_f32_e32 v16, v167, v16
	v_mul_f32_e32 v16, v167, v16
	v_fmamk_f32 v16, v16, 0x3c800000, v204
	v_cmp_gt_f32_e32 vcc, s96, v16
	v_mul_f32_e32 v17, 0x4b800000, v16
	s_nop 0
	v_cndmask_b32_e32 v16, v16, v17, vcc
	v_rsq_f32_e32 v16, v16
	s_nop 0
	v_mul_f32_e32 v17, 0x45800000, v16
	v_cndmask_b32_e32 v16, v16, v17, vcc
	v_mul_f32_e32 v16, v167, v16
	v_pk_mul_f32 v[12:13], v[12:13], v[16:17] op_sel_hi:[1,0]
	v_pk_mul_f32 v[8:9], v[8:9], v[16:17] op_sel_hi:[1,0]
	v_pk_mul_f32 v[12:13], v[124:125], v[12:13]
	v_pk_mul_f32 v[10:11], v[10:11], v[16:17] op_sel_hi:[1,0]
	v_pk_mul_f32 v[14:15], v[14:15], v[16:17] op_sel_hi:[1,0]
	v_pk_mul_f32 v[18:19], v[122:123], v[10:11]
	v_pk_mul_f32 v[10:11], v[120:121], v[8:9]
	v_cvt_pk_bf16_f32 v8, v12, v13
	v_add_co_u32_e32 v12, vcc, s85, v168
	v_pk_mul_f32 v[14:15], v[126:127], v[14:15]
	s_nop 0
	v_addc_co_u32_e32 v13, vcc, 0, v169, vcc
	v_cvt_pk_bf16_f32 v9, v14, v15
	v_pk_mul_f32 v[0:1], v[0:1], v[16:17] op_sel_hi:[1,0]
	v_pk_mul_f32 v[2:3], v[2:3], v[16:17] op_sel_hi:[1,0]
	v_cvt_pk_bf16_f32 v10, v10, v11
	v_cvt_pk_bf16_f32 v11, v18, v19
	global_store_dwordx4 v[12:13], v[8:11], off
	v_pk_mul_f32 v[4:5], v[4:5], v[16:17] op_sel_hi:[1,0]
	v_pk_mul_f32 v[6:7], v[6:7], v[16:17] op_sel_hi:[1,0]
	v_pk_mul_f32 v[8:9], v[114:115], v[2:3]
	v_pk_mul_f32 v[2:3], v[112:113], v[0:1]
	v_pk_mul_f32 v[6:7], v[118:119], v[6:7]
	v_pk_mul_f32 v[4:5], v[116:117], v[4:5]
	v_cvt_pk_bf16_f32 v1, v6, v7
	v_cvt_pk_bf16_f32 v2, v2, v3
	v_cvt_pk_bf16_f32 v3, v8, v9
	s_nop 0
	v_cvt_pk_bf16_f32 v0, v4, v5
	global_store_dwordx4 v[12:13], v[0:3], off offset:64

.LBB0_432:
	ds_read_b128 v[112:115], v153
	ds_read_b128 v[116:119], v189
	ds_read_b128 v[120:123], v190
	ds_read_b128 v[124:127], v191
	s_add_u32 s20, s16, 0xfffc0080
	s_addc_u32 s21, s17, -1
	s_cmp_eq_u32 s33, 12
	s_cselect_b32 s39, s7, s21
	s_cselect_b32 s38, vcc_lo, s20
	s_cselect_b32 s37, s5, s19
	s_cselect_b32 s36, vcc_hi, s18
	s_mov_b32 m0, s94
	v_lshl_add_u64 v[174:175], s[16:17], 0, v[164:165]
	ds_read_b128 v[166:169], v185
	ds_read_b128 v[170:173], v185 offset:1024
	ds_read_b128 v[206:209], v185 offset:2048
	ds_read_b128 v[210:213], v185 offset:3072
	ds_read_b128 v[214:217], v185 offset:4096
	ds_read_b128 v[218:221], v185 offset:5120
	ds_read_b128 v[222:225], v185 offset:6144
	ds_read_b128 v[226:229], v185 offset:7168
	global_load_lds_dwordx4 v[174:175], off
	v_lshl_add_u64 v[174:175], s[16:17], 0, v[162:163]
	s_mov_b32 m0, s95
	s_nop 0
	global_load_lds_dwordx4 v[174:175], off
	s_waitcnt lgkmcnt(8)
	s_barrier
	s_waitcnt lgkmcnt(0)
	s_setprio 1
	s_waitcnt lgkmcnt(0)
	v_mfma_f32_16x16x32_bf16 v[140:143], v[112:115], v[166:169], v[140:143]
	v_mfma_f32_16x16x32_bf16 v[136:139], v[120:123], v[166:169], v[136:139]
	v_mfma_f32_16x16x32_bf16 v[108:111], v[112:115], v[206:209], v[108:111]
	v_mfma_f32_16x16x32_bf16 v[104:107], v[120:123], v[206:209], v[104:107]
	v_mfma_f32_16x16x32_bf16 v[92:95], v[112:115], v[214:217], v[92:95]
	v_mfma_f32_16x16x32_bf16 v[88:91], v[120:123], v[214:217], v[88:91]
	v_mfma_f32_16x16x32_bf16 v[76:79], v[112:115], v[222:225], v[76:79]
	v_mfma_f32_16x16x32_bf16 v[72:75], v[120:123], v[222:225], v[72:75]
	v_mfma_f32_16x16x32_bf16 v[140:143], v[116:119], v[170:173], v[140:143]
	v_mfma_f32_16x16x32_bf16 v[136:139], v[124:127], v[170:173], v[136:139]
	v_mfma_f32_16x16x32_bf16 v[108:111], v[116:119], v[210:213], v[108:111]
	v_mfma_f32_16x16x32_bf16 v[104:107], v[124:127], v[210:213], v[104:107]
	v_mfma_f32_16x16x32_bf16 v[92:95], v[116:119], v[218:221], v[92:95]
	v_mfma_f32_16x16x32_bf16 v[88:91], v[124:127], v[218:221], v[88:91]
	v_mfma_f32_16x16x32_bf16 v[76:79], v[116:119], v[226:229], v[76:79]
	v_mfma_f32_16x16x32_bf16 v[72:75], v[124:127], v[226:229], v[72:75]
	s_setprio 0
	s_barrier
	s_mov_b32 m0, s66
	v_lshl_add_u64 v[174:175], s[36:37], 0, v[146:147]
	ds_read_b128 v[230:233], v192
	ds_read_b128 v[234:237], v193
	ds_read_b128 v[238:241], v194
	ds_read_b128 v[242:245], v195
	global_load_lds_dwordx4 v[174:175], off
	v_lshl_add_u64 v[246:247], s[36:37], 0, v[150:151]
	s_mov_b32 m0, s67
	s_nop 0
	global_load_lds_dwordx4 v[246:247], off
	s_barrier
	s_waitcnt lgkmcnt(0)
	s_setprio 1
	s_waitcnt lgkmcnt(0)
	v_mfma_f32_16x16x32_bf16 v[132:135], v[230:233], v[166:169], v[132:135]
	v_mfma_f32_16x16x32_bf16 v[128:131], v[238:241], v[166:169], v[128:131]
	v_mfma_f32_16x16x32_bf16 v[100:103], v[230:233], v[206:209], v[100:103]
	v_mfma_f32_16x16x32_bf16 v[96:99], v[238:241], v[206:209], v[96:99]
	v_mfma_f32_16x16x32_bf16 v[84:87], v[230:233], v[214:217], v[84:87]
	v_mfma_f32_16x16x32_bf16 v[80:83], v[238:241], v[214:217], v[80:83]
	v_mfma_f32_16x16x32_bf16 v[68:71], v[230:233], v[222:225], v[68:71]
	v_mfma_f32_16x16x32_bf16 v[64:67], v[238:241], v[222:225], v[64:67]
	v_mfma_f32_16x16x32_bf16 v[132:135], v[234:237], v[170:173], v[132:135]
	v_mfma_f32_16x16x32_bf16 v[128:131], v[242:245], v[170:173], v[128:131]
	v_mfma_f32_16x16x32_bf16 v[100:103], v[234:237], v[210:213], v[100:103]
	v_mfma_f32_16x16x32_bf16 v[96:99], v[242:245], v[210:213], v[96:99]
	v_mfma_f32_16x16x32_bf16 v[84:87], v[234:237], v[218:221], v[84:87]
	v_mfma_f32_16x16x32_bf16 v[80:83], v[242:245], v[218:221], v[80:83]
	v_mfma_f32_16x16x32_bf16 v[68:71], v[234:237], v[226:229], v[68:71]
	v_mfma_f32_16x16x32_bf16 v[64:67], v[242:245], v[226:229], v[64:67]
	s_setprio 0
	s_mov_b32 m0, s65
	v_lshl_add_u64 v[248:249], s[38:39], 0, v[144:145]
	s_barrier
	ds_read_b128 v[166:169], v185 offset:16384
	ds_read_b128 v[170:173], v185 offset:17408
	ds_read_b128 v[206:209], v185 offset:18432
	ds_read_b128 v[210:213], v185 offset:19456
	ds_read_b128 v[214:217], v185 offset:20480
	ds_read_b128 v[218:221], v185 offset:21504
	ds_read_b128 v[222:225], v185 offset:22528
	ds_read_b128 v[226:229], v185 offset:23552
	global_load_lds_dwordx4 v[248:249], off
	v_lshl_add_u64 v[250:251], s[38:39], 0, v[148:149]
	s_mov_b32 m0, s68
	s_nop 0
	global_load_lds_dwordx4 v[250:251], off
	s_barrier
	s_waitcnt lgkmcnt(0)
	s_setprio 1
	s_waitcnt lgkmcnt(0)
	v_mfma_f32_16x16x32_bf16 v[60:63], v[112:115], v[166:169], v[60:63]
	v_mfma_f32_16x16x32_bf16 v[56:59], v[120:123], v[166:169], v[56:59]
	v_mfma_f32_16x16x32_bf16 v[44:47], v[112:115], v[206:209], v[44:47]
	v_mfma_f32_16x16x32_bf16 v[40:43], v[120:123], v[206:209], v[40:43]
	v_mfma_f32_16x16x32_bf16 v[28:31], v[112:115], v[214:217], v[28:31]
	v_mfma_f32_16x16x32_bf16 v[24:27], v[120:123], v[214:217], v[24:27]
	v_mfma_f32_16x16x32_bf16 v[12:15], v[112:115], v[222:225], v[12:15]
	v_mfma_f32_16x16x32_bf16 v[8:11], v[120:123], v[222:225], v[8:11]
	v_mfma_f32_16x16x32_bf16 v[60:63], v[116:119], v[170:173], v[60:63]
	v_mfma_f32_16x16x32_bf16 v[56:59], v[124:127], v[170:173], v[56:59]
	v_mfma_f32_16x16x32_bf16 v[44:47], v[116:119], v[210:213], v[44:47]
	v_mfma_f32_16x16x32_bf16 v[40:43], v[124:127], v[210:213], v[40:43]
	v_mfma_f32_16x16x32_bf16 v[28:31], v[116:119], v[218:221], v[28:31]
	v_mfma_f32_16x16x32_bf16 v[24:27], v[124:127], v[218:221], v[24:27]
	v_mfma_f32_16x16x32_bf16 v[12:15], v[116:119], v[226:229], v[12:15]
	v_mfma_f32_16x16x32_bf16 v[8:11], v[124:127], v[226:229], v[8:11]
	s_setprio 0
	s_barrier
	s_add_u32 s20, s36, 0x40000
	s_addc_u32 s21, s37, 0
	s_mov_b32 m0, s69
	v_lshl_add_u64 v[112:113], s[20:21], 0, v[146:147]
	global_load_lds_dwordx4 v[112:113], off
	v_lshl_add_u64 v[112:113], s[20:21], 0, v[150:151]
	s_mov_b32 m0, s70
	s_nop 0
	global_load_lds_dwordx4 v[112:113], off
	s_waitcnt vmcnt(6)
	s_barrier
	s_setprio 1
	v_mfma_f32_16x16x32_bf16 v[52:55], v[230:233], v[166:169], v[52:55]
	v_mfma_f32_16x16x32_bf16 v[48:51], v[238:241], v[166:169], v[48:51]
	v_mfma_f32_16x16x32_bf16 v[36:39], v[230:233], v[206:209], v[36:39]
	v_mfma_f32_16x16x32_bf16 v[32:35], v[238:241], v[206:209], v[32:35]
	v_mfma_f32_16x16x32_bf16 v[20:23], v[230:233], v[214:217], v[20:23]
	v_mfma_f32_16x16x32_bf16 v[16:19], v[238:241], v[214:217], v[16:19]
	v_mfma_f32_16x16x32_bf16 v[4:7], v[230:233], v[222:225], v[4:7]
	v_mfma_f32_16x16x32_bf16 v[0:3], v[238:241], v[222:225], v[0:3]
	v_mfma_f32_16x16x32_bf16 v[52:55], v[234:237], v[170:173], v[52:55]
	v_mfma_f32_16x16x32_bf16 v[48:51], v[242:245], v[170:173], v[48:51]
	v_mfma_f32_16x16x32_bf16 v[36:39], v[234:237], v[210:213], v[36:39]
	v_mfma_f32_16x16x32_bf16 v[32:35], v[242:245], v[210:213], v[32:35]
	v_mfma_f32_16x16x32_bf16 v[20:23], v[234:237], v[218:221], v[20:23]
	v_mfma_f32_16x16x32_bf16 v[16:19], v[242:245], v[218:221], v[16:19]
	v_mfma_f32_16x16x32_bf16 v[4:7], v[234:237], v[226:229], v[4:7]
	v_mfma_f32_16x16x32_bf16 v[0:3], v[242:245], v[226:229], v[0:3]
	s_setprio 0
	s_barrier
	ds_read_b128 v[112:115], v196
	ds_read_b128 v[116:119], v197
	ds_read_b128 v[120:123], v198
	ds_read_b128 v[124:127], v199
	s_add_u32 s20, s38, 0x40000
	s_addc_u32 s21, s39, 0
	s_mov_b32 m0, s71
	v_lshl_add_u64 v[230:231], s[20:21], 0, v[144:145]
	ds_read_b128 v[166:169], v185 offset:32768
	ds_read_b128 v[170:173], v185 offset:33792
	ds_read_b128 v[206:209], v185 offset:34816
	ds_read_b128 v[210:213], v185 offset:35840
	ds_read_b128 v[214:217], v185 offset:36864
	ds_read_b128 v[218:221], v185 offset:37888
	ds_read_b128 v[222:225], v185 offset:38912
	ds_read_b128 v[226:229], v185 offset:39936
	global_load_lds_dwordx4 v[230:231], off
	v_lshl_add_u64 v[230:231], s[20:21], 0, v[148:149]
	s_mov_b32 m0, s80
	s_nop 0
	global_load_lds_dwordx4 v[230:231], off
	s_waitcnt lgkmcnt(8)
	s_barrier
	s_waitcnt lgkmcnt(0)
	s_setprio 1
	s_waitcnt lgkmcnt(0)
	v_mfma_f32_16x16x32_bf16 v[140:143], v[112:115], v[166:169], v[140:143]
	v_mfma_f32_16x16x32_bf16 v[136:139], v[120:123], v[166:169], v[136:139]
	v_mfma_f32_16x16x32_bf16 v[108:111], v[112:115], v[206:209], v[108:111]
	v_mfma_f32_16x16x32_bf16 v[104:107], v[120:123], v[206:209], v[104:107]
	v_mfma_f32_16x16x32_bf16 v[92:95], v[112:115], v[214:217], v[92:95]
	v_mfma_f32_16x16x32_bf16 v[88:91], v[120:123], v[214:217], v[88:91]
	v_mfma_f32_16x16x32_bf16 v[76:79], v[112:115], v[222:225], v[76:79]
	v_mfma_f32_16x16x32_bf16 v[72:75], v[120:123], v[222:225], v[72:75]
	v_mfma_f32_16x16x32_bf16 v[140:143], v[116:119], v[170:173], v[140:143]
	v_mfma_f32_16x16x32_bf16 v[136:139], v[124:127], v[170:173], v[136:139]
	v_mfma_f32_16x16x32_bf16 v[108:111], v[116:119], v[210:213], v[108:111]
	v_mfma_f32_16x16x32_bf16 v[104:107], v[124:127], v[210:213], v[104:107]
	v_mfma_f32_16x16x32_bf16 v[92:95], v[116:119], v[218:221], v[92:95]
	v_mfma_f32_16x16x32_bf16 v[88:91], v[124:127], v[218:221], v[88:91]
	v_mfma_f32_16x16x32_bf16 v[76:79], v[116:119], v[226:229], v[76:79]
	v_mfma_f32_16x16x32_bf16 v[72:75], v[124:127], v[226:229], v[72:75]
	s_setprio 0
	s_barrier
	s_mov_b32 m0, s88
	v_lshl_add_u64 v[174:175], v[174:175], 0, s[0:1]
	ds_read_b128 v[230:233], v200
	ds_read_b128 v[234:237], v201
	ds_read_b128 v[238:241], v202
	ds_read_b128 v[242:245], v203
	global_load_lds_dwordx4 v[174:175], off
	v_lshl_add_u64 v[174:175], v[246:247], 0, s[0:1]
	s_mov_b32 m0, s89
	s_nop 0
	global_load_lds_dwordx4 v[174:175], off
	s_barrier
	s_waitcnt lgkmcnt(0)
	s_setprio 1
	s_waitcnt lgkmcnt(0)
	v_mfma_f32_16x16x32_bf16 v[132:135], v[230:233], v[166:169], v[132:135]
	v_mfma_f32_16x16x32_bf16 v[128:131], v[238:241], v[166:169], v[128:131]
	v_mfma_f32_16x16x32_bf16 v[100:103], v[230:233], v[206:209], v[100:103]
	v_mfma_f32_16x16x32_bf16 v[96:99], v[238:241], v[206:209], v[96:99]
	v_mfma_f32_16x16x32_bf16 v[84:87], v[230:233], v[214:217], v[84:87]
	v_mfma_f32_16x16x32_bf16 v[80:83], v[238:241], v[214:217], v[80:83]
	v_mfma_f32_16x16x32_bf16 v[68:71], v[230:233], v[222:225], v[68:71]
	v_mfma_f32_16x16x32_bf16 v[64:67], v[238:241], v[222:225], v[64:67]
	v_mfma_f32_16x16x32_bf16 v[132:135], v[234:237], v[170:173], v[132:135]
	v_mfma_f32_16x16x32_bf16 v[128:131], v[242:245], v[170:173], v[128:131]
	v_mfma_f32_16x16x32_bf16 v[100:103], v[234:237], v[210:213], v[100:103]
	v_mfma_f32_16x16x32_bf16 v[96:99], v[242:245], v[210:213], v[96:99]
	v_mfma_f32_16x16x32_bf16 v[84:87], v[234:237], v[218:221], v[84:87]
	v_mfma_f32_16x16x32_bf16 v[80:83], v[242:245], v[218:221], v[80:83]
	v_mfma_f32_16x16x32_bf16 v[68:71], v[234:237], v[226:229], v[68:71]
	v_mfma_f32_16x16x32_bf16 v[64:67], v[242:245], v[226:229], v[64:67]
	s_setprio 0
	s_mov_b32 m0, s90
	v_lshl_add_u64 v[174:175], v[248:249], 0, s[0:1]
	s_barrier
	ds_read_b128 v[166:169], v185 offset:49152
	ds_read_b128 v[170:173], v185 offset:50176
	ds_read_b128 v[206:209], v185 offset:51200
	ds_read_b128 v[210:213], v185 offset:52224
	ds_read_b128 v[214:217], v185 offset:53248
	ds_read_b128 v[218:221], v185 offset:54272
	ds_read_b128 v[222:225], v185 offset:55296
	ds_read_b128 v[226:229], v185 offset:56320
	global_load_lds_dwordx4 v[174:175], off
	v_lshl_add_u64 v[174:175], v[250:251], 0, s[0:1]
	s_mov_b32 m0, s91
	s_nop 0
	global_load_lds_dwordx4 v[174:175], off
	s_barrier
	s_waitcnt lgkmcnt(0)
	s_setprio 1
	s_waitcnt lgkmcnt(0)
	v_mfma_f32_16x16x32_bf16 v[60:63], v[112:115], v[166:169], v[60:63]
	v_mfma_f32_16x16x32_bf16 v[56:59], v[120:123], v[166:169], v[56:59]
	v_mfma_f32_16x16x32_bf16 v[44:47], v[112:115], v[206:209], v[44:47]
	v_mfma_f32_16x16x32_bf16 v[40:43], v[120:123], v[206:209], v[40:43]
	v_mfma_f32_16x16x32_bf16 v[28:31], v[112:115], v[214:217], v[28:31]
	v_mfma_f32_16x16x32_bf16 v[24:27], v[120:123], v[214:217], v[24:27]
	v_mfma_f32_16x16x32_bf16 v[12:15], v[112:115], v[222:225], v[12:15]
	v_mfma_f32_16x16x32_bf16 v[8:11], v[120:123], v[222:225], v[8:11]
	v_mfma_f32_16x16x32_bf16 v[60:63], v[116:119], v[170:173], v[60:63]
	v_mfma_f32_16x16x32_bf16 v[56:59], v[124:127], v[170:173], v[56:59]
	v_mfma_f32_16x16x32_bf16 v[44:47], v[116:119], v[210:213], v[44:47]
	v_mfma_f32_16x16x32_bf16 v[40:43], v[124:127], v[210:213], v[40:43]
	v_mfma_f32_16x16x32_bf16 v[28:31], v[116:119], v[218:221], v[28:31]
	v_mfma_f32_16x16x32_bf16 v[24:27], v[124:127], v[218:221], v[24:27]
	v_mfma_f32_16x16x32_bf16 v[12:15], v[116:119], v[226:229], v[12:15]
	v_mfma_f32_16x16x32_bf16 v[8:11], v[124:127], v[226:229], v[8:11]
	s_setprio 0
	s_barrier
	s_add_u32 s20, s36, 0x40080
	s_addc_u32 s21, s37, 0
	s_mov_b32 m0, s92
	v_lshl_add_u64 v[112:113], s[20:21], 0, v[146:147]
	global_load_lds_dwordx4 v[112:113], off
	v_lshl_add_u64 v[112:113], s[20:21], 0, v[150:151]
	s_mov_b32 m0, s93
	s_nop 0
	global_load_lds_dwordx4 v[112:113], off
	s_waitcnt vmcnt(6)
	s_barrier
	s_setprio 1
	v_mfma_f32_16x16x32_bf16 v[52:55], v[230:233], v[166:169], v[52:55]
	v_mfma_f32_16x16x32_bf16 v[48:51], v[238:241], v[166:169], v[48:51]
	v_mfma_f32_16x16x32_bf16 v[36:39], v[230:233], v[206:209], v[36:39]
	v_mfma_f32_16x16x32_bf16 v[32:35], v[238:241], v[206:209], v[32:35]
	v_mfma_f32_16x16x32_bf16 v[20:23], v[230:233], v[214:217], v[20:23]
	v_mfma_f32_16x16x32_bf16 v[16:19], v[238:241], v[214:217], v[16:19]
	v_mfma_f32_16x16x32_bf16 v[4:7], v[230:233], v[222:225], v[4:7]
	v_mfma_f32_16x16x32_bf16 v[0:3], v[238:241], v[222:225], v[0:3]
	v_mfma_f32_16x16x32_bf16 v[52:55], v[234:237], v[170:173], v[52:55]
	v_mfma_f32_16x16x32_bf16 v[48:51], v[242:245], v[170:173], v[48:51]
	v_mfma_f32_16x16x32_bf16 v[36:39], v[234:237], v[210:213], v[36:39]
	v_mfma_f32_16x16x32_bf16 v[32:35], v[242:245], v[210:213], v[32:35]
	v_mfma_f32_16x16x32_bf16 v[20:23], v[234:237], v[218:221], v[20:23]
	v_mfma_f32_16x16x32_bf16 v[16:19], v[242:245], v[218:221], v[16:19]
	v_mfma_f32_16x16x32_bf16 v[4:7], v[234:237], v[226:229], v[4:7]
	v_mfma_f32_16x16x32_bf16 v[0:3], v[242:245], v[226:229], v[0:3]
	s_setprio 0
	s_add_i32 s33, s33, 2
	s_add_u32 s18, s18, 0x100
	s_addc_u32 s19, s19, 0
	s_add_u32 s16, s16, 0x100
	s_addc_u32 s17, s17, 0
	s_cmp_gt_u32 s33, 13
	s_barrier
	s_cbranch_scc0 .LBB0_432
	s_cmp_lg_u32 s60, 0
	v_lshl_add_u32 v166, s15, 10, v188
	s_cbranch_scc0 .LBB0_435
	ds_read2_b32 v[122:123], v166 offset1:16
	ds_read2_b32 v[124:125], v166 offset0:32 offset1:48
	ds_read2_b32 v[116:117], v166 offset0:128 offset1:144
	ds_read2_b32 v[114:115], v166 offset0:160 offset1:176
	s_ashr_i32 s15, s14, 31
	s_lshl_b64 s[16:17], s[14:15], 17
	s_waitcnt lgkmcnt(0)
	v_pk_mul_f32 v[120:121], v[142:143], v[122:123] op_sel_hi:[1,0]
	v_pk_mul_f32 v[118:119], v[140:141], v[122:123] op_sel_hi:[1,0]
	v_lshl_add_u64 v[112:113], v[156:157], 0, s[16:17]
	v_pk_mul_f32 v[126:127], v[138:139], v[122:123] op_sel_hi:[1,0]
	v_pk_mul_f32 v[168:169], v[136:137], v[122:123] op_sel_hi:[1,0]
	v_cvt_pk_bf16_f32 v118, v118, v119
	v_cvt_pk_bf16_f32 v119, v120, v121
	v_cvt_pk_bf16_f32 v121, v126, v127
	v_pk_mul_f32 v[126:127], v[130:131], v[122:123] op_sel_hi:[1,0]
	v_cvt_pk_bf16_f32 v120, v168, v169
	s_waitcnt vmcnt(0)
	global_store_dwordx4 v[112:113], v[118:121], off
	v_pk_mul_f32 v[168:169], v[128:129], v[122:123] op_sel_hi:[1,0]
	s_nop 0
	v_pk_mul_f32 v[120:121], v[134:135], v[122:123] op_sel_hi:[1,0]
	v_pk_mul_f32 v[118:119], v[132:133], v[122:123] op_sel_hi:[1,0]
	v_mov_b32_e32 v122, v123
	v_cvt_pk_bf16_f32 v118, v118, v119
	v_cvt_pk_bf16_f32 v119, v120, v121
	v_cvt_pk_bf16_f32 v120, v168, v169
	v_cvt_pk_bf16_f32 v121, v126, v127
	global_store_dwordx4 v[112:113], v[118:121], off offset:256
	v_pk_mul_f32 v[126:127], v[106:107], v[122:123] op_sel_hi:[1,0]
	v_pk_mul_f32 v[168:169], v[104:105], v[122:123] op_sel_hi:[1,0]
	v_pk_mul_f32 v[120:121], v[110:111], v[122:123] op_sel_hi:[1,0]
	v_pk_mul_f32 v[118:119], v[108:109], v[122:123] op_sel_hi:[1,0]
	s_nop 0
	v_cvt_pk_bf16_f32 v118, v118, v119
	v_cvt_pk_bf16_f32 v119, v120, v121
	v_cvt_pk_bf16_f32 v121, v126, v127
	v_add_co_u32_e32 v126, vcc, s83, v112
	v_cvt_pk_bf16_f32 v120, v168, v169
	v_pk_mul_f32 v[168:169], v[98:99], v[122:123] op_sel_hi:[1,0]
	s_nop 0
	v_addc_co_u32_e32 v127, vcc, 0, v113, vcc
	global_store_dwordx4 v[126:127], v[118:121], off
	s_nop 1
	v_pk_mul_f32 v[120:121], v[102:103], v[122:123] op_sel_hi:[1,0]
	v_pk_mul_f32 v[118:119], v[100:101], v[122:123] op_sel_hi:[1,0]
	v_pk_mul_f32 v[122:123], v[96:97], v[122:123] op_sel_hi:[1,0]
	v_cvt_pk_bf16_f32 v118, v118, v119
	v_cvt_pk_bf16_f32 v119, v120, v121
	v_cvt_pk_bf16_f32 v121, v168, v169
	v_pk_mul_f32 v[168:169], v[80:81], v[124:125] op_sel_hi:[1,0]
	v_cvt_pk_bf16_f32 v120, v122, v123
	global_store_dwordx4 v[126:127], v[118:121], off offset:256
	v_pk_mul_f32 v[122:123], v[90:91], v[124:125] op_sel_hi:[1,0]
	v_pk_mul_f32 v[126:127], v[88:89], v[124:125] op_sel_hi:[1,0]
	v_pk_mul_f32 v[120:121], v[94:95], v[124:125] op_sel_hi:[1,0]
	v_pk_mul_f32 v[118:119], v[92:93], v[124:125] op_sel_hi:[1,0]
	s_nop 0
	v_cvt_pk_bf16_f32 v118, v118, v119
	v_cvt_pk_bf16_f32 v119, v120, v121
	v_cvt_pk_bf16_f32 v121, v122, v123
	v_add_co_u32_e32 v122, vcc, s86, v112
	v_cvt_pk_bf16_f32 v120, v126, v127
	v_pk_mul_f32 v[126:127], v[82:83], v[124:125] op_sel_hi:[1,0]
	s_nop 0
	v_addc_co_u32_e32 v123, vcc, 0, v113, vcc
	global_store_dwordx4 v[122:123], v[118:121], off
	s_nop 1
	v_pk_mul_f32 v[120:121], v[86:87], v[124:125] op_sel_hi:[1,0]
	v_pk_mul_f32 v[118:119], v[84:85], v[124:125] op_sel_hi:[1,0]
	s_nop 0
	v_cvt_pk_bf16_f32 v118, v118, v119
	v_cvt_pk_bf16_f32 v119, v120, v121
	v_cvt_pk_bf16_f32 v120, v168, v169
	v_cvt_pk_bf16_f32 v121, v126, v127
	global_store_dwordx4 v[122:123], v[118:121], off offset:256
	v_mov_b32_e32 v122, v125
	v_pk_mul_f32 v[124:125], v[74:75], v[122:123] op_sel_hi:[1,0]
	v_pk_mul_f32 v[120:121], v[78:79], v[122:123] op_sel_hi:[1,0]
	v_pk_mul_f32 v[118:119], v[76:77], v[122:123] op_sel_hi:[1,0]
	v_pk_mul_f32 v[126:127], v[72:73], v[122:123] op_sel_hi:[1,0]
	v_cvt_pk_bf16_f32 v118, v118, v119
	v_cvt_pk_bf16_f32 v119, v120, v121
	v_cvt_pk_bf16_f32 v121, v124, v125
	v_add_co_u32_e32 v124, vcc, s87, v112
	v_cvt_pk_bf16_f32 v120, v126, v127
	v_pk_mul_f32 v[126:127], v[66:67], v[122:123] op_sel_hi:[1,0]
	s_nop 0
	v_addc_co_u32_e32 v125, vcc, 0, v113, vcc
	global_store_dwordx4 v[124:125], v[118:121], off
	s_nop 1
	v_pk_mul_f32 v[120:121], v[70:71], v[122:123] op_sel_hi:[1,0]
	v_pk_mul_f32 v[118:119], v[68:69], v[122:123] op_sel_hi:[1,0]
	v_pk_mul_f32 v[122:123], v[64:65], v[122:123] op_sel_hi:[1,0]
	v_cvt_pk_bf16_f32 v118, v118, v119
	v_cvt_pk_bf16_f32 v119, v120, v121
	v_cvt_pk_bf16_f32 v121, v126, v127
	v_pk_mul_f32 v[126:127], v[48:49], v[116:117] op_sel_hi:[1,0]
	v_cvt_pk_bf16_f32 v120, v122, v123
	global_store_dwordx4 v[124:125], v[118:121], off offset:256
	v_pk_mul_f32 v[122:123], v[58:59], v[116:117] op_sel_hi:[1,0]
	v_pk_mul_f32 v[124:125], v[56:57], v[116:117] op_sel_hi:[1,0]
	v_pk_mul_f32 v[120:121], v[62:63], v[116:117] op_sel_hi:[1,0]
	v_pk_mul_f32 v[118:119], v[60:61], v[116:117] op_sel_hi:[1,0]
	s_nop 0
	v_cvt_pk_bf16_f32 v118, v118, v119
	v_cvt_pk_bf16_f32 v119, v120, v121
	v_cvt_pk_bf16_f32 v121, v122, v123
	v_add_co_u32_e32 v122, vcc, s81, v112
	v_cvt_pk_bf16_f32 v120, v124, v125
	v_pk_mul_f32 v[124:125], v[50:51], v[116:117] op_sel_hi:[1,0]
	s_nop 0
	v_addc_co_u32_e32 v123, vcc, 0, v113, vcc
	global_store_dwordx4 v[122:123], v[118:121], off
	s_nop 1
	v_pk_mul_f32 v[120:121], v[54:55], v[116:117] op_sel_hi:[1,0]
	v_pk_mul_f32 v[118:119], v[52:53], v[116:117] op_sel_hi:[1,0]
	s_nop 0
	v_cvt_pk_bf16_f32 v118, v118, v119
	v_cvt_pk_bf16_f32 v119, v120, v121
	v_cvt_pk_bf16_f32 v120, v126, v127
	v_cvt_pk_bf16_f32 v121, v124, v125
	global_store_dwordx4 v[122:123], v[118:121], off offset:256
	s_nop 1
	v_mov_b32_e32 v120, v117
	v_pk_mul_f32 v[118:119], v[46:47], v[120:121] op_sel_hi:[1,0]
	v_pk_mul_f32 v[116:117], v[44:45], v[120:121] op_sel_hi:[1,0]
	v_pk_mul_f32 v[122:123], v[42:43], v[120:121] op_sel_hi:[1,0]
	v_cvt_pk_bf16_f32 v116, v116, v117
	v_cvt_pk_bf16_f32 v117, v118, v119
	v_pk_mul_f32 v[124:125], v[40:41], v[120:121] op_sel_hi:[1,0]
	v_cvt_pk_bf16_f32 v119, v122, v123
	v_add_co_u32_e32 v122, vcc, s82, v112
	v_cvt_pk_bf16_f32 v118, v124, v125
	v_pk_mul_f32 v[124:125], v[34:35], v[120:121] op_sel_hi:[1,0]
	s_nop 0
	v_addc_co_u32_e32 v123, vcc, 0, v113, vcc
	global_store_dwordx4 v[122:123], v[116:119], off
	s_nop 1
	v_pk_mul_f32 v[118:119], v[38:39], v[120:121] op_sel_hi:[1,0]
	v_pk_mul_f32 v[116:117], v[36:37], v[120:121] op_sel_hi:[1,0]
	v_pk_mul_f32 v[120:121], v[32:33], v[120:121] op_sel_hi:[1,0]
	v_cvt_pk_bf16_f32 v116, v116, v117
	v_cvt_pk_bf16_f32 v117, v118, v119
	v_cvt_pk_bf16_f32 v119, v124, v125
	v_pk_mul_f32 v[124:125], v[16:17], v[114:115] op_sel_hi:[1,0]
	v_cvt_pk_bf16_f32 v118, v120, v121
	global_store_dwordx4 v[122:123], v[116:119], off offset:256
	v_pk_mul_f32 v[120:121], v[26:27], v[114:115] op_sel_hi:[1,0]
	v_pk_mul_f32 v[122:123], v[24:25], v[114:115] op_sel_hi:[1,0]
	v_pk_mul_f32 v[118:119], v[30:31], v[114:115] op_sel_hi:[1,0]
	v_pk_mul_f32 v[116:117], v[28:29], v[114:115] op_sel_hi:[1,0]
	s_nop 0
	v_cvt_pk_bf16_f32 v116, v116, v117
	v_cvt_pk_bf16_f32 v117, v118, v119
	v_cvt_pk_bf16_f32 v119, v120, v121
	v_add_co_u32_e32 v120, vcc, s84, v112
	v_cvt_pk_bf16_f32 v118, v122, v123
	v_pk_mul_f32 v[122:123], v[18:19], v[114:115] op_sel_hi:[1,0]
	s_nop 0
	v_addc_co_u32_e32 v121, vcc, 0, v113, vcc
	global_store_dwordx4 v[120:121], v[116:119], off
	s_nop 1
	v_pk_mul_f32 v[118:119], v[22:23], v[114:115] op_sel_hi:[1,0]
	v_pk_mul_f32 v[116:117], v[20:21], v[114:115] op_sel_hi:[1,0]
	s_nop 0
	v_cvt_pk_bf16_f32 v116, v116, v117
	v_cvt_pk_bf16_f32 v117, v118, v119
	v_cvt_pk_bf16_f32 v118, v124, v125
	v_cvt_pk_bf16_f32 v119, v122, v123
	global_store_dwordx4 v[120:121], v[116:119], off offset:256
	s_nop 1
	v_mov_b32_e32 v118, v115
	v_pk_mul_f32 v[116:117], v[14:15], v[118:119] op_sel_hi:[1,0]
	v_pk_mul_f32 v[114:115], v[12:13], v[118:119] op_sel_hi:[1,0]
	v_pk_mul_f32 v[120:121], v[10:11], v[118:119] op_sel_hi:[1,0]
	v_cvt_pk_bf16_f32 v114, v114, v115
	v_cvt_pk_bf16_f32 v115, v116, v117
	v_pk_mul_f32 v[122:123], v[8:9], v[118:119] op_sel_hi:[1,0]
	v_cvt_pk_bf16_f32 v117, v120, v121
	v_add_co_u32_e32 v120, vcc, s85, v112
	v_cvt_pk_bf16_f32 v116, v122, v123
	s_nop 1
	v_addc_co_u32_e32 v121, vcc, 0, v113, vcc
	global_store_dwordx4 v[120:121], v[114:117], off
	v_pk_mul_f32 v[112:113], v[4:5], v[118:119] op_sel_hi:[1,0]
	s_nop 0
	v_pk_mul_f32 v[114:115], v[6:7], v[118:119] op_sel_hi:[1,0]
	v_pk_mul_f32 v[116:117], v[2:3], v[118:119] op_sel_hi:[1,0]
	v_pk_mul_f32 v[118:119], v[0:1], v[118:119] op_sel_hi:[1,0]
	v_cvt_pk_bf16_f32 v112, v112, v113
	v_cvt_pk_bf16_f32 v113, v114, v115
	v_cvt_pk_bf16_f32 v115, v116, v117
	s_nop 0
	v_cvt_pk_bf16_f32 v114, v118, v119
	global_store_dwordx4 v[120:121], v[112:115], off offset:256
	s_cbranch_execnz .LBB0_428
	s_branch .LBB0_427

.LBB0_442:
	s_add_u32 s2, s36, s0
	s_addc_u32 s3, s37, s1
	v_cmp_gt_i64_e64 s[6:7], s[2:3], 3
	s_mov_b64 s[2:3], -1
	s_and_b64 vcc, exec, s[6:7]
	s_cbranch_vccnz .LBB0_441
	s_and_saveexec_b64 s[2:3], s[8:9]
	s_cbranch_execz .LBB0_440
	s_add_i32 s5, s36, s0
	s_ashr_i32 s6, s5, 31
	s_lshr_b32 s6, s6, 29
	s_add_i32 s6, s5, s6
	s_ashr_i32 s7, s6, 3
	s_and_b32 s6, s6, -8
	s_sub_i32 s5, s5, s6
	s_min_i32 s5, s5, 4
	s_add_i32 s5, s5, s7
	s_ashr_i32 s6, s5, 31
	s_lshr_b32 s6, s6, 28
	s_add_i32 s6, s5, s6
	s_ashr_i32 s7, s6, 4
	s_lshl_b32 s7, s7, 3
	s_sub_i32 s10, 2, s7
	s_min_i32 s10, s10, 8
	s_abs_i32 s10, s10
	v_cvt_f32_u32_e32 v1, s10
	s_sub_i32 s11, 0, s10
	s_and_b32 s6, s6, -16
	s_sub_i32 s5, s5, s6
	v_rcp_iflag_f32_e32 v1, v1
	s_ashr_i32 s6, s5, 31
	s_abs_i32 s5, s5
	v_mul_f32_e32 v1, 0x4f7ffffe, v1
	v_cvt_u32_f32_e32 v1, v1
	s_nop 0
	v_readfirstlane_b32 s12, v1
	s_mul_i32 s11, s11, s12
	s_mul_hi_u32 s11, s12, s11
	s_add_i32 s12, s12, s11
	s_mul_hi_u32 s11, s5, s12
	s_mul_i32 s11, s11, s10
	s_sub_i32 s5, s5, s11
	s_sub_i32 s11, s5, s10
	s_cmp_ge_u32 s5, s10
	s_cselect_b32 s5, s11, s5
	s_sub_i32 s11, s5, s10
	s_cmp_ge_u32 s5, s10
	s_cselect_b32 s5, s11, s5
	s_xor_b32 s5, s5, s6
	s_sub_i32 s5, s5, s6
	s_add_i32 s6, s5, s7
	s_ashr_i32 s7, s6, 31
	s_lshl_b64 s[6:7], s[6:7], 14
	v_lshl_add_u64 v[14:15], v[154:155], 0, s[6:7]
	s_waitcnt vmcnt(0)
	global_load_dwordx4 v[2:5], v[14:15], off
	global_load_dwordx4 v[6:9], v[14:15], off offset:16
	global_load_dwordx4 v[10:13], v[14:15], off offset:32
	s_nop 0
	global_load_dwordx4 v[14:17], v[14:15], off offset:48
	s_waitcnt vmcnt(0) lgkmcnt(0)
	v_mov_b32_e32 v18, v3
	v_mov_b32_e32 v19, v4
	v_mov_b32_e32 v20, v7
	v_mov_b32_e32 v21, v8
	v_mov_b32_e32 v3, v5
	v_mov_b32_e32 v7, v9
	v_mov_b32_e32 v4, v11
	v_mov_b32_e32 v8, v13
	v_pk_add_f32 v[2:3], v[18:19], v[2:3]
	v_pk_add_f32 v[6:7], v[20:21], v[6:7]
	v_pk_add_f32 v[4:5], v[10:11], v[4:5]
	v_pk_add_f32 v[8:9], v[12:13], v[8:9]
	v_pk_add_f32 v[2:3], v[2:3], v[2:3] op_sel:[0,1] op_sel_hi:[1,0]
	v_pk_add_f32 v[6:7], v[6:7], v[6:7] op_sel:[0,1] op_sel_hi:[1,0]
	v_mov_b32_e32 v5, v16
	v_mov_b32_e32 v9, v17
	v_mov_b32_e32 v3, v14
	v_mov_b32_e32 v7, v15
	v_pk_add_f32 v[4:5], v[4:5], v[8:9]
	v_pk_add_f32 v[2:3], v[2:3], v[6:7]
	s_nop 0
	v_pk_add_f32 v[2:3], v[2:3], v[4:5]
	s_nop 0
	v_add_f32_e32 v1, v2, v3
	v_fmamk_f32 v1, v1, 0x3a800000, v0
	v_mul_f32_e32 v2, 0x4b800000, v1
	v_cmp_gt_f32_e32 vcc, s4, v1
	s_nop 1
	v_cndmask_b32_e32 v1, v1, v2, vcc
	v_rsq_f32_e32 v1, v1
	s_nop 0
	v_mul_f32_e32 v2, 0x45800000, v1
	v_cndmask_b32_e32 v1, v1, v2, vcc
	ds_write_b32 v187, v1
	s_branch .LBB0_440

.LBB0_449:
	global_load_dwordx4 v[120:123], v[156:157], off offset:272
	global_load_dwordx4 v[124:127], v[156:157], off offset:256
	global_load_dwordx4 v[112:115], v[156:157], off offset:400
	global_load_dwordx4 v[116:119], v[156:157], off offset:384
	v_and_b32_e32 v165, 64, v194
	v_xor_b32_e32 v164, 16, v194
	v_add_u32_e32 v165, 64, v165
	v_cmp_lt_i32_e32 vcc, v164, v165
	v_mov_b32_e32 v198, v141
	v_mov_b32_e32 v199, v137
	v_cndmask_b32_e32 v164, v194, v164, vcc
	v_lshlrev_b32_e32 v195, 2, v164
	v_xor_b32_e32 v164, 32, v194
	v_cmp_lt_i32_e32 vcc, v164, v165
	v_mov_b32_e32 v165, v136
	v_pk_mul_f32 v[198:199], v[198:199], v[198:199]
	v_cndmask_b32_e32 v164, v194, v164, vcc
	v_lshlrev_b32_e32 v196, 2, v164
	v_mov_b32_e32 v164, v140
	v_pk_fma_f32 v[164:165], v[164:165], v[164:165], v[198:199]
	v_mov_b32_e32 v198, v142
	v_mov_b32_e32 v199, v138
	v_pk_fma_f32 v[164:165], v[198:199], v[198:199], v[164:165]
	v_mov_b32_e32 v198, v143
	v_mov_b32_e32 v199, v139
	v_mov_b32_e32 v200, v133
	v_mov_b32_e32 v201, v129
	v_pk_fma_f32 v[164:165], v[198:199], v[198:199], v[164:165]
	v_mov_b32_e32 v198, v132
	v_mov_b32_e32 v199, v128
	v_pk_mul_f32 v[200:201], v[200:201], v[200:201]
	v_add_f32_e32 v164, v164, v165
	v_pk_fma_f32 v[198:199], v[198:199], v[198:199], v[200:201]
	v_mov_b32_e32 v200, v134
	v_mov_b32_e32 v201, v130
	v_pk_fma_f32 v[198:199], v[200:201], v[200:201], v[198:199]
	v_mov_b32_e32 v200, v135
	v_mov_b32_e32 v201, v131
	v_pk_fma_f32 v[198:199], v[200:201], v[200:201], v[198:199]
	s_waitcnt vmcnt(0)
	ds_read2_b32 v[170:171], v162 offset1:16
	ds_read2_b32 v[168:169], v162 offset0:32 offset1:48
	ds_read2_b32 v[166:167], v162 offset0:128 offset1:144
	ds_read2_b32 v[162:163], v162 offset0:160 offset1:176
	v_add_f32_e32 v164, v164, v198
	v_add_f32_e32 v164, v164, v199
	ds_bpermute_b32 v165, v195, v164
	s_ashr_i32 s13, s12, 31
	s_lshl_b64 s[12:13], s[12:13], 17
	s_waitcnt lgkmcnt(0)
	v_add_f32_e32 v164, v164, v165
	ds_bpermute_b32 v165, v196, v164
	s_waitcnt lgkmcnt(0)
	v_add_f32_e32 v164, v164, v165
	v_mul_f32_e32 v164, v170, v164
	v_mul_f32_e32 v164, v170, v164
	v_fmamk_f32 v164, v164, 0x3c800000, v193
	v_cmp_gt_f32_e32 vcc, s91, v164
	v_mul_f32_e32 v165, 0x4b800000, v164
	s_nop 0
	v_cndmask_b32_e32 v164, v164, v165, vcc
	v_rsq_f32_e32 v164, v164
	s_nop 0
	v_mul_f32_e32 v165, 0x45800000, v164
	v_cndmask_b32_e32 v164, v164, v165, vcc
	v_mul_f32_e32 v170, v170, v164
	v_pk_mul_f32 v[140:141], v[140:141], v[170:171] op_sel_hi:[1,0]
	v_pk_mul_f32 v[142:143], v[142:143], v[170:171] op_sel_hi:[1,0]
	v_pk_mul_f32 v[136:137], v[136:137], v[170:171] op_sel_hi:[1,0]
	v_pk_mul_f32 v[138:139], v[138:139], v[170:171] op_sel_hi:[1,0]
	v_lshl_add_u64 v[164:165], v[152:153], 0, s[12:13]
	v_pk_mul_f32 v[128:129], v[128:129], v[170:171] op_sel_hi:[1,0]
	v_pk_mul_f32 v[130:131], v[130:131], v[170:171] op_sel_hi:[1,0]
	v_pk_mul_f32 v[132:133], v[132:133], v[170:171] op_sel_hi:[1,0]
	v_pk_mul_f32 v[134:135], v[134:135], v[170:171] op_sel_hi:[1,0]
	s_waitcnt vmcnt(0)
	v_pk_mul_f32 v[198:199], v[122:123], v[138:139]
	v_pk_mul_f32 v[142:143], v[126:127], v[142:143]
	v_pk_mul_f32 v[140:141], v[124:125], v[140:141]
	v_pk_mul_f32 v[138:139], v[120:121], v[136:137]
	v_cvt_pk_bf16_f32 v136, v140, v141
	v_cvt_pk_bf16_f32 v137, v142, v143
	v_pk_mul_f32 v[134:135], v[118:119], v[134:135]
	v_cvt_pk_bf16_f32 v138, v138, v139
	v_cvt_pk_bf16_f32 v139, v198, v199
	global_store_dwordx4 v[164:165], v[136:139], off
	v_pk_mul_f32 v[132:133], v[116:117], v[132:133]
	s_nop 0
	v_pk_mul_f32 v[136:137], v[114:115], v[130:131]
	v_pk_mul_f32 v[130:131], v[112:113], v[128:129]
	v_cvt_pk_bf16_f32 v128, v132, v133
	v_cvt_pk_bf16_f32 v129, v134, v135
	v_mov_b32_e32 v132, v101
	v_cvt_pk_bf16_f32 v130, v130, v131
	v_cvt_pk_bf16_f32 v131, v136, v137
	global_store_dwordx4 v[164:165], v[128:131], off offset:64
	v_mov_b32_e32 v133, v97
	v_pk_mul_f32 v[132:133], v[132:133], v[132:133]
	v_mov_b32_e32 v130, v109
	v_mov_b32_e32 v131, v105
	v_mov_b32_e32 v128, v108
	v_mov_b32_e32 v129, v104
	v_pk_mul_f32 v[130:131], v[130:131], v[130:131]
	s_nop 0
	v_pk_fma_f32 v[128:129], v[128:129], v[128:129], v[130:131]
	v_mov_b32_e32 v130, v110
	v_mov_b32_e32 v131, v106
	v_pk_fma_f32 v[128:129], v[130:131], v[130:131], v[128:129]
	v_mov_b32_e32 v130, v111
	v_mov_b32_e32 v131, v107
	v_pk_fma_f32 v[128:129], v[130:131], v[130:131], v[128:129]
	v_mov_b32_e32 v130, v100
	v_mov_b32_e32 v131, v96
	v_pk_fma_f32 v[130:131], v[130:131], v[130:131], v[132:133]
	v_mov_b32_e32 v132, v102
	v_mov_b32_e32 v133, v98
	v_pk_fma_f32 v[130:131], v[132:133], v[132:133], v[130:131]
	v_mov_b32_e32 v132, v103
	v_mov_b32_e32 v133, v99
	v_pk_fma_f32 v[130:131], v[132:133], v[132:133], v[130:131]
	v_add_f32_e32 v128, v128, v129
	v_add_f32_e32 v128, v128, v130
	v_add_f32_e32 v128, v128, v131
	ds_bpermute_b32 v129, v195, v128
	s_waitcnt lgkmcnt(0)
	v_add_f32_e32 v128, v128, v129
	ds_bpermute_b32 v129, v196, v128
	s_waitcnt lgkmcnt(0)
	v_add_f32_e32 v128, v128, v129
	v_mul_f32_e32 v128, v171, v128
	v_mul_f32_e32 v128, v171, v128
	v_fmamk_f32 v128, v128, 0x3c800000, v193
	v_cmp_gt_f32_e32 vcc, s91, v128
	v_mul_f32_e32 v129, 0x4b800000, v128
	s_nop 0
	v_cndmask_b32_e32 v128, v128, v129, vcc
	v_rsq_f32_e32 v128, v128
	s_nop 0
	v_mul_f32_e32 v129, 0x45800000, v128
	v_cndmask_b32_e32 v128, v128, v129, vcc
	v_mul_f32_e32 v128, v171, v128
	v_pk_mul_f32 v[108:109], v[108:109], v[128:129] op_sel_hi:[1,0]
	v_pk_mul_f32 v[104:105], v[104:105], v[128:129] op_sel_hi:[1,0]
	v_pk_mul_f32 v[108:109], v[124:125], v[108:109]
	v_pk_mul_f32 v[106:107], v[106:107], v[128:129] op_sel_hi:[1,0]
	v_pk_mul_f32 v[110:111], v[110:111], v[128:129] op_sel_hi:[1,0]
	v_pk_mul_f32 v[130:131], v[122:123], v[106:107]
	v_pk_mul_f32 v[106:107], v[120:121], v[104:105]
	v_cvt_pk_bf16_f32 v104, v108, v109
	v_add_co_u32_e32 v108, vcc, s70, v164
	v_pk_mul_f32 v[110:111], v[126:127], v[110:111]
	s_nop 0
	v_addc_co_u32_e32 v109, vcc, 0, v165, vcc
	v_cvt_pk_bf16_f32 v105, v110, v111
	v_pk_mul_f32 v[96:97], v[96:97], v[128:129] op_sel_hi:[1,0]
	v_pk_mul_f32 v[98:99], v[98:99], v[128:129] op_sel_hi:[1,0]
	v_cvt_pk_bf16_f32 v106, v106, v107
	v_cvt_pk_bf16_f32 v107, v130, v131
	global_store_dwordx4 v[108:109], v[104:107], off
	v_pk_mul_f32 v[100:101], v[100:101], v[128:129] op_sel_hi:[1,0]
	v_pk_mul_f32 v[102:103], v[102:103], v[128:129] op_sel_hi:[1,0]
	v_pk_mul_f32 v[104:105], v[114:115], v[98:99]
	v_pk_mul_f32 v[98:99], v[112:113], v[96:97]
	v_pk_mul_f32 v[102:103], v[118:119], v[102:103]
	v_cvt_pk_bf16_f32 v98, v98, v99
	v_cvt_pk_bf16_f32 v99, v104, v105
	v_pk_mul_f32 v[100:101], v[116:117], v[100:101]
	v_cvt_pk_bf16_f32 v97, v102, v103
	s_nop 0
	v_cvt_pk_bf16_f32 v96, v100, v101
	global_store_dwordx4 v[108:109], v[96:99], off offset:64
	v_mov_b32_e32 v100, v85
	v_mov_b32_e32 v101, v81
	v_mov_b32_e32 v98, v93
	v_mov_b32_e32 v99, v89
	v_mov_b32_e32 v96, v92
	v_mov_b32_e32 v97, v88
	v_pk_mul_f32 v[98:99], v[98:99], v[98:99]
	v_pk_mul_f32 v[100:101], v[100:101], v[100:101]
	v_pk_fma_f32 v[96:97], v[96:97], v[96:97], v[98:99]
	v_mov_b32_e32 v98, v94
	v_mov_b32_e32 v99, v90
	v_pk_fma_f32 v[96:97], v[98:99], v[98:99], v[96:97]
	v_mov_b32_e32 v98, v95
	v_mov_b32_e32 v99, v91
	v_pk_fma_f32 v[96:97], v[98:99], v[98:99], v[96:97]
	v_mov_b32_e32 v98, v84
	v_mov_b32_e32 v99, v80
	v_pk_fma_f32 v[98:99], v[98:99], v[98:99], v[100:101]
	v_mov_b32_e32 v100, v86
	v_mov_b32_e32 v101, v82
	v_pk_fma_f32 v[98:99], v[100:101], v[100:101], v[98:99]
	v_mov_b32_e32 v100, v87
	v_mov_b32_e32 v101, v83
	v_pk_fma_f32 v[98:99], v[100:101], v[100:101], v[98:99]
	v_add_f32_e32 v96, v96, v97
	v_add_f32_e32 v96, v96, v98
	v_add_f32_e32 v96, v96, v99
	ds_bpermute_b32 v97, v195, v96
	s_waitcnt lgkmcnt(0)
	v_add_f32_e32 v96, v96, v97
	ds_bpermute_b32 v97, v196, v96
	s_waitcnt lgkmcnt(0)
	v_add_f32_e32 v96, v96, v97
	v_mul_f32_e32 v96, v168, v96
	v_mul_f32_e32 v96, v168, v96
	v_fmamk_f32 v96, v96, 0x3c800000, v193
	v_cmp_gt_f32_e32 vcc, s91, v96
	v_mul_f32_e32 v97, 0x4b800000, v96
	s_nop 0
	v_cndmask_b32_e32 v96, v96, v97, vcc
	v_rsq_f32_e32 v96, v96
	s_nop 0
	v_mul_f32_e32 v97, 0x45800000, v96
	v_cndmask_b32_e32 v96, v96, v97, vcc
	v_mul_f32_e32 v96, v168, v96
	v_pk_mul_f32 v[92:93], v[92:93], v[96:97] op_sel_hi:[1,0]
	v_pk_mul_f32 v[88:89], v[88:89], v[96:97] op_sel_hi:[1,0]
	v_pk_mul_f32 v[92:93], v[124:125], v[92:93]
	v_pk_mul_f32 v[90:91], v[90:91], v[96:97] op_sel_hi:[1,0]
	v_pk_mul_f32 v[94:95], v[94:95], v[96:97] op_sel_hi:[1,0]
	v_pk_mul_f32 v[98:99], v[122:123], v[90:91]
	v_pk_mul_f32 v[90:91], v[120:121], v[88:89]
	v_cvt_pk_bf16_f32 v88, v92, v93
	v_add_co_u32_e32 v92, vcc, s81, v164
	v_pk_mul_f32 v[94:95], v[126:127], v[94:95]
	s_nop 0
	v_addc_co_u32_e32 v93, vcc, 0, v165, vcc
	v_cvt_pk_bf16_f32 v89, v94, v95
	v_pk_mul_f32 v[80:81], v[80:81], v[96:97] op_sel_hi:[1,0]
	v_pk_mul_f32 v[82:83], v[82:83], v[96:97] op_sel_hi:[1,0]
	v_cvt_pk_bf16_f32 v90, v90, v91
	v_cvt_pk_bf16_f32 v91, v98, v99
	global_store_dwordx4 v[92:93], v[88:91], off
	v_pk_mul_f32 v[84:85], v[84:85], v[96:97] op_sel_hi:[1,0]
	v_pk_mul_f32 v[86:87], v[86:87], v[96:97] op_sel_hi:[1,0]
	v_pk_mul_f32 v[88:89], v[114:115], v[82:83]
	v_pk_mul_f32 v[82:83], v[112:113], v[80:81]
	v_pk_mul_f32 v[86:87], v[118:119], v[86:87]
	v_cvt_pk_bf16_f32 v82, v82, v83
	v_cvt_pk_bf16_f32 v83, v88, v89
	v_pk_mul_f32 v[84:85], v[116:117], v[84:85]
	v_cvt_pk_bf16_f32 v81, v86, v87
	s_nop 0
	v_cvt_pk_bf16_f32 v80, v84, v85
	global_store_dwordx4 v[92:93], v[80:83], off offset:64
	v_mov_b32_e32 v84, v69
	v_mov_b32_e32 v85, v65
	v_mov_b32_e32 v82, v77
	v_mov_b32_e32 v83, v73
	v_mov_b32_e32 v80, v76
	v_mov_b32_e32 v81, v72
	v_pk_mul_f32 v[82:83], v[82:83], v[82:83]
	v_pk_mul_f32 v[84:85], v[84:85], v[84:85]
	v_pk_fma_f32 v[80:81], v[80:81], v[80:81], v[82:83]
	v_mov_b32_e32 v82, v78
	v_mov_b32_e32 v83, v74
	v_pk_fma_f32 v[80:81], v[82:83], v[82:83], v[80:81]
	v_mov_b32_e32 v82, v79
	v_mov_b32_e32 v83, v75
	v_pk_fma_f32 v[80:81], v[82:83], v[82:83], v[80:81]
	v_mov_b32_e32 v82, v68
	v_mov_b32_e32 v83, v64
	v_pk_fma_f32 v[82:83], v[82:83], v[82:83], v[84:85]
	v_mov_b32_e32 v84, v70
	v_mov_b32_e32 v85, v66
	v_pk_fma_f32 v[82:83], v[84:85], v[84:85], v[82:83]
	v_mov_b32_e32 v84, v71
	v_mov_b32_e32 v85, v67
	v_pk_fma_f32 v[82:83], v[84:85], v[84:85], v[82:83]
	v_add_f32_e32 v80, v80, v81
	v_add_f32_e32 v80, v80, v82
	v_add_f32_e32 v80, v80, v83
	ds_bpermute_b32 v81, v195, v80
	s_waitcnt lgkmcnt(0)
	v_add_f32_e32 v80, v80, v81
	ds_bpermute_b32 v81, v196, v80
	s_waitcnt lgkmcnt(0)
	v_add_f32_e32 v80, v80, v81
	v_mul_f32_e32 v80, v169, v80
	v_mul_f32_e32 v80, v169, v80
	v_fmamk_f32 v80, v80, 0x3c800000, v193
	v_cmp_gt_f32_e32 vcc, s91, v80
	v_mul_f32_e32 v81, 0x4b800000, v80
	s_nop 0
	v_cndmask_b32_e32 v80, v80, v81, vcc
	v_rsq_f32_e32 v80, v80
	s_nop 0
	v_mul_f32_e32 v81, 0x45800000, v80
	v_cndmask_b32_e32 v80, v80, v81, vcc
	v_mul_f32_e32 v80, v169, v80
	v_pk_mul_f32 v[76:77], v[76:77], v[80:81] op_sel_hi:[1,0]
	v_pk_mul_f32 v[72:73], v[72:73], v[80:81] op_sel_hi:[1,0]
	v_pk_mul_f32 v[76:77], v[124:125], v[76:77]
	v_pk_mul_f32 v[74:75], v[74:75], v[80:81] op_sel_hi:[1,0]
	v_pk_mul_f32 v[78:79], v[78:79], v[80:81] op_sel_hi:[1,0]
	v_pk_mul_f32 v[82:83], v[122:123], v[74:75]
	v_pk_mul_f32 v[74:75], v[120:121], v[72:73]
	v_cvt_pk_bf16_f32 v72, v76, v77
	v_add_co_u32_e32 v76, vcc, s82, v164
	v_pk_mul_f32 v[78:79], v[126:127], v[78:79]
	s_nop 0
	v_addc_co_u32_e32 v77, vcc, 0, v165, vcc
	v_cvt_pk_bf16_f32 v73, v78, v79
	v_pk_mul_f32 v[64:65], v[64:65], v[80:81] op_sel_hi:[1,0]
	v_pk_mul_f32 v[66:67], v[66:67], v[80:81] op_sel_hi:[1,0]
	v_cvt_pk_bf16_f32 v74, v74, v75
	v_cvt_pk_bf16_f32 v75, v82, v83
	global_store_dwordx4 v[76:77], v[72:75], off
	v_pk_mul_f32 v[68:69], v[68:69], v[80:81] op_sel_hi:[1,0]
	v_pk_mul_f32 v[70:71], v[70:71], v[80:81] op_sel_hi:[1,0]
	v_pk_mul_f32 v[72:73], v[114:115], v[66:67]
	v_pk_mul_f32 v[66:67], v[112:113], v[64:65]
	v_pk_mul_f32 v[70:71], v[118:119], v[70:71]
	v_cvt_pk_bf16_f32 v66, v66, v67
	v_cvt_pk_bf16_f32 v67, v72, v73
	v_pk_mul_f32 v[68:69], v[116:117], v[68:69]
	v_cvt_pk_bf16_f32 v65, v70, v71
	s_nop 0
	v_cvt_pk_bf16_f32 v64, v68, v69
	global_store_dwordx4 v[76:77], v[64:67], off offset:64
	v_mov_b32_e32 v68, v53
	v_mov_b32_e32 v69, v49
	v_mov_b32_e32 v66, v61
	v_mov_b32_e32 v67, v57
	v_mov_b32_e32 v64, v60
	v_mov_b32_e32 v65, v56
	v_pk_mul_f32 v[66:67], v[66:67], v[66:67]
	v_pk_mul_f32 v[68:69], v[68:69], v[68:69]
	v_pk_fma_f32 v[64:65], v[64:65], v[64:65], v[66:67]
	v_mov_b32_e32 v66, v62
	v_mov_b32_e32 v67, v58
	v_pk_fma_f32 v[64:65], v[66:67], v[66:67], v[64:65]
	v_mov_b32_e32 v66, v63
	v_mov_b32_e32 v67, v59
	v_pk_fma_f32 v[64:65], v[66:67], v[66:67], v[64:65]
	v_mov_b32_e32 v66, v52
	v_mov_b32_e32 v67, v48
	v_pk_fma_f32 v[66:67], v[66:67], v[66:67], v[68:69]
	v_mov_b32_e32 v68, v54
	v_mov_b32_e32 v69, v50
	v_pk_fma_f32 v[66:67], v[68:69], v[68:69], v[66:67]
	v_mov_b32_e32 v68, v55
	v_mov_b32_e32 v69, v51
	v_pk_fma_f32 v[66:67], v[68:69], v[68:69], v[66:67]
	v_add_f32_e32 v64, v64, v65
	v_add_f32_e32 v64, v64, v66
	v_add_f32_e32 v64, v64, v67
	ds_bpermute_b32 v65, v195, v64
	s_waitcnt lgkmcnt(0)
	v_add_f32_e32 v64, v64, v65
	ds_bpermute_b32 v65, v196, v64
	s_waitcnt lgkmcnt(0)
	v_add_f32_e32 v64, v64, v65
	v_mul_f32_e32 v64, v166, v64
	v_mul_f32_e32 v64, v166, v64
	v_fmamk_f32 v64, v64, 0x3c800000, v193
	v_cmp_gt_f32_e32 vcc, s91, v64
	v_mul_f32_e32 v65, 0x4b800000, v64
	s_nop 0
	v_cndmask_b32_e32 v64, v64, v65, vcc
	v_rsq_f32_e32 v64, v64
	s_nop 0
	v_mul_f32_e32 v65, 0x45800000, v64
	v_cndmask_b32_e32 v64, v64, v65, vcc
	v_mul_f32_e32 v64, v166, v64
	v_pk_mul_f32 v[60:61], v[60:61], v[64:65] op_sel_hi:[1,0]
	v_pk_mul_f32 v[56:57], v[56:57], v[64:65] op_sel_hi:[1,0]
	v_pk_mul_f32 v[60:61], v[124:125], v[60:61]
	v_pk_mul_f32 v[58:59], v[58:59], v[64:65] op_sel_hi:[1,0]
	v_pk_mul_f32 v[62:63], v[62:63], v[64:65] op_sel_hi:[1,0]
	v_pk_mul_f32 v[66:67], v[122:123], v[58:59]
	v_pk_mul_f32 v[58:59], v[120:121], v[56:57]
	v_cvt_pk_bf16_f32 v56, v60, v61
	v_add_co_u32_e32 v60, vcc, s68, v164
	v_pk_mul_f32 v[62:63], v[126:127], v[62:63]
	s_nop 0
	v_addc_co_u32_e32 v61, vcc, 0, v165, vcc
	v_cvt_pk_bf16_f32 v57, v62, v63
	v_pk_mul_f32 v[48:49], v[48:49], v[64:65] op_sel_hi:[1,0]
	v_pk_mul_f32 v[50:51], v[50:51], v[64:65] op_sel_hi:[1,0]
	v_cvt_pk_bf16_f32 v58, v58, v59
	v_cvt_pk_bf16_f32 v59, v66, v67
	global_store_dwordx4 v[60:61], v[56:59], off
	v_pk_mul_f32 v[52:53], v[52:53], v[64:65] op_sel_hi:[1,0]
	v_pk_mul_f32 v[54:55], v[54:55], v[64:65] op_sel_hi:[1,0]
	v_pk_mul_f32 v[56:57], v[114:115], v[50:51]
	v_pk_mul_f32 v[50:51], v[112:113], v[48:49]
	v_pk_mul_f32 v[54:55], v[118:119], v[54:55]
	v_cvt_pk_bf16_f32 v50, v50, v51
	v_cvt_pk_bf16_f32 v51, v56, v57
	v_pk_mul_f32 v[52:53], v[116:117], v[52:53]
	v_cvt_pk_bf16_f32 v49, v54, v55
	s_nop 0
	v_cvt_pk_bf16_f32 v48, v52, v53
	global_store_dwordx4 v[60:61], v[48:51], off offset:64
	v_mov_b32_e32 v52, v37
	v_mov_b32_e32 v53, v33
	v_mov_b32_e32 v50, v45
	v_mov_b32_e32 v51, v41
	v_mov_b32_e32 v48, v44
	v_mov_b32_e32 v49, v40
	v_pk_mul_f32 v[50:51], v[50:51], v[50:51]
	v_pk_mul_f32 v[52:53], v[52:53], v[52:53]
	v_pk_fma_f32 v[48:49], v[48:49], v[48:49], v[50:51]
	v_mov_b32_e32 v50, v46
	v_mov_b32_e32 v51, v42
	v_pk_fma_f32 v[48:49], v[50:51], v[50:51], v[48:49]
	v_mov_b32_e32 v50, v47
	v_mov_b32_e32 v51, v43
	v_pk_fma_f32 v[48:49], v[50:51], v[50:51], v[48:49]
	v_mov_b32_e32 v50, v36
	v_mov_b32_e32 v51, v32
	v_pk_fma_f32 v[50:51], v[50:51], v[50:51], v[52:53]
	v_mov_b32_e32 v52, v38
	v_mov_b32_e32 v53, v34
	v_pk_fma_f32 v[50:51], v[52:53], v[52:53], v[50:51]
	v_mov_b32_e32 v52, v39
	v_mov_b32_e32 v53, v35
	v_pk_fma_f32 v[50:51], v[52:53], v[52:53], v[50:51]
	v_add_f32_e32 v48, v48, v49
	v_add_f32_e32 v48, v48, v50
	v_add_f32_e32 v48, v48, v51
	ds_bpermute_b32 v49, v195, v48
	s_waitcnt lgkmcnt(0)
	v_add_f32_e32 v48, v48, v49
	ds_bpermute_b32 v49, v196, v48
	s_waitcnt lgkmcnt(0)
	v_add_f32_e32 v48, v48, v49
	v_mul_f32_e32 v48, v167, v48
	v_mul_f32_e32 v48, v167, v48
	v_fmamk_f32 v48, v48, 0x3c800000, v193
	v_cmp_gt_f32_e32 vcc, s91, v48
	v_mul_f32_e32 v49, 0x4b800000, v48
	s_nop 0
	v_cndmask_b32_e32 v48, v48, v49, vcc
	v_rsq_f32_e32 v48, v48
	s_nop 0
	v_mul_f32_e32 v49, 0x45800000, v48
	v_cndmask_b32_e32 v48, v48, v49, vcc
	v_mul_f32_e32 v48, v167, v48
	v_pk_mul_f32 v[44:45], v[44:45], v[48:49] op_sel_hi:[1,0]
	v_pk_mul_f32 v[40:41], v[40:41], v[48:49] op_sel_hi:[1,0]
	v_pk_mul_f32 v[44:45], v[124:125], v[44:45]
	v_pk_mul_f32 v[42:43], v[42:43], v[48:49] op_sel_hi:[1,0]
	v_pk_mul_f32 v[46:47], v[46:47], v[48:49] op_sel_hi:[1,0]
	v_pk_mul_f32 v[50:51], v[122:123], v[42:43]
	v_pk_mul_f32 v[42:43], v[120:121], v[40:41]
	v_cvt_pk_bf16_f32 v40, v44, v45
	v_add_co_u32_e32 v44, vcc, s69, v164
	v_pk_mul_f32 v[46:47], v[126:127], v[46:47]
	s_nop 0
	v_addc_co_u32_e32 v45, vcc, 0, v165, vcc
	v_cvt_pk_bf16_f32 v41, v46, v47
	v_pk_mul_f32 v[32:33], v[32:33], v[48:49] op_sel_hi:[1,0]
	v_pk_mul_f32 v[34:35], v[34:35], v[48:49] op_sel_hi:[1,0]
	v_cvt_pk_bf16_f32 v42, v42, v43
	v_cvt_pk_bf16_f32 v43, v50, v51
	global_store_dwordx4 v[44:45], v[40:43], off
	v_pk_mul_f32 v[36:37], v[36:37], v[48:49] op_sel_hi:[1,0]
	v_pk_mul_f32 v[38:39], v[38:39], v[48:49] op_sel_hi:[1,0]
	v_pk_mul_f32 v[40:41], v[114:115], v[34:35]
	v_pk_mul_f32 v[34:35], v[112:113], v[32:33]
	v_pk_mul_f32 v[38:39], v[118:119], v[38:39]
	v_cvt_pk_bf16_f32 v34, v34, v35
	v_cvt_pk_bf16_f32 v35, v40, v41
	v_pk_mul_f32 v[36:37], v[116:117], v[36:37]
	v_cvt_pk_bf16_f32 v33, v38, v39
	s_nop 0
	v_cvt_pk_bf16_f32 v32, v36, v37
	global_store_dwordx4 v[44:45], v[32:35], off offset:64
	v_mov_b32_e32 v36, v21
	v_mov_b32_e32 v37, v17
	v_mov_b32_e32 v34, v29
	v_mov_b32_e32 v35, v25
	v_mov_b32_e32 v32, v28
	v_mov_b32_e32 v33, v24
	v_pk_mul_f32 v[34:35], v[34:35], v[34:35]
	v_pk_mul_f32 v[36:37], v[36:37], v[36:37]
	v_pk_fma_f32 v[32:33], v[32:33], v[32:33], v[34:35]
	v_mov_b32_e32 v34, v30
	v_mov_b32_e32 v35, v26
	v_pk_fma_f32 v[32:33], v[34:35], v[34:35], v[32:33]
	v_mov_b32_e32 v34, v31
	v_mov_b32_e32 v35, v27
	v_pk_fma_f32 v[32:33], v[34:35], v[34:35], v[32:33]
	v_mov_b32_e32 v34, v20
	v_mov_b32_e32 v35, v16
	v_pk_fma_f32 v[34:35], v[34:35], v[34:35], v[36:37]
	v_mov_b32_e32 v36, v22
	v_mov_b32_e32 v37, v18
	v_pk_fma_f32 v[34:35], v[36:37], v[36:37], v[34:35]
	v_mov_b32_e32 v36, v23
	v_mov_b32_e32 v37, v19
	v_pk_fma_f32 v[34:35], v[36:37], v[36:37], v[34:35]
	v_add_f32_e32 v32, v32, v33
	v_add_f32_e32 v32, v32, v34
	v_add_f32_e32 v32, v32, v35
	ds_bpermute_b32 v33, v195, v32
	s_waitcnt lgkmcnt(0)
	v_add_f32_e32 v32, v32, v33
	ds_bpermute_b32 v33, v196, v32
	s_waitcnt lgkmcnt(0)
	v_add_f32_e32 v32, v32, v33
	v_mul_f32_e32 v32, v162, v32
	v_mul_f32_e32 v32, v162, v32
	v_fmamk_f32 v32, v32, 0x3c800000, v193
	v_cmp_gt_f32_e32 vcc, s91, v32
	v_mul_f32_e32 v33, 0x4b800000, v32
	s_nop 0
	v_cndmask_b32_e32 v32, v32, v33, vcc
	v_rsq_f32_e32 v32, v32
	s_nop 0
	v_mul_f32_e32 v33, 0x45800000, v32
	v_cndmask_b32_e32 v32, v32, v33, vcc
	v_mul_f32_e32 v32, v162, v32
	v_pk_mul_f32 v[28:29], v[28:29], v[32:33] op_sel_hi:[1,0]
	v_pk_mul_f32 v[24:25], v[24:25], v[32:33] op_sel_hi:[1,0]
	v_pk_mul_f32 v[28:29], v[124:125], v[28:29]
	v_pk_mul_f32 v[26:27], v[26:27], v[32:33] op_sel_hi:[1,0]
	v_pk_mul_f32 v[30:31], v[30:31], v[32:33] op_sel_hi:[1,0]
	v_pk_mul_f32 v[34:35], v[122:123], v[26:27]
	v_pk_mul_f32 v[26:27], v[120:121], v[24:25]
	v_cvt_pk_bf16_f32 v24, v28, v29
	v_add_co_u32_e32 v28, vcc, s71, v164
	v_pk_mul_f32 v[30:31], v[126:127], v[30:31]
	s_nop 0
	v_addc_co_u32_e32 v29, vcc, 0, v165, vcc
	v_cvt_pk_bf16_f32 v25, v30, v31
	v_pk_mul_f32 v[16:17], v[16:17], v[32:33] op_sel_hi:[1,0]
	v_pk_mul_f32 v[18:19], v[18:19], v[32:33] op_sel_hi:[1,0]
	v_cvt_pk_bf16_f32 v26, v26, v27
	v_cvt_pk_bf16_f32 v27, v34, v35
	global_store_dwordx4 v[28:29], v[24:27], off
	v_pk_mul_f32 v[20:21], v[20:21], v[32:33] op_sel_hi:[1,0]
	v_pk_mul_f32 v[22:23], v[22:23], v[32:33] op_sel_hi:[1,0]
	v_pk_mul_f32 v[24:25], v[114:115], v[18:19]
	v_pk_mul_f32 v[18:19], v[112:113], v[16:17]
	v_pk_mul_f32 v[22:23], v[118:119], v[22:23]
	v_cvt_pk_bf16_f32 v18, v18, v19
	v_cvt_pk_bf16_f32 v19, v24, v25
	v_pk_mul_f32 v[20:21], v[116:117], v[20:21]
	v_cvt_pk_bf16_f32 v17, v22, v23
	s_nop 0
	v_cvt_pk_bf16_f32 v16, v20, v21
	global_store_dwordx4 v[28:29], v[16:19], off offset:64
	v_mov_b32_e32 v20, v5
	v_mov_b32_e32 v21, v1
	v_mov_b32_e32 v18, v13
	v_mov_b32_e32 v19, v9
	v_mov_b32_e32 v16, v12
	v_mov_b32_e32 v17, v8
	v_pk_mul_f32 v[18:19], v[18:19], v[18:19]
	v_pk_mul_f32 v[20:21], v[20:21], v[20:21]
	v_pk_fma_f32 v[16:17], v[16:17], v[16:17], v[18:19]
	v_mov_b32_e32 v18, v14
	v_mov_b32_e32 v19, v10
	v_pk_fma_f32 v[16:17], v[18:19], v[18:19], v[16:17]
	v_mov_b32_e32 v18, v15
	v_mov_b32_e32 v19, v11
	v_pk_fma_f32 v[16:17], v[18:19], v[18:19], v[16:17]
	v_mov_b32_e32 v18, v4
	v_mov_b32_e32 v19, v0
	v_pk_fma_f32 v[18:19], v[18:19], v[18:19], v[20:21]
	v_mov_b32_e32 v20, v6
	v_mov_b32_e32 v21, v2
	v_pk_fma_f32 v[18:19], v[20:21], v[20:21], v[18:19]
	v_mov_b32_e32 v20, v7
	v_mov_b32_e32 v21, v3
	v_pk_fma_f32 v[18:19], v[20:21], v[20:21], v[18:19]
	v_add_f32_e32 v16, v16, v17
	v_add_f32_e32 v16, v16, v18
	v_add_f32_e32 v16, v16, v19
	ds_bpermute_b32 v17, v195, v16
	s_waitcnt lgkmcnt(0)
	v_add_f32_e32 v16, v16, v17
	ds_bpermute_b32 v17, v196, v16
	s_waitcnt lgkmcnt(0)
	v_add_f32_e32 v16, v16, v17
	v_mul_f32_e32 v16, v163, v16
	v_mul_f32_e32 v16, v163, v16
	v_fmamk_f32 v16, v16, 0x3c800000, v193
	v_cmp_gt_f32_e32 vcc, s91, v16
	v_mul_f32_e32 v17, 0x4b800000, v16
	s_nop 0
	v_cndmask_b32_e32 v16, v16, v17, vcc
	v_rsq_f32_e32 v16, v16
	s_nop 0
	v_mul_f32_e32 v17, 0x45800000, v16
	v_cndmask_b32_e32 v16, v16, v17, vcc
	v_mul_f32_e32 v16, v163, v16
	v_pk_mul_f32 v[12:13], v[12:13], v[16:17] op_sel_hi:[1,0]
	v_pk_mul_f32 v[8:9], v[8:9], v[16:17] op_sel_hi:[1,0]
	v_pk_mul_f32 v[12:13], v[124:125], v[12:13]
	v_pk_mul_f32 v[10:11], v[10:11], v[16:17] op_sel_hi:[1,0]
	v_pk_mul_f32 v[14:15], v[14:15], v[16:17] op_sel_hi:[1,0]
	v_pk_mul_f32 v[18:19], v[122:123], v[10:11]
	v_pk_mul_f32 v[10:11], v[120:121], v[8:9]
	v_cvt_pk_bf16_f32 v8, v12, v13
	v_add_co_u32_e32 v12, vcc, s80, v164
	v_pk_mul_f32 v[14:15], v[126:127], v[14:15]
	s_nop 0
	v_addc_co_u32_e32 v13, vcc, 0, v165, vcc
	v_cvt_pk_bf16_f32 v9, v14, v15
	v_pk_mul_f32 v[0:1], v[0:1], v[16:17] op_sel_hi:[1,0]
	v_pk_mul_f32 v[2:3], v[2:3], v[16:17] op_sel_hi:[1,0]
	v_cvt_pk_bf16_f32 v10, v10, v11
	v_cvt_pk_bf16_f32 v11, v18, v19
	global_store_dwordx4 v[12:13], v[8:11], off
	v_pk_mul_f32 v[4:5], v[4:5], v[16:17] op_sel_hi:[1,0]
	v_pk_mul_f32 v[6:7], v[6:7], v[16:17] op_sel_hi:[1,0]
	v_pk_mul_f32 v[8:9], v[114:115], v[2:3]
	v_pk_mul_f32 v[2:3], v[112:113], v[0:1]
	v_pk_mul_f32 v[6:7], v[118:119], v[6:7]
	v_pk_mul_f32 v[4:5], v[116:117], v[4:5]
	v_cvt_pk_bf16_f32 v1, v6, v7
	v_cvt_pk_bf16_f32 v2, v2, v3
	v_cvt_pk_bf16_f32 v3, v8, v9
	s_nop 0
	v_cvt_pk_bf16_f32 v0, v4, v5
	global_store_dwordx4 v[12:13], v[0:3], off offset:64

.LBB0_454:
	ds_read_b128 v[112:115], v174
	ds_read_b128 v[116:119], v175
	ds_read_b128 v[120:123], v177
	ds_read_b128 v[124:127], v180
	s_add_u32 s16, s14, 0xfffc0080
	s_addc_u32 s17, s15, -1
	s_cmp_eq_u32 s96, 12
	s_cselect_b32 s35, s7, s17
	s_cselect_b32 s34, s94, s16
	s_cselect_b32 s17, s5, s19
	s_cselect_b32 s16, s95, s18
	s_mov_b32 m0, s89
	v_lshl_add_u64 v[170:171], s[14:15], 0, v[160:161]
	ds_read_b128 v[162:165], v172
	ds_read_b128 v[166:169], v172 offset:1024
	ds_read_b128 v[196:199], v172 offset:2048
	ds_read_b128 v[200:203], v172 offset:3072
	ds_read_b128 v[204:207], v172 offset:4096
	ds_read_b128 v[208:211], v172 offset:5120
	ds_read_b128 v[212:215], v172 offset:6144
	ds_read_b128 v[216:219], v172 offset:7168
	global_load_lds_dwordx4 v[170:171], off
	v_lshl_add_u64 v[170:171], s[14:15], 0, v[158:159]
	s_mov_b32 m0, s90
	s_nop 0
	global_load_lds_dwordx4 v[170:171], off
	s_waitcnt lgkmcnt(8)
	s_barrier
	s_waitcnt lgkmcnt(0)
	s_setprio 1
	s_waitcnt lgkmcnt(0)
	v_mfma_f32_16x16x32_bf16 v[140:143], v[112:115], v[162:165], v[140:143]
	v_mfma_f32_16x16x32_bf16 v[136:139], v[120:123], v[162:165], v[136:139]
	v_mfma_f32_16x16x32_bf16 v[108:111], v[112:115], v[196:199], v[108:111]
	v_mfma_f32_16x16x32_bf16 v[104:107], v[120:123], v[196:199], v[104:107]
	v_mfma_f32_16x16x32_bf16 v[92:95], v[112:115], v[204:207], v[92:95]
	v_mfma_f32_16x16x32_bf16 v[88:91], v[120:123], v[204:207], v[88:91]
	v_mfma_f32_16x16x32_bf16 v[76:79], v[112:115], v[212:215], v[76:79]
	v_mfma_f32_16x16x32_bf16 v[72:75], v[120:123], v[212:215], v[72:75]
	v_mfma_f32_16x16x32_bf16 v[140:143], v[116:119], v[166:169], v[140:143]
	v_mfma_f32_16x16x32_bf16 v[136:139], v[124:127], v[166:169], v[136:139]
	v_mfma_f32_16x16x32_bf16 v[108:111], v[116:119], v[200:203], v[108:111]
	v_mfma_f32_16x16x32_bf16 v[104:107], v[124:127], v[200:203], v[104:107]
	v_mfma_f32_16x16x32_bf16 v[92:95], v[116:119], v[208:211], v[92:95]
	v_mfma_f32_16x16x32_bf16 v[88:91], v[124:127], v[208:211], v[88:91]
	v_mfma_f32_16x16x32_bf16 v[76:79], v[116:119], v[216:219], v[76:79]
	v_mfma_f32_16x16x32_bf16 v[72:75], v[124:127], v[216:219], v[72:75]
	s_setprio 0
	s_barrier
	s_mov_b32 m0, s61
	v_lshl_add_u64 v[170:171], s[16:17], 0, v[146:147]
	ds_read_b128 v[220:223], v181
	ds_read_b128 v[224:227], v182
	ds_read_b128 v[228:231], v183
	ds_read_b128 v[232:235], v184
	global_load_lds_dwordx4 v[170:171], off
	v_lshl_add_u64 v[236:237], s[16:17], 0, v[150:151]
	s_mov_b32 m0, s62
	s_nop 0
	global_load_lds_dwordx4 v[236:237], off
	s_barrier
	s_waitcnt lgkmcnt(0)
	s_setprio 1
	s_waitcnt lgkmcnt(0)
	v_mfma_f32_16x16x32_bf16 v[132:135], v[220:223], v[162:165], v[132:135]
	v_mfma_f32_16x16x32_bf16 v[128:131], v[228:231], v[162:165], v[128:131]
	v_mfma_f32_16x16x32_bf16 v[100:103], v[220:223], v[196:199], v[100:103]
	v_mfma_f32_16x16x32_bf16 v[96:99], v[228:231], v[196:199], v[96:99]
	v_mfma_f32_16x16x32_bf16 v[84:87], v[220:223], v[204:207], v[84:87]
	v_mfma_f32_16x16x32_bf16 v[80:83], v[228:231], v[204:207], v[80:83]
	v_mfma_f32_16x16x32_bf16 v[68:71], v[220:223], v[212:215], v[68:71]
	v_mfma_f32_16x16x32_bf16 v[64:67], v[228:231], v[212:215], v[64:67]
	v_mfma_f32_16x16x32_bf16 v[132:135], v[224:227], v[166:169], v[132:135]
	v_mfma_f32_16x16x32_bf16 v[128:131], v[232:235], v[166:169], v[128:131]
	v_mfma_f32_16x16x32_bf16 v[100:103], v[224:227], v[200:203], v[100:103]
	v_mfma_f32_16x16x32_bf16 v[96:99], v[232:235], v[200:203], v[96:99]
	v_mfma_f32_16x16x32_bf16 v[84:87], v[224:227], v[208:211], v[84:87]
	v_mfma_f32_16x16x32_bf16 v[80:83], v[232:235], v[208:211], v[80:83]
	v_mfma_f32_16x16x32_bf16 v[68:71], v[224:227], v[216:219], v[68:71]
	v_mfma_f32_16x16x32_bf16 v[64:67], v[232:235], v[216:219], v[64:67]
	s_setprio 0
	s_mov_b32 m0, s38
	v_lshl_add_u64 v[238:239], s[34:35], 0, v[144:145]
	s_barrier
	ds_read_b128 v[162:165], v172 offset:16384
	ds_read_b128 v[166:169], v172 offset:17408
	ds_read_b128 v[196:199], v172 offset:18432
	ds_read_b128 v[200:203], v172 offset:19456
	ds_read_b128 v[204:207], v172 offset:20480
	ds_read_b128 v[208:211], v172 offset:21504
	ds_read_b128 v[212:215], v172 offset:22528
	ds_read_b128 v[216:219], v172 offset:23552
	global_load_lds_dwordx4 v[238:239], off
	v_lshl_add_u64 v[240:241], s[34:35], 0, v[148:149]
	s_mov_b32 m0, s63
	s_nop 0
	global_load_lds_dwordx4 v[240:241], off
	s_barrier
	s_waitcnt lgkmcnt(0)
	s_setprio 1
	s_waitcnt lgkmcnt(0)
	v_mfma_f32_16x16x32_bf16 v[60:63], v[112:115], v[162:165], v[60:63]
	v_mfma_f32_16x16x32_bf16 v[56:59], v[120:123], v[162:165], v[56:59]
	v_mfma_f32_16x16x32_bf16 v[44:47], v[112:115], v[196:199], v[44:47]
	v_mfma_f32_16x16x32_bf16 v[40:43], v[120:123], v[196:199], v[40:43]
	v_mfma_f32_16x16x32_bf16 v[28:31], v[112:115], v[204:207], v[28:31]
	v_mfma_f32_16x16x32_bf16 v[24:27], v[120:123], v[204:207], v[24:27]
	v_mfma_f32_16x16x32_bf16 v[12:15], v[112:115], v[212:215], v[12:15]
	v_mfma_f32_16x16x32_bf16 v[8:11], v[120:123], v[212:215], v[8:11]
	v_mfma_f32_16x16x32_bf16 v[60:63], v[116:119], v[166:169], v[60:63]
	v_mfma_f32_16x16x32_bf16 v[56:59], v[124:127], v[166:169], v[56:59]
	v_mfma_f32_16x16x32_bf16 v[44:47], v[116:119], v[200:203], v[44:47]
	v_mfma_f32_16x16x32_bf16 v[40:43], v[124:127], v[200:203], v[40:43]
	v_mfma_f32_16x16x32_bf16 v[28:31], v[116:119], v[208:211], v[28:31]
	v_mfma_f32_16x16x32_bf16 v[24:27], v[124:127], v[208:211], v[24:27]
	v_mfma_f32_16x16x32_bf16 v[12:15], v[116:119], v[216:219], v[12:15]
	v_mfma_f32_16x16x32_bf16 v[8:11], v[124:127], v[216:219], v[8:11]
	s_setprio 0
	s_barrier
	s_add_u32 s20, s16, 0x40000
	s_addc_u32 s21, s17, 0
	s_mov_b32 m0, s64
	v_lshl_add_u64 v[112:113], s[20:21], 0, v[146:147]
	global_load_lds_dwordx4 v[112:113], off
	v_lshl_add_u64 v[112:113], s[20:21], 0, v[150:151]
	s_mov_b32 m0, s65
	s_nop 0
	global_load_lds_dwordx4 v[112:113], off
	s_waitcnt vmcnt(6)
	s_barrier
	s_setprio 1
	v_mfma_f32_16x16x32_bf16 v[52:55], v[220:223], v[162:165], v[52:55]
	v_mfma_f32_16x16x32_bf16 v[48:51], v[228:231], v[162:165], v[48:51]
	v_mfma_f32_16x16x32_bf16 v[36:39], v[220:223], v[196:199], v[36:39]
	v_mfma_f32_16x16x32_bf16 v[32:35], v[228:231], v[196:199], v[32:35]
	v_mfma_f32_16x16x32_bf16 v[20:23], v[220:223], v[204:207], v[20:23]
	v_mfma_f32_16x16x32_bf16 v[16:19], v[228:231], v[204:207], v[16:19]
	v_mfma_f32_16x16x32_bf16 v[4:7], v[220:223], v[212:215], v[4:7]
	v_mfma_f32_16x16x32_bf16 v[0:3], v[228:231], v[212:215], v[0:3]
	v_mfma_f32_16x16x32_bf16 v[52:55], v[224:227], v[166:169], v[52:55]
	v_mfma_f32_16x16x32_bf16 v[48:51], v[232:235], v[166:169], v[48:51]
	v_mfma_f32_16x16x32_bf16 v[36:39], v[224:227], v[200:203], v[36:39]
	v_mfma_f32_16x16x32_bf16 v[32:35], v[232:235], v[200:203], v[32:35]
	v_mfma_f32_16x16x32_bf16 v[20:23], v[224:227], v[208:211], v[20:23]
	v_mfma_f32_16x16x32_bf16 v[16:19], v[232:235], v[208:211], v[16:19]
	v_mfma_f32_16x16x32_bf16 v[4:7], v[224:227], v[216:219], v[4:7]
	v_mfma_f32_16x16x32_bf16 v[0:3], v[232:235], v[216:219], v[0:3]
	s_setprio 0
	s_barrier
	ds_read_b128 v[112:115], v185
	ds_read_b128 v[116:119], v186
	ds_read_b128 v[120:123], v187
	ds_read_b128 v[124:127], v188
	s_add_u32 s20, s34, 0x40000
	s_addc_u32 s21, s35, 0
	s_mov_b32 m0, s66
	v_lshl_add_u64 v[220:221], s[20:21], 0, v[144:145]
	ds_read_b128 v[162:165], v172 offset:32768
	ds_read_b128 v[166:169], v172 offset:33792
	ds_read_b128 v[196:199], v172 offset:34816
	ds_read_b128 v[200:203], v172 offset:35840
	ds_read_b128 v[204:207], v172 offset:36864
	ds_read_b128 v[208:211], v172 offset:37888
	ds_read_b128 v[212:215], v172 offset:38912
	ds_read_b128 v[216:219], v172 offset:39936
	global_load_lds_dwordx4 v[220:221], off
	v_lshl_add_u64 v[220:221], s[20:21], 0, v[148:149]
	s_mov_b32 m0, s67
	s_nop 0
	global_load_lds_dwordx4 v[220:221], off
	s_waitcnt lgkmcnt(8)
	s_barrier
	s_waitcnt lgkmcnt(0)
	s_setprio 1
	s_waitcnt lgkmcnt(0)
	v_mfma_f32_16x16x32_bf16 v[140:143], v[112:115], v[162:165], v[140:143]
	v_mfma_f32_16x16x32_bf16 v[136:139], v[120:123], v[162:165], v[136:139]
	v_mfma_f32_16x16x32_bf16 v[108:111], v[112:115], v[196:199], v[108:111]
	v_mfma_f32_16x16x32_bf16 v[104:107], v[120:123], v[196:199], v[104:107]
	v_mfma_f32_16x16x32_bf16 v[92:95], v[112:115], v[204:207], v[92:95]
	v_mfma_f32_16x16x32_bf16 v[88:91], v[120:123], v[204:207], v[88:91]
	v_mfma_f32_16x16x32_bf16 v[76:79], v[112:115], v[212:215], v[76:79]
	v_mfma_f32_16x16x32_bf16 v[72:75], v[120:123], v[212:215], v[72:75]
	v_mfma_f32_16x16x32_bf16 v[140:143], v[116:119], v[166:169], v[140:143]
	v_mfma_f32_16x16x32_bf16 v[136:139], v[124:127], v[166:169], v[136:139]
	v_mfma_f32_16x16x32_bf16 v[108:111], v[116:119], v[200:203], v[108:111]
	v_mfma_f32_16x16x32_bf16 v[104:107], v[124:127], v[200:203], v[104:107]
	v_mfma_f32_16x16x32_bf16 v[92:95], v[116:119], v[208:211], v[92:95]
	v_mfma_f32_16x16x32_bf16 v[88:91], v[124:127], v[208:211], v[88:91]
	v_mfma_f32_16x16x32_bf16 v[76:79], v[116:119], v[216:219], v[76:79]
	v_mfma_f32_16x16x32_bf16 v[72:75], v[124:127], v[216:219], v[72:75]
	s_setprio 0
	s_barrier
	s_mov_b32 m0, s83
	v_lshl_add_u64 v[170:171], v[170:171], 0, s[0:1]
	ds_read_b128 v[220:223], v189
	ds_read_b128 v[224:227], v190
	ds_read_b128 v[228:231], v191
	ds_read_b128 v[232:235], v192
	global_load_lds_dwordx4 v[170:171], off
	v_lshl_add_u64 v[170:171], v[236:237], 0, s[0:1]
	s_mov_b32 m0, s84
	s_nop 0
	global_load_lds_dwordx4 v[170:171], off
	s_barrier
	s_waitcnt lgkmcnt(0)
	s_setprio 1
	s_waitcnt lgkmcnt(0)
	v_mfma_f32_16x16x32_bf16 v[132:135], v[220:223], v[162:165], v[132:135]
	v_mfma_f32_16x16x32_bf16 v[128:131], v[228:231], v[162:165], v[128:131]
	v_mfma_f32_16x16x32_bf16 v[100:103], v[220:223], v[196:199], v[100:103]
	v_mfma_f32_16x16x32_bf16 v[96:99], v[228:231], v[196:199], v[96:99]
	v_mfma_f32_16x16x32_bf16 v[84:87], v[220:223], v[204:207], v[84:87]
	v_mfma_f32_16x16x32_bf16 v[80:83], v[228:231], v[204:207], v[80:83]
	v_mfma_f32_16x16x32_bf16 v[68:71], v[220:223], v[212:215], v[68:71]
	v_mfma_f32_16x16x32_bf16 v[64:67], v[228:231], v[212:215], v[64:67]
	v_mfma_f32_16x16x32_bf16 v[132:135], v[224:227], v[166:169], v[132:135]
	v_mfma_f32_16x16x32_bf16 v[128:131], v[232:235], v[166:169], v[128:131]
	v_mfma_f32_16x16x32_bf16 v[100:103], v[224:227], v[200:203], v[100:103]
	v_mfma_f32_16x16x32_bf16 v[96:99], v[232:235], v[200:203], v[96:99]
	v_mfma_f32_16x16x32_bf16 v[84:87], v[224:227], v[208:211], v[84:87]
	v_mfma_f32_16x16x32_bf16 v[80:83], v[232:235], v[208:211], v[80:83]
	v_mfma_f32_16x16x32_bf16 v[68:71], v[224:227], v[216:219], v[68:71]
	v_mfma_f32_16x16x32_bf16 v[64:67], v[232:235], v[216:219], v[64:67]
	s_setprio 0
	s_mov_b32 m0, s85
	v_lshl_add_u64 v[170:171], v[238:239], 0, s[0:1]
	s_barrier
	ds_read_b128 v[162:165], v172 offset:49152
	ds_read_b128 v[166:169], v172 offset:50176
	ds_read_b128 v[196:199], v172 offset:51200
	ds_read_b128 v[200:203], v172 offset:52224
	ds_read_b128 v[204:207], v172 offset:53248
	ds_read_b128 v[208:211], v172 offset:54272
	ds_read_b128 v[212:215], v172 offset:55296
	ds_read_b128 v[216:219], v172 offset:56320
	global_load_lds_dwordx4 v[170:171], off
	v_lshl_add_u64 v[170:171], v[240:241], 0, s[0:1]
	s_mov_b32 m0, s86
	s_nop 0
	global_load_lds_dwordx4 v[170:171], off
	s_barrier
	s_waitcnt lgkmcnt(0)
	s_setprio 1
	s_waitcnt lgkmcnt(0)
	v_mfma_f32_16x16x32_bf16 v[60:63], v[112:115], v[162:165], v[60:63]
	v_mfma_f32_16x16x32_bf16 v[56:59], v[120:123], v[162:165], v[56:59]
	v_mfma_f32_16x16x32_bf16 v[44:47], v[112:115], v[196:199], v[44:47]
	v_mfma_f32_16x16x32_bf16 v[40:43], v[120:123], v[196:199], v[40:43]
	v_mfma_f32_16x16x32_bf16 v[28:31], v[112:115], v[204:207], v[28:31]
	v_mfma_f32_16x16x32_bf16 v[24:27], v[120:123], v[204:207], v[24:27]
	v_mfma_f32_16x16x32_bf16 v[12:15], v[112:115], v[212:215], v[12:15]
	v_mfma_f32_16x16x32_bf16 v[8:11], v[120:123], v[212:215], v[8:11]
	v_mfma_f32_16x16x32_bf16 v[60:63], v[116:119], v[166:169], v[60:63]
	v_mfma_f32_16x16x32_bf16 v[56:59], v[124:127], v[166:169], v[56:59]
	v_mfma_f32_16x16x32_bf16 v[44:47], v[116:119], v[200:203], v[44:47]
	v_mfma_f32_16x16x32_bf16 v[40:43], v[124:127], v[200:203], v[40:43]
	v_mfma_f32_16x16x32_bf16 v[28:31], v[116:119], v[208:211], v[28:31]
	v_mfma_f32_16x16x32_bf16 v[24:27], v[124:127], v[208:211], v[24:27]
	v_mfma_f32_16x16x32_bf16 v[12:15], v[116:119], v[216:219], v[12:15]
	v_mfma_f32_16x16x32_bf16 v[8:11], v[124:127], v[216:219], v[8:11]
	s_setprio 0
	s_barrier
	s_add_u32 s16, s16, 0x40080
	s_addc_u32 s17, s17, 0
	s_mov_b32 m0, s87
	v_lshl_add_u64 v[112:113], s[16:17], 0, v[146:147]
	global_load_lds_dwordx4 v[112:113], off
	v_lshl_add_u64 v[112:113], s[16:17], 0, v[150:151]
	s_mov_b32 m0, s88
	s_nop 0
	global_load_lds_dwordx4 v[112:113], off
	s_waitcnt vmcnt(6)
	s_barrier
	s_setprio 1
	v_mfma_f32_16x16x32_bf16 v[52:55], v[220:223], v[162:165], v[52:55]
	v_mfma_f32_16x16x32_bf16 v[48:51], v[228:231], v[162:165], v[48:51]
	v_mfma_f32_16x16x32_bf16 v[36:39], v[220:223], v[196:199], v[36:39]
	v_mfma_f32_16x16x32_bf16 v[32:35], v[228:231], v[196:199], v[32:35]
	v_mfma_f32_16x16x32_bf16 v[20:23], v[220:223], v[204:207], v[20:23]
	v_mfma_f32_16x16x32_bf16 v[16:19], v[228:231], v[204:207], v[16:19]
	v_mfma_f32_16x16x32_bf16 v[4:7], v[220:223], v[212:215], v[4:7]
	v_mfma_f32_16x16x32_bf16 v[0:3], v[228:231], v[212:215], v[0:3]
	v_mfma_f32_16x16x32_bf16 v[52:55], v[224:227], v[166:169], v[52:55]
	v_mfma_f32_16x16x32_bf16 v[48:51], v[232:235], v[166:169], v[48:51]
	v_mfma_f32_16x16x32_bf16 v[36:39], v[224:227], v[200:203], v[36:39]
	v_mfma_f32_16x16x32_bf16 v[32:35], v[232:235], v[200:203], v[32:35]
	v_mfma_f32_16x16x32_bf16 v[20:23], v[224:227], v[208:211], v[20:23]
	v_mfma_f32_16x16x32_bf16 v[16:19], v[232:235], v[208:211], v[16:19]
	v_mfma_f32_16x16x32_bf16 v[4:7], v[224:227], v[216:219], v[4:7]
	v_mfma_f32_16x16x32_bf16 v[0:3], v[232:235], v[216:219], v[0:3]
	s_setprio 0
	s_add_i32 s96, s96, 2
	s_add_u32 s18, s18, 0x100
	s_addc_u32 s19, s19, 0
	s_add_u32 s14, s14, 0x100
	s_addc_u32 s15, s15, 0
	s_cmp_gt_u32 s96, 13
	s_barrier
	s_cbranch_scc0 .LBB0_454
	s_cmp_lg_u32 s93, 0
	v_lshl_add_u32 v162, s13, 10, v173
	s_cbranch_scc0 .LBB0_457
	ds_read2_b32 v[122:123], v162 offset1:16
	ds_read2_b32 v[124:125], v162 offset0:32 offset1:48
	ds_read2_b32 v[116:117], v162 offset0:128 offset1:144
	ds_read2_b32 v[114:115], v162 offset0:160 offset1:176
	s_ashr_i32 s13, s12, 31
	s_lshl_b64 s[14:15], s[12:13], 17
	s_waitcnt lgkmcnt(0)
	v_pk_mul_f32 v[120:121], v[142:143], v[122:123] op_sel_hi:[1,0]
	v_pk_mul_f32 v[118:119], v[140:141], v[122:123] op_sel_hi:[1,0]
	v_lshl_add_u64 v[112:113], v[154:155], 0, s[14:15]
	v_pk_mul_f32 v[126:127], v[138:139], v[122:123] op_sel_hi:[1,0]
	v_pk_mul_f32 v[164:165], v[136:137], v[122:123] op_sel_hi:[1,0]
	v_cvt_pk_bf16_f32 v118, v118, v119
	v_cvt_pk_bf16_f32 v119, v120, v121
	v_cvt_pk_bf16_f32 v121, v126, v127
	v_pk_mul_f32 v[126:127], v[130:131], v[122:123] op_sel_hi:[1,0]
	v_cvt_pk_bf16_f32 v120, v164, v165
	s_waitcnt vmcnt(0)
	global_store_dwordx4 v[112:113], v[118:121], off
	v_pk_mul_f32 v[164:165], v[128:129], v[122:123] op_sel_hi:[1,0]
	s_nop 0
	v_pk_mul_f32 v[120:121], v[134:135], v[122:123] op_sel_hi:[1,0]
	v_pk_mul_f32 v[118:119], v[132:133], v[122:123] op_sel_hi:[1,0]
	v_mov_b32_e32 v122, v123
	v_cvt_pk_bf16_f32 v118, v118, v119
	v_cvt_pk_bf16_f32 v119, v120, v121
	v_cvt_pk_bf16_f32 v120, v164, v165
	v_cvt_pk_bf16_f32 v121, v126, v127
	global_store_dwordx4 v[112:113], v[118:121], off offset:256
	v_pk_mul_f32 v[126:127], v[106:107], v[122:123] op_sel_hi:[1,0]
	v_pk_mul_f32 v[164:165], v[104:105], v[122:123] op_sel_hi:[1,0]
	v_pk_mul_f32 v[120:121], v[110:111], v[122:123] op_sel_hi:[1,0]
	v_pk_mul_f32 v[118:119], v[108:109], v[122:123] op_sel_hi:[1,0]
	s_nop 0
	v_cvt_pk_bf16_f32 v118, v118, v119
	v_cvt_pk_bf16_f32 v119, v120, v121
	v_cvt_pk_bf16_f32 v121, v126, v127
	v_add_co_u32_e32 v126, vcc, s70, v112
	v_cvt_pk_bf16_f32 v120, v164, v165
	v_pk_mul_f32 v[164:165], v[98:99], v[122:123] op_sel_hi:[1,0]
	s_nop 0
	v_addc_co_u32_e32 v127, vcc, 0, v113, vcc
	global_store_dwordx4 v[126:127], v[118:121], off
	s_nop 1
	v_pk_mul_f32 v[120:121], v[102:103], v[122:123] op_sel_hi:[1,0]
	v_pk_mul_f32 v[118:119], v[100:101], v[122:123] op_sel_hi:[1,0]
	v_pk_mul_f32 v[122:123], v[96:97], v[122:123] op_sel_hi:[1,0]
	v_cvt_pk_bf16_f32 v118, v118, v119
	v_cvt_pk_bf16_f32 v119, v120, v121
	v_cvt_pk_bf16_f32 v121, v164, v165
	v_pk_mul_f32 v[164:165], v[80:81], v[124:125] op_sel_hi:[1,0]
	v_cvt_pk_bf16_f32 v120, v122, v123
	global_store_dwordx4 v[126:127], v[118:121], off offset:256
	v_pk_mul_f32 v[122:123], v[90:91], v[124:125] op_sel_hi:[1,0]
	v_pk_mul_f32 v[126:127], v[88:89], v[124:125] op_sel_hi:[1,0]
	v_pk_mul_f32 v[120:121], v[94:95], v[124:125] op_sel_hi:[1,0]
	v_pk_mul_f32 v[118:119], v[92:93], v[124:125] op_sel_hi:[1,0]
	s_nop 0
	v_cvt_pk_bf16_f32 v118, v118, v119
	v_cvt_pk_bf16_f32 v119, v120, v121
	v_cvt_pk_bf16_f32 v121, v122, v123
	v_add_co_u32_e32 v122, vcc, s81, v112
	v_cvt_pk_bf16_f32 v120, v126, v127
	v_pk_mul_f32 v[126:127], v[82:83], v[124:125] op_sel_hi:[1,0]
	s_nop 0
	v_addc_co_u32_e32 v123, vcc, 0, v113, vcc
	global_store_dwordx4 v[122:123], v[118:121], off
	s_nop 1
	v_pk_mul_f32 v[120:121], v[86:87], v[124:125] op_sel_hi:[1,0]
	v_pk_mul_f32 v[118:119], v[84:85], v[124:125] op_sel_hi:[1,0]
	s_nop 0
	v_cvt_pk_bf16_f32 v118, v118, v119
	v_cvt_pk_bf16_f32 v119, v120, v121
	v_cvt_pk_bf16_f32 v120, v164, v165
	v_cvt_pk_bf16_f32 v121, v126, v127
	global_store_dwordx4 v[122:123], v[118:121], off offset:256
	v_mov_b32_e32 v122, v125
	v_pk_mul_f32 v[124:125], v[74:75], v[122:123] op_sel_hi:[1,0]
	v_pk_mul_f32 v[120:121], v[78:79], v[122:123] op_sel_hi:[1,0]
	v_pk_mul_f32 v[118:119], v[76:77], v[122:123] op_sel_hi:[1,0]
	v_pk_mul_f32 v[126:127], v[72:73], v[122:123] op_sel_hi:[1,0]
	v_cvt_pk_bf16_f32 v118, v118, v119
	v_cvt_pk_bf16_f32 v119, v120, v121
	v_cvt_pk_bf16_f32 v121, v124, v125
	v_add_co_u32_e32 v124, vcc, s82, v112
	v_cvt_pk_bf16_f32 v120, v126, v127
	v_pk_mul_f32 v[126:127], v[66:67], v[122:123] op_sel_hi:[1,0]
	s_nop 0
	v_addc_co_u32_e32 v125, vcc, 0, v113, vcc
	global_store_dwordx4 v[124:125], v[118:121], off
	s_nop 1
	v_pk_mul_f32 v[120:121], v[70:71], v[122:123] op_sel_hi:[1,0]
	v_pk_mul_f32 v[118:119], v[68:69], v[122:123] op_sel_hi:[1,0]
	v_pk_mul_f32 v[122:123], v[64:65], v[122:123] op_sel_hi:[1,0]
	v_cvt_pk_bf16_f32 v118, v118, v119
	v_cvt_pk_bf16_f32 v119, v120, v121
	v_cvt_pk_bf16_f32 v121, v126, v127
	v_pk_mul_f32 v[126:127], v[48:49], v[116:117] op_sel_hi:[1,0]
	v_cvt_pk_bf16_f32 v120, v122, v123
	global_store_dwordx4 v[124:125], v[118:121], off offset:256
	v_pk_mul_f32 v[122:123], v[58:59], v[116:117] op_sel_hi:[1,0]
	v_pk_mul_f32 v[124:125], v[56:57], v[116:117] op_sel_hi:[1,0]
	v_pk_mul_f32 v[120:121], v[62:63], v[116:117] op_sel_hi:[1,0]
	v_pk_mul_f32 v[118:119], v[60:61], v[116:117] op_sel_hi:[1,0]
	s_nop 0
	v_cvt_pk_bf16_f32 v118, v118, v119
	v_cvt_pk_bf16_f32 v119, v120, v121
	v_cvt_pk_bf16_f32 v121, v122, v123
	v_add_co_u32_e32 v122, vcc, s68, v112
	v_cvt_pk_bf16_f32 v120, v124, v125
	v_pk_mul_f32 v[124:125], v[50:51], v[116:117] op_sel_hi:[1,0]
	s_nop 0
	v_addc_co_u32_e32 v123, vcc, 0, v113, vcc
	global_store_dwordx4 v[122:123], v[118:121], off
	s_nop 1
	v_pk_mul_f32 v[120:121], v[54:55], v[116:117] op_sel_hi:[1,0]
	v_pk_mul_f32 v[118:119], v[52:53], v[116:117] op_sel_hi:[1,0]
	s_nop 0
	v_cvt_pk_bf16_f32 v118, v118, v119
	v_cvt_pk_bf16_f32 v119, v120, v121
	v_cvt_pk_bf16_f32 v120, v126, v127
	v_cvt_pk_bf16_f32 v121, v124, v125
	global_store_dwordx4 v[122:123], v[118:121], off offset:256
	s_nop 1
	v_mov_b32_e32 v120, v117
	v_pk_mul_f32 v[118:119], v[46:47], v[120:121] op_sel_hi:[1,0]
	v_pk_mul_f32 v[116:117], v[44:45], v[120:121] op_sel_hi:[1,0]
	v_pk_mul_f32 v[122:123], v[42:43], v[120:121] op_sel_hi:[1,0]
	v_cvt_pk_bf16_f32 v116, v116, v117
	v_cvt_pk_bf16_f32 v117, v118, v119
	v_pk_mul_f32 v[124:125], v[40:41], v[120:121] op_sel_hi:[1,0]
	v_cvt_pk_bf16_f32 v119, v122, v123
	v_add_co_u32_e32 v122, vcc, s69, v112
	v_cvt_pk_bf16_f32 v118, v124, v125
	v_pk_mul_f32 v[124:125], v[34:35], v[120:121] op_sel_hi:[1,0]
	s_nop 0
	v_addc_co_u32_e32 v123, vcc, 0, v113, vcc
	global_store_dwordx4 v[122:123], v[116:119], off
	s_nop 1
	v_pk_mul_f32 v[118:119], v[38:39], v[120:121] op_sel_hi:[1,0]
	v_pk_mul_f32 v[116:117], v[36:37], v[120:121] op_sel_hi:[1,0]
	v_pk_mul_f32 v[120:121], v[32:33], v[120:121] op_sel_hi:[1,0]
	v_cvt_pk_bf16_f32 v116, v116, v117
	v_cvt_pk_bf16_f32 v117, v118, v119
	v_cvt_pk_bf16_f32 v119, v124, v125
	v_pk_mul_f32 v[124:125], v[16:17], v[114:115] op_sel_hi:[1,0]
	v_cvt_pk_bf16_f32 v118, v120, v121
	global_store_dwordx4 v[122:123], v[116:119], off offset:256
	v_pk_mul_f32 v[120:121], v[26:27], v[114:115] op_sel_hi:[1,0]
	v_pk_mul_f32 v[122:123], v[24:25], v[114:115] op_sel_hi:[1,0]
	v_pk_mul_f32 v[118:119], v[30:31], v[114:115] op_sel_hi:[1,0]
	v_pk_mul_f32 v[116:117], v[28:29], v[114:115] op_sel_hi:[1,0]
	s_nop 0
	v_cvt_pk_bf16_f32 v116, v116, v117
	v_cvt_pk_bf16_f32 v117, v118, v119
	v_cvt_pk_bf16_f32 v119, v120, v121
	v_add_co_u32_e32 v120, vcc, s71, v112
	v_cvt_pk_bf16_f32 v118, v122, v123
	v_pk_mul_f32 v[122:123], v[18:19], v[114:115] op_sel_hi:[1,0]
	s_nop 0
	v_addc_co_u32_e32 v121, vcc, 0, v113, vcc
	global_store_dwordx4 v[120:121], v[116:119], off
	s_nop 1
	v_pk_mul_f32 v[118:119], v[22:23], v[114:115] op_sel_hi:[1,0]
	v_pk_mul_f32 v[116:117], v[20:21], v[114:115] op_sel_hi:[1,0]
	s_nop 0
	v_cvt_pk_bf16_f32 v116, v116, v117
	v_cvt_pk_bf16_f32 v117, v118, v119
	v_cvt_pk_bf16_f32 v118, v124, v125
	v_cvt_pk_bf16_f32 v119, v122, v123
	global_store_dwordx4 v[120:121], v[116:119], off offset:256
	s_nop 1
	v_mov_b32_e32 v118, v115
	v_pk_mul_f32 v[116:117], v[14:15], v[118:119] op_sel_hi:[1,0]
	v_pk_mul_f32 v[114:115], v[12:13], v[118:119] op_sel_hi:[1,0]
	v_pk_mul_f32 v[120:121], v[10:11], v[118:119] op_sel_hi:[1,0]
	v_cvt_pk_bf16_f32 v114, v114, v115
	v_cvt_pk_bf16_f32 v115, v116, v117
	v_pk_mul_f32 v[122:123], v[8:9], v[118:119] op_sel_hi:[1,0]
	v_cvt_pk_bf16_f32 v117, v120, v121
	v_add_co_u32_e32 v120, vcc, s80, v112
	v_cvt_pk_bf16_f32 v116, v122, v123
	s_nop 1
	v_addc_co_u32_e32 v121, vcc, 0, v113, vcc
	global_store_dwordx4 v[120:121], v[114:117], off
	v_pk_mul_f32 v[112:113], v[4:5], v[118:119] op_sel_hi:[1,0]
	s_nop 0
	v_pk_mul_f32 v[114:115], v[6:7], v[118:119] op_sel_hi:[1,0]
	v_pk_mul_f32 v[116:117], v[2:3], v[118:119] op_sel_hi:[1,0]
	v_pk_mul_f32 v[118:119], v[0:1], v[118:119] op_sel_hi:[1,0]
	v_cvt_pk_bf16_f32 v112, v112, v113
	v_cvt_pk_bf16_f32 v113, v114, v115
	v_cvt_pk_bf16_f32 v115, v116, v117
	s_nop 0
	v_cvt_pk_bf16_f32 v114, v118, v119
	global_store_dwordx4 v[120:121], v[112:115], off offset:256
	s_cbranch_execnz .LBB0_450
	s_branch .LBB0_449

.LBB0_515:
	v_cmp_gt_i64_e32 vcc, s[6:7], v[4:5]
	s_mov_b64 s[10:11], -1
	s_cbranch_vccnz .LBB0_514
	s_mov_b64 s[10:11], exec
	s_cbranch_execz .LBB0_513
	s_ashr_i32 s15, s6, 31
	s_lshr_b32 s15, s15, 29
	s_add_i32 s15, s6, s15
	s_ashr_i32 s16, s15, 3
	s_and_b32 s15, s15, -8
	s_sub_i32 s15, s6, s15
	s_cmp_lt_i32 s15, 0
	s_cselect_b32 s17, s12, 0xe0
	s_mul_i32 s15, s17, s15
	s_add_i32 s15, s15, s16
	s_mul_hi_i32 s16, s15, 0x92492493
	s_add_i32 s16, s16, s15
	s_lshr_b32 s17, s16, 31
	s_ashr_i32 s16, s16, 6
	s_add_i32 s16, s16, s17
	s_lshl_b32 s17, s16, 3
	s_sub_i32 s18, 0x80, s17
	s_min_i32 s18, s18, 8
	s_abs_i32 s18, s18
	v_cvt_f32_u32_e32 v7, s18
	s_sub_i32 s19, 0, s18
	s_mulk_i32 s16, 0x70
	s_sub_i32 s15, s15, s16
	v_rcp_iflag_f32_e32 v7, v7
	s_ashr_i32 s16, s15, 31
	s_abs_i32 s15, s15
	v_mul_f32_e32 v7, 0x4f7ffffe, v7
	v_cvt_u32_f32_e32 v7, v7
	s_nop 0
	v_readfirstlane_b32 s20, v7
	s_mul_i32 s19, s19, s20
	s_mul_hi_u32 s19, s20, s19
	s_add_i32 s20, s20, s19
	s_mul_hi_u32 s19, s15, s20
	s_mul_i32 s19, s19, s18
	s_sub_i32 s15, s15, s19
	s_sub_i32 s19, s15, s18
	s_cmp_ge_u32 s15, s18
	s_cselect_b32 s15, s19, s15
	s_sub_i32 s19, s15, s18
	s_cmp_ge_u32 s15, s18
	s_cselect_b32 s15, s19, s15
	s_xor_b32 s15, s15, s16
	s_sub_i32 s15, s15, s16
	s_add_i32 s16, s15, s17
	s_ashr_i32 s17, s16, 31
	s_lshl_b64 s[16:17], s[16:17], 14
	v_lshl_add_u64 v[8:9], v[2:3], 0, s[16:17]
	s_waitcnt vmcnt(0)
	global_load_dwordx4 v[12:15], v[8:9], off
	global_load_dwordx4 v[16:19], v[8:9], off offset:16
	global_load_dwordx4 v[20:23], v[8:9], off offset:32
	global_load_dwordx4 v[24:27], v[8:9], off offset:48
	s_waitcnt vmcnt(0) lgkmcnt(0)
	v_mov_b32_e32 v8, v13
	v_mov_b32_e32 v9, v14
	v_mov_b32_e32 v28, v17
	v_mov_b32_e32 v29, v18
	v_mov_b32_e32 v13, v15
	v_mov_b32_e32 v17, v19
	v_mov_b32_e32 v14, v21
	v_mov_b32_e32 v18, v23
	v_pk_add_f32 v[8:9], v[8:9], v[12:13]
	v_pk_add_f32 v[12:13], v[28:29], v[16:17]
	v_pk_add_f32 v[14:15], v[20:21], v[14:15]
	v_pk_add_f32 v[16:17], v[22:23], v[18:19]
	v_pk_add_f32 v[8:9], v[8:9], v[8:9] op_sel:[0,1] op_sel_hi:[1,0]
	v_pk_add_f32 v[12:13], v[12:13], v[12:13] op_sel:[0,1] op_sel_hi:[1,0]
	v_mov_b32_e32 v15, v26
	v_mov_b32_e32 v17, v27
	v_mov_b32_e32 v9, v24
	v_mov_b32_e32 v13, v25
	v_pk_add_f32 v[14:15], v[14:15], v[16:17]
	v_pk_add_f32 v[8:9], v[8:9], v[12:13]
	s_nop 0
	v_pk_add_f32 v[8:9], v[8:9], v[14:15]
	s_nop 0
	v_add_f32_e32 v7, v8, v9
	v_fmamk_f32 v7, v7, 0x3a800000, v6
	v_mul_f32_e32 v8, 0x4b800000, v7
	v_cmp_gt_f32_e32 vcc, s14, v7
	s_nop 1
	v_cndmask_b32_e32 v7, v7, v8, vcc
	v_rsq_f32_e32 v7, v7
	s_nop 0
	v_mul_f32_e32 v8, 0x45800000, v7
	v_cndmask_b32_e32 v7, v7, v8, vcc
	ds_write_b32 v1, v7
	s_branch .LBB0_513

.LBB0_526:
	ds_read_b128 v[154:157], v185
	ds_read_b128 v[158:161], v186
	ds_read_b128 v[162:165], v187
	ds_read_b128 v[166:169], v188
	s_add_u32 s20, s38, 0xfffc0080
	s_addc_u32 s21, s39, -1
	s_cmp_eq_u32 s66, 12
	s_cselect_b32 s59, s17, s21
	s_cselect_b32 s58, s37, s20
	s_cselect_b32 s57, s15, s33
	s_cselect_b32 s56, vcc_lo, vcc_hi
	s_mov_b32 m0, s90
	v_lshl_add_u64 v[174:175], s[38:39], 0, v[148:149]
	ds_read_b128 v[170:173], v177
	ds_read_b128 v[180:183], v177 offset:1024
	ds_read_b128 v[204:207], v177 offset:2048
	ds_read_b128 v[208:211], v177 offset:3072
	ds_read_b128 v[212:215], v177 offset:4096
	ds_read_b128 v[216:219], v177 offset:5120
	ds_read_b128 v[220:223], v177 offset:6144
	ds_read_b128 v[224:227], v177 offset:7168
	global_load_lds_dwordx4 v[174:175], off
	v_lshl_add_u64 v[174:175], s[38:39], 0, v[146:147]
	s_mov_b32 m0, s91
	s_nop 0
	global_load_lds_dwordx4 v[174:175], off
	s_waitcnt lgkmcnt(8)
	s_barrier
	s_waitcnt lgkmcnt(0)
	s_setprio 1
	s_waitcnt lgkmcnt(0)
	v_mfma_f32_16x16x32_bf16 v[124:127], v[154:157], v[170:173], v[124:127]
	v_mfma_f32_16x16x32_bf16 v[120:123], v[162:165], v[170:173], v[120:123]
	v_mfma_f32_16x16x32_bf16 v[112:115], v[154:157], v[204:207], v[112:115]
	v_mfma_f32_16x16x32_bf16 v[104:107], v[162:165], v[204:207], v[104:107]
	v_mfma_f32_16x16x32_bf16 v[96:99], v[154:157], v[212:215], v[96:99]
	v_mfma_f32_16x16x32_bf16 v[88:91], v[162:165], v[212:215], v[88:91]
	v_mfma_f32_16x16x32_bf16 v[80:83], v[154:157], v[220:223], v[80:83]
	v_mfma_f32_16x16x32_bf16 v[72:75], v[162:165], v[220:223], v[72:75]
	v_mfma_f32_16x16x32_bf16 v[124:127], v[158:161], v[180:183], v[124:127]
	v_mfma_f32_16x16x32_bf16 v[120:123], v[166:169], v[180:183], v[120:123]
	v_mfma_f32_16x16x32_bf16 v[112:115], v[158:161], v[208:211], v[112:115]
	v_mfma_f32_16x16x32_bf16 v[104:107], v[166:169], v[208:211], v[104:107]
	v_mfma_f32_16x16x32_bf16 v[96:99], v[158:161], v[216:219], v[96:99]
	v_mfma_f32_16x16x32_bf16 v[88:91], v[166:169], v[216:219], v[88:91]
	v_mfma_f32_16x16x32_bf16 v[80:83], v[158:161], v[224:227], v[80:83]
	v_mfma_f32_16x16x32_bf16 v[72:75], v[166:169], v[224:227], v[72:75]
	s_setprio 0
	s_barrier
	s_mov_b32 m0, s67
	v_lshl_add_u64 v[174:175], s[56:57], 0, v[132:133]
	ds_read_b128 v[228:231], v189
	ds_read_b128 v[232:235], v190
	ds_read_b128 v[236:239], v191
	ds_read_b128 v[240:243], v192
	global_load_lds_dwordx4 v[174:175], off
	v_lshl_add_u64 v[244:245], s[56:57], 0, v[128:129]
	s_mov_b32 m0, s68
	s_nop 0
	global_load_lds_dwordx4 v[244:245], off
	s_barrier
	s_waitcnt lgkmcnt(0)
	s_setprio 1
	s_waitcnt lgkmcnt(0)
	v_mfma_f32_16x16x32_bf16 v[116:119], v[228:231], v[170:173], v[116:119]
	v_mfma_f32_16x16x32_bf16 v[108:111], v[236:239], v[170:173], v[108:111]
	v_mfma_f32_16x16x32_bf16 v[100:103], v[228:231], v[204:207], v[100:103]
	v_mfma_f32_16x16x32_bf16 v[92:95], v[236:239], v[204:207], v[92:95]
	v_mfma_f32_16x16x32_bf16 v[84:87], v[228:231], v[212:215], v[84:87]
	v_mfma_f32_16x16x32_bf16 v[76:79], v[236:239], v[212:215], v[76:79]
	v_mfma_f32_16x16x32_bf16 v[68:71], v[228:231], v[220:223], v[68:71]
	v_mfma_f32_16x16x32_bf16 v[64:67], v[236:239], v[220:223], v[64:67]
	v_mfma_f32_16x16x32_bf16 v[116:119], v[232:235], v[180:183], v[116:119]
	v_mfma_f32_16x16x32_bf16 v[108:111], v[240:243], v[180:183], v[108:111]
	v_mfma_f32_16x16x32_bf16 v[100:103], v[232:235], v[208:211], v[100:103]
	v_mfma_f32_16x16x32_bf16 v[92:95], v[240:243], v[208:211], v[92:95]
	v_mfma_f32_16x16x32_bf16 v[84:87], v[232:235], v[216:219], v[84:87]
	v_mfma_f32_16x16x32_bf16 v[76:79], v[240:243], v[216:219], v[76:79]
	v_mfma_f32_16x16x32_bf16 v[68:71], v[232:235], v[224:227], v[68:71]
	v_mfma_f32_16x16x32_bf16 v[64:67], v[240:243], v[224:227], v[64:67]
	s_setprio 0
	s_mov_b32 m0, s63
	v_lshl_add_u64 v[246:247], s[58:59], 0, v[134:135]
	s_barrier
	ds_read_b128 v[170:173], v177 offset:16384
	ds_read_b128 v[180:183], v177 offset:17408
	ds_read_b128 v[204:207], v177 offset:18432
	ds_read_b128 v[208:211], v177 offset:19456
	ds_read_b128 v[212:215], v177 offset:20480
	ds_read_b128 v[216:219], v177 offset:21504
	ds_read_b128 v[220:223], v177 offset:22528
	ds_read_b128 v[224:227], v177 offset:23552
	global_load_lds_dwordx4 v[246:247], off
	v_lshl_add_u64 v[248:249], s[58:59], 0, v[130:131]
	s_mov_b32 m0, s69
	s_nop 0
	global_load_lds_dwordx4 v[248:249], off
	s_barrier
	s_waitcnt lgkmcnt(0)
	s_setprio 1
	s_waitcnt lgkmcnt(0)
	v_mfma_f32_16x16x32_bf16 v[60:63], v[154:157], v[170:173], v[60:63]
	v_mfma_f32_16x16x32_bf16 v[56:59], v[162:165], v[170:173], v[56:59]
	v_mfma_f32_16x16x32_bf16 v[48:51], v[154:157], v[204:207], v[48:51]
	v_mfma_f32_16x16x32_bf16 v[40:43], v[162:165], v[204:207], v[40:43]
	v_mfma_f32_16x16x32_bf16 v[32:35], v[154:157], v[212:215], v[32:35]
	v_mfma_f32_16x16x32_bf16 v[24:27], v[162:165], v[212:215], v[24:27]
	v_mfma_f32_16x16x32_bf16 v[16:19], v[154:157], v[220:223], v[16:19]
	v_mfma_f32_16x16x32_bf16 v[8:11], v[162:165], v[220:223], v[8:11]
	v_mfma_f32_16x16x32_bf16 v[60:63], v[158:161], v[180:183], v[60:63]
	v_mfma_f32_16x16x32_bf16 v[56:59], v[166:169], v[180:183], v[56:59]
	v_mfma_f32_16x16x32_bf16 v[48:51], v[158:161], v[208:211], v[48:51]
	v_mfma_f32_16x16x32_bf16 v[40:43], v[166:169], v[208:211], v[40:43]
	v_mfma_f32_16x16x32_bf16 v[32:35], v[158:161], v[216:219], v[32:35]
	v_mfma_f32_16x16x32_bf16 v[24:27], v[166:169], v[216:219], v[24:27]
	v_mfma_f32_16x16x32_bf16 v[16:19], v[158:161], v[224:227], v[16:19]
	v_mfma_f32_16x16x32_bf16 v[8:11], v[166:169], v[224:227], v[8:11]
	s_setprio 0
	s_barrier
	s_add_u32 s20, s56, 0x40000
	s_addc_u32 s21, s57, 0
	s_mov_b32 m0, s70
	v_lshl_add_u64 v[154:155], s[20:21], 0, v[132:133]
	global_load_lds_dwordx4 v[154:155], off
	v_lshl_add_u64 v[154:155], s[20:21], 0, v[128:129]
	s_mov_b32 m0, s71
	s_nop 0
	global_load_lds_dwordx4 v[154:155], off
	s_waitcnt vmcnt(6)
	s_barrier
	s_setprio 1
	v_mfma_f32_16x16x32_bf16 v[52:55], v[228:231], v[170:173], v[52:55]
	v_mfma_f32_16x16x32_bf16 v[44:47], v[236:239], v[170:173], v[44:47]
	v_mfma_f32_16x16x32_bf16 v[36:39], v[228:231], v[204:207], v[36:39]
	v_mfma_f32_16x16x32_bf16 v[28:31], v[236:239], v[204:207], v[28:31]
	v_mfma_f32_16x16x32_bf16 v[20:23], v[228:231], v[212:215], v[20:23]
	v_mfma_f32_16x16x32_bf16 v[12:15], v[236:239], v[212:215], v[12:15]
	v_mfma_f32_16x16x32_bf16 v[4:7], v[228:231], v[220:223], v[4:7]
	v_mfma_f32_16x16x32_bf16 v[0:3], v[236:239], v[220:223], v[0:3]
	v_mfma_f32_16x16x32_bf16 v[52:55], v[232:235], v[180:183], v[52:55]
	v_mfma_f32_16x16x32_bf16 v[44:47], v[240:243], v[180:183], v[44:47]
	v_mfma_f32_16x16x32_bf16 v[36:39], v[232:235], v[208:211], v[36:39]
	v_mfma_f32_16x16x32_bf16 v[28:31], v[240:243], v[208:211], v[28:31]
	v_mfma_f32_16x16x32_bf16 v[20:23], v[232:235], v[216:219], v[20:23]
	v_mfma_f32_16x16x32_bf16 v[12:15], v[240:243], v[216:219], v[12:15]
	v_mfma_f32_16x16x32_bf16 v[4:7], v[232:235], v[224:227], v[4:7]
	v_mfma_f32_16x16x32_bf16 v[0:3], v[240:243], v[224:227], v[0:3]
	s_setprio 0
	s_barrier
	ds_read_b128 v[154:157], v193
	ds_read_b128 v[158:161], v194
	ds_read_b128 v[162:165], v195
	ds_read_b128 v[166:169], v196
	s_add_u32 s20, s58, 0x40000
	s_addc_u32 s21, s59, 0
	s_mov_b32 m0, s80
	v_lshl_add_u64 v[228:229], s[20:21], 0, v[134:135]
	ds_read_b128 v[170:173], v177 offset:32768
	ds_read_b128 v[180:183], v177 offset:33792
	ds_read_b128 v[204:207], v177 offset:34816
	ds_read_b128 v[208:211], v177 offset:35840
	ds_read_b128 v[212:215], v177 offset:36864
	ds_read_b128 v[216:219], v177 offset:37888
	ds_read_b128 v[220:223], v177 offset:38912
	ds_read_b128 v[224:227], v177 offset:39936
	global_load_lds_dwordx4 v[228:229], off
	v_lshl_add_u64 v[228:229], s[20:21], 0, v[130:131]
	s_mov_b32 m0, s81
	s_nop 0
	global_load_lds_dwordx4 v[228:229], off
	s_waitcnt lgkmcnt(8)
	s_barrier
	s_waitcnt lgkmcnt(0)
	s_setprio 1
	s_waitcnt lgkmcnt(0)
	v_mfma_f32_16x16x32_bf16 v[124:127], v[154:157], v[170:173], v[124:127]
	v_mfma_f32_16x16x32_bf16 v[120:123], v[162:165], v[170:173], v[120:123]
	v_mfma_f32_16x16x32_bf16 v[112:115], v[154:157], v[204:207], v[112:115]
	v_mfma_f32_16x16x32_bf16 v[104:107], v[162:165], v[204:207], v[104:107]
	v_mfma_f32_16x16x32_bf16 v[96:99], v[154:157], v[212:215], v[96:99]
	v_mfma_f32_16x16x32_bf16 v[88:91], v[162:165], v[212:215], v[88:91]
	v_mfma_f32_16x16x32_bf16 v[80:83], v[154:157], v[220:223], v[80:83]
	v_mfma_f32_16x16x32_bf16 v[72:75], v[162:165], v[220:223], v[72:75]
	v_mfma_f32_16x16x32_bf16 v[124:127], v[158:161], v[180:183], v[124:127]
	v_mfma_f32_16x16x32_bf16 v[120:123], v[166:169], v[180:183], v[120:123]
	v_mfma_f32_16x16x32_bf16 v[112:115], v[158:161], v[208:211], v[112:115]
	v_mfma_f32_16x16x32_bf16 v[104:107], v[166:169], v[208:211], v[104:107]
	v_mfma_f32_16x16x32_bf16 v[96:99], v[158:161], v[216:219], v[96:99]
	v_mfma_f32_16x16x32_bf16 v[88:91], v[166:169], v[216:219], v[88:91]
	v_mfma_f32_16x16x32_bf16 v[80:83], v[158:161], v[224:227], v[80:83]
	v_mfma_f32_16x16x32_bf16 v[72:75], v[166:169], v[224:227], v[72:75]
	s_setprio 0
	s_barrier
	s_mov_b32 m0, s84
	v_lshl_add_u64 v[174:175], v[174:175], 0, s[6:7]
	ds_read_b128 v[228:231], v197
	ds_read_b128 v[232:235], v198
	ds_read_b128 v[236:239], v199
	ds_read_b128 v[240:243], v200
	global_load_lds_dwordx4 v[174:175], off
	v_lshl_add_u64 v[174:175], v[244:245], 0, s[6:7]
	s_mov_b32 m0, s85
	s_nop 0
	global_load_lds_dwordx4 v[174:175], off
	s_barrier
	s_waitcnt lgkmcnt(0)
	s_setprio 1
	s_waitcnt lgkmcnt(0)
	v_mfma_f32_16x16x32_bf16 v[116:119], v[228:231], v[170:173], v[116:119]
	v_mfma_f32_16x16x32_bf16 v[108:111], v[236:239], v[170:173], v[108:111]
	v_mfma_f32_16x16x32_bf16 v[100:103], v[228:231], v[204:207], v[100:103]
	v_mfma_f32_16x16x32_bf16 v[92:95], v[236:239], v[204:207], v[92:95]
	v_mfma_f32_16x16x32_bf16 v[84:87], v[228:231], v[212:215], v[84:87]
	v_mfma_f32_16x16x32_bf16 v[76:79], v[236:239], v[212:215], v[76:79]
	v_mfma_f32_16x16x32_bf16 v[68:71], v[228:231], v[220:223], v[68:71]
	v_mfma_f32_16x16x32_bf16 v[64:67], v[236:239], v[220:223], v[64:67]
	v_mfma_f32_16x16x32_bf16 v[116:119], v[232:235], v[180:183], v[116:119]
	v_mfma_f32_16x16x32_bf16 v[108:111], v[240:243], v[180:183], v[108:111]
	v_mfma_f32_16x16x32_bf16 v[100:103], v[232:235], v[208:211], v[100:103]
	v_mfma_f32_16x16x32_bf16 v[92:95], v[240:243], v[208:211], v[92:95]
	v_mfma_f32_16x16x32_bf16 v[84:87], v[232:235], v[216:219], v[84:87]
	v_mfma_f32_16x16x32_bf16 v[76:79], v[240:243], v[216:219], v[76:79]
	v_mfma_f32_16x16x32_bf16 v[68:71], v[232:235], v[224:227], v[68:71]
	v_mfma_f32_16x16x32_bf16 v[64:67], v[240:243], v[224:227], v[64:67]
	s_setprio 0
	s_mov_b32 m0, s86
	v_lshl_add_u64 v[174:175], v[246:247], 0, s[6:7]
	s_barrier
	ds_read_b128 v[170:173], v177 offset:49152
	ds_read_b128 v[180:183], v177 offset:50176
	ds_read_b128 v[204:207], v177 offset:51200
	ds_read_b128 v[208:211], v177 offset:52224
	ds_read_b128 v[212:215], v177 offset:53248
	ds_read_b128 v[216:219], v177 offset:54272
	ds_read_b128 v[220:223], v177 offset:55296
	ds_read_b128 v[224:227], v177 offset:56320
	global_load_lds_dwordx4 v[174:175], off
	v_lshl_add_u64 v[174:175], v[248:249], 0, s[6:7]
	s_mov_b32 m0, s87
	s_nop 0
	global_load_lds_dwordx4 v[174:175], off
	s_barrier
	s_waitcnt lgkmcnt(0)
	s_setprio 1
	s_waitcnt lgkmcnt(0)
	v_mfma_f32_16x16x32_bf16 v[60:63], v[154:157], v[170:173], v[60:63]
	v_mfma_f32_16x16x32_bf16 v[56:59], v[162:165], v[170:173], v[56:59]
	v_mfma_f32_16x16x32_bf16 v[48:51], v[154:157], v[204:207], v[48:51]
	v_mfma_f32_16x16x32_bf16 v[40:43], v[162:165], v[204:207], v[40:43]
	v_mfma_f32_16x16x32_bf16 v[32:35], v[154:157], v[212:215], v[32:35]
	v_mfma_f32_16x16x32_bf16 v[24:27], v[162:165], v[212:215], v[24:27]
	v_mfma_f32_16x16x32_bf16 v[16:19], v[154:157], v[220:223], v[16:19]
	v_mfma_f32_16x16x32_bf16 v[8:11], v[162:165], v[220:223], v[8:11]
	v_mfma_f32_16x16x32_bf16 v[60:63], v[158:161], v[180:183], v[60:63]
	v_mfma_f32_16x16x32_bf16 v[56:59], v[166:169], v[180:183], v[56:59]
	v_mfma_f32_16x16x32_bf16 v[48:51], v[158:161], v[208:211], v[48:51]
	v_mfma_f32_16x16x32_bf16 v[40:43], v[166:169], v[208:211], v[40:43]
	v_mfma_f32_16x16x32_bf16 v[32:35], v[158:161], v[216:219], v[32:35]
	v_mfma_f32_16x16x32_bf16 v[24:27], v[166:169], v[216:219], v[24:27]
	v_mfma_f32_16x16x32_bf16 v[16:19], v[158:161], v[224:227], v[16:19]
	v_mfma_f32_16x16x32_bf16 v[8:11], v[166:169], v[224:227], v[8:11]
	s_setprio 0
	s_barrier
	s_add_u32 s20, s56, 0x40080
	s_addc_u32 s21, s57, 0
	s_mov_b32 m0, s88
	v_lshl_add_u64 v[154:155], s[20:21], 0, v[132:133]
	global_load_lds_dwordx4 v[154:155], off
	v_lshl_add_u64 v[154:155], s[20:21], 0, v[128:129]
	s_mov_b32 m0, s89
	s_nop 0
	global_load_lds_dwordx4 v[154:155], off
	s_waitcnt vmcnt(6)
	s_barrier
	s_setprio 1
	v_mfma_f32_16x16x32_bf16 v[52:55], v[228:231], v[170:173], v[52:55]
	v_mfma_f32_16x16x32_bf16 v[44:47], v[236:239], v[170:173], v[44:47]
	v_mfma_f32_16x16x32_bf16 v[36:39], v[228:231], v[204:207], v[36:39]
	v_mfma_f32_16x16x32_bf16 v[28:31], v[236:239], v[204:207], v[28:31]
	v_mfma_f32_16x16x32_bf16 v[20:23], v[228:231], v[212:215], v[20:23]
	v_mfma_f32_16x16x32_bf16 v[12:15], v[236:239], v[212:215], v[12:15]
	v_mfma_f32_16x16x32_bf16 v[4:7], v[228:231], v[220:223], v[4:7]
	v_mfma_f32_16x16x32_bf16 v[0:3], v[236:239], v[220:223], v[0:3]
	v_mfma_f32_16x16x32_bf16 v[52:55], v[232:235], v[180:183], v[52:55]
	v_mfma_f32_16x16x32_bf16 v[44:47], v[240:243], v[180:183], v[44:47]
	v_mfma_f32_16x16x32_bf16 v[36:39], v[232:235], v[208:211], v[36:39]
	v_mfma_f32_16x16x32_bf16 v[28:31], v[240:243], v[208:211], v[28:31]
	v_mfma_f32_16x16x32_bf16 v[20:23], v[232:235], v[216:219], v[20:23]
	v_mfma_f32_16x16x32_bf16 v[12:15], v[240:243], v[216:219], v[12:15]
	v_mfma_f32_16x16x32_bf16 v[4:7], v[232:235], v[224:227], v[4:7]
	v_mfma_f32_16x16x32_bf16 v[0:3], v[240:243], v[224:227], v[0:3]
	s_setprio 0
	s_add_i32 s66, s66, 2
	s_add_u32 vcc_hi, vcc_hi, 0x100
	s_addc_u32 s33, s33, 0
	s_add_u32 s38, s38, 0x100
	s_addc_u32 s39, s39, 0
	s_cmp_gt_u32 s66, 13
	s_barrier
	s_cbranch_scc0 .LBB0_526
	s_cmp_gt_i32 s97, 11
	s_mov_b64 s[38:39], -1
	s_cbranch_scc0 .LBB0_535
	s_cmp_lg_u32 s97, 12
	s_cbranch_scc0 .LBB0_532
	s_and_saveexec_b64 s[38:39], s[8:9]
	s_cbranch_execz .LBB0_531
	v_lshl_add_u32 v154, s96, 10, v184
	ds_read2_b32 v[158:159], v154 offset1:16
	s_ashr_i32 s37, s36, 31
	ds_read2_b32 v[160:161], v154 offset0:160 offset1:176
	ds_read2_b32 v[162:163], v154 offset0:128 offset1:144
	ds_read2_b32 v[164:165], v154 offset0:32 offset1:48
	s_lshl_b64 s[20:21], s[36:37], 13
	v_lshl_add_u64 v[166:167], v[144:145], 0, s[20:21]
	s_waitcnt lgkmcnt(0)
	v_pk_mul_f32 v[156:157], v[126:127], v[158:159] op_sel_hi:[1,0]
	v_pk_mul_f32 v[154:155], v[124:125], v[158:159] op_sel_hi:[1,0]
	global_store_dwordx4 v[166:167], v[154:157], off
	s_movk_i32 s15, 0x1000
	s_nop 0
	v_pk_mul_f32 v[156:157], v[122:123], v[158:159] op_sel_hi:[1,0]
	v_pk_mul_f32 v[154:155], v[120:121], v[158:159] op_sel_hi:[1,0]
	v_mov_b32_e32 v158, v159
	global_store_dwordx4 v[166:167], v[154:157], off offset:16
	s_nop 1
	v_pk_mul_f32 v[156:157], v[114:115], v[158:159] op_sel_hi:[1,0]
	v_pk_mul_f32 v[154:155], v[112:113], v[158:159] op_sel_hi:[1,0]
	global_store_dwordx4 v[166:167], v[154:157], off offset:512
	s_nop 1
	v_pk_mul_f32 v[156:157], v[106:107], v[158:159] op_sel_hi:[1,0]
	v_pk_mul_f32 v[154:155], v[104:105], v[158:159] op_sel_hi:[1,0]
	global_store_dwordx4 v[166:167], v[154:157], off offset:528
	v_mov_b32_e32 v158, v165
	s_nop 0
	v_pk_mul_f32 v[156:157], v[98:99], v[164:165] op_sel_hi:[1,0]
	v_pk_mul_f32 v[154:155], v[96:97], v[164:165] op_sel_hi:[1,0]
	global_store_dwordx4 v[166:167], v[154:157], off offset:1024
	s_nop 1
	v_pk_mul_f32 v[156:157], v[90:91], v[164:165] op_sel_hi:[1,0]
	v_pk_mul_f32 v[154:155], v[88:89], v[164:165] op_sel_hi:[1,0]
	global_store_dwordx4 v[166:167], v[154:157], off offset:1040
	s_nop 1
	v_pk_mul_f32 v[156:157], v[82:83], v[158:159] op_sel_hi:[1,0]
	v_pk_mul_f32 v[154:155], v[80:81], v[158:159] op_sel_hi:[1,0]
	global_store_dwordx4 v[166:167], v[154:157], off offset:1536
	s_nop 1
	v_pk_mul_f32 v[156:157], v[74:75], v[158:159] op_sel_hi:[1,0]
	v_pk_mul_f32 v[154:155], v[72:73], v[158:159] op_sel_hi:[1,0]
	v_add_co_u32_e32 v158, vcc, s15, v166
	global_store_dwordx4 v[166:167], v[154:157], off offset:1552
	s_nop 0
	v_addc_co_u32_e32 v159, vcc, 0, v167, vcc
	v_pk_mul_f32 v[156:157], v[62:63], v[162:163] op_sel_hi:[1,0]
	v_pk_mul_f32 v[154:155], v[60:61], v[162:163] op_sel_hi:[1,0]
	global_store_dwordx4 v[158:159], v[154:157], off
	s_nop 1
	v_pk_mul_f32 v[156:157], v[58:59], v[162:163] op_sel_hi:[1,0]
	v_pk_mul_f32 v[154:155], v[56:57], v[162:163] op_sel_hi:[1,0]
	v_mov_b32_e32 v162, v163
	global_store_dwordx4 v[158:159], v[154:157], off offset:16
	s_nop 1
	v_pk_mul_f32 v[156:157], v[50:51], v[162:163] op_sel_hi:[1,0]
	v_pk_mul_f32 v[154:155], v[48:49], v[162:163] op_sel_hi:[1,0]
	global_store_dwordx4 v[158:159], v[154:157], off offset:512
	s_nop 1
	v_pk_mul_f32 v[156:157], v[42:43], v[162:163] op_sel_hi:[1,0]
	v_pk_mul_f32 v[154:155], v[40:41], v[162:163] op_sel_hi:[1,0]
	global_store_dwordx4 v[158:159], v[154:157], off offset:528
	s_nop 1
	v_pk_mul_f32 v[156:157], v[34:35], v[160:161] op_sel_hi:[1,0]
	v_pk_mul_f32 v[154:155], v[32:33], v[160:161] op_sel_hi:[1,0]
	global_store_dwordx4 v[158:159], v[154:157], off offset:1024
	s_nop 1
	v_pk_mul_f32 v[156:157], v[26:27], v[160:161] op_sel_hi:[1,0]
	v_pk_mul_f32 v[154:155], v[24:25], v[160:161] op_sel_hi:[1,0]
	v_mov_b32_e32 v160, v161
	global_store_dwordx4 v[158:159], v[154:157], off offset:1040
	s_nop 1
	v_pk_mul_f32 v[156:157], v[18:19], v[160:161] op_sel_hi:[1,0]
	v_pk_mul_f32 v[154:155], v[16:17], v[160:161] op_sel_hi:[1,0]
	global_store_dwordx4 v[158:159], v[154:157], off offset:1536
	s_nop 1
	v_pk_mul_f32 v[156:157], v[10:11], v[160:161] op_sel_hi:[1,0]
	v_pk_mul_f32 v[154:155], v[8:9], v[160:161] op_sel_hi:[1,0]
	global_store_dwordx4 v[158:159], v[154:157], off offset:1552

.LBB0_532:
	s_andn2_b64 vcc, exec, s[38:39]
	s_cbranch_vccnz .LBB0_534
	global_load_dwordx4 v[154:157], v[140:141], off offset:16
	global_load_dwordx4 v[158:161], v[140:141], off
	v_mov_b32_e32 v206, v125
	v_mov_b32_e32 v207, v121
	v_pk_mul_f32 v[206:207], v[206:207], v[206:207]
	v_mov_b32_e32 v208, v117
	v_mov_b32_e32 v209, v109
	v_pk_mul_f32 v[208:209], v[208:209], v[208:209]
	s_ashr_i32 s37, s36, 31
	s_lshl_b64 s[20:21], s[36:37], 19
	s_mov_b32 s15, 0x8000
	s_waitcnt vmcnt(0)
	v_pk_mul_f32 v[166:167], v[160:161], s[12:13] op_sel_hi:[1,0]
	v_pk_mul_f32 v[168:169], v[158:159], s[12:13] op_sel_hi:[1,0]
	v_pk_mul_f32 v[158:159], v[156:157], s[12:13] op_sel_hi:[1,0]
	v_pk_mul_f32 v[160:161], v[154:155], s[12:13] op_sel_hi:[1,0]
	global_load_dwordx4 v[170:173], v[140:141], off offset:144
	global_load_dwordx4 v[154:157], v[140:141], off offset:128
	s_waitcnt vmcnt(0)
	s_waitcnt vmcnt(0)
	v_pk_mul_f32 v[164:165], v[154:155], s[12:13] op_sel_hi:[1,0]
	v_pk_mul_f32 v[154:155], v[172:173], s[12:13] op_sel_hi:[1,0]
	v_and_b32_e32 v173, 64, v202
	v_xor_b32_e32 v172, 16, v202
	v_add_u32_e32 v173, 64, v173
	v_cmp_lt_i32_e32 vcc, v172, v173
	v_pk_mul_f32 v[162:163], v[156:157], s[12:13] op_sel_hi:[1,0]
	v_pk_mul_f32 v[156:157], v[170:171], s[12:13] op_sel_hi:[1,0]
	v_cndmask_b32_e32 v172, v202, v172, vcc
	v_lshlrev_b32_e32 v204, 2, v172
	v_xor_b32_e32 v172, 32, v202
	v_cmp_lt_i32_e32 vcc, v172, v173
	v_mov_b32_e32 v173, v120
	v_lshl_add_u32 v170, s96, 10, v184
	v_cndmask_b32_e32 v172, v202, v172, vcc
	v_lshlrev_b32_e32 v203, 2, v172
	v_mov_b32_e32 v172, v124
	v_pk_fma_f32 v[172:173], v[172:173], v[172:173], v[206:207]
	v_mov_b32_e32 v206, v126
	v_mov_b32_e32 v207, v122
	v_pk_fma_f32 v[172:173], v[206:207], v[206:207], v[172:173]
	v_mov_b32_e32 v206, v127
	v_mov_b32_e32 v207, v123
	v_pk_fma_f32 v[172:173], v[206:207], v[206:207], v[172:173]
	v_mov_b32_e32 v206, v116
	v_mov_b32_e32 v207, v108
	v_pk_fma_f32 v[206:207], v[206:207], v[206:207], v[208:209]
	v_mov_b32_e32 v208, v118
	v_mov_b32_e32 v209, v110
	v_pk_fma_f32 v[206:207], v[208:209], v[208:209], v[206:207]
	v_mov_b32_e32 v208, v119
	v_mov_b32_e32 v209, v111
	v_pk_fma_f32 v[206:207], v[208:209], v[208:209], v[206:207]
	v_add_f32_e32 v172, v172, v173
	v_add_f32_e32 v172, v172, v206
	v_add_f32_e32 v172, v172, v207
	ds_bpermute_b32 v173, v204, v172
	ds_read2_b32 v[182:183], v170 offset1:16
	ds_read2_b32 v[180:181], v170 offset0:32 offset1:48
	ds_read2_b32 v[174:175], v170 offset0:128 offset1:144
	ds_read2_b32 v[170:171], v170 offset0:160 offset1:176
	s_waitcnt lgkmcnt(0)
	v_add_f32_e32 v172, v172, v173
	ds_bpermute_b32 v173, v203, v172
	s_waitcnt lgkmcnt(0)
	v_add_f32_e32 v172, v172, v173
	v_mul_f32_e32 v172, v182, v172
	v_mul_f32_e32 v172, v182, v172
	v_fmamk_f32 v172, v172, 0x3c800000, v201
	v_cmp_gt_f32_e32 vcc, s92, v172
	v_mul_f32_e32 v173, 0x4b800000, v172
	s_nop 0
	v_cndmask_b32_e32 v172, v172, v173, vcc
	v_rsq_f32_e32 v172, v172
	s_nop 0
	v_mul_f32_e32 v173, 0x45800000, v172
	v_cndmask_b32_e32 v172, v172, v173, vcc
	v_mul_f32_e32 v182, v182, v172
	v_pk_mul_f32 v[206:207], v[124:125], v[182:183] op_sel_hi:[1,0]
	v_pk_mul_f32 v[208:209], v[126:127], v[182:183] op_sel_hi:[1,0]
	v_pk_mul_f32 v[206:207], v[168:169], v[206:207]
	v_pk_mul_f32 v[208:209], v[166:167], v[208:209]
	v_pk_mul_f32 v[210:211], v[120:121], v[182:183] op_sel_hi:[1,0]
	v_pk_mul_f32 v[212:213], v[122:123], v[182:183] op_sel_hi:[1,0]
	v_lshl_add_u64 v[172:173], v[142:143], 0, s[20:21]
	v_pk_mul_f32 v[212:213], v[158:159], v[212:213]
	v_pk_mul_f32 v[210:211], v[160:161], v[210:211]
	v_cvt_pk_bf16_f32 v206, v206, v207
	v_cvt_pk_bf16_f32 v207, v208, v209
	v_cvt_pk_bf16_f32 v209, v212, v213
	v_pk_mul_f32 v[212:213], v[110:111], v[182:183] op_sel_hi:[1,0]
	v_cvt_pk_bf16_f32 v208, v210, v211
	global_store_dwordx4 v[172:173], v[206:209], off
	v_pk_mul_f32 v[210:211], v[108:109], v[182:183] op_sel_hi:[1,0]
	v_pk_mul_f32 v[212:213], v[154:155], v[212:213]
	v_pk_mul_f32 v[206:207], v[116:117], v[182:183] op_sel_hi:[1,0]
	v_pk_mul_f32 v[208:209], v[118:119], v[182:183] op_sel_hi:[1,0]
	v_pk_mul_f32 v[206:207], v[164:165], v[206:207]
	v_pk_mul_f32 v[208:209], v[162:163], v[208:209]
	v_pk_mul_f32 v[210:211], v[156:157], v[210:211]
	v_cvt_pk_bf16_f32 v206, v206, v207
	v_cvt_pk_bf16_f32 v207, v208, v209
	v_cvt_pk_bf16_f32 v209, v212, v213
	s_nop 0
	v_cvt_pk_bf16_f32 v208, v210, v211
	global_store_dwordx4 v[172:173], v[206:209], off offset:64
	v_mov_b32_e32 v210, v101
	v_mov_b32_e32 v211, v93
	v_mov_b32_e32 v208, v113
	v_mov_b32_e32 v209, v105
	v_mov_b32_e32 v206, v112
	v_mov_b32_e32 v207, v104
	v_pk_mul_f32 v[208:209], v[208:209], v[208:209]
	v_pk_mul_f32 v[210:211], v[210:211], v[210:211]
	v_pk_fma_f32 v[206:207], v[206:207], v[206:207], v[208:209]
	v_mov_b32_e32 v208, v114
	v_mov_b32_e32 v209, v106
	v_pk_fma_f32 v[206:207], v[208:209], v[208:209], v[206:207]
	v_mov_b32_e32 v208, v115
	v_mov_b32_e32 v209, v107
	v_pk_fma_f32 v[206:207], v[208:209], v[208:209], v[206:207]
	v_mov_b32_e32 v208, v100
	v_mov_b32_e32 v209, v92
	v_pk_fma_f32 v[208:209], v[208:209], v[208:209], v[210:211]
	v_mov_b32_e32 v210, v102
	v_mov_b32_e32 v211, v94
	v_pk_fma_f32 v[208:209], v[210:211], v[210:211], v[208:209]
	v_mov_b32_e32 v210, v103
	v_mov_b32_e32 v211, v95
	v_pk_fma_f32 v[208:209], v[210:211], v[210:211], v[208:209]
	v_add_f32_e32 v182, v206, v207
	v_add_f32_e32 v182, v182, v208
	v_add_f32_e32 v182, v182, v209
	ds_bpermute_b32 v205, v204, v182
	s_waitcnt lgkmcnt(0)
	v_add_f32_e32 v182, v182, v205
	ds_bpermute_b32 v205, v203, v182
	s_waitcnt lgkmcnt(0)
	v_add_f32_e32 v182, v182, v205
	v_mul_f32_e32 v182, v183, v182
	v_mul_f32_e32 v182, v183, v182
	v_fmamk_f32 v182, v182, 0x3c800000, v201
	v_cmp_gt_f32_e32 vcc, s92, v182
	v_mul_f32_e32 v205, 0x4b800000, v182
	s_nop 0
	v_cndmask_b32_e32 v182, v182, v205, vcc
	v_rsq_f32_e32 v182, v182
	s_nop 0
	v_mul_f32_e32 v205, 0x45800000, v182
	v_cndmask_b32_e32 v182, v182, v205, vcc
	v_mul_f32_e32 v182, v183, v182
	v_pk_mul_f32 v[206:207], v[112:113], v[182:183] op_sel_hi:[1,0]
	v_pk_mul_f32 v[208:209], v[114:115], v[182:183] op_sel_hi:[1,0]
	v_pk_mul_f32 v[210:211], v[104:105], v[182:183] op_sel_hi:[1,0]
	v_pk_mul_f32 v[208:209], v[166:167], v[208:209]
	v_pk_mul_f32 v[206:207], v[168:169], v[206:207]
	v_pk_mul_f32 v[210:211], v[160:161], v[210:211]
	v_cvt_pk_bf16_f32 v206, v206, v207
	v_cvt_pk_bf16_f32 v207, v208, v209
	v_pk_mul_f32 v[212:213], v[106:107], v[182:183] op_sel_hi:[1,0]
	v_cvt_pk_bf16_f32 v208, v210, v211
	v_add_co_u32_e32 v210, vcc, s15, v172
	v_pk_mul_f32 v[212:213], v[158:159], v[212:213]
	s_nop 0
	v_addc_co_u32_e32 v211, vcc, 0, v173, vcc
	v_cvt_pk_bf16_f32 v209, v212, v213
	global_store_dwordx4 v[210:211], v[206:209], off
	v_pk_mul_f32 v[212:213], v[92:93], v[182:183] op_sel_hi:[1,0]
	s_mov_b32 s15, 0x10000
	v_pk_mul_f32 v[206:207], v[100:101], v[182:183] op_sel_hi:[1,0]
	v_pk_mul_f32 v[208:209], v[102:103], v[182:183] op_sel_hi:[1,0]
	v_pk_mul_f32 v[206:207], v[164:165], v[206:207]
	v_pk_mul_f32 v[208:209], v[162:163], v[208:209]
	v_pk_mul_f32 v[182:183], v[94:95], v[182:183] op_sel_hi:[1,0]
	v_cvt_pk_bf16_f32 v206, v206, v207
	v_cvt_pk_bf16_f32 v207, v208, v209
	v_pk_mul_f32 v[212:213], v[156:157], v[212:213]
	v_pk_mul_f32 v[182:183], v[154:155], v[182:183]
	v_cvt_pk_bf16_f32 v208, v212, v213
	s_nop 0
	v_cvt_pk_bf16_f32 v209, v182, v183
	global_store_dwordx4 v[210:211], v[206:209], off offset:64
	v_mov_b32_e32 v182, v96
	v_mov_b32_e32 v183, v88
	v_mov_b32_e32 v206, v97
	v_mov_b32_e32 v207, v89
	v_pk_mul_f32 v[206:207], v[206:207], v[206:207]
	v_mov_b32_e32 v208, v85
	v_pk_fma_f32 v[182:183], v[182:183], v[182:183], v[206:207]
	v_mov_b32_e32 v206, v98
	v_mov_b32_e32 v207, v90
	v_pk_fma_f32 v[182:183], v[206:207], v[206:207], v[182:183]
	v_mov_b32_e32 v206, v99
	v_mov_b32_e32 v207, v91
	v_mov_b32_e32 v209, v77
	v_pk_fma_f32 v[182:183], v[206:207], v[206:207], v[182:183]
	v_mov_b32_e32 v206, v84
	v_mov_b32_e32 v207, v76
	v_pk_mul_f32 v[208:209], v[208:209], v[208:209]
	v_add_f32_e32 v182, v182, v183
	v_pk_fma_f32 v[206:207], v[206:207], v[206:207], v[208:209]
	v_mov_b32_e32 v208, v86
	v_mov_b32_e32 v209, v78
	v_pk_fma_f32 v[206:207], v[208:209], v[208:209], v[206:207]
	v_mov_b32_e32 v208, v87
	v_mov_b32_e32 v209, v79
	v_pk_fma_f32 v[206:207], v[208:209], v[208:209], v[206:207]
	s_nop 0
	v_add_f32_e32 v182, v182, v206
	v_add_f32_e32 v182, v182, v207
	ds_bpermute_b32 v183, v204, v182
	s_waitcnt lgkmcnt(0)
	v_add_f32_e32 v182, v182, v183
	ds_bpermute_b32 v183, v203, v182
	s_waitcnt lgkmcnt(0)
	v_add_f32_e32 v182, v182, v183
	v_mul_f32_e32 v182, v180, v182
	v_mul_f32_e32 v182, v180, v182
	v_fmamk_f32 v182, v182, 0x3c800000, v201
	v_cmp_gt_f32_e32 vcc, s92, v182
	v_mul_f32_e32 v183, 0x4b800000, v182
	s_nop 0
	v_cndmask_b32_e32 v182, v182, v183, vcc
	v_rsq_f32_e32 v182, v182
	s_nop 0
	v_mul_f32_e32 v183, 0x45800000, v182
	v_cndmask_b32_e32 v182, v182, v183, vcc
	v_mul_f32_e32 v180, v180, v182
	v_pk_mul_f32 v[182:183], v[96:97], v[180:181] op_sel_hi:[1,0]
	v_pk_mul_f32 v[206:207], v[98:99], v[180:181] op_sel_hi:[1,0]
	v_pk_mul_f32 v[182:183], v[168:169], v[182:183]
	v_pk_mul_f32 v[208:209], v[166:167], v[206:207]
	v_pk_mul_f32 v[206:207], v[88:89], v[180:181] op_sel_hi:[1,0]
	v_pk_mul_f32 v[210:211], v[90:91], v[180:181] op_sel_hi:[1,0]
	v_pk_mul_f32 v[212:213], v[160:161], v[206:207]
	v_cvt_pk_bf16_f32 v206, v182, v183
	v_add_co_u32_e32 v182, vcc, s15, v172
	v_cvt_pk_bf16_f32 v207, v208, v209
	v_pk_mul_f32 v[210:211], v[158:159], v[210:211]
	s_nop 0
	v_addc_co_u32_e32 v183, vcc, 0, v173, vcc
	v_cvt_pk_bf16_f32 v208, v212, v213
	v_cvt_pk_bf16_f32 v209, v210, v211
	global_store_dwordx4 v[182:183], v[206:209], off
	v_pk_mul_f32 v[210:211], v[76:77], v[180:181] op_sel_hi:[1,0]
	v_pk_mul_f32 v[212:213], v[78:79], v[180:181] op_sel_hi:[1,0]
	v_pk_mul_f32 v[206:207], v[84:85], v[180:181] op_sel_hi:[1,0]
	v_pk_mul_f32 v[208:209], v[86:87], v[180:181] op_sel_hi:[1,0]
	v_pk_mul_f32 v[206:207], v[164:165], v[206:207]
	v_pk_mul_f32 v[208:209], v[162:163], v[208:209]
	v_cvt_pk_bf16_f32 v206, v206, v207
	v_pk_mul_f32 v[212:213], v[154:155], v[212:213]
	v_cvt_pk_bf16_f32 v207, v208, v209
	v_pk_mul_f32 v[210:211], v[156:157], v[210:211]
	v_cvt_pk_bf16_f32 v209, v212, v213
	s_mov_b32 s15, 0x18000
	v_cvt_pk_bf16_f32 v208, v210, v211
	global_store_dwordx4 v[182:183], v[206:209], off offset:64
	v_mov_b32_e32 v182, v80
	v_mov_b32_e32 v183, v72
	v_mov_b32_e32 v206, v81
	v_mov_b32_e32 v207, v73
	v_pk_mul_f32 v[206:207], v[206:207], v[206:207]
	v_mov_b32_e32 v208, v69
	v_pk_fma_f32 v[182:183], v[182:183], v[182:183], v[206:207]
	v_mov_b32_e32 v206, v82
	v_mov_b32_e32 v207, v74
	v_pk_fma_f32 v[182:183], v[206:207], v[206:207], v[182:183]
	v_mov_b32_e32 v206, v83
	v_mov_b32_e32 v207, v75
	v_mov_b32_e32 v209, v65
	v_pk_fma_f32 v[182:183], v[206:207], v[206:207], v[182:183]
	v_mov_b32_e32 v206, v68
	v_mov_b32_e32 v207, v64
	v_pk_mul_f32 v[208:209], v[208:209], v[208:209]
	v_add_f32_e32 v180, v182, v183
	v_pk_fma_f32 v[206:207], v[206:207], v[206:207], v[208:209]
	v_mov_b32_e32 v208, v70
	v_mov_b32_e32 v209, v66
	v_pk_fma_f32 v[206:207], v[208:209], v[208:209], v[206:207]
	v_mov_b32_e32 v208, v71
	v_mov_b32_e32 v209, v67
	v_pk_fma_f32 v[206:207], v[208:209], v[208:209], v[206:207]
	s_nop 0
	v_add_f32_e32 v180, v180, v206
	v_add_f32_e32 v180, v180, v207
	ds_bpermute_b32 v182, v204, v180
	s_waitcnt lgkmcnt(0)
	v_add_f32_e32 v180, v180, v182
	ds_bpermute_b32 v182, v203, v180
	s_waitcnt lgkmcnt(0)
	v_add_f32_e32 v180, v180, v182
	v_mul_f32_e32 v180, v181, v180
	v_mul_f32_e32 v180, v181, v180
	v_fmamk_f32 v180, v180, 0x3c800000, v201
	v_cmp_gt_f32_e32 vcc, s92, v180
	v_mul_f32_e32 v182, 0x4b800000, v180
	s_nop 0
	v_cndmask_b32_e32 v180, v180, v182, vcc
	v_rsq_f32_e32 v180, v180
	s_nop 0
	v_mul_f32_e32 v182, 0x45800000, v180
	v_cndmask_b32_e32 v180, v180, v182, vcc
	v_mul_f32_e32 v206, v181, v180
	v_pk_mul_f32 v[180:181], v[80:81], v[206:207] op_sel_hi:[1,0]
	v_pk_mul_f32 v[182:183], v[82:83], v[206:207] op_sel_hi:[1,0]
	v_pk_mul_f32 v[208:209], v[72:73], v[206:207] op_sel_hi:[1,0]
	v_pk_mul_f32 v[182:183], v[166:167], v[182:183]
	v_pk_mul_f32 v[180:181], v[168:169], v[180:181]
	v_pk_mul_f32 v[208:209], v[160:161], v[208:209]
	v_pk_mul_f32 v[210:211], v[74:75], v[206:207] op_sel_hi:[1,0]
	v_cvt_pk_bf16_f32 v180, v180, v181
	v_cvt_pk_bf16_f32 v181, v182, v183
	v_cvt_pk_bf16_f32 v182, v208, v209
	v_add_co_u32_e32 v208, vcc, s15, v172
	v_pk_mul_f32 v[210:211], v[158:159], v[210:211]
	s_nop 0
	v_addc_co_u32_e32 v209, vcc, 0, v173, vcc
	v_cvt_pk_bf16_f32 v183, v210, v211
	global_store_dwordx4 v[208:209], v[180:183], off
	v_pk_mul_f32 v[210:211], v[64:65], v[206:207] op_sel_hi:[1,0]
	s_mov_b32 s15, 0x40000
	v_pk_mul_f32 v[180:181], v[68:69], v[206:207] op_sel_hi:[1,0]
	v_pk_mul_f32 v[182:183], v[70:71], v[206:207] op_sel_hi:[1,0]
	v_pk_mul_f32 v[180:181], v[164:165], v[180:181]
	v_pk_mul_f32 v[182:183], v[162:163], v[182:183]
	v_pk_mul_f32 v[206:207], v[66:67], v[206:207] op_sel_hi:[1,0]
	v_pk_mul_f32 v[210:211], v[156:157], v[210:211]
	v_pk_mul_f32 v[206:207], v[154:155], v[206:207]
	v_cvt_pk_bf16_f32 v180, v180, v181
	v_cvt_pk_bf16_f32 v181, v182, v183
	v_cvt_pk_bf16_f32 v182, v210, v211
	s_nop 0
	v_cvt_pk_bf16_f32 v183, v206, v207
	global_store_dwordx4 v[208:209], v[180:183], off offset:64
	v_mov_b32_e32 v206, v53
	v_mov_b32_e32 v207, v45
	v_mov_b32_e32 v182, v61
	v_mov_b32_e32 v183, v57
	v_mov_b32_e32 v180, v60
	v_mov_b32_e32 v181, v56
	v_pk_mul_f32 v[182:183], v[182:183], v[182:183]
	v_pk_mul_f32 v[206:207], v[206:207], v[206:207]
	v_pk_fma_f32 v[180:181], v[180:181], v[180:181], v[182:183]
	v_mov_b32_e32 v182, v62
	v_mov_b32_e32 v183, v58
	v_pk_fma_f32 v[180:181], v[182:183], v[182:183], v[180:181]
	v_mov_b32_e32 v182, v63
	v_mov_b32_e32 v183, v59
	v_pk_fma_f32 v[180:181], v[182:183], v[182:183], v[180:181]
	v_mov_b32_e32 v182, v52
	v_mov_b32_e32 v183, v44
	v_pk_fma_f32 v[182:183], v[182:183], v[182:183], v[206:207]
	v_mov_b32_e32 v206, v54
	v_mov_b32_e32 v207, v46
	v_pk_fma_f32 v[182:183], v[206:207], v[206:207], v[182:183]
	v_mov_b32_e32 v206, v55
	v_mov_b32_e32 v207, v47
	v_pk_fma_f32 v[182:183], v[206:207], v[206:207], v[182:183]
	v_add_f32_e32 v180, v180, v181
	v_add_f32_e32 v180, v180, v182
	v_add_f32_e32 v180, v180, v183
	ds_bpermute_b32 v181, v204, v180
	s_waitcnt lgkmcnt(0)
	v_add_f32_e32 v180, v180, v181
	ds_bpermute_b32 v181, v203, v180
	s_waitcnt lgkmcnt(0)
	v_add_f32_e32 v180, v180, v181
	v_mul_f32_e32 v180, v174, v180
	v_mul_f32_e32 v180, v174, v180
	v_fmamk_f32 v180, v180, 0x3c800000, v201
	v_cmp_gt_f32_e32 vcc, s92, v180
	v_mul_f32_e32 v181, 0x4b800000, v180
	s_nop 0
	v_cndmask_b32_e32 v180, v180, v181, vcc
	v_rsq_f32_e32 v180, v180
	s_nop 0
	v_mul_f32_e32 v181, 0x45800000, v180
	v_cndmask_b32_e32 v180, v180, v181, vcc
	v_mul_f32_e32 v174, v174, v180
	v_pk_mul_f32 v[180:181], v[60:61], v[174:175] op_sel_hi:[1,0]
	v_pk_mul_f32 v[182:183], v[62:63], v[174:175] op_sel_hi:[1,0]
	v_pk_mul_f32 v[206:207], v[56:57], v[174:175] op_sel_hi:[1,0]
	v_pk_mul_f32 v[182:183], v[166:167], v[182:183]
	v_pk_mul_f32 v[180:181], v[168:169], v[180:181]
	v_pk_mul_f32 v[206:207], v[160:161], v[206:207]
	v_pk_mul_f32 v[208:209], v[58:59], v[174:175] op_sel_hi:[1,0]
	v_cvt_pk_bf16_f32 v180, v180, v181
	v_cvt_pk_bf16_f32 v181, v182, v183
	v_cvt_pk_bf16_f32 v182, v206, v207
	v_add_co_u32_e32 v206, vcc, s15, v172
	v_pk_mul_f32 v[208:209], v[158:159], v[208:209]
	s_nop 0
	v_addc_co_u32_e32 v207, vcc, 0, v173, vcc
	v_cvt_pk_bf16_f32 v183, v208, v209
	global_store_dwordx4 v[206:207], v[180:183], off
	v_pk_mul_f32 v[208:209], v[44:45], v[174:175] op_sel_hi:[1,0]
	v_pk_mul_f32 v[210:211], v[46:47], v[174:175] op_sel_hi:[1,0]
	v_pk_mul_f32 v[180:181], v[52:53], v[174:175] op_sel_hi:[1,0]
	v_pk_mul_f32 v[182:183], v[54:55], v[174:175] op_sel_hi:[1,0]
	v_pk_mul_f32 v[180:181], v[164:165], v[180:181]
	v_pk_mul_f32 v[182:183], v[162:163], v[182:183]
	v_pk_mul_f32 v[210:211], v[154:155], v[210:211]
	v_pk_mul_f32 v[208:209], v[156:157], v[208:209]
	v_cvt_pk_bf16_f32 v180, v180, v181
	v_cvt_pk_bf16_f32 v181, v182, v183
	v_cvt_pk_bf16_f32 v183, v210, v211
	s_mov_b32 s15, 0x48000
	v_cvt_pk_bf16_f32 v182, v208, v209
	global_store_dwordx4 v[206:207], v[180:183], off offset:64
	v_mov_b32_e32 v206, v37
	v_mov_b32_e32 v207, v29
	v_mov_b32_e32 v182, v49
	v_mov_b32_e32 v183, v41
	v_mov_b32_e32 v180, v48
	v_mov_b32_e32 v181, v40
	v_pk_mul_f32 v[182:183], v[182:183], v[182:183]
	v_pk_mul_f32 v[206:207], v[206:207], v[206:207]
	v_pk_fma_f32 v[180:181], v[180:181], v[180:181], v[182:183]
	v_mov_b32_e32 v182, v50
	v_mov_b32_e32 v183, v42
	v_pk_fma_f32 v[180:181], v[182:183], v[182:183], v[180:181]
	v_mov_b32_e32 v182, v51
	v_mov_b32_e32 v183, v43
	v_pk_fma_f32 v[180:181], v[182:183], v[182:183], v[180:181]
	v_mov_b32_e32 v182, v36
	v_mov_b32_e32 v183, v28
	v_pk_fma_f32 v[182:183], v[182:183], v[182:183], v[206:207]
	v_mov_b32_e32 v206, v38
	v_mov_b32_e32 v207, v30
	v_pk_fma_f32 v[182:183], v[206:207], v[206:207], v[182:183]
	v_mov_b32_e32 v206, v39
	v_mov_b32_e32 v207, v31
	v_pk_fma_f32 v[182:183], v[206:207], v[206:207], v[182:183]
	v_add_f32_e32 v174, v180, v181
	v_add_f32_e32 v174, v174, v182
	v_add_f32_e32 v174, v174, v183
	ds_bpermute_b32 v180, v204, v174
	s_waitcnt lgkmcnt(0)
	v_add_f32_e32 v174, v174, v180
	ds_bpermute_b32 v180, v203, v174
	s_waitcnt lgkmcnt(0)
	v_add_f32_e32 v174, v174, v180
	v_mul_f32_e32 v174, v175, v174
	v_mul_f32_e32 v174, v175, v174
	v_fmamk_f32 v174, v174, 0x3c800000, v201
	v_cmp_gt_f32_e32 vcc, s92, v174
	v_mul_f32_e32 v180, 0x4b800000, v174
	s_nop 0
	v_cndmask_b32_e32 v174, v174, v180, vcc
	v_rsq_f32_e32 v174, v174
	s_nop 0
	v_mul_f32_e32 v180, 0x45800000, v174
	v_cndmask_b32_e32 v174, v174, v180, vcc
	v_mul_f32_e32 v174, v175, v174
	v_pk_mul_f32 v[180:181], v[48:49], v[174:175] op_sel_hi:[1,0]
	v_pk_mul_f32 v[182:183], v[50:51], v[174:175] op_sel_hi:[1,0]
	v_pk_mul_f32 v[206:207], v[40:41], v[174:175] op_sel_hi:[1,0]
	v_pk_mul_f32 v[182:183], v[166:167], v[182:183]
	v_pk_mul_f32 v[180:181], v[168:169], v[180:181]
	v_pk_mul_f32 v[206:207], v[160:161], v[206:207]
	v_cvt_pk_bf16_f32 v180, v180, v181
	v_cvt_pk_bf16_f32 v181, v182, v183
	v_pk_mul_f32 v[208:209], v[42:43], v[174:175] op_sel_hi:[1,0]
	v_cvt_pk_bf16_f32 v182, v206, v207
	v_add_co_u32_e32 v206, vcc, s15, v172
	v_pk_mul_f32 v[208:209], v[158:159], v[208:209]
	s_nop 0
	v_addc_co_u32_e32 v207, vcc, 0, v173, vcc
	v_cvt_pk_bf16_f32 v183, v208, v209
	global_store_dwordx4 v[206:207], v[180:183], off
	v_pk_mul_f32 v[208:209], v[28:29], v[174:175] op_sel_hi:[1,0]
	s_mov_b32 s15, 0x50000
	v_pk_mul_f32 v[180:181], v[36:37], v[174:175] op_sel_hi:[1,0]
	v_pk_mul_f32 v[182:183], v[38:39], v[174:175] op_sel_hi:[1,0]
	v_pk_mul_f32 v[180:181], v[164:165], v[180:181]
	v_pk_mul_f32 v[182:183], v[162:163], v[182:183]
	v_pk_mul_f32 v[174:175], v[30:31], v[174:175] op_sel_hi:[1,0]
	v_cvt_pk_bf16_f32 v180, v180, v181
	v_cvt_pk_bf16_f32 v181, v182, v183
	v_pk_mul_f32 v[208:209], v[156:157], v[208:209]
	v_pk_mul_f32 v[174:175], v[154:155], v[174:175]
	v_cvt_pk_bf16_f32 v182, v208, v209
	s_nop 0
	v_cvt_pk_bf16_f32 v183, v174, v175
	global_store_dwordx4 v[206:207], v[180:183], off offset:64
	v_mov_b32_e32 v174, v32
	v_mov_b32_e32 v175, v24
	v_mov_b32_e32 v180, v33
	v_mov_b32_e32 v181, v25
	v_pk_mul_f32 v[180:181], v[180:181], v[180:181]
	v_mov_b32_e32 v182, v21
	v_pk_fma_f32 v[174:175], v[174:175], v[174:175], v[180:181]
	v_mov_b32_e32 v180, v34
	v_mov_b32_e32 v181, v26
	v_pk_fma_f32 v[174:175], v[180:181], v[180:181], v[174:175]
	v_mov_b32_e32 v180, v35
	v_mov_b32_e32 v181, v27
	v_mov_b32_e32 v183, v13
	v_pk_fma_f32 v[174:175], v[180:181], v[180:181], v[174:175]
	v_mov_b32_e32 v180, v20
	v_mov_b32_e32 v181, v12
	v_pk_mul_f32 v[182:183], v[182:183], v[182:183]
	v_add_f32_e32 v174, v174, v175
	v_pk_fma_f32 v[180:181], v[180:181], v[180:181], v[182:183]
	v_mov_b32_e32 v182, v22
	v_mov_b32_e32 v183, v14
	v_pk_fma_f32 v[180:181], v[182:183], v[182:183], v[180:181]
	v_mov_b32_e32 v182, v23
	v_mov_b32_e32 v183, v15
	v_pk_fma_f32 v[180:181], v[182:183], v[182:183], v[180:181]
	s_nop 0
	v_add_f32_e32 v174, v174, v180
	v_add_f32_e32 v174, v174, v181
	ds_bpermute_b32 v175, v204, v174
	s_waitcnt lgkmcnt(0)
	v_add_f32_e32 v174, v174, v175
	ds_bpermute_b32 v175, v203, v174
	s_waitcnt lgkmcnt(0)
	v_add_f32_e32 v174, v174, v175
	v_mul_f32_e32 v174, v170, v174
	v_mul_f32_e32 v174, v170, v174
	v_fmamk_f32 v174, v174, 0x3c800000, v201
	v_cmp_gt_f32_e32 vcc, s92, v174
	v_mul_f32_e32 v175, 0x4b800000, v174
	s_nop 0
	v_cndmask_b32_e32 v174, v174, v175, vcc
	v_rsq_f32_e32 v174, v174
	s_nop 0
	v_mul_f32_e32 v175, 0x45800000, v174
	v_cndmask_b32_e32 v174, v174, v175, vcc
	v_mul_f32_e32 v170, v170, v174
	v_pk_mul_f32 v[174:175], v[32:33], v[170:171] op_sel_hi:[1,0]
	v_pk_mul_f32 v[180:181], v[34:35], v[170:171] op_sel_hi:[1,0]
	v_pk_mul_f32 v[174:175], v[168:169], v[174:175]
	v_pk_mul_f32 v[182:183], v[166:167], v[180:181]
	v_pk_mul_f32 v[180:181], v[24:25], v[170:171] op_sel_hi:[1,0]
	v_pk_mul_f32 v[206:207], v[26:27], v[170:171] op_sel_hi:[1,0]
	v_pk_mul_f32 v[208:209], v[160:161], v[180:181]
	v_cvt_pk_bf16_f32 v180, v174, v175
	v_add_co_u32_e32 v174, vcc, s15, v172
	v_cvt_pk_bf16_f32 v181, v182, v183
	v_pk_mul_f32 v[206:207], v[158:159], v[206:207]
	s_nop 0
	v_addc_co_u32_e32 v175, vcc, 0, v173, vcc
	v_cvt_pk_bf16_f32 v182, v208, v209
	v_cvt_pk_bf16_f32 v183, v206, v207
	global_store_dwordx4 v[174:175], v[180:183], off
	v_pk_mul_f32 v[206:207], v[12:13], v[170:171] op_sel_hi:[1,0]
	v_pk_mul_f32 v[208:209], v[14:15], v[170:171] op_sel_hi:[1,0]
	v_pk_mul_f32 v[180:181], v[20:21], v[170:171] op_sel_hi:[1,0]
	v_pk_mul_f32 v[182:183], v[22:23], v[170:171] op_sel_hi:[1,0]
	v_pk_mul_f32 v[180:181], v[164:165], v[180:181]
	v_pk_mul_f32 v[182:183], v[162:163], v[182:183]
	v_cvt_pk_bf16_f32 v180, v180, v181
	v_pk_mul_f32 v[208:209], v[154:155], v[208:209]
	v_cvt_pk_bf16_f32 v181, v182, v183
	v_pk_mul_f32 v[206:207], v[156:157], v[206:207]
	v_cvt_pk_bf16_f32 v183, v208, v209
	s_mov_b32 s15, 0x58000
	v_cvt_pk_bf16_f32 v182, v206, v207
	global_store_dwordx4 v[174:175], v[180:183], off offset:64
	v_mov_b32_e32 v174, v16
	v_mov_b32_e32 v175, v8
	v_mov_b32_e32 v180, v17
	v_mov_b32_e32 v181, v9
	v_pk_mul_f32 v[180:181], v[180:181], v[180:181]
	v_mov_b32_e32 v182, v5
	v_pk_fma_f32 v[174:175], v[174:175], v[174:175], v[180:181]
	v_mov_b32_e32 v180, v18
	v_mov_b32_e32 v181, v10
	v_pk_fma_f32 v[174:175], v[180:181], v[180:181], v[174:175]
	v_mov_b32_e32 v180, v19
	v_mov_b32_e32 v181, v11
	v_mov_b32_e32 v183, v1
	v_pk_fma_f32 v[174:175], v[180:181], v[180:181], v[174:175]
	v_mov_b32_e32 v180, v4
	v_mov_b32_e32 v181, v0
	v_pk_mul_f32 v[182:183], v[182:183], v[182:183]
	v_add_f32_e32 v170, v174, v175
	v_pk_fma_f32 v[180:181], v[180:181], v[180:181], v[182:183]
	v_mov_b32_e32 v182, v6
	v_mov_b32_e32 v183, v2
	v_pk_fma_f32 v[180:181], v[182:183], v[182:183], v[180:181]
	v_mov_b32_e32 v182, v7
	v_mov_b32_e32 v183, v3
	v_pk_fma_f32 v[180:181], v[182:183], v[182:183], v[180:181]
	s_nop 0
	v_add_f32_e32 v170, v170, v180
	v_add_f32_e32 v170, v170, v181
	ds_bpermute_b32 v174, v204, v170
	s_waitcnt lgkmcnt(0)
	v_add_f32_e32 v170, v170, v174
	ds_bpermute_b32 v174, v203, v170
	s_waitcnt lgkmcnt(0)
	v_add_f32_e32 v170, v170, v174
	v_mul_f32_e32 v170, v171, v170
	v_mul_f32_e32 v170, v171, v170
	v_fmamk_f32 v170, v170, 0x3c800000, v201
	v_cmp_gt_f32_e32 vcc, s92, v170
	v_mul_f32_e32 v174, 0x4b800000, v170
	s_nop 0
	v_cndmask_b32_e32 v170, v170, v174, vcc
	v_rsq_f32_e32 v170, v170
	s_nop 0
	v_mul_f32_e32 v174, 0x45800000, v170
	v_cndmask_b32_e32 v170, v170, v174, vcc
	v_mul_f32_e32 v170, v171, v170
	v_pk_mul_f32 v[174:175], v[16:17], v[170:171] op_sel_hi:[1,0]
	v_pk_mul_f32 v[180:181], v[18:19], v[170:171] op_sel_hi:[1,0]
	v_pk_mul_f32 v[168:169], v[168:169], v[174:175]
	v_pk_mul_f32 v[166:167], v[166:167], v[180:181]
	v_pk_mul_f32 v[174:175], v[8:9], v[170:171] op_sel_hi:[1,0]
	v_pk_mul_f32 v[180:181], v[10:11], v[170:171] op_sel_hi:[1,0]
	v_pk_mul_f32 v[160:161], v[160:161], v[174:175]
	v_pk_mul_f32 v[180:181], v[158:159], v[180:181]
	v_cvt_pk_bf16_f32 v159, v166, v167
	v_add_co_u32_e32 v166, vcc, s15, v172
	v_cvt_pk_bf16_f32 v160, v160, v161
	v_cvt_pk_bf16_f32 v161, v180, v181
	v_cvt_pk_bf16_f32 v158, v168, v169
	s_nop 1
	v_addc_co_u32_e32 v167, vcc, 0, v173, vcc
	global_store_dwordx4 v[166:167], v[158:161], off
	s_nop 1
	v_pk_mul_f32 v[160:161], v[6:7], v[170:171] op_sel_hi:[1,0]
	v_pk_mul_f32 v[158:159], v[4:5], v[170:171] op_sel_hi:[1,0]
	v_pk_mul_f32 v[160:161], v[162:163], v[160:161]
	v_pk_mul_f32 v[162:163], v[0:1], v[170:171] op_sel_hi:[1,0]
	v_pk_mul_f32 v[158:159], v[164:165], v[158:159]
	v_pk_mul_f32 v[164:165], v[2:3], v[170:171] op_sel_hi:[1,0]
	v_pk_mul_f32 v[156:157], v[156:157], v[162:163]
	v_pk_mul_f32 v[164:165], v[154:155], v[164:165]
	v_cvt_pk_bf16_f32 v154, v158, v159
	v_cvt_pk_bf16_f32 v155, v160, v161
	v_cvt_pk_bf16_f32 v156, v156, v157
	s_nop 0
	v_cvt_pk_bf16_f32 v157, v164, v165
	global_store_dwordx4 v[166:167], v[154:157], off offset:64

.LBB0_535:
	s_andn2_b64 vcc, exec, s[38:39]
	s_cbranch_vccnz .LBB0_522
	s_mul_hi_i32 s15, s97, 0x55555556
	s_lshr_b32 s17, s15, 31
	s_add_i32 s15, s15, s17
	s_mul_i32 s17, s15, -3
	s_add_i32 s17, s17, s97
	s_lshl_b32 s20, s17, 8
	s_mul_hi_i32 s17, s15, 0x3000000
	s_mul_i32 s15, s15, 0x3000000
	s_add_u32 s15, s82, s15
	s_addc_u32 s17, s83, s17
	s_ashr_i32 s21, s20, 31
	s_lshl_b64 s[20:21], s[20:21], 1
	s_add_u32 s15, s15, s20
	s_addc_u32 s17, s17, s21
	s_add_u32 s20, s15, s93
	v_lshl_add_u32 v154, s96, 10, v184
	s_addc_u32 s21, s17, 0
	s_ashr_i32 s37, s36, 31
	ds_read2_b32 v[160:161], v154 offset1:16
	ds_read2_b32 v[162:163], v154 offset0:32 offset1:48
	ds_read2_b32 v[158:159], v154 offset0:128 offset1:144
	ds_read2_b32 v[156:157], v154 offset0:160 offset1:176
	v_lshl_add_u64 v[154:155], s[20:21], 0, v[136:137]
	s_lshl_b64 s[20:21], s[36:37], 8
	v_lshl_add_u64 v[164:165], s[20:21], 0, v[138:139]
	v_mad_u64_u32 v[154:155], s[20:21], v164, s94, v[154:155]
	v_mad_i32_i24 v155, v165, s94, v155
	s_waitcnt lgkmcnt(0)
	v_pk_mul_f32 v[126:127], v[126:127], v[160:161] op_sel_hi:[1,0]
	v_pk_mul_f32 v[124:125], v[124:125], v[160:161] op_sel_hi:[1,0]
	v_pk_mul_f32 v[164:165], v[122:123], v[160:161] op_sel_hi:[1,0]
	v_pk_mul_f32 v[122:123], v[120:121], v[160:161] op_sel_hi:[1,0]
	v_cvt_pk_bf16_f32 v120, v124, v125
	v_cvt_pk_bf16_f32 v121, v126, v127
	v_pk_mul_f32 v[116:117], v[116:117], v[160:161] op_sel_hi:[1,0]
	v_cvt_pk_bf16_f32 v122, v122, v123
	v_cvt_pk_bf16_f32 v123, v164, v165
	s_waitcnt vmcnt(0)
	global_store_dwordx4 v[154:155], v[120:123], off
	v_pk_mul_f32 v[118:119], v[118:119], v[160:161] op_sel_hi:[1,0]
	s_movk_i32 s15, 0x6000
	v_pk_mul_f32 v[120:121], v[110:111], v[160:161] op_sel_hi:[1,0]
	v_pk_mul_f32 v[110:111], v[108:109], v[160:161] op_sel_hi:[1,0]
	v_cvt_pk_bf16_f32 v108, v116, v117
	v_cvt_pk_bf16_f32 v109, v118, v119
	v_pk_mul_f32 v[84:85], v[84:85], v[162:163] op_sel_hi:[1,0]
	v_cvt_pk_bf16_f32 v110, v110, v111
	v_cvt_pk_bf16_f32 v111, v120, v121
	global_store_dwordx4 v[154:155], v[108:111], off offset:256
	v_pk_mul_f32 v[86:87], v[86:87], v[162:163] op_sel_hi:[1,0]
	v_pk_mul_f32 v[60:61], v[60:61], v[158:159] op_sel_hi:[1,0]
	v_mov_b32_e32 v108, v161
	v_pk_mul_f32 v[110:111], v[114:115], v[108:109] op_sel_hi:[1,0]
	v_pk_mul_f32 v[114:115], v[106:107], v[108:109] op_sel_hi:[1,0]
	v_pk_mul_f32 v[106:107], v[104:105], v[108:109] op_sel_hi:[1,0]
	v_cvt_pk_bf16_f32 v105, v110, v111
	v_add_co_u32_e32 v110, vcc, s15, v154
	v_pk_mul_f32 v[112:113], v[112:113], v[108:109] op_sel_hi:[1,0]
	s_nop 0
	v_addc_co_u32_e32 v111, vcc, 0, v155, vcc
	v_cvt_pk_bf16_f32 v104, v112, v113
	v_cvt_pk_bf16_f32 v106, v106, v107
	v_cvt_pk_bf16_f32 v107, v114, v115
	global_store_dwordx4 v[110:111], v[104:107], off
	v_pk_mul_f32 v[102:103], v[102:103], v[108:109] op_sel_hi:[1,0]
	v_pk_mul_f32 v[100:101], v[100:101], v[108:109] op_sel_hi:[1,0]
	v_pk_mul_f32 v[104:105], v[94:95], v[108:109] op_sel_hi:[1,0]
	v_pk_mul_f32 v[94:95], v[92:93], v[108:109] op_sel_hi:[1,0]
	v_cvt_pk_bf16_f32 v92, v100, v101
	v_cvt_pk_bf16_f32 v93, v102, v103
	s_mov_b32 s15, 0xc000
	v_cvt_pk_bf16_f32 v94, v94, v95
	v_cvt_pk_bf16_f32 v95, v104, v105
	global_store_dwordx4 v[110:111], v[92:95], off offset:256
	v_pk_mul_f32 v[62:63], v[62:63], v[158:159] op_sel_hi:[1,0]
	v_pk_mul_f32 v[52:53], v[52:53], v[158:159] op_sel_hi:[1,0]
	v_pk_mul_f32 v[92:93], v[98:99], v[162:163] op_sel_hi:[1,0]
	v_pk_mul_f32 v[94:95], v[96:97], v[162:163] op_sel_hi:[1,0]
	v_pk_mul_f32 v[96:97], v[90:91], v[162:163] op_sel_hi:[1,0]
	v_pk_mul_f32 v[90:91], v[88:89], v[162:163] op_sel_hi:[1,0]
	v_cvt_pk_bf16_f32 v89, v92, v93
	v_add_co_u32_e32 v92, vcc, s15, v154
	v_cvt_pk_bf16_f32 v88, v94, v95
	v_cvt_pk_bf16_f32 v90, v90, v91
	v_cvt_pk_bf16_f32 v91, v96, v97
	s_mov_b32 s15, 0x12000
	s_nop 0
	v_addc_co_u32_e32 v93, vcc, 0, v155, vcc
	global_store_dwordx4 v[92:93], v[88:91], off
	v_pk_mul_f32 v[54:55], v[54:55], v[158:159] op_sel_hi:[1,0]
	v_pk_mul_f32 v[20:21], v[20:21], v[156:157] op_sel_hi:[1,0]
	v_pk_mul_f32 v[88:89], v[78:79], v[162:163] op_sel_hi:[1,0]
	v_pk_mul_f32 v[78:79], v[76:77], v[162:163] op_sel_hi:[1,0]
	v_cvt_pk_bf16_f32 v76, v84, v85
	v_cvt_pk_bf16_f32 v77, v86, v87
	v_pk_mul_f32 v[22:23], v[22:23], v[156:157] op_sel_hi:[1,0]
	v_cvt_pk_bf16_f32 v78, v78, v79
	v_cvt_pk_bf16_f32 v79, v88, v89
	global_store_dwordx4 v[92:93], v[76:79], off offset:256
	s_nop 1
	v_mov_b32_e32 v76, v163
	v_pk_mul_f32 v[78:79], v[82:83], v[76:77] op_sel_hi:[1,0]
	v_pk_mul_f32 v[82:83], v[74:75], v[76:77] op_sel_hi:[1,0]
	v_pk_mul_f32 v[74:75], v[72:73], v[76:77] op_sel_hi:[1,0]
	v_cvt_pk_bf16_f32 v73, v78, v79
	v_add_co_u32_e32 v78, vcc, s15, v154
	v_pk_mul_f32 v[80:81], v[80:81], v[76:77] op_sel_hi:[1,0]
	s_nop 0
	v_addc_co_u32_e32 v79, vcc, 0, v155, vcc
	v_cvt_pk_bf16_f32 v72, v80, v81
	v_cvt_pk_bf16_f32 v74, v74, v75
	v_cvt_pk_bf16_f32 v75, v82, v83
	global_store_dwordx4 v[78:79], v[72:75], off
	v_pk_mul_f32 v[70:71], v[70:71], v[76:77] op_sel_hi:[1,0]
	v_pk_mul_f32 v[68:69], v[68:69], v[76:77] op_sel_hi:[1,0]
	v_pk_mul_f32 v[72:73], v[66:67], v[76:77] op_sel_hi:[1,0]
	v_pk_mul_f32 v[66:67], v[64:65], v[76:77] op_sel_hi:[1,0]
	v_cvt_pk_bf16_f32 v64, v68, v69
	v_cvt_pk_bf16_f32 v65, v70, v71
	s_mov_b32 s15, 0x30000
	v_cvt_pk_bf16_f32 v66, v66, v67
	v_cvt_pk_bf16_f32 v67, v72, v73
	global_store_dwordx4 v[78:79], v[64:67], off offset:256
	s_nop 1
	v_pk_mul_f32 v[64:65], v[58:59], v[158:159] op_sel_hi:[1,0]
	v_pk_mul_f32 v[58:59], v[56:57], v[158:159] op_sel_hi:[1,0]
	v_cvt_pk_bf16_f32 v56, v60, v61
	v_add_co_u32_e32 v60, vcc, s15, v154
	v_cvt_pk_bf16_f32 v57, v62, v63
	v_cvt_pk_bf16_f32 v58, v58, v59
	v_cvt_pk_bf16_f32 v59, v64, v65
	s_mov_b32 s15, 0x36000
	s_nop 0
	v_addc_co_u32_e32 v61, vcc, 0, v155, vcc
	global_store_dwordx4 v[60:61], v[56:59], off
	s_nop 1
	v_pk_mul_f32 v[56:57], v[46:47], v[158:159] op_sel_hi:[1,0]
	v_pk_mul_f32 v[46:47], v[44:45], v[158:159] op_sel_hi:[1,0]
	v_cvt_pk_bf16_f32 v44, v52, v53
	v_cvt_pk_bf16_f32 v45, v54, v55
	s_nop 0
	v_cvt_pk_bf16_f32 v46, v46, v47
	v_cvt_pk_bf16_f32 v47, v56, v57
	global_store_dwordx4 v[60:61], v[44:47], off offset:256
	s_nop 1
	v_mov_b32_e32 v44, v159
	v_pk_mul_f32 v[46:47], v[50:51], v[44:45] op_sel_hi:[1,0]
	v_pk_mul_f32 v[50:51], v[42:43], v[44:45] op_sel_hi:[1,0]
	v_pk_mul_f32 v[42:43], v[40:41], v[44:45] op_sel_hi:[1,0]
	v_cvt_pk_bf16_f32 v41, v46, v47
	v_add_co_u32_e32 v46, vcc, s15, v154
	v_pk_mul_f32 v[48:49], v[48:49], v[44:45] op_sel_hi:[1,0]
	s_nop 0
	v_addc_co_u32_e32 v47, vcc, 0, v155, vcc
	v_cvt_pk_bf16_f32 v40, v48, v49
	v_cvt_pk_bf16_f32 v42, v42, v43
	v_cvt_pk_bf16_f32 v43, v50, v51
	global_store_dwordx4 v[46:47], v[40:43], off
	v_pk_mul_f32 v[38:39], v[38:39], v[44:45] op_sel_hi:[1,0]
	v_pk_mul_f32 v[36:37], v[36:37], v[44:45] op_sel_hi:[1,0]
	v_pk_mul_f32 v[40:41], v[30:31], v[44:45] op_sel_hi:[1,0]
	v_pk_mul_f32 v[30:31], v[28:29], v[44:45] op_sel_hi:[1,0]
	v_cvt_pk_bf16_f32 v28, v36, v37
	v_cvt_pk_bf16_f32 v29, v38, v39
	s_mov_b32 s15, 0x3c000
	v_cvt_pk_bf16_f32 v30, v30, v31
	v_cvt_pk_bf16_f32 v31, v40, v41
	global_store_dwordx4 v[46:47], v[28:31], off offset:256
	s_nop 1
	v_pk_mul_f32 v[28:29], v[34:35], v[156:157] op_sel_hi:[1,0]
	v_pk_mul_f32 v[30:31], v[32:33], v[156:157] op_sel_hi:[1,0]
	v_pk_mul_f32 v[32:33], v[26:27], v[156:157] op_sel_hi:[1,0]
	v_pk_mul_f32 v[26:27], v[24:25], v[156:157] op_sel_hi:[1,0]
	v_cvt_pk_bf16_f32 v25, v28, v29
	v_add_co_u32_e32 v28, vcc, s15, v154
	v_cvt_pk_bf16_f32 v24, v30, v31
	v_cvt_pk_bf16_f32 v26, v26, v27
	v_cvt_pk_bf16_f32 v27, v32, v33
	s_mov_b32 s15, 0x42000
	s_nop 0
	v_addc_co_u32_e32 v29, vcc, 0, v155, vcc
	global_store_dwordx4 v[28:29], v[24:27], off
	s_nop 1
	v_pk_mul_f32 v[24:25], v[14:15], v[156:157] op_sel_hi:[1,0]
	v_pk_mul_f32 v[14:15], v[12:13], v[156:157] op_sel_hi:[1,0]
	v_cvt_pk_bf16_f32 v12, v20, v21
	v_cvt_pk_bf16_f32 v13, v22, v23
	s_nop 0
	v_cvt_pk_bf16_f32 v14, v14, v15
	v_cvt_pk_bf16_f32 v15, v24, v25
	global_store_dwordx4 v[28:29], v[12:15], off offset:256
	s_nop 1
	v_mov_b32_e32 v12, v157
	v_pk_mul_f32 v[14:15], v[18:19], v[12:13] op_sel_hi:[1,0]
	v_pk_mul_f32 v[18:19], v[10:11], v[12:13] op_sel_hi:[1,0]
	v_pk_mul_f32 v[10:11], v[8:9], v[12:13] op_sel_hi:[1,0]
	v_cvt_pk_bf16_f32 v9, v14, v15
	v_add_co_u32_e32 v14, vcc, s15, v154
	v_pk_mul_f32 v[16:17], v[16:17], v[12:13] op_sel_hi:[1,0]
	s_nop 0
	v_addc_co_u32_e32 v15, vcc, 0, v155, vcc
	v_cvt_pk_bf16_f32 v8, v16, v17
	v_cvt_pk_bf16_f32 v10, v10, v11
	v_cvt_pk_bf16_f32 v11, v18, v19
	global_store_dwordx4 v[14:15], v[8:11], off
	v_pk_mul_f32 v[6:7], v[6:7], v[12:13] op_sel_hi:[1,0]
	v_pk_mul_f32 v[4:5], v[4:5], v[12:13] op_sel_hi:[1,0]
	v_pk_mul_f32 v[8:9], v[2:3], v[12:13] op_sel_hi:[1,0]
	v_pk_mul_f32 v[2:3], v[0:1], v[12:13] op_sel_hi:[1,0]
	v_cvt_pk_bf16_f32 v0, v4, v5
	v_cvt_pk_bf16_f32 v1, v6, v7
	s_nop 0
	v_cvt_pk_bf16_f32 v2, v2, v3
	v_cvt_pk_bf16_f32 v3, v8, v9
	global_store_dwordx4 v[14:15], v[0:3], off offset:256
	s_branch .LBB0_522

.LBB0_542:
	v_ashrrev_i32_e32 v6, 16, v0
	v_ashrrev_i32_e32 v7, 31, v6
	v_and_b32_e32 v1, 0xff00, v4
	v_lshlrev_b64 v[6:7], 17, v[6:7]
	v_lshlrev_b32_e32 v2, 1, v1
	v_lshl_add_u64 v[6:7], s[6:7], 0, v[6:7]
	v_lshl_add_u64 v[6:7], v[6:7], 0, v[2:3]
	v_lshlrev_b32_sdwa v2, v5, v0 dst_sel:DWORD dst_unused:UNUSED_PAD src0_sel:DWORD src1_sel:BYTE_1
	v_lshl_add_u64 v[6:7], v[6:7], 0, v[2:3]
	global_load_ushort v2, v[6:7], off
	v_ashrrev_i32_e32 v1, 31, v0
	v_lshl_add_u64 v[6:7], v[0:1], 1, s[2:3]
	v_add_u32_e32 v0, s10, v0
	v_cmp_lt_i32_e32 vcc, s12, v0
	v_add_u32_e32 v4, s11, v4
	s_or_b64 s[8:9], vcc, s[8:9]
	s_waitcnt vmcnt(0) lgkmcnt(0)
	global_store_short v[6:7], v2, off
	s_andn2_b64 exec, exec, s[8:9]
	s_cbranch_execnz .LBB0_542

.LBB0_1554:
	v_cmp_gt_i64_e32 vcc, s[4:5], v[4:5]
	s_mov_b64 s[10:11], -1
	s_cbranch_vccnz .LBB0_1553
	s_mov_b64 s[10:11], exec
	s_cbranch_execz .LBB0_1552
	s_ashr_i32 s14, s4, 31
	s_lshr_b32 s14, s14, 29
	s_add_i32 s14, s4, s14
	s_ashr_i32 s15, s14, 3
	s_and_b32 s14, s14, -8
	s_sub_i32 s14, s4, s14
	s_cmp_lt_i32 s14, 0
	s_cselect_b32 s16, s12, 0x160
	s_mul_i32 s14, s16, s14
	s_add_i32 s14, s14, s15
	s_mul_hi_i32 s15, s14, 0x2e8ba2e9
	s_lshr_b32 s16, s15, 31
	s_ashr_i32 s15, s15, 5
	s_add_i32 s15, s15, s16
	s_lshl_b32 s16, s15, 3
	s_sub_i32 s17, 0x80, s16
	s_min_i32 s17, s17, 8
	s_abs_i32 s17, s17
	v_cvt_f32_u32_e32 v7, s17
	s_sub_i32 s18, 0, s17
	s_mulk_i32 s15, 0xb0
	s_sub_i32 s14, s14, s15
	v_rcp_iflag_f32_e32 v7, v7
	s_ashr_i32 s15, s14, 31
	s_abs_i32 s14, s14
	v_mul_f32_e32 v7, 0x4f7ffffe, v7
	v_cvt_u32_f32_e32 v7, v7
	s_nop 0
	v_readfirstlane_b32 s19, v7
	s_mul_i32 s18, s18, s19
	s_mul_hi_u32 s18, s19, s18
	s_add_i32 s19, s19, s18
	s_mul_hi_u32 s18, s14, s19
	s_mul_i32 s18, s18, s17
	s_sub_i32 s14, s14, s18
	s_sub_i32 s18, s14, s17
	s_cmp_ge_u32 s14, s17
	s_cselect_b32 s14, s18, s14
	s_sub_i32 s18, s14, s17
	s_cmp_ge_u32 s14, s17
	s_cselect_b32 s14, s18, s14
	s_xor_b32 s14, s14, s15
	s_sub_i32 s14, s14, s15
	s_add_i32 s14, s14, s16
	s_ashr_i32 s15, s14, 31
	s_lshl_b64 s[14:15], s[14:15], 14
	v_lshl_add_u64 v[26:27], v[2:3], 0, s[14:15]
	s_waitcnt vmcnt(0)
	global_load_dwordx4 v[8:11], v[26:27], off
	global_load_dwordx4 v[14:17], v[26:27], off offset:16
	global_load_dwordx4 v[18:21], v[26:27], off offset:32
	global_load_dwordx4 v[22:25], v[26:27], off offset:48
	s_waitcnt vmcnt(0) lgkmcnt(0)
	v_mov_b32_e32 v26, v9
	v_mov_b32_e32 v27, v10
	v_mov_b32_e32 v28, v15
	v_mov_b32_e32 v29, v16
	v_mov_b32_e32 v9, v11
	v_mov_b32_e32 v15, v17
	v_mov_b32_e32 v10, v19
	v_mov_b32_e32 v16, v21
	v_pk_add_f32 v[8:9], v[26:27], v[8:9]
	v_pk_add_f32 v[14:15], v[28:29], v[14:15]
	v_pk_add_f32 v[10:11], v[18:19], v[10:11]
	v_pk_add_f32 v[16:17], v[20:21], v[16:17]
	v_pk_add_f32 v[8:9], v[8:9], v[8:9] op_sel:[0,1] op_sel_hi:[1,0]
	v_pk_add_f32 v[14:15], v[14:15], v[14:15] op_sel:[0,1] op_sel_hi:[1,0]
	v_mov_b32_e32 v11, v24
	v_mov_b32_e32 v17, v25
	v_mov_b32_e32 v9, v22
	v_mov_b32_e32 v15, v23
	v_pk_add_f32 v[10:11], v[10:11], v[16:17]
	v_pk_add_f32 v[8:9], v[8:9], v[14:15]
	s_nop 0
	v_pk_add_f32 v[8:9], v[8:9], v[10:11]
	s_nop 0
	v_add_f32_e32 v7, v8, v9
	v_fmamk_f32 v7, v7, 0x3a800000, v6
	v_mul_f32_e32 v8, 0x4b800000, v7
	v_cmp_gt_f32_e32 vcc, s13, v7
	s_nop 1
	v_cndmask_b32_e32 v7, v7, v8, vcc
	v_rsq_f32_e32 v7, v7
	s_nop 0
	v_mul_f32_e32 v8, 0x45800000, v7
	v_cndmask_b32_e32 v7, v7, v8, vcc
	ds_write_b32 v1, v7
	s_branch .LBB0_1552

.LBB0_1564:
	ds_read_b128 v[148:151], v156
	ds_read_b128 v[172:175], v157
	ds_read_b128 v[180:183], v158
	ds_read_b128 v[184:187], v159
	s_add_u32 s24, s22, 0xfffc0080
	s_addc_u32 s25, s23, -1
	s_cmp_eq_u32 s68, 12
	s_cselect_b32 s27, s15, s25
	s_cselect_b32 s26, s64, s24
	s_cselect_b32 s25, s13, s67
	s_cselect_b32 s24, s65, s66
	s_mov_b32 m0, s54
	v_lshl_add_u64 v[152:153], s[22:23], 0, v[142:143]
	ds_read_b128 v[188:191], v154
	ds_read_b128 v[192:195], v154 offset:1024
	ds_read_b128 v[196:199], v154 offset:2048
	ds_read_b128 v[200:203], v154 offset:3072
	ds_read_b128 v[204:207], v154 offset:4096
	ds_read_b128 v[208:211], v154 offset:5120
	ds_read_b128 v[212:215], v154 offset:6144
	ds_read_b128 v[216:219], v154 offset:7168
	global_load_lds_dwordx4 v[152:153], off
	v_lshl_add_u64 v[152:153], s[22:23], 0, v[140:141]
	s_mov_b32 m0, s55
	s_nop 0
	global_load_lds_dwordx4 v[152:153], off
	s_waitcnt lgkmcnt(8)
	s_barrier
	s_waitcnt lgkmcnt(0)
	s_setprio 1
	s_waitcnt lgkmcnt(0)
	v_mfma_f32_16x16x32_bf16 v[124:127], v[148:151], v[188:191], v[124:127]
	v_mfma_f32_16x16x32_bf16 v[120:123], v[180:183], v[188:191], v[120:123]
	v_mfma_f32_16x16x32_bf16 v[108:111], v[148:151], v[196:199], v[108:111]
	v_mfma_f32_16x16x32_bf16 v[104:107], v[180:183], v[196:199], v[104:107]
	v_mfma_f32_16x16x32_bf16 v[92:95], v[148:151], v[204:207], v[92:95]
	v_mfma_f32_16x16x32_bf16 v[88:91], v[180:183], v[204:207], v[88:91]
	v_mfma_f32_16x16x32_bf16 v[76:79], v[148:151], v[212:215], v[76:79]
	v_mfma_f32_16x16x32_bf16 v[72:75], v[180:183], v[212:215], v[72:75]
	v_mfma_f32_16x16x32_bf16 v[124:127], v[172:175], v[192:195], v[124:127]
	v_mfma_f32_16x16x32_bf16 v[120:123], v[184:187], v[192:195], v[120:123]
	v_mfma_f32_16x16x32_bf16 v[108:111], v[172:175], v[200:203], v[108:111]
	v_mfma_f32_16x16x32_bf16 v[104:107], v[184:187], v[200:203], v[104:107]
	v_mfma_f32_16x16x32_bf16 v[92:95], v[172:175], v[208:211], v[92:95]
	v_mfma_f32_16x16x32_bf16 v[88:91], v[184:187], v[208:211], v[88:91]
	v_mfma_f32_16x16x32_bf16 v[76:79], v[172:175], v[216:219], v[76:79]
	v_mfma_f32_16x16x32_bf16 v[72:75], v[184:187], v[216:219], v[72:75]
	s_setprio 0
	s_barrier
	s_mov_b32 m0, s38
	v_lshl_add_u64 v[152:153], s[24:25], 0, v[132:133]
	ds_read_b128 v[220:223], v160
	ds_read_b128 v[224:227], v161
	ds_read_b128 v[228:231], v162
	ds_read_b128 v[232:235], v163
	global_load_lds_dwordx4 v[152:153], off
	v_lshl_add_u64 v[236:237], s[24:25], 0, v[128:129]
	s_mov_b32 m0, s39
	s_nop 0
	global_load_lds_dwordx4 v[236:237], off
	s_barrier
	s_waitcnt lgkmcnt(0)
	s_setprio 1
	s_waitcnt lgkmcnt(0)
	v_mfma_f32_16x16x32_bf16 v[116:119], v[220:223], v[188:191], v[116:119]
	v_mfma_f32_16x16x32_bf16 v[112:115], v[228:231], v[188:191], v[112:115]
	v_mfma_f32_16x16x32_bf16 v[100:103], v[220:223], v[196:199], v[100:103]
	v_mfma_f32_16x16x32_bf16 v[96:99], v[228:231], v[196:199], v[96:99]
	v_mfma_f32_16x16x32_bf16 v[84:87], v[220:223], v[204:207], v[84:87]
	v_mfma_f32_16x16x32_bf16 v[80:83], v[228:231], v[204:207], v[80:83]
	v_mfma_f32_16x16x32_bf16 v[68:71], v[220:223], v[212:215], v[68:71]
	v_mfma_f32_16x16x32_bf16 v[64:67], v[228:231], v[212:215], v[64:67]
	v_mfma_f32_16x16x32_bf16 v[116:119], v[224:227], v[192:195], v[116:119]
	v_mfma_f32_16x16x32_bf16 v[112:115], v[232:235], v[192:195], v[112:115]
	v_mfma_f32_16x16x32_bf16 v[100:103], v[224:227], v[200:203], v[100:103]
	v_mfma_f32_16x16x32_bf16 v[96:99], v[232:235], v[200:203], v[96:99]
	v_mfma_f32_16x16x32_bf16 v[84:87], v[224:227], v[208:211], v[84:87]
	v_mfma_f32_16x16x32_bf16 v[80:83], v[232:235], v[208:211], v[80:83]
	v_mfma_f32_16x16x32_bf16 v[68:71], v[224:227], v[216:219], v[68:71]
	v_mfma_f32_16x16x32_bf16 v[64:67], v[232:235], v[216:219], v[64:67]
	s_setprio 0
	s_mov_b32 m0, s34
	v_lshl_add_u64 v[238:239], s[26:27], 0, v[134:135]
	s_barrier
	ds_read_b128 v[188:191], v154 offset:16384
	ds_read_b128 v[192:195], v154 offset:17408
	ds_read_b128 v[196:199], v154 offset:18432
	ds_read_b128 v[200:203], v154 offset:19456
	ds_read_b128 v[204:207], v154 offset:20480
	ds_read_b128 v[208:211], v154 offset:21504
	ds_read_b128 v[212:215], v154 offset:22528
	ds_read_b128 v[216:219], v154 offset:23552
	global_load_lds_dwordx4 v[238:239], off
	v_lshl_add_u64 v[240:241], s[26:27], 0, v[130:131]
	s_mov_b32 m0, s40
	s_nop 0
	global_load_lds_dwordx4 v[240:241], off
	s_barrier
	s_waitcnt lgkmcnt(0)
	s_setprio 1
	s_waitcnt lgkmcnt(0)
	v_mfma_f32_16x16x32_bf16 v[60:63], v[148:151], v[188:191], v[60:63]
	v_mfma_f32_16x16x32_bf16 v[56:59], v[180:183], v[188:191], v[56:59]
	v_mfma_f32_16x16x32_bf16 v[44:47], v[148:151], v[196:199], v[44:47]
	v_mfma_f32_16x16x32_bf16 v[40:43], v[180:183], v[196:199], v[40:43]
	v_mfma_f32_16x16x32_bf16 v[28:31], v[148:151], v[204:207], v[28:31]
	v_mfma_f32_16x16x32_bf16 v[24:27], v[180:183], v[204:207], v[24:27]
	v_mfma_f32_16x16x32_bf16 v[12:15], v[148:151], v[212:215], v[12:15]
	v_mfma_f32_16x16x32_bf16 v[8:11], v[180:183], v[212:215], v[8:11]
	v_mfma_f32_16x16x32_bf16 v[60:63], v[172:175], v[192:195], v[60:63]
	v_mfma_f32_16x16x32_bf16 v[56:59], v[184:187], v[192:195], v[56:59]
	v_mfma_f32_16x16x32_bf16 v[44:47], v[172:175], v[200:203], v[44:47]
	v_mfma_f32_16x16x32_bf16 v[40:43], v[184:187], v[200:203], v[40:43]
	v_mfma_f32_16x16x32_bf16 v[28:31], v[172:175], v[208:211], v[28:31]
	v_mfma_f32_16x16x32_bf16 v[24:27], v[184:187], v[208:211], v[24:27]
	v_mfma_f32_16x16x32_bf16 v[12:15], v[172:175], v[216:219], v[12:15]
	v_mfma_f32_16x16x32_bf16 v[8:11], v[184:187], v[216:219], v[8:11]
	s_setprio 0
	s_barrier
	s_add_u32 s70, s24, 0x40000
	s_addc_u32 s71, s25, 0
	s_mov_b32 m0, s41
	v_lshl_add_u64 v[148:149], s[70:71], 0, v[132:133]
	global_load_lds_dwordx4 v[148:149], off
	v_lshl_add_u64 v[148:149], s[70:71], 0, v[128:129]
	s_mov_b32 m0, s42
	s_nop 0
	global_load_lds_dwordx4 v[148:149], off
	s_waitcnt vmcnt(6)
	s_barrier
	s_setprio 1
	v_mfma_f32_16x16x32_bf16 v[52:55], v[220:223], v[188:191], v[52:55]
	v_mfma_f32_16x16x32_bf16 v[48:51], v[228:231], v[188:191], v[48:51]
	v_mfma_f32_16x16x32_bf16 v[36:39], v[220:223], v[196:199], v[36:39]
	v_mfma_f32_16x16x32_bf16 v[32:35], v[228:231], v[196:199], v[32:35]
	v_mfma_f32_16x16x32_bf16 v[20:23], v[220:223], v[204:207], v[20:23]
	v_mfma_f32_16x16x32_bf16 v[16:19], v[228:231], v[204:207], v[16:19]
	v_mfma_f32_16x16x32_bf16 v[4:7], v[220:223], v[212:215], v[4:7]
	v_mfma_f32_16x16x32_bf16 v[0:3], v[228:231], v[212:215], v[0:3]
	v_mfma_f32_16x16x32_bf16 v[52:55], v[224:227], v[192:195], v[52:55]
	v_mfma_f32_16x16x32_bf16 v[48:51], v[232:235], v[192:195], v[48:51]
	v_mfma_f32_16x16x32_bf16 v[36:39], v[224:227], v[200:203], v[36:39]
	v_mfma_f32_16x16x32_bf16 v[32:35], v[232:235], v[200:203], v[32:35]
	v_mfma_f32_16x16x32_bf16 v[20:23], v[224:227], v[208:211], v[20:23]
	v_mfma_f32_16x16x32_bf16 v[16:19], v[232:235], v[208:211], v[16:19]
	v_mfma_f32_16x16x32_bf16 v[4:7], v[224:227], v[216:219], v[4:7]
	v_mfma_f32_16x16x32_bf16 v[0:3], v[232:235], v[216:219], v[0:3]
	s_setprio 0
	s_barrier
	ds_read_b128 v[148:151], v164
	ds_read_b128 v[172:175], v165
	ds_read_b128 v[180:183], v166
	ds_read_b128 v[184:187], v167
	s_add_u32 s26, s26, 0x40000
	s_addc_u32 s27, s27, 0
	s_mov_b32 m0, s43
	v_lshl_add_u64 v[220:221], s[26:27], 0, v[134:135]
	ds_read_b128 v[188:191], v154 offset:32768
	ds_read_b128 v[192:195], v154 offset:33792
	ds_read_b128 v[196:199], v154 offset:34816
	ds_read_b128 v[200:203], v154 offset:35840
	ds_read_b128 v[204:207], v154 offset:36864
	ds_read_b128 v[208:211], v154 offset:37888
	ds_read_b128 v[212:215], v154 offset:38912
	ds_read_b128 v[216:219], v154 offset:39936
	global_load_lds_dwordx4 v[220:221], off
	v_lshl_add_u64 v[220:221], s[26:27], 0, v[130:131]
	s_mov_b32 m0, s44
	s_nop 0
	global_load_lds_dwordx4 v[220:221], off
	s_waitcnt lgkmcnt(8)
	s_barrier
	s_waitcnt lgkmcnt(0)
	s_setprio 1
	s_waitcnt lgkmcnt(0)
	v_mfma_f32_16x16x32_bf16 v[124:127], v[148:151], v[188:191], v[124:127]
	v_mfma_f32_16x16x32_bf16 v[120:123], v[180:183], v[188:191], v[120:123]
	v_mfma_f32_16x16x32_bf16 v[108:111], v[148:151], v[196:199], v[108:111]
	v_mfma_f32_16x16x32_bf16 v[104:107], v[180:183], v[196:199], v[104:107]
	v_mfma_f32_16x16x32_bf16 v[92:95], v[148:151], v[204:207], v[92:95]
	v_mfma_f32_16x16x32_bf16 v[88:91], v[180:183], v[204:207], v[88:91]
	v_mfma_f32_16x16x32_bf16 v[76:79], v[148:151], v[212:215], v[76:79]
	v_mfma_f32_16x16x32_bf16 v[72:75], v[180:183], v[212:215], v[72:75]
	v_mfma_f32_16x16x32_bf16 v[124:127], v[172:175], v[192:195], v[124:127]
	v_mfma_f32_16x16x32_bf16 v[120:123], v[184:187], v[192:195], v[120:123]
	v_mfma_f32_16x16x32_bf16 v[108:111], v[172:175], v[200:203], v[108:111]
	v_mfma_f32_16x16x32_bf16 v[104:107], v[184:187], v[200:203], v[104:107]
	v_mfma_f32_16x16x32_bf16 v[92:95], v[172:175], v[208:211], v[92:95]
	v_mfma_f32_16x16x32_bf16 v[88:91], v[184:187], v[208:211], v[88:91]
	v_mfma_f32_16x16x32_bf16 v[76:79], v[172:175], v[216:219], v[76:79]
	v_mfma_f32_16x16x32_bf16 v[72:75], v[184:187], v[216:219], v[72:75]
	s_setprio 0
	s_barrier
	s_mov_b32 m0, s46
	v_lshl_add_u64 v[152:153], v[152:153], 0, s[10:11]
	ds_read_b128 v[220:223], v168
	ds_read_b128 v[224:227], v169
	ds_read_b128 v[228:231], v170
	ds_read_b128 v[232:235], v171
	global_load_lds_dwordx4 v[152:153], off
	v_lshl_add_u64 v[152:153], v[236:237], 0, s[10:11]
	s_mov_b32 m0, s47
	s_nop 0
	global_load_lds_dwordx4 v[152:153], off
	s_barrier
	s_waitcnt lgkmcnt(0)
	s_setprio 1
	s_waitcnt lgkmcnt(0)
	v_mfma_f32_16x16x32_bf16 v[116:119], v[220:223], v[188:191], v[116:119]
	v_mfma_f32_16x16x32_bf16 v[112:115], v[228:231], v[188:191], v[112:115]
	v_mfma_f32_16x16x32_bf16 v[100:103], v[220:223], v[196:199], v[100:103]
	v_mfma_f32_16x16x32_bf16 v[96:99], v[228:231], v[196:199], v[96:99]
	v_mfma_f32_16x16x32_bf16 v[84:87], v[220:223], v[204:207], v[84:87]
	v_mfma_f32_16x16x32_bf16 v[80:83], v[228:231], v[204:207], v[80:83]
	v_mfma_f32_16x16x32_bf16 v[68:71], v[220:223], v[212:215], v[68:71]
	v_mfma_f32_16x16x32_bf16 v[64:67], v[228:231], v[212:215], v[64:67]
	v_mfma_f32_16x16x32_bf16 v[116:119], v[224:227], v[192:195], v[116:119]
	v_mfma_f32_16x16x32_bf16 v[112:115], v[232:235], v[192:195], v[112:115]
	v_mfma_f32_16x16x32_bf16 v[100:103], v[224:227], v[200:203], v[100:103]
	v_mfma_f32_16x16x32_bf16 v[96:99], v[232:235], v[200:203], v[96:99]
	v_mfma_f32_16x16x32_bf16 v[84:87], v[224:227], v[208:211], v[84:87]
	v_mfma_f32_16x16x32_bf16 v[80:83], v[232:235], v[208:211], v[80:83]
	v_mfma_f32_16x16x32_bf16 v[68:71], v[224:227], v[216:219], v[68:71]
	v_mfma_f32_16x16x32_bf16 v[64:67], v[232:235], v[216:219], v[64:67]
	s_setprio 0
	s_mov_b32 m0, s48
	v_lshl_add_u64 v[152:153], v[238:239], 0, s[10:11]
	s_barrier
	ds_read_b128 v[188:191], v154 offset:49152
	ds_read_b128 v[192:195], v154 offset:50176
	ds_read_b128 v[196:199], v154 offset:51200
	ds_read_b128 v[200:203], v154 offset:52224
	ds_read_b128 v[204:207], v154 offset:53248
	ds_read_b128 v[208:211], v154 offset:54272
	ds_read_b128 v[212:215], v154 offset:55296
	ds_read_b128 v[216:219], v154 offset:56320
	global_load_lds_dwordx4 v[152:153], off
	v_lshl_add_u64 v[152:153], v[240:241], 0, s[10:11]
	s_mov_b32 m0, s49
	s_nop 0
	global_load_lds_dwordx4 v[152:153], off
	s_barrier
	s_waitcnt lgkmcnt(0)
	s_setprio 1
	s_waitcnt lgkmcnt(0)
	v_mfma_f32_16x16x32_bf16 v[60:63], v[148:151], v[188:191], v[60:63]
	v_mfma_f32_16x16x32_bf16 v[56:59], v[180:183], v[188:191], v[56:59]
	v_mfma_f32_16x16x32_bf16 v[44:47], v[148:151], v[196:199], v[44:47]
	v_mfma_f32_16x16x32_bf16 v[40:43], v[180:183], v[196:199], v[40:43]
	v_mfma_f32_16x16x32_bf16 v[28:31], v[148:151], v[204:207], v[28:31]
	v_mfma_f32_16x16x32_bf16 v[24:27], v[180:183], v[204:207], v[24:27]
	v_mfma_f32_16x16x32_bf16 v[12:15], v[148:151], v[212:215], v[12:15]
	v_mfma_f32_16x16x32_bf16 v[8:11], v[180:183], v[212:215], v[8:11]
	v_mfma_f32_16x16x32_bf16 v[60:63], v[172:175], v[192:195], v[60:63]
	v_mfma_f32_16x16x32_bf16 v[56:59], v[184:187], v[192:195], v[56:59]
	v_mfma_f32_16x16x32_bf16 v[44:47], v[172:175], v[200:203], v[44:47]
	v_mfma_f32_16x16x32_bf16 v[40:43], v[184:187], v[200:203], v[40:43]
	v_mfma_f32_16x16x32_bf16 v[28:31], v[172:175], v[208:211], v[28:31]
	v_mfma_f32_16x16x32_bf16 v[24:27], v[184:187], v[208:211], v[24:27]
	v_mfma_f32_16x16x32_bf16 v[12:15], v[172:175], v[216:219], v[12:15]
	v_mfma_f32_16x16x32_bf16 v[8:11], v[184:187], v[216:219], v[8:11]
	s_setprio 0
	s_barrier
	s_add_u32 s24, s24, 0x40080
	s_addc_u32 s25, s25, 0
	s_mov_b32 m0, s52
	v_lshl_add_u64 v[148:149], s[24:25], 0, v[132:133]
	global_load_lds_dwordx4 v[148:149], off
	v_lshl_add_u64 v[148:149], s[24:25], 0, v[128:129]
	s_mov_b32 m0, s53
	s_nop 0
	global_load_lds_dwordx4 v[148:149], off
	s_waitcnt vmcnt(6)
	s_barrier
	s_setprio 1
	v_mfma_f32_16x16x32_bf16 v[52:55], v[220:223], v[188:191], v[52:55]
	v_mfma_f32_16x16x32_bf16 v[48:51], v[228:231], v[188:191], v[48:51]
	v_mfma_f32_16x16x32_bf16 v[36:39], v[220:223], v[196:199], v[36:39]
	v_mfma_f32_16x16x32_bf16 v[32:35], v[228:231], v[196:199], v[32:35]
	v_mfma_f32_16x16x32_bf16 v[20:23], v[220:223], v[204:207], v[20:23]
	v_mfma_f32_16x16x32_bf16 v[16:19], v[228:231], v[204:207], v[16:19]
	v_mfma_f32_16x16x32_bf16 v[4:7], v[220:223], v[212:215], v[4:7]
	v_mfma_f32_16x16x32_bf16 v[0:3], v[228:231], v[212:215], v[0:3]
	v_mfma_f32_16x16x32_bf16 v[52:55], v[224:227], v[192:195], v[52:55]
	v_mfma_f32_16x16x32_bf16 v[48:51], v[232:235], v[192:195], v[48:51]
	v_mfma_f32_16x16x32_bf16 v[36:39], v[224:227], v[200:203], v[36:39]
	v_mfma_f32_16x16x32_bf16 v[32:35], v[232:235], v[200:203], v[32:35]
	v_mfma_f32_16x16x32_bf16 v[20:23], v[224:227], v[208:211], v[20:23]
	v_mfma_f32_16x16x32_bf16 v[16:19], v[232:235], v[208:211], v[16:19]
	v_mfma_f32_16x16x32_bf16 v[4:7], v[224:227], v[216:219], v[4:7]
	v_mfma_f32_16x16x32_bf16 v[0:3], v[232:235], v[216:219], v[0:3]
	s_setprio 0
	s_add_i32 s68, s68, 2
	s_add_u32 s66, s66, 0x100
	s_addc_u32 s67, s67, 0
	s_add_u32 s22, s22, 0x100
	s_addc_u32 s23, s23, 0
	s_cmp_gt_u32 s68, 13
	s_barrier
	s_cbranch_scc0 .LBB0_1564
	v_lshl_add_u32 v148, s21, 10, v155
	ds_read2_b32 v[172:173], v148 offset1:16
	s_ashr_i32 s21, s20, 31
	s_lshl_b64 s[20:21], s[20:21], 8
	ds_read2_b32 v[152:153], v148 offset0:32 offset1:48
	ds_read2_b32 v[150:151], v148 offset0:128 offset1:144
	ds_read2_b32 v[148:149], v148 offset0:160 offset1:176
	s_mov_b64 s[22:23], s[18:19]
	s_waitcnt lgkmcnt(0)
	v_mul_f32_e32 v120, v120, v172
	v_mul_f32_e32 v124, v124, v172
	v_mul_f32_e32 v175, 0xbfb8aa3b, v120
	v_mul_f32_e32 v174, 0xbfb8aa3b, v124
	v_exp_f32_e32 v175, v175
	v_exp_f32_e32 v174, v174
	v_mul_f32_e32 v112, v112, v172
	v_mul_f32_e32 v116, v116, v172
	v_add_f32_e32 v175, 1.0, v175
	v_add_f32_e32 v174, 1.0, v174
	v_rcp_f32_e32 v175, v175
	v_rcp_f32_e32 v174, v174
	v_mul_f32_e32 v121, v121, v172
	v_mul_f32_e32 v117, v117, v172
	v_mul_f32_e32 v120, v120, v175
	v_mul_f32_e32 v124, v124, v174
	v_mul_f32_e32 v120, v112, v120
	v_mul_f32_e32 v112, v125, v172
	v_mul_f32_e32 v116, v116, v124
	v_mul_f32_e32 v124, 0xbfb8aa3b, v112
	v_exp_f32_e32 v124, v124
	v_mul_f32_e32 v125, 0xbfb8aa3b, v121
	v_exp_f32_e32 v125, v125
	v_mul_f32_e32 v113, v113, v172
	v_add_f32_e32 v124, 1.0, v124
	v_rcp_f32_e32 v124, v124
	v_add_f32_e32 v125, 1.0, v125
	v_rcp_f32_e32 v125, v125
	v_mul_f32_e32 v118, v118, v172
	v_mul_f32_e32 v112, v112, v124
	v_mul_f32_e32 v117, v117, v112
	v_mul_f32_e32 v112, v121, v125
	v_mul_f32_e32 v121, v113, v112
	v_mul_f32_e32 v112, v126, v172
	v_mul_f32_e32 v113, v122, v172
	v_mul_f32_e32 v122, 0xbfb8aa3b, v112
	v_exp_f32_e32 v122, v122
	v_mul_f32_e32 v124, 0xbfb8aa3b, v113
	v_exp_f32_e32 v124, v124
	v_mul_f32_e32 v114, v114, v172
	v_add_f32_e32 v122, 1.0, v122
	v_rcp_f32_e32 v122, v122
	v_add_f32_e32 v124, 1.0, v124
	v_rcp_f32_e32 v124, v124
	v_mul_f32_e32 v119, v119, v172
	v_mul_f32_e32 v112, v112, v122
	v_mul_f32_e32 v118, v118, v112
	v_mul_f32_e32 v112, v113, v124
	v_mul_f32_e32 v122, v114, v112
	v_mul_f32_e32 v112, v127, v172
	v_mul_f32_e32 v113, v123, v172
	v_mul_f32_e32 v114, 0xbfb8aa3b, v112
	v_exp_f32_e32 v114, v114
	v_mul_f32_e32 v123, 0xbfb8aa3b, v113
	v_exp_f32_e32 v123, v123
	v_mul_f32_e32 v115, v115, v172
	v_add_f32_e32 v114, 1.0, v114
	v_rcp_f32_e32 v114, v114
	v_add_f32_e32 v123, 1.0, v123
	v_rcp_f32_e32 v123, v123
	v_mul_f32_e32 v104, v104, v173
	v_mul_f32_e32 v112, v112, v114
	v_mul_f32_e32 v119, v119, v112
	v_mul_f32_e32 v112, v113, v123
	v_mul_f32_e32 v123, v115, v112
	v_lshl_add_u64 v[112:113], s[20:21], 0, v[138:139]
	v_cvt_pk_bf16_f32 v115, v118, v119
	v_mov_b64_e32 v[118:119], s[8:9]
	v_mad_u64_u32 v[118:119], s[20:21], v112, s56, v[118:119]
	s_lshl_b32 s20, s63, 7
	v_mad_i32_i24 v119, v113, s56, v119
	s_ashr_i32 s21, s20, 31
	v_lshl_add_u64 v[112:113], s[20:21], 1, v[118:119]
	v_lshl_add_u64 v[112:113], v[112:113], 0, s[4:5]
	v_lshl_add_u64 v[112:113], v[112:113], 0, v[136:137]
	v_cvt_pk_bf16_f32 v114, v116, v117
	v_cvt_pk_bf16_f32 v116, v120, v121
	v_cvt_pk_bf16_f32 v117, v122, v123
	s_waitcnt vmcnt(0)
	global_store_dwordx4 v[112:113], v[114:117], off
	v_mul_f32_e32 v108, v108, v173
	v_mul_f32_e32 v96, v96, v173
	v_mul_f32_e32 v115, 0xbfb8aa3b, v104
	v_mul_f32_e32 v114, 0xbfb8aa3b, v108
	v_exp_f32_e32 v115, v115
	v_exp_f32_e32 v114, v114
	v_mul_f32_e32 v100, v100, v173
	v_mul_f32_e32 v105, v105, v173
	v_add_f32_e32 v115, 1.0, v115
	v_add_f32_e32 v114, 1.0, v114
	v_rcp_f32_e32 v115, v115
	v_rcp_f32_e32 v114, v114
	v_mul_f32_e32 v101, v101, v173
	v_mul_f32_e32 v97, v97, v173
	v_mul_f32_e32 v104, v104, v115
	v_mul_f32_e32 v108, v108, v114
	v_mul_f32_e32 v104, v96, v104
	v_mul_f32_e32 v96, v109, v173
	v_mul_f32_e32 v100, v100, v108
	v_mul_f32_e32 v108, 0xbfb8aa3b, v96
	v_exp_f32_e32 v108, v108
	v_mul_f32_e32 v109, 0xbfb8aa3b, v105
	v_exp_f32_e32 v109, v109
	v_mul_f32_e32 v102, v102, v173
	v_add_f32_e32 v108, 1.0, v108
	v_rcp_f32_e32 v108, v108
	v_add_f32_e32 v109, 1.0, v109
	v_rcp_f32_e32 v109, v109
	v_mul_f32_e32 v98, v98, v173
	v_mul_f32_e32 v96, v96, v108
	v_mul_f32_e32 v96, v101, v96
	v_mul_f32_e32 v101, v105, v109
	v_mul_f32_e32 v101, v97, v101
	v_mul_f32_e32 v97, v110, v173
	v_mul_f32_e32 v105, v106, v173
	v_mul_f32_e32 v106, 0xbfb8aa3b, v97
	v_exp_f32_e32 v106, v106
	v_mul_f32_e32 v108, 0xbfb8aa3b, v105
	v_exp_f32_e32 v108, v108
	v_mul_f32_e32 v103, v103, v173
	v_add_f32_e32 v106, 1.0, v106
	v_rcp_f32_e32 v106, v106
	v_add_f32_e32 v108, 1.0, v108
	v_rcp_f32_e32 v108, v108
	v_mul_f32_e32 v99, v99, v173
	v_mul_f32_e32 v97, v97, v106
	v_mul_f32_e32 v97, v102, v97
	v_mul_f32_e32 v102, v105, v108
	v_mul_f32_e32 v102, v98, v102
	v_mul_f32_e32 v98, v111, v173
	v_mul_f32_e32 v105, v107, v173
	v_mul_f32_e32 v106, 0xbfb8aa3b, v98
	v_exp_f32_e32 v106, v106
	v_mul_f32_e32 v107, 0xbfb8aa3b, v105
	v_exp_f32_e32 v107, v107
	v_cvt_pk_bf16_f32 v96, v100, v96
	v_add_f32_e32 v106, 1.0, v106
	v_rcp_f32_e32 v106, v106
	v_add_f32_e32 v107, 1.0, v107
	v_rcp_f32_e32 v107, v107
	v_add_co_u32_e32 v100, vcc, s45, v112
	v_mul_f32_e32 v98, v98, v106
	v_mul_f32_e32 v98, v103, v98
	v_mul_f32_e32 v103, v105, v107
	v_mul_f32_e32 v99, v99, v103
	v_cvt_pk_bf16_f32 v97, v97, v98
	v_cvt_pk_bf16_f32 v98, v104, v101
	v_addc_co_u32_e32 v101, vcc, 0, v113, vcc
	v_mul_f32_e32 v88, v88, v152
	v_cvt_pk_bf16_f32 v99, v102, v99
	global_store_dwordx4 v[100:101], v[96:99], off
	v_mul_f32_e32 v92, v92, v152
	v_mul_f32_e32 v80, v80, v152
	v_mul_f32_e32 v97, 0xbfb8aa3b, v88
	v_mul_f32_e32 v96, 0xbfb8aa3b, v92
	v_exp_f32_e32 v97, v97
	v_exp_f32_e32 v96, v96
	v_mul_f32_e32 v84, v84, v152
	v_mul_f32_e32 v89, v89, v152
	v_add_f32_e32 v97, 1.0, v97
	v_add_f32_e32 v96, 1.0, v96
	v_rcp_f32_e32 v97, v97
	v_rcp_f32_e32 v96, v96
	v_mul_f32_e32 v85, v85, v152
	v_mul_f32_e32 v81, v81, v152
	v_mul_f32_e32 v88, v88, v97
	v_mul_f32_e32 v92, v92, v96
	v_mul_f32_e32 v88, v80, v88
	v_mul_f32_e32 v80, v93, v152
	v_mul_f32_e32 v84, v84, v92
	v_mul_f32_e32 v92, 0xbfb8aa3b, v80
	v_exp_f32_e32 v92, v92
	v_mul_f32_e32 v93, 0xbfb8aa3b, v89
	v_exp_f32_e32 v93, v93
	v_mul_f32_e32 v86, v86, v152
	v_add_f32_e32 v92, 1.0, v92
	v_rcp_f32_e32 v92, v92
	v_add_f32_e32 v93, 1.0, v93
	v_rcp_f32_e32 v93, v93
	v_mul_f32_e32 v82, v82, v152
	v_mul_f32_e32 v80, v80, v92
	v_mul_f32_e32 v80, v85, v80
	v_mul_f32_e32 v85, v89, v93
	v_mul_f32_e32 v85, v81, v85
	v_mul_f32_e32 v81, v94, v152
	v_mul_f32_e32 v89, v90, v152
	v_mul_f32_e32 v90, 0xbfb8aa3b, v81
	v_exp_f32_e32 v90, v90
	v_mul_f32_e32 v92, 0xbfb8aa3b, v89
	v_exp_f32_e32 v92, v92
	v_mul_f32_e32 v87, v87, v152
	v_add_f32_e32 v90, 1.0, v90
	v_rcp_f32_e32 v90, v90
	v_add_f32_e32 v92, 1.0, v92
	v_rcp_f32_e32 v92, v92
	v_mul_f32_e32 v83, v83, v152
	v_mul_f32_e32 v81, v81, v90
	v_mul_f32_e32 v81, v86, v81
	v_mul_f32_e32 v86, v89, v92
	v_mul_f32_e32 v86, v82, v86
	v_mul_f32_e32 v82, v95, v152
	v_mul_f32_e32 v89, v91, v152
	v_mul_f32_e32 v90, 0xbfb8aa3b, v82
	v_exp_f32_e32 v90, v90
	v_mul_f32_e32 v91, 0xbfb8aa3b, v89
	v_exp_f32_e32 v91, v91
	v_cvt_pk_bf16_f32 v80, v84, v80
	v_add_f32_e32 v90, 1.0, v90
	v_rcp_f32_e32 v90, v90
	v_add_f32_e32 v91, 1.0, v91
	v_rcp_f32_e32 v91, v91
	v_add_co_u32_e32 v84, vcc, s57, v112
	v_mul_f32_e32 v82, v82, v90
	v_mul_f32_e32 v82, v87, v82
	v_mul_f32_e32 v87, v89, v91
	v_mul_f32_e32 v83, v83, v87
	v_cvt_pk_bf16_f32 v81, v81, v82
	v_cvt_pk_bf16_f32 v82, v88, v85
	v_addc_co_u32_e32 v85, vcc, 0, v113, vcc
	v_mul_f32_e32 v72, v72, v153
	v_cvt_pk_bf16_f32 v83, v86, v83
	global_store_dwordx4 v[84:85], v[80:83], off
	v_mul_f32_e32 v76, v76, v153
	v_mul_f32_e32 v64, v64, v153
	v_mul_f32_e32 v81, 0xbfb8aa3b, v72
	v_mul_f32_e32 v80, 0xbfb8aa3b, v76
	v_exp_f32_e32 v81, v81
	v_exp_f32_e32 v80, v80
	v_mul_f32_e32 v68, v68, v153
	v_mul_f32_e32 v73, v73, v153
	v_add_f32_e32 v81, 1.0, v81
	v_add_f32_e32 v80, 1.0, v80
	v_rcp_f32_e32 v81, v81
	v_rcp_f32_e32 v80, v80
	v_mul_f32_e32 v69, v69, v153
	v_mul_f32_e32 v65, v65, v153
	v_mul_f32_e32 v72, v72, v81
	v_mul_f32_e32 v76, v76, v80
	v_mul_f32_e32 v72, v64, v72
	v_mul_f32_e32 v64, v77, v153
	v_mul_f32_e32 v68, v68, v76
	v_mul_f32_e32 v76, 0xbfb8aa3b, v64
	v_exp_f32_e32 v76, v76
	v_mul_f32_e32 v77, 0xbfb8aa3b, v73
	v_exp_f32_e32 v77, v77
	v_mul_f32_e32 v70, v70, v153
	v_add_f32_e32 v76, 1.0, v76
	v_rcp_f32_e32 v76, v76
	v_add_f32_e32 v77, 1.0, v77
	v_rcp_f32_e32 v77, v77
	v_mul_f32_e32 v66, v66, v153
	v_mul_f32_e32 v64, v64, v76
	v_mul_f32_e32 v64, v69, v64
	v_mul_f32_e32 v69, v73, v77
	v_mul_f32_e32 v69, v65, v69
	v_mul_f32_e32 v65, v78, v153
	v_mul_f32_e32 v73, v74, v153
	v_mul_f32_e32 v74, 0xbfb8aa3b, v65
	v_exp_f32_e32 v74, v74
	v_mul_f32_e32 v76, 0xbfb8aa3b, v73
	v_exp_f32_e32 v76, v76
	v_mul_f32_e32 v71, v71, v153
	v_add_f32_e32 v74, 1.0, v74
	v_rcp_f32_e32 v74, v74
	v_add_f32_e32 v76, 1.0, v76
	v_rcp_f32_e32 v76, v76
	v_mul_f32_e32 v67, v67, v153
	v_mul_f32_e32 v65, v65, v74
	v_mul_f32_e32 v65, v70, v65
	v_mul_f32_e32 v70, v73, v76
	v_mul_f32_e32 v70, v66, v70
	v_mul_f32_e32 v66, v79, v153
	v_mul_f32_e32 v73, v75, v153
	v_mul_f32_e32 v74, 0xbfb8aa3b, v66
	v_exp_f32_e32 v74, v74
	v_mul_f32_e32 v75, 0xbfb8aa3b, v73
	v_exp_f32_e32 v75, v75
	v_cvt_pk_bf16_f32 v64, v68, v64
	v_add_f32_e32 v74, 1.0, v74
	v_rcp_f32_e32 v74, v74
	v_add_f32_e32 v75, 1.0, v75
	v_rcp_f32_e32 v75, v75
	v_add_co_u32_e32 v68, vcc, s58, v112
	v_mul_f32_e32 v66, v66, v74
	v_mul_f32_e32 v66, v71, v66
	v_mul_f32_e32 v71, v73, v75
	v_mul_f32_e32 v67, v67, v71
	v_cvt_pk_bf16_f32 v65, v65, v66
	v_cvt_pk_bf16_f32 v66, v72, v69
	v_addc_co_u32_e32 v69, vcc, 0, v113, vcc
	v_mul_f32_e32 v56, v56, v150
	v_cvt_pk_bf16_f32 v67, v70, v67
	global_store_dwordx4 v[68:69], v[64:67], off
	v_mul_f32_e32 v60, v60, v150
	v_mul_f32_e32 v48, v48, v150
	v_mul_f32_e32 v65, 0xbfb8aa3b, v56
	v_mul_f32_e32 v64, 0xbfb8aa3b, v60
	v_exp_f32_e32 v65, v65
	v_exp_f32_e32 v64, v64
	v_mul_f32_e32 v52, v52, v150
	v_mul_f32_e32 v57, v57, v150
	v_add_f32_e32 v65, 1.0, v65
	v_add_f32_e32 v64, 1.0, v64
	v_rcp_f32_e32 v65, v65
	v_rcp_f32_e32 v64, v64
	v_mul_f32_e32 v53, v53, v150
	v_mul_f32_e32 v49, v49, v150
	v_mul_f32_e32 v56, v56, v65
	v_mul_f32_e32 v60, v60, v64
	v_mul_f32_e32 v56, v48, v56
	v_mul_f32_e32 v48, v61, v150
	v_mul_f32_e32 v52, v52, v60
	v_mul_f32_e32 v60, 0xbfb8aa3b, v48
	v_exp_f32_e32 v60, v60
	v_mul_f32_e32 v61, 0xbfb8aa3b, v57
	v_exp_f32_e32 v61, v61
	v_mul_f32_e32 v54, v54, v150
	v_add_f32_e32 v60, 1.0, v60
	v_rcp_f32_e32 v60, v60
	v_add_f32_e32 v61, 1.0, v61
	v_rcp_f32_e32 v61, v61
	v_mul_f32_e32 v50, v50, v150
	v_mul_f32_e32 v48, v48, v60
	v_mul_f32_e32 v48, v53, v48
	v_mul_f32_e32 v53, v57, v61
	v_mul_f32_e32 v53, v49, v53
	v_mul_f32_e32 v49, v62, v150
	v_mul_f32_e32 v57, v58, v150
	v_mul_f32_e32 v58, 0xbfb8aa3b, v49
	v_exp_f32_e32 v58, v58
	v_mul_f32_e32 v60, 0xbfb8aa3b, v57
	v_exp_f32_e32 v60, v60
	v_mul_f32_e32 v55, v55, v150
	v_add_f32_e32 v58, 1.0, v58
	v_rcp_f32_e32 v58, v58
	v_add_f32_e32 v60, 1.0, v60
	v_rcp_f32_e32 v60, v60
	v_mul_f32_e32 v51, v51, v150
	v_mul_f32_e32 v49, v49, v58
	v_mul_f32_e32 v49, v54, v49
	v_mul_f32_e32 v54, v57, v60
	v_mul_f32_e32 v54, v50, v54
	v_mul_f32_e32 v50, v63, v150
	v_mul_f32_e32 v57, v59, v150
	v_mul_f32_e32 v58, 0xbfb8aa3b, v50
	v_exp_f32_e32 v58, v58
	v_mul_f32_e32 v59, 0xbfb8aa3b, v57
	v_exp_f32_e32 v59, v59
	v_cvt_pk_bf16_f32 v48, v52, v48
	v_add_f32_e32 v58, 1.0, v58
	v_rcp_f32_e32 v58, v58
	v_add_f32_e32 v59, 1.0, v59
	v_rcp_f32_e32 v59, v59
	v_add_co_u32_e32 v52, vcc, s59, v112
	v_mul_f32_e32 v50, v50, v58
	v_mul_f32_e32 v50, v55, v50
	v_mul_f32_e32 v55, v57, v59
	v_mul_f32_e32 v51, v51, v55
	v_cvt_pk_bf16_f32 v49, v49, v50
	v_cvt_pk_bf16_f32 v50, v56, v53
	v_addc_co_u32_e32 v53, vcc, 0, v113, vcc
	v_mul_f32_e32 v40, v40, v151
	v_cvt_pk_bf16_f32 v51, v54, v51
	global_store_dwordx4 v[52:53], v[48:51], off
	v_mul_f32_e32 v44, v44, v151
	v_mul_f32_e32 v32, v32, v151
	v_mul_f32_e32 v49, 0xbfb8aa3b, v40
	v_mul_f32_e32 v48, 0xbfb8aa3b, v44
	v_exp_f32_e32 v49, v49
	v_exp_f32_e32 v48, v48
	v_mul_f32_e32 v36, v36, v151
	v_mul_f32_e32 v41, v41, v151
	v_add_f32_e32 v49, 1.0, v49
	v_add_f32_e32 v48, 1.0, v48
	v_rcp_f32_e32 v49, v49
	v_rcp_f32_e32 v48, v48
	v_mul_f32_e32 v37, v37, v151
	v_mul_f32_e32 v33, v33, v151
	v_mul_f32_e32 v40, v40, v49
	v_mul_f32_e32 v44, v44, v48
	v_mul_f32_e32 v40, v32, v40
	v_mul_f32_e32 v32, v45, v151
	v_mul_f32_e32 v36, v36, v44
	v_mul_f32_e32 v44, 0xbfb8aa3b, v32
	v_exp_f32_e32 v44, v44
	v_mul_f32_e32 v45, 0xbfb8aa3b, v41
	v_exp_f32_e32 v45, v45
	v_mul_f32_e32 v38, v38, v151
	v_add_f32_e32 v44, 1.0, v44
	v_rcp_f32_e32 v44, v44
	v_add_f32_e32 v45, 1.0, v45
	v_rcp_f32_e32 v45, v45
	v_mul_f32_e32 v34, v34, v151
	v_mul_f32_e32 v32, v32, v44
	v_mul_f32_e32 v32, v37, v32
	v_mul_f32_e32 v37, v41, v45
	v_mul_f32_e32 v37, v33, v37
	v_mul_f32_e32 v33, v46, v151
	v_mul_f32_e32 v41, v42, v151
	v_mul_f32_e32 v42, 0xbfb8aa3b, v33
	v_exp_f32_e32 v42, v42
	v_mul_f32_e32 v44, 0xbfb8aa3b, v41
	v_exp_f32_e32 v44, v44
	v_mul_f32_e32 v39, v39, v151
	v_add_f32_e32 v42, 1.0, v42
	v_rcp_f32_e32 v42, v42
	v_add_f32_e32 v44, 1.0, v44
	v_rcp_f32_e32 v44, v44
	v_mul_f32_e32 v35, v35, v151
	v_mul_f32_e32 v33, v33, v42
	v_mul_f32_e32 v33, v38, v33
	v_mul_f32_e32 v38, v41, v44
	v_mul_f32_e32 v38, v34, v38
	v_mul_f32_e32 v34, v47, v151
	v_mul_f32_e32 v41, v43, v151
	v_mul_f32_e32 v42, 0xbfb8aa3b, v34
	v_exp_f32_e32 v42, v42
	v_mul_f32_e32 v43, 0xbfb8aa3b, v41
	v_exp_f32_e32 v43, v43
	v_cvt_pk_bf16_f32 v32, v36, v32
	v_add_f32_e32 v42, 1.0, v42
	v_rcp_f32_e32 v42, v42
	v_add_f32_e32 v43, 1.0, v43
	v_rcp_f32_e32 v43, v43
	v_add_co_u32_e32 v36, vcc, s60, v112
	v_mul_f32_e32 v34, v34, v42
	v_mul_f32_e32 v34, v39, v34
	v_mul_f32_e32 v39, v41, v43
	v_mul_f32_e32 v35, v35, v39
	v_cvt_pk_bf16_f32 v33, v33, v34
	v_cvt_pk_bf16_f32 v34, v40, v37
	v_addc_co_u32_e32 v37, vcc, 0, v113, vcc
	v_mul_f32_e32 v24, v24, v148
	v_cvt_pk_bf16_f32 v35, v38, v35
	global_store_dwordx4 v[36:37], v[32:35], off
	v_mul_f32_e32 v28, v28, v148
	v_mul_f32_e32 v16, v16, v148
	v_mul_f32_e32 v33, 0xbfb8aa3b, v24
	v_mul_f32_e32 v32, 0xbfb8aa3b, v28
	v_exp_f32_e32 v33, v33
	v_exp_f32_e32 v32, v32
	v_mul_f32_e32 v20, v20, v148
	v_mul_f32_e32 v25, v25, v148
	v_add_f32_e32 v33, 1.0, v33
	v_add_f32_e32 v32, 1.0, v32
	v_rcp_f32_e32 v33, v33
	v_rcp_f32_e32 v32, v32
	v_mul_f32_e32 v21, v21, v148
	v_mul_f32_e32 v17, v17, v148
	v_mul_f32_e32 v24, v24, v33
	v_mul_f32_e32 v28, v28, v32
	v_mul_f32_e32 v24, v16, v24
	v_mul_f32_e32 v16, v29, v148
	v_mul_f32_e32 v20, v20, v28
	v_mul_f32_e32 v28, 0xbfb8aa3b, v16
	v_exp_f32_e32 v28, v28
	v_mul_f32_e32 v29, 0xbfb8aa3b, v25
	v_exp_f32_e32 v29, v29
	v_mul_f32_e32 v22, v22, v148
	v_add_f32_e32 v28, 1.0, v28
	v_rcp_f32_e32 v28, v28
	v_add_f32_e32 v29, 1.0, v29
	v_rcp_f32_e32 v29, v29
	v_mul_f32_e32 v18, v18, v148
	v_mul_f32_e32 v16, v16, v28
	v_mul_f32_e32 v16, v21, v16
	v_mul_f32_e32 v21, v25, v29
	v_mul_f32_e32 v21, v17, v21
	v_mul_f32_e32 v17, v30, v148
	v_mul_f32_e32 v25, v26, v148
	v_mul_f32_e32 v26, 0xbfb8aa3b, v17
	v_exp_f32_e32 v26, v26
	v_mul_f32_e32 v28, 0xbfb8aa3b, v25
	v_exp_f32_e32 v28, v28
	v_mul_f32_e32 v23, v23, v148
	v_add_f32_e32 v26, 1.0, v26
	v_rcp_f32_e32 v26, v26
	v_add_f32_e32 v28, 1.0, v28
	v_rcp_f32_e32 v28, v28
	v_mul_f32_e32 v19, v19, v148
	v_mul_f32_e32 v17, v17, v26
	v_mul_f32_e32 v17, v22, v17
	v_mul_f32_e32 v22, v25, v28
	v_mul_f32_e32 v22, v18, v22
	v_mul_f32_e32 v18, v31, v148
	v_mul_f32_e32 v25, v27, v148
	v_mul_f32_e32 v26, 0xbfb8aa3b, v18
	v_exp_f32_e32 v26, v26
	v_mul_f32_e32 v27, 0xbfb8aa3b, v25
	v_exp_f32_e32 v27, v27
	v_cvt_pk_bf16_f32 v16, v20, v16
	v_add_f32_e32 v26, 1.0, v26
	v_rcp_f32_e32 v26, v26
	v_add_f32_e32 v27, 1.0, v27
	v_rcp_f32_e32 v27, v27
	v_add_co_u32_e32 v20, vcc, s61, v112
	v_mul_f32_e32 v18, v18, v26
	v_mul_f32_e32 v18, v23, v18
	v_mul_f32_e32 v23, v25, v27
	v_mul_f32_e32 v19, v19, v23
	v_cvt_pk_bf16_f32 v17, v17, v18
	v_cvt_pk_bf16_f32 v18, v24, v21
	v_addc_co_u32_e32 v21, vcc, 0, v113, vcc
	v_mul_f32_e32 v8, v8, v149
	v_cvt_pk_bf16_f32 v19, v22, v19
	global_store_dwordx4 v[20:21], v[16:19], off
	v_mul_f32_e32 v12, v12, v149
	v_mul_f32_e32 v0, v0, v149
	v_mul_f32_e32 v17, 0xbfb8aa3b, v8
	v_mul_f32_e32 v16, 0xbfb8aa3b, v12
	v_exp_f32_e32 v17, v17
	v_exp_f32_e32 v16, v16
	v_mul_f32_e32 v4, v4, v149
	v_mul_f32_e32 v9, v9, v149
	v_add_f32_e32 v17, 1.0, v17
	v_add_f32_e32 v16, 1.0, v16
	v_rcp_f32_e32 v17, v17
	v_rcp_f32_e32 v16, v16
	v_mul_f32_e32 v5, v5, v149
	v_mul_f32_e32 v1, v1, v149
	v_mul_f32_e32 v8, v8, v17
	v_mul_f32_e32 v12, v12, v16
	v_mul_f32_e32 v8, v0, v8
	v_mul_f32_e32 v0, v13, v149
	v_mul_f32_e32 v4, v4, v12
	v_mul_f32_e32 v12, 0xbfb8aa3b, v0
	v_exp_f32_e32 v12, v12
	v_mul_f32_e32 v13, 0xbfb8aa3b, v9
	v_exp_f32_e32 v13, v13
	v_mul_f32_e32 v6, v6, v149
	v_add_f32_e32 v12, 1.0, v12
	v_rcp_f32_e32 v12, v12
	v_add_f32_e32 v13, 1.0, v13
	v_rcp_f32_e32 v13, v13
	v_mul_f32_e32 v2, v2, v149
	v_mul_f32_e32 v0, v0, v12
	v_mul_f32_e32 v0, v5, v0
	v_mul_f32_e32 v5, v9, v13
	v_mul_f32_e32 v5, v1, v5
	v_mul_f32_e32 v1, v14, v149
	v_mul_f32_e32 v9, v10, v149
	v_mul_f32_e32 v10, 0xbfb8aa3b, v1
	v_exp_f32_e32 v10, v10
	v_mul_f32_e32 v12, 0xbfb8aa3b, v9
	v_exp_f32_e32 v12, v12
	v_mul_f32_e32 v7, v7, v149
	v_add_f32_e32 v10, 1.0, v10
	v_rcp_f32_e32 v10, v10
	v_add_f32_e32 v12, 1.0, v12
	v_rcp_f32_e32 v12, v12
	v_cvt_pk_bf16_f32 v0, v4, v0
	v_mul_f32_e32 v1, v1, v10
	v_mul_f32_e32 v1, v6, v1
	v_mul_f32_e32 v6, v9, v12
	v_mul_f32_e32 v6, v2, v6
	v_mul_f32_e32 v2, v15, v149
	v_mul_f32_e32 v10, 0xbfb8aa3b, v2
	v_mul_f32_e32 v9, v11, v149
	v_exp_f32_e32 v10, v10
	v_mul_f32_e32 v11, 0xbfb8aa3b, v9
	v_exp_f32_e32 v11, v11
	v_add_co_u32_e32 v4, vcc, 0xf2000, v112
	v_add_f32_e32 v10, 1.0, v10
	v_rcp_f32_e32 v10, v10
	v_add_f32_e32 v11, 1.0, v11
	v_rcp_f32_e32 v11, v11
	v_mul_f32_e32 v3, v3, v149
	v_mul_f32_e32 v2, v2, v10
	v_mul_f32_e32 v2, v7, v2
	v_mul_f32_e32 v7, v9, v11
	v_cvt_pk_bf16_f32 v1, v1, v2
	v_cvt_pk_bf16_f32 v2, v8, v5
	v_addc_co_u32_e32 v5, vcc, 0, v113, vcc
	v_mul_f32_e32 v3, v3, v7
	s_and_b64 vcc, exec, s[6:7]
	s_mov_b32 s20, s14
	s_mov_b32 s63, s12
	s_mov_b64 s[24:25], s[16:17]
	s_mov_b32 s21, s62
	v_cvt_pk_bf16_f32 v3, v6, v3
	global_store_dwordx4 v[4:5], v[0:3], off
	s_cbranch_vccz .LBB0_1561
	s_waitcnt vmcnt(0)
	s_cmpk_gt_u32 s28, 0xff
	s_cbranch_scc1 .LBB0_1568
	s_barrier

.LBB0_1716:
	v_cmp_gt_i64_e32 vcc, s[8:9], v[4:5]
	s_mov_b64 s[10:11], -1
	s_cbranch_vccnz .LBB0_1715
	s_mov_b64 s[10:11], exec
	s_cbranch_execz .LBB0_1714
	s_ashr_i32 s14, s8, 31
	s_lshr_b32 s14, s14, 29
	s_add_i32 s14, s8, s14
	s_ashr_i32 s15, s14, 3
	s_and_b32 s14, s14, -8
	s_sub_i32 s14, s8, s14
	s_cmp_lt_i32 s14, 0
	s_cselect_b32 s16, s12, 0x1c0
	s_mul_i32 s14, s16, s14
	s_add_i32 s14, s14, s15
	s_mul_hi_i32 s15, s14, 0x92492493
	s_add_i32 s15, s15, s14
	s_lshr_b32 s16, s15, 31
	s_ashr_i32 s15, s15, 7
	s_add_i32 s15, s15, s16
	s_lshl_b32 s16, s15, 3
	s_sub_i32 s17, 0x80, s16
	s_min_i32 s17, s17, 8
	s_abs_i32 s17, s17
	v_cvt_f32_u32_e32 v7, s17
	s_sub_i32 s18, 0, s17
	s_mulk_i32 s15, 0xe0
	s_sub_i32 s14, s14, s15
	v_rcp_iflag_f32_e32 v7, v7
	s_ashr_i32 s15, s14, 31
	s_abs_i32 s14, s14
	v_mul_f32_e32 v7, 0x4f7ffffe, v7
	v_cvt_u32_f32_e32 v7, v7
	s_nop 0
	v_readfirstlane_b32 s19, v7
	s_mul_i32 s18, s18, s19
	s_mul_hi_u32 s18, s19, s18
	s_add_i32 s19, s19, s18
	s_mul_hi_u32 s18, s14, s19
	s_mul_i32 s18, s18, s17
	s_sub_i32 s14, s14, s18
	s_sub_i32 s18, s14, s17
	s_cmp_ge_u32 s14, s17
	s_cselect_b32 s14, s18, s14
	s_sub_i32 s18, s14, s17
	s_cmp_ge_u32 s14, s17
	s_cselect_b32 s14, s18, s14
	s_xor_b32 s14, s14, s15
	s_sub_i32 s14, s14, s15
	s_add_i32 s14, s14, s16
	s_ashr_i32 s15, s14, 31
	s_lshl_b64 s[14:15], s[14:15], 14
	v_lshl_add_u64 v[8:9], v[2:3], 0, s[14:15]
	s_waitcnt vmcnt(0)
	global_load_dwordx4 v[12:15], v[8:9], off
	global_load_dwordx4 v[16:19], v[8:9], off offset:16
	global_load_dwordx4 v[20:23], v[8:9], off offset:32
	global_load_dwordx4 v[24:27], v[8:9], off offset:48
	s_waitcnt vmcnt(0) lgkmcnt(0)
	v_mov_b32_e32 v8, v13
	v_mov_b32_e32 v9, v14
	v_mov_b32_e32 v28, v17
	v_mov_b32_e32 v29, v18
	v_mov_b32_e32 v13, v15
	v_mov_b32_e32 v17, v19
	v_mov_b32_e32 v14, v21
	v_mov_b32_e32 v18, v23
	v_pk_add_f32 v[8:9], v[8:9], v[12:13]
	v_pk_add_f32 v[12:13], v[28:29], v[16:17]
	v_pk_add_f32 v[14:15], v[20:21], v[14:15]
	v_pk_add_f32 v[16:17], v[22:23], v[18:19]
	v_pk_add_f32 v[8:9], v[8:9], v[8:9] op_sel:[0,1] op_sel_hi:[1,0]
	v_pk_add_f32 v[12:13], v[12:13], v[12:13] op_sel:[0,1] op_sel_hi:[1,0]
	v_mov_b32_e32 v15, v26
	v_mov_b32_e32 v17, v27
	v_mov_b32_e32 v9, v24
	v_mov_b32_e32 v13, v25
	v_pk_add_f32 v[14:15], v[14:15], v[16:17]
	v_pk_add_f32 v[8:9], v[8:9], v[12:13]
	s_nop 0
	v_pk_add_f32 v[8:9], v[8:9], v[14:15]
	s_nop 0
	v_add_f32_e32 v7, v8, v9
	v_fmamk_f32 v7, v7, 0x3a800000, v6
	v_mul_f32_e32 v8, 0x4b800000, v7
	v_cmp_gt_f32_e32 vcc, s13, v7
	s_nop 1
	v_cndmask_b32_e32 v7, v7, v8, vcc
	v_rsq_f32_e32 v7, v7
	s_nop 0
	v_mul_f32_e32 v8, 0x45800000, v7
	v_cndmask_b32_e32 v7, v7, v8, vcc
	ds_write_b32 v1, v7
	s_branch .LBB0_1714

.LBB0_1727:
	ds_read_b128 v[128:131], v178
	ds_read_b128 v[132:135], v180
	ds_read_b128 v[136:139], v181
	ds_read_b128 v[140:143], v182
	s_add_u32 s30, s28, 0xfffc0080
	s_addc_u32 s31, s29, -1
	s_cmp_eq_u32 s86, 12
	s_cselect_b32 s35, s21, s31
	s_cselect_b32 s34, s27, s30
	s_cselect_b32 s31, s19, s85
	s_cselect_b32 s30, s83, s84
	s_mov_b32 m0, s63
	v_lshl_add_u64 v[222:223], s[28:29], 0, v[162:163]
	ds_read_b128 v[168:171], v145
	ds_read_b128 v[172:175], v145 offset:1024
	ds_read_b128 v[198:201], v145 offset:2048
	ds_read_b128 v[202:205], v145 offset:3072
	ds_read_b128 v[206:209], v145 offset:4096
	ds_read_b128 v[210:213], v145 offset:5120
	ds_read_b128 v[214:217], v145 offset:6144
	ds_read_b128 v[218:221], v145 offset:7168
	global_load_lds_dwordx4 v[222:223], off
	v_lshl_add_u64 v[222:223], s[28:29], 0, v[160:161]
	s_mov_b32 m0, s64
	s_nop 0
	global_load_lds_dwordx4 v[222:223], off
	s_waitcnt lgkmcnt(8)
	s_barrier
	s_waitcnt lgkmcnt(0)
	s_setprio 1
	s_waitcnt lgkmcnt(0)
	v_mfma_f32_16x16x32_bf16 v[124:127], v[128:131], v[168:171], v[124:127]
	v_mfma_f32_16x16x32_bf16 v[120:123], v[136:139], v[168:171], v[120:123]
	v_mfma_f32_16x16x32_bf16 v[108:111], v[128:131], v[198:201], v[108:111]
	v_mfma_f32_16x16x32_bf16 v[104:107], v[136:139], v[198:201], v[104:107]
	v_mfma_f32_16x16x32_bf16 v[92:95], v[128:131], v[206:209], v[92:95]
	v_mfma_f32_16x16x32_bf16 v[88:91], v[136:139], v[206:209], v[88:91]
	v_mfma_f32_16x16x32_bf16 v[76:79], v[128:131], v[214:217], v[76:79]
	v_mfma_f32_16x16x32_bf16 v[72:75], v[136:139], v[214:217], v[72:75]
	v_mfma_f32_16x16x32_bf16 v[124:127], v[132:135], v[172:175], v[124:127]
	v_mfma_f32_16x16x32_bf16 v[120:123], v[140:143], v[172:175], v[120:123]
	v_mfma_f32_16x16x32_bf16 v[108:111], v[132:135], v[202:205], v[108:111]
	v_mfma_f32_16x16x32_bf16 v[104:107], v[140:143], v[202:205], v[104:107]
	v_mfma_f32_16x16x32_bf16 v[92:95], v[132:135], v[210:213], v[92:95]
	v_mfma_f32_16x16x32_bf16 v[88:91], v[140:143], v[210:213], v[88:91]
	v_mfma_f32_16x16x32_bf16 v[76:79], v[132:135], v[218:221], v[76:79]
	v_mfma_f32_16x16x32_bf16 v[72:75], v[140:143], v[218:221], v[72:75]
	s_setprio 0
	s_barrier
	s_mov_b32 m0, s44
	v_lshl_add_u64 v[238:239], s[30:31], 0, v[150:151]
	ds_read_b128 v[222:225], v183
	ds_read_b128 v[226:229], v184
	ds_read_b128 v[230:233], v185
	ds_read_b128 v[234:237], v186
	global_load_lds_dwordx4 v[238:239], off
	v_lshl_add_u64 v[240:241], s[30:31], 0, v[146:147]
	s_mov_b32 m0, s45
	s_nop 0
	global_load_lds_dwordx4 v[240:241], off
	s_barrier
	s_waitcnt lgkmcnt(0)
	s_setprio 1
	s_waitcnt lgkmcnt(0)
	v_mfma_f32_16x16x32_bf16 v[116:119], v[222:225], v[168:171], v[116:119]
	v_mfma_f32_16x16x32_bf16 v[112:115], v[230:233], v[168:171], v[112:115]
	v_mfma_f32_16x16x32_bf16 v[100:103], v[222:225], v[198:201], v[100:103]
	v_mfma_f32_16x16x32_bf16 v[96:99], v[230:233], v[198:201], v[96:99]
	v_mfma_f32_16x16x32_bf16 v[84:87], v[222:225], v[206:209], v[84:87]
	v_mfma_f32_16x16x32_bf16 v[80:83], v[230:233], v[206:209], v[80:83]
	v_mfma_f32_16x16x32_bf16 v[68:71], v[222:225], v[214:217], v[68:71]
	v_mfma_f32_16x16x32_bf16 v[64:67], v[230:233], v[214:217], v[64:67]
	v_mfma_f32_16x16x32_bf16 v[116:119], v[226:229], v[172:175], v[116:119]
	v_mfma_f32_16x16x32_bf16 v[112:115], v[234:237], v[172:175], v[112:115]
	v_mfma_f32_16x16x32_bf16 v[100:103], v[226:229], v[202:205], v[100:103]
	v_mfma_f32_16x16x32_bf16 v[96:99], v[234:237], v[202:205], v[96:99]
	v_mfma_f32_16x16x32_bf16 v[84:87], v[226:229], v[210:213], v[84:87]
	v_mfma_f32_16x16x32_bf16 v[80:83], v[234:237], v[210:213], v[80:83]
	v_mfma_f32_16x16x32_bf16 v[68:71], v[226:229], v[218:221], v[68:71]
	v_mfma_f32_16x16x32_bf16 v[64:67], v[234:237], v[218:221], v[64:67]
	s_setprio 0
	s_mov_b32 m0, s40
	v_lshl_add_u64 v[242:243], s[34:35], 0, v[152:153]
	s_barrier
	ds_read_b128 v[168:171], v145 offset:16384
	ds_read_b128 v[172:175], v145 offset:17408
	ds_read_b128 v[198:201], v145 offset:18432
	ds_read_b128 v[202:205], v145 offset:19456
	ds_read_b128 v[206:209], v145 offset:20480
	ds_read_b128 v[210:213], v145 offset:21504
	ds_read_b128 v[214:217], v145 offset:22528
	ds_read_b128 v[218:221], v145 offset:23552
	global_load_lds_dwordx4 v[242:243], off
	v_lshl_add_u64 v[244:245], s[34:35], 0, v[148:149]
	s_mov_b32 m0, s46
	s_nop 0
	global_load_lds_dwordx4 v[244:245], off
	s_barrier
	s_waitcnt lgkmcnt(0)
	s_setprio 1
	s_waitcnt lgkmcnt(0)
	v_mfma_f32_16x16x32_bf16 v[60:63], v[128:131], v[168:171], v[60:63]
	v_mfma_f32_16x16x32_bf16 v[56:59], v[136:139], v[168:171], v[56:59]
	v_mfma_f32_16x16x32_bf16 v[44:47], v[128:131], v[198:201], v[44:47]
	v_mfma_f32_16x16x32_bf16 v[40:43], v[136:139], v[198:201], v[40:43]
	v_mfma_f32_16x16x32_bf16 v[28:31], v[128:131], v[206:209], v[28:31]
	v_mfma_f32_16x16x32_bf16 v[24:27], v[136:139], v[206:209], v[24:27]
	v_mfma_f32_16x16x32_bf16 v[12:15], v[128:131], v[214:217], v[12:15]
	v_mfma_f32_16x16x32_bf16 v[8:11], v[136:139], v[214:217], v[8:11]
	v_mfma_f32_16x16x32_bf16 v[60:63], v[132:135], v[172:175], v[60:63]
	v_mfma_f32_16x16x32_bf16 v[56:59], v[140:143], v[172:175], v[56:59]
	v_mfma_f32_16x16x32_bf16 v[44:47], v[132:135], v[202:205], v[44:47]
	v_mfma_f32_16x16x32_bf16 v[40:43], v[140:143], v[202:205], v[40:43]
	v_mfma_f32_16x16x32_bf16 v[28:31], v[132:135], v[210:213], v[28:31]
	v_mfma_f32_16x16x32_bf16 v[24:27], v[140:143], v[210:213], v[24:27]
	v_mfma_f32_16x16x32_bf16 v[12:15], v[132:135], v[218:221], v[12:15]
	v_mfma_f32_16x16x32_bf16 v[8:11], v[140:143], v[218:221], v[8:11]
	s_setprio 0
	s_barrier
	s_add_u32 s88, s30, 0x40000
	s_addc_u32 s89, s31, 0
	s_mov_b32 m0, s47
	v_lshl_add_u64 v[128:129], s[88:89], 0, v[150:151]
	global_load_lds_dwordx4 v[128:129], off
	v_lshl_add_u64 v[128:129], s[88:89], 0, v[146:147]
	s_mov_b32 m0, s48
	s_nop 0
	global_load_lds_dwordx4 v[128:129], off
	s_waitcnt vmcnt(6)
	s_barrier
	s_setprio 1
	v_mfma_f32_16x16x32_bf16 v[52:55], v[222:225], v[168:171], v[52:55]
	v_mfma_f32_16x16x32_bf16 v[48:51], v[230:233], v[168:171], v[48:51]
	v_mfma_f32_16x16x32_bf16 v[36:39], v[222:225], v[198:201], v[36:39]
	v_mfma_f32_16x16x32_bf16 v[32:35], v[230:233], v[198:201], v[32:35]
	v_mfma_f32_16x16x32_bf16 v[20:23], v[222:225], v[206:209], v[20:23]
	v_mfma_f32_16x16x32_bf16 v[16:19], v[230:233], v[206:209], v[16:19]
	v_mfma_f32_16x16x32_bf16 v[4:7], v[222:225], v[214:217], v[4:7]
	v_mfma_f32_16x16x32_bf16 v[0:3], v[230:233], v[214:217], v[0:3]
	v_mfma_f32_16x16x32_bf16 v[52:55], v[226:229], v[172:175], v[52:55]
	v_mfma_f32_16x16x32_bf16 v[48:51], v[234:237], v[172:175], v[48:51]
	v_mfma_f32_16x16x32_bf16 v[36:39], v[226:229], v[202:205], v[36:39]
	v_mfma_f32_16x16x32_bf16 v[32:35], v[234:237], v[202:205], v[32:35]
	v_mfma_f32_16x16x32_bf16 v[20:23], v[226:229], v[210:213], v[20:23]
	v_mfma_f32_16x16x32_bf16 v[16:19], v[234:237], v[210:213], v[16:19]
	v_mfma_f32_16x16x32_bf16 v[4:7], v[226:229], v[218:221], v[4:7]
	v_mfma_f32_16x16x32_bf16 v[0:3], v[234:237], v[218:221], v[0:3]
	s_setprio 0
	s_barrier
	ds_read_b128 v[128:131], v187
	ds_read_b128 v[132:135], v188
	ds_read_b128 v[136:139], v189
	ds_read_b128 v[140:143], v190
	s_add_u32 s34, s34, 0x40000
	s_addc_u32 s35, s35, 0
	s_mov_b32 m0, s49
	v_lshl_add_u64 v[222:223], s[34:35], 0, v[152:153]
	ds_read_b128 v[168:171], v145 offset:32768
	ds_read_b128 v[172:175], v145 offset:33792
	ds_read_b128 v[198:201], v145 offset:34816
	ds_read_b128 v[202:205], v145 offset:35840
	ds_read_b128 v[206:209], v145 offset:36864
	ds_read_b128 v[210:213], v145 offset:37888
	ds_read_b128 v[214:217], v145 offset:38912
	ds_read_b128 v[218:221], v145 offset:39936
	global_load_lds_dwordx4 v[222:223], off
	v_lshl_add_u64 v[222:223], s[34:35], 0, v[148:149]
	s_mov_b32 m0, s52
	s_nop 0
	global_load_lds_dwordx4 v[222:223], off
	s_waitcnt lgkmcnt(8)
	s_barrier
	s_waitcnt lgkmcnt(0)
	s_setprio 1
	s_waitcnt lgkmcnt(0)
	v_mfma_f32_16x16x32_bf16 v[124:127], v[128:131], v[168:171], v[124:127]
	v_mfma_f32_16x16x32_bf16 v[120:123], v[136:139], v[168:171], v[120:123]
	v_mfma_f32_16x16x32_bf16 v[108:111], v[128:131], v[198:201], v[108:111]
	v_mfma_f32_16x16x32_bf16 v[104:107], v[136:139], v[198:201], v[104:107]
	v_mfma_f32_16x16x32_bf16 v[92:95], v[128:131], v[206:209], v[92:95]
	v_mfma_f32_16x16x32_bf16 v[88:91], v[136:139], v[206:209], v[88:91]
	v_mfma_f32_16x16x32_bf16 v[76:79], v[128:131], v[214:217], v[76:79]
	v_mfma_f32_16x16x32_bf16 v[72:75], v[136:139], v[214:217], v[72:75]
	v_mfma_f32_16x16x32_bf16 v[124:127], v[132:135], v[172:175], v[124:127]
	v_mfma_f32_16x16x32_bf16 v[120:123], v[140:143], v[172:175], v[120:123]
	v_mfma_f32_16x16x32_bf16 v[108:111], v[132:135], v[202:205], v[108:111]
	v_mfma_f32_16x16x32_bf16 v[104:107], v[140:143], v[202:205], v[104:107]
	v_mfma_f32_16x16x32_bf16 v[92:95], v[132:135], v[210:213], v[92:95]
	v_mfma_f32_16x16x32_bf16 v[88:91], v[140:143], v[210:213], v[88:91]
	v_mfma_f32_16x16x32_bf16 v[76:79], v[132:135], v[218:221], v[76:79]
	v_mfma_f32_16x16x32_bf16 v[72:75], v[140:143], v[218:221], v[72:75]
	s_setprio 0
	s_barrier
	s_mov_b32 m0, s56
	v_lshl_add_u64 v[238:239], v[238:239], 0, s[12:13]
	ds_read_b128 v[222:225], v191
	ds_read_b128 v[226:229], v192
	ds_read_b128 v[230:233], v193
	ds_read_b128 v[234:237], v194
	global_load_lds_dwordx4 v[238:239], off
	v_lshl_add_u64 v[238:239], v[240:241], 0, s[12:13]
	s_mov_b32 m0, s57
	s_nop 0
	global_load_lds_dwordx4 v[238:239], off
	s_barrier
	s_waitcnt lgkmcnt(0)
	s_setprio 1
	s_waitcnt lgkmcnt(0)
	v_mfma_f32_16x16x32_bf16 v[116:119], v[222:225], v[168:171], v[116:119]
	v_mfma_f32_16x16x32_bf16 v[112:115], v[230:233], v[168:171], v[112:115]
	v_mfma_f32_16x16x32_bf16 v[100:103], v[222:225], v[198:201], v[100:103]
	v_mfma_f32_16x16x32_bf16 v[96:99], v[230:233], v[198:201], v[96:99]
	v_mfma_f32_16x16x32_bf16 v[84:87], v[222:225], v[206:209], v[84:87]
	v_mfma_f32_16x16x32_bf16 v[80:83], v[230:233], v[206:209], v[80:83]
	v_mfma_f32_16x16x32_bf16 v[68:71], v[222:225], v[214:217], v[68:71]
	v_mfma_f32_16x16x32_bf16 v[64:67], v[230:233], v[214:217], v[64:67]
	v_mfma_f32_16x16x32_bf16 v[116:119], v[226:229], v[172:175], v[116:119]
	v_mfma_f32_16x16x32_bf16 v[112:115], v[234:237], v[172:175], v[112:115]
	v_mfma_f32_16x16x32_bf16 v[100:103], v[226:229], v[202:205], v[100:103]
	v_mfma_f32_16x16x32_bf16 v[96:99], v[234:237], v[202:205], v[96:99]
	v_mfma_f32_16x16x32_bf16 v[84:87], v[226:229], v[210:213], v[84:87]
	v_mfma_f32_16x16x32_bf16 v[80:83], v[234:237], v[210:213], v[80:83]
	v_mfma_f32_16x16x32_bf16 v[68:71], v[226:229], v[218:221], v[68:71]
	v_mfma_f32_16x16x32_bf16 v[64:67], v[234:237], v[218:221], v[64:67]
	s_setprio 0
	s_mov_b32 m0, s58
	v_lshl_add_u64 v[238:239], v[242:243], 0, s[12:13]
	s_barrier
	ds_read_b128 v[168:171], v145 offset:49152
	ds_read_b128 v[172:175], v145 offset:50176
	ds_read_b128 v[198:201], v145 offset:51200
	ds_read_b128 v[202:205], v145 offset:52224
	ds_read_b128 v[206:209], v145 offset:53248
	ds_read_b128 v[210:213], v145 offset:54272
	ds_read_b128 v[214:217], v145 offset:55296
	ds_read_b128 v[218:221], v145 offset:56320
	global_load_lds_dwordx4 v[238:239], off
	v_lshl_add_u64 v[238:239], v[244:245], 0, s[12:13]
	s_mov_b32 m0, s59
	s_nop 0
	global_load_lds_dwordx4 v[238:239], off
	s_barrier
	s_waitcnt lgkmcnt(0)
	s_setprio 1
	s_waitcnt lgkmcnt(0)
	v_mfma_f32_16x16x32_bf16 v[60:63], v[128:131], v[168:171], v[60:63]
	v_mfma_f32_16x16x32_bf16 v[56:59], v[136:139], v[168:171], v[56:59]
	v_mfma_f32_16x16x32_bf16 v[44:47], v[128:131], v[198:201], v[44:47]
	v_mfma_f32_16x16x32_bf16 v[40:43], v[136:139], v[198:201], v[40:43]
	v_mfma_f32_16x16x32_bf16 v[28:31], v[128:131], v[206:209], v[28:31]
	v_mfma_f32_16x16x32_bf16 v[24:27], v[136:139], v[206:209], v[24:27]
	v_mfma_f32_16x16x32_bf16 v[12:15], v[128:131], v[214:217], v[12:15]
	v_mfma_f32_16x16x32_bf16 v[8:11], v[136:139], v[214:217], v[8:11]
	v_mfma_f32_16x16x32_bf16 v[60:63], v[132:135], v[172:175], v[60:63]
	v_mfma_f32_16x16x32_bf16 v[56:59], v[140:143], v[172:175], v[56:59]
	v_mfma_f32_16x16x32_bf16 v[44:47], v[132:135], v[202:205], v[44:47]
	v_mfma_f32_16x16x32_bf16 v[40:43], v[140:143], v[202:205], v[40:43]
	v_mfma_f32_16x16x32_bf16 v[28:31], v[132:135], v[210:213], v[28:31]
	v_mfma_f32_16x16x32_bf16 v[24:27], v[140:143], v[210:213], v[24:27]
	v_mfma_f32_16x16x32_bf16 v[12:15], v[132:135], v[218:221], v[12:15]
	v_mfma_f32_16x16x32_bf16 v[8:11], v[140:143], v[218:221], v[8:11]
	s_setprio 0
	s_barrier
	s_add_u32 s30, s30, 0x40080
	s_addc_u32 s31, s31, 0
	s_mov_b32 m0, s60
	v_lshl_add_u64 v[128:129], s[30:31], 0, v[150:151]
	global_load_lds_dwordx4 v[128:129], off
	v_lshl_add_u64 v[128:129], s[30:31], 0, v[146:147]
	s_mov_b32 m0, s61
	s_nop 0
	global_load_lds_dwordx4 v[128:129], off
	s_waitcnt vmcnt(6)
	s_barrier
	s_setprio 1
	v_mfma_f32_16x16x32_bf16 v[52:55], v[222:225], v[168:171], v[52:55]
	v_mfma_f32_16x16x32_bf16 v[48:51], v[230:233], v[168:171], v[48:51]
	v_mfma_f32_16x16x32_bf16 v[36:39], v[222:225], v[198:201], v[36:39]
	v_mfma_f32_16x16x32_bf16 v[32:35], v[230:233], v[198:201], v[32:35]
	v_mfma_f32_16x16x32_bf16 v[20:23], v[222:225], v[206:209], v[20:23]
	v_mfma_f32_16x16x32_bf16 v[16:19], v[230:233], v[206:209], v[16:19]
	v_mfma_f32_16x16x32_bf16 v[4:7], v[222:225], v[214:217], v[4:7]
	v_mfma_f32_16x16x32_bf16 v[0:3], v[230:233], v[214:217], v[0:3]
	v_mfma_f32_16x16x32_bf16 v[52:55], v[226:229], v[172:175], v[52:55]
	v_mfma_f32_16x16x32_bf16 v[48:51], v[234:237], v[172:175], v[48:51]
	v_mfma_f32_16x16x32_bf16 v[36:39], v[226:229], v[202:205], v[36:39]
	v_mfma_f32_16x16x32_bf16 v[32:35], v[234:237], v[202:205], v[32:35]
	v_mfma_f32_16x16x32_bf16 v[20:23], v[226:229], v[210:213], v[20:23]
	v_mfma_f32_16x16x32_bf16 v[16:19], v[234:237], v[210:213], v[16:19]
	v_mfma_f32_16x16x32_bf16 v[4:7], v[226:229], v[218:221], v[4:7]
	v_mfma_f32_16x16x32_bf16 v[0:3], v[234:237], v[218:221], v[0:3]
	s_setprio 0
	s_add_i32 s86, s86, 2
	s_add_u32 s84, s84, 0x100
	s_addc_u32 s85, s85, 0
	s_add_u32 s28, s28, 0x100
	s_addc_u32 s29, s29, 0
	s_cmp_gt_u32 s86, 13
	s_barrier
	s_cbranch_scc0 .LBB0_1727
	s_cmp_gt_i32 s8, 21
	s_mov_b64 s[28:29], -1
	s_cbranch_scc0 .LBB0_1734
	s_lshl_b32 s19, s8, 8
	s_cmp_gt_u32 s8, 24
	s_cbranch_scc0 .LBB0_1731
	s_lshl_b32 s21, s19, 1
	s_add_u32 s21, s2, s21
	s_addc_u32 s27, s3, 0
	s_lshl_b32 s28, s55, 1
	s_add_u32 s28, s21, s28
	v_lshl_add_u32 v128, s82, 10, v177
	s_addc_u32 s29, s27, 0
	v_lshlrev_b32_e32 v154, 1, v144
	s_ashr_i32 s27, s26, 31
	ds_read2_b32 v[138:139], v128 offset1:16
	ds_read2_b32 v[140:141], v128 offset0:32 offset1:48
	ds_read2_b32 v[132:133], v128 offset0:128 offset1:144
	ds_read2_b32 v[130:131], v128 offset0:160 offset1:176
	v_lshl_add_u64 v[128:129], s[28:29], 0, v[154:155]
	s_lshl_b64 s[28:29], s[26:27], 8
	v_lshl_add_u64 v[128:129], v[128:129], 0, s[14:15]
	v_lshl_add_u64 v[134:135], s[28:29], 0, v[156:157]
	v_mad_u64_u32 v[128:129], s[28:29], v134, s65, v[128:129]
	v_mad_i32_i24 v129, v135, s65, v129
	s_waitcnt lgkmcnt(0)
	v_pk_mul_f32 v[136:137], v[126:127], v[138:139] op_sel_hi:[1,0]
	v_pk_mul_f32 v[134:135], v[124:125], v[138:139] op_sel_hi:[1,0]
	v_pk_mul_f32 v[142:143], v[122:123], v[138:139] op_sel_hi:[1,0]
	v_pk_mul_f32 v[168:169], v[120:121], v[138:139] op_sel_hi:[1,0]
	v_cvt_pk_bf16_f32 v134, v134, v135
	v_cvt_pk_bf16_f32 v135, v136, v137
	v_cvt_pk_bf16_f32 v137, v142, v143
	v_pk_mul_f32 v[142:143], v[114:115], v[138:139] op_sel_hi:[1,0]
	v_cvt_pk_bf16_f32 v136, v168, v169
	s_waitcnt vmcnt(0)
	global_store_dwordx4 v[128:129], v[134:137], off
	v_pk_mul_f32 v[168:169], v[112:113], v[138:139] op_sel_hi:[1,0]
	s_mov_b64 s[28:29], 0
	v_pk_mul_f32 v[136:137], v[118:119], v[138:139] op_sel_hi:[1,0]
	v_pk_mul_f32 v[134:135], v[116:117], v[138:139] op_sel_hi:[1,0]
	v_mov_b32_e32 v138, v139
	v_cvt_pk_bf16_f32 v134, v134, v135
	v_cvt_pk_bf16_f32 v135, v136, v137
	v_cvt_pk_bf16_f32 v136, v168, v169
	v_cvt_pk_bf16_f32 v137, v142, v143
	global_store_dwordx4 v[128:129], v[134:137], off offset:256
	v_pk_mul_f32 v[142:143], v[106:107], v[138:139] op_sel_hi:[1,0]
	v_pk_mul_f32 v[168:169], v[104:105], v[138:139] op_sel_hi:[1,0]
	v_pk_mul_f32 v[136:137], v[110:111], v[138:139] op_sel_hi:[1,0]
	v_pk_mul_f32 v[134:135], v[108:109], v[138:139] op_sel_hi:[1,0]
	s_nop 0
	v_cvt_pk_bf16_f32 v134, v134, v135
	v_cvt_pk_bf16_f32 v135, v136, v137
	v_cvt_pk_bf16_f32 v137, v142, v143
	v_add_co_u32_e32 v142, vcc, s54, v128
	v_cvt_pk_bf16_f32 v136, v168, v169
	v_pk_mul_f32 v[168:169], v[98:99], v[138:139] op_sel_hi:[1,0]
	s_nop 0
	v_addc_co_u32_e32 v143, vcc, 0, v129, vcc
	global_store_dwordx4 v[142:143], v[134:137], off
	s_nop 1
	v_pk_mul_f32 v[136:137], v[102:103], v[138:139] op_sel_hi:[1,0]
	v_pk_mul_f32 v[134:135], v[100:101], v[138:139] op_sel_hi:[1,0]
	v_pk_mul_f32 v[138:139], v[96:97], v[138:139] op_sel_hi:[1,0]
	v_cvt_pk_bf16_f32 v134, v134, v135
	v_cvt_pk_bf16_f32 v135, v136, v137
	v_cvt_pk_bf16_f32 v137, v168, v169
	v_pk_mul_f32 v[168:169], v[80:81], v[140:141] op_sel_hi:[1,0]
	v_cvt_pk_bf16_f32 v136, v138, v139
	global_store_dwordx4 v[142:143], v[134:137], off offset:256
	v_pk_mul_f32 v[138:139], v[90:91], v[140:141] op_sel_hi:[1,0]
	v_pk_mul_f32 v[142:143], v[88:89], v[140:141] op_sel_hi:[1,0]
	v_pk_mul_f32 v[136:137], v[94:95], v[140:141] op_sel_hi:[1,0]
	v_pk_mul_f32 v[134:135], v[92:93], v[140:141] op_sel_hi:[1,0]
	s_nop 0
	v_cvt_pk_bf16_f32 v134, v134, v135
	v_cvt_pk_bf16_f32 v135, v136, v137
	v_cvt_pk_bf16_f32 v137, v138, v139
	v_add_co_u32_e32 v138, vcc, s62, v128
	v_cvt_pk_bf16_f32 v136, v142, v143
	v_pk_mul_f32 v[142:143], v[82:83], v[140:141] op_sel_hi:[1,0]
	s_nop 0
	v_addc_co_u32_e32 v139, vcc, 0, v129, vcc
	global_store_dwordx4 v[138:139], v[134:137], off
	s_nop 1
	v_pk_mul_f32 v[136:137], v[86:87], v[140:141] op_sel_hi:[1,0]
	v_pk_mul_f32 v[134:135], v[84:85], v[140:141] op_sel_hi:[1,0]
	s_nop 0
	v_cvt_pk_bf16_f32 v134, v134, v135
	v_cvt_pk_bf16_f32 v135, v136, v137
	v_cvt_pk_bf16_f32 v136, v168, v169
	v_cvt_pk_bf16_f32 v137, v142, v143
	global_store_dwordx4 v[138:139], v[134:137], off offset:256
	v_mov_b32_e32 v138, v141
	v_pk_mul_f32 v[140:141], v[74:75], v[138:139] op_sel_hi:[1,0]
	v_pk_mul_f32 v[136:137], v[78:79], v[138:139] op_sel_hi:[1,0]
	v_pk_mul_f32 v[134:135], v[76:77], v[138:139] op_sel_hi:[1,0]
	v_pk_mul_f32 v[142:143], v[72:73], v[138:139] op_sel_hi:[1,0]
	v_cvt_pk_bf16_f32 v134, v134, v135
	v_cvt_pk_bf16_f32 v135, v136, v137
	v_cvt_pk_bf16_f32 v137, v140, v141
	v_add_co_u32_e32 v140, vcc, s53, v128
	v_cvt_pk_bf16_f32 v136, v142, v143
	v_pk_mul_f32 v[142:143], v[66:67], v[138:139] op_sel_hi:[1,0]
	s_nop 0
	v_addc_co_u32_e32 v141, vcc, 0, v129, vcc
	global_store_dwordx4 v[140:141], v[134:137], off
	s_nop 1
	v_pk_mul_f32 v[136:137], v[70:71], v[138:139] op_sel_hi:[1,0]
	v_pk_mul_f32 v[134:135], v[68:69], v[138:139] op_sel_hi:[1,0]
	v_pk_mul_f32 v[138:139], v[64:65], v[138:139] op_sel_hi:[1,0]
	v_cvt_pk_bf16_f32 v134, v134, v135
	v_cvt_pk_bf16_f32 v135, v136, v137
	v_cvt_pk_bf16_f32 v137, v142, v143
	v_pk_mul_f32 v[142:143], v[48:49], v[132:133] op_sel_hi:[1,0]
	v_cvt_pk_bf16_f32 v136, v138, v139
	global_store_dwordx4 v[140:141], v[134:137], off offset:256
	v_pk_mul_f32 v[138:139], v[58:59], v[132:133] op_sel_hi:[1,0]
	v_pk_mul_f32 v[140:141], v[56:57], v[132:133] op_sel_hi:[1,0]
	v_pk_mul_f32 v[136:137], v[62:63], v[132:133] op_sel_hi:[1,0]
	v_pk_mul_f32 v[134:135], v[60:61], v[132:133] op_sel_hi:[1,0]
	s_nop 0
	v_cvt_pk_bf16_f32 v134, v134, v135
	v_cvt_pk_bf16_f32 v135, v136, v137
	v_cvt_pk_bf16_f32 v137, v138, v139
	v_add_co_u32_e32 v138, vcc, s66, v128
	v_cvt_pk_bf16_f32 v136, v140, v141
	v_pk_mul_f32 v[140:141], v[50:51], v[132:133] op_sel_hi:[1,0]
	s_nop 0
	v_addc_co_u32_e32 v139, vcc, 0, v129, vcc
	global_store_dwordx4 v[138:139], v[134:137], off
	s_nop 1
	v_pk_mul_f32 v[136:137], v[54:55], v[132:133] op_sel_hi:[1,0]
	v_pk_mul_f32 v[134:135], v[52:53], v[132:133] op_sel_hi:[1,0]
	s_nop 0
	v_cvt_pk_bf16_f32 v134, v134, v135
	v_cvt_pk_bf16_f32 v135, v136, v137
	v_cvt_pk_bf16_f32 v136, v142, v143
	v_cvt_pk_bf16_f32 v137, v140, v141
	global_store_dwordx4 v[138:139], v[134:137], off offset:256
	s_nop 1
	v_mov_b32_e32 v136, v133
	v_pk_mul_f32 v[134:135], v[46:47], v[136:137] op_sel_hi:[1,0]
	v_pk_mul_f32 v[132:133], v[44:45], v[136:137] op_sel_hi:[1,0]
	v_pk_mul_f32 v[138:139], v[42:43], v[136:137] op_sel_hi:[1,0]
	v_cvt_pk_bf16_f32 v132, v132, v133
	v_cvt_pk_bf16_f32 v133, v134, v135
	v_pk_mul_f32 v[140:141], v[40:41], v[136:137] op_sel_hi:[1,0]
	v_cvt_pk_bf16_f32 v135, v138, v139
	v_add_co_u32_e32 v138, vcc, s67, v128
	v_cvt_pk_bf16_f32 v134, v140, v141
	v_pk_mul_f32 v[140:141], v[34:35], v[136:137] op_sel_hi:[1,0]
	s_nop 0
	v_addc_co_u32_e32 v139, vcc, 0, v129, vcc
	global_store_dwordx4 v[138:139], v[132:135], off
	s_nop 1
	v_pk_mul_f32 v[134:135], v[38:39], v[136:137] op_sel_hi:[1,0]
	v_pk_mul_f32 v[132:133], v[36:37], v[136:137] op_sel_hi:[1,0]
	v_pk_mul_f32 v[136:137], v[32:33], v[136:137] op_sel_hi:[1,0]
	v_cvt_pk_bf16_f32 v132, v132, v133
	v_cvt_pk_bf16_f32 v133, v134, v135
	v_cvt_pk_bf16_f32 v135, v140, v141
	v_pk_mul_f32 v[140:141], v[16:17], v[130:131] op_sel_hi:[1,0]
	v_cvt_pk_bf16_f32 v134, v136, v137
	global_store_dwordx4 v[138:139], v[132:135], off offset:256
	v_pk_mul_f32 v[136:137], v[26:27], v[130:131] op_sel_hi:[1,0]
	v_pk_mul_f32 v[138:139], v[24:25], v[130:131] op_sel_hi:[1,0]
	v_pk_mul_f32 v[134:135], v[30:31], v[130:131] op_sel_hi:[1,0]
	v_pk_mul_f32 v[132:133], v[28:29], v[130:131] op_sel_hi:[1,0]
	s_nop 0
	v_cvt_pk_bf16_f32 v132, v132, v133
	v_cvt_pk_bf16_f32 v133, v134, v135
	v_cvt_pk_bf16_f32 v135, v136, v137
	v_add_co_u32_e32 v136, vcc, s68, v128
	v_cvt_pk_bf16_f32 v134, v138, v139
	v_pk_mul_f32 v[138:139], v[18:19], v[130:131] op_sel_hi:[1,0]
	s_nop 0
	v_addc_co_u32_e32 v137, vcc, 0, v129, vcc
	global_store_dwordx4 v[136:137], v[132:135], off
	s_nop 1
	v_pk_mul_f32 v[134:135], v[22:23], v[130:131] op_sel_hi:[1,0]
	v_pk_mul_f32 v[132:133], v[20:21], v[130:131] op_sel_hi:[1,0]
	s_nop 0
	v_cvt_pk_bf16_f32 v132, v132, v133
	v_cvt_pk_bf16_f32 v133, v134, v135
	v_cvt_pk_bf16_f32 v134, v140, v141
	v_cvt_pk_bf16_f32 v135, v138, v139
	global_store_dwordx4 v[136:137], v[132:135], off offset:256
	s_nop 1
	v_mov_b32_e32 v134, v131
	v_pk_mul_f32 v[132:133], v[14:15], v[134:135] op_sel_hi:[1,0]
	v_pk_mul_f32 v[130:131], v[12:13], v[134:135] op_sel_hi:[1,0]
	v_pk_mul_f32 v[136:137], v[10:11], v[134:135] op_sel_hi:[1,0]
	v_cvt_pk_bf16_f32 v130, v130, v131
	v_cvt_pk_bf16_f32 v131, v132, v133
	v_pk_mul_f32 v[138:139], v[8:9], v[134:135] op_sel_hi:[1,0]
	v_cvt_pk_bf16_f32 v133, v136, v137
	v_add_co_u32_e32 v136, vcc, s69, v128
	v_cvt_pk_bf16_f32 v132, v138, v139
	s_nop 1
	v_addc_co_u32_e32 v137, vcc, 0, v129, vcc
	global_store_dwordx4 v[136:137], v[130:133], off
	v_pk_mul_f32 v[128:129], v[4:5], v[134:135] op_sel_hi:[1,0]
	s_nop 0
	v_pk_mul_f32 v[130:131], v[6:7], v[134:135] op_sel_hi:[1,0]
	v_pk_mul_f32 v[132:133], v[2:3], v[134:135] op_sel_hi:[1,0]
	v_pk_mul_f32 v[134:135], v[0:1], v[134:135] op_sel_hi:[1,0]
	v_cvt_pk_bf16_f32 v128, v128, v129
	v_cvt_pk_bf16_f32 v129, v130, v131
	v_cvt_pk_bf16_f32 v131, v132, v133
	s_nop 0
	v_cvt_pk_bf16_f32 v130, v134, v135
	global_store_dwordx4 v[136:137], v[128:131], off offset:256
.LBB0_1731:
	s_andn2_b64 vcc, exec, s[28:29]
	s_cbranch_vccnz .LBB0_1733
	global_load_dwordx4 v[140:143], v[158:159], off
	global_load_dwordx4 v[136:139], v[158:159], off offset:16
	global_load_dwordx4 v[128:131], v[158:159], off offset:144
	global_load_dwordx4 v[132:135], v[158:159], off offset:128
	v_mov_b32_e32 v198, v125
	v_mov_b32_e32 v199, v121
	v_mov_b32_e32 v170, v124
	v_mov_b32_e32 v171, v120
	v_mov_b32_e32 v206, v117
	v_mov_b32_e32 v207, v113
	v_pk_mul_f32 v[198:199], v[198:199], v[198:199]
	v_mov_b32_e32 v200, v126
	v_mov_b32_e32 v201, v122
	v_mov_b32_e32 v204, v116
	v_mov_b32_e32 v205, v112
	v_pk_mul_f32 v[206:207], v[206:207], v[206:207]
	v_pk_fma_f32 v[170:171], v[170:171], v[170:171], v[198:199]
	v_and_b32_e32 v214, 64, v196
	v_mov_b32_e32 v202, v127
	v_mov_b32_e32 v203, v123
	v_mov_b32_e32 v208, v118
	v_mov_b32_e32 v209, v114
	v_pk_fma_f32 v[198:199], v[204:205], v[204:205], v[206:207]
	v_pk_fma_f32 v[170:171], v[200:201], v[200:201], v[170:171]
	v_xor_b32_e32 v197, 16, v196
	v_mov_b32_e32 v210, v119
	v_mov_b32_e32 v211, v115
	v_add_u32_e32 v214, 64, v214
	v_pk_fma_f32 v[198:199], v[208:209], v[208:209], v[198:199]
	v_pk_fma_f32 v[170:171], v[202:203], v[202:203], v[170:171]
	v_cmp_lt_i32_e32 vcc, v197, v214
	v_pk_fma_f32 v[198:199], v[210:211], v[210:211], v[198:199]
	v_add_f32_e32 v170, v170, v171
	v_cndmask_b32_e32 v197, v196, v197, vcc
	v_add_f32_e32 v170, v170, v198
	v_lshlrev_b32_e32 v197, 2, v197
	v_add_f32_e32 v170, v170, v199
	ds_bpermute_b32 v171, v197, v170
	v_xor_b32_e32 v215, 32, v196
	v_cmp_lt_i32_e32 vcc, v215, v214
	s_lshl_b32 s19, s19, 1
	s_add_u32 s19, s2, s19
	v_cndmask_b32_e32 v214, v196, v215, vcc
	v_lshlrev_b32_e32 v198, 2, v214
	s_waitcnt lgkmcnt(0)
	v_add_f32_e32 v199, v170, v171
	ds_bpermute_b32 v202, v198, v199
	s_addc_u32 s21, s3, 0
	s_waitcnt vmcnt(0)
	v_lshl_add_u32 v168, s82, 10, v177
	s_add_u32 s28, s19, s70
	v_lshlrev_b32_e32 v154, 1, v144
	ds_read2_b32 v[212:213], v168 offset1:16
	ds_read2_b32 v[174:175], v168 offset0:32 offset1:48
	ds_read2_b32 v[172:173], v168 offset0:128 offset1:144
	ds_read2_b32 v[168:169], v168 offset0:160 offset1:176
	s_addc_u32 s29, s21, 0
	v_lshl_add_u64 v[170:171], s[28:29], 0, v[154:155]
	s_waitcnt lgkmcnt(0)
	v_add_f32_e32 v154, v199, v202
	v_mul_f32_e32 v154, v212, v154
	v_mul_f32_e32 v154, v212, v154
	v_fmamk_f32 v154, v154, 0x3c800000, v195
	v_mul_f32_e32 v199, 0x4b800000, v154
	v_cmp_gt_f32_e32 vcc, s71, v154
	s_ashr_i32 s27, s26, 31
	s_lshl_b64 s[28:29], s[26:27], 8
	v_cndmask_b32_e32 v154, v154, v199, vcc
	v_rsq_f32_e32 v154, v154
	v_lshl_add_u64 v[170:171], v[170:171], 0, s[16:17]
	v_lshl_add_u64 v[200:201], s[28:29], 0, v[156:157]
	v_mad_u64_u32 v[170:171], s[28:29], v200, s65, v[170:171]
	v_mul_f32_e32 v199, 0x45800000, v154
	v_cndmask_b32_e32 v154, v154, v199, vcc
	v_mul_f32_e32 v154, v212, v154
	v_mad_i32_i24 v171, v201, s65, v171
	v_pk_mul_f32 v[200:201], v[124:125], v[154:155] op_sel_hi:[1,0]
	v_pk_mul_f32 v[202:203], v[126:127], v[154:155] op_sel_hi:[1,0]
	v_pk_mul_f32 v[206:207], v[122:123], v[154:155] op_sel_hi:[1,0]
	v_pk_mul_f32 v[204:205], v[120:121], v[154:155] op_sel_hi:[1,0]
	v_mov_b32_e32 v208, v101
	v_mov_b32_e32 v209, v97
	v_pk_mul_f32 v[208:209], v[208:209], v[208:209]
	v_mov_b32_e32 v210, v85
	s_waitcnt vmcnt(0)
	v_pk_mul_f32 v[202:203], v[142:143], v[202:203]
	v_pk_mul_f32 v[200:201], v[140:141], v[200:201]
	v_pk_mul_f32 v[206:207], v[138:139], v[206:207]
	v_pk_mul_f32 v[204:205], v[136:137], v[204:205]
	v_cvt_pk_bf16_f32 v200, v200, v201
	v_cvt_pk_bf16_f32 v201, v202, v203
	v_cvt_pk_bf16_f32 v203, v206, v207
	v_mov_b32_e32 v206, v109
	v_mov_b32_e32 v207, v105
	v_cvt_pk_bf16_f32 v202, v204, v205
	v_mov_b32_e32 v204, v108
	v_mov_b32_e32 v205, v104
	v_pk_mul_f32 v[206:207], v[206:207], v[206:207]
	global_store_dwordx4 v[170:171], v[200:203], off
	v_pk_fma_f32 v[204:205], v[204:205], v[204:205], v[206:207]
	v_mov_b32_e32 v206, v110
	v_mov_b32_e32 v207, v106
	v_pk_fma_f32 v[204:205], v[206:207], v[206:207], v[204:205]
	v_mov_b32_e32 v206, v111
	v_mov_b32_e32 v207, v107
	v_pk_fma_f32 v[204:205], v[206:207], v[206:207], v[204:205]
	v_mov_b32_e32 v206, v100
	v_mov_b32_e32 v207, v96
	v_pk_fma_f32 v[206:207], v[206:207], v[206:207], v[208:209]
	v_mov_b32_e32 v208, v102
	v_mov_b32_e32 v209, v98
	v_pk_fma_f32 v[206:207], v[208:209], v[208:209], v[206:207]
	v_mov_b32_e32 v208, v103
	v_mov_b32_e32 v209, v99
	v_pk_fma_f32 v[206:207], v[208:209], v[208:209], v[206:207]
	v_add_f32_e32 v199, v204, v205
	v_add_f32_e32 v199, v199, v206
	v_add_f32_e32 v199, v199, v207
	ds_bpermute_b32 v208, v197, v199
	v_pk_mul_f32 v[200:201], v[116:117], v[154:155] op_sel_hi:[1,0]
	v_pk_mul_f32 v[202:203], v[118:119], v[154:155] op_sel_hi:[1,0]
	v_pk_mul_f32 v[204:205], v[112:113], v[154:155] op_sel_hi:[1,0]
	v_pk_mul_f32 v[206:207], v[114:115], v[154:155] op_sel_hi:[1,0]
	s_waitcnt lgkmcnt(0)
	v_add_f32_e32 v154, v199, v208
	ds_bpermute_b32 v199, v198, v154
	v_pk_mul_f32 v[202:203], v[134:135], v[202:203]
	v_pk_mul_f32 v[200:201], v[132:133], v[200:201]
	v_pk_mul_f32 v[206:207], v[130:131], v[206:207]
	v_pk_mul_f32 v[204:205], v[128:129], v[204:205]
	s_waitcnt lgkmcnt(0)
	v_add_f32_e32 v154, v154, v199
	v_mul_f32_e32 v154, v213, v154
	v_mul_f32_e32 v154, v213, v154
	v_fmamk_f32 v154, v154, 0x3c800000, v195
	v_mul_f32_e32 v199, 0x4b800000, v154
	v_cmp_gt_f32_e32 vcc, s71, v154
	v_cvt_pk_bf16_f32 v200, v200, v201
	v_cvt_pk_bf16_f32 v201, v202, v203
	v_cvt_pk_bf16_f32 v202, v204, v205
	v_cvt_pk_bf16_f32 v203, v206, v207
	global_store_dwordx4 v[170:171], v[200:203], off offset:64
	s_nop 0
	v_cndmask_b32_e32 v154, v154, v199, vcc
	v_rsq_f32_e32 v154, v154
	v_mov_b32_e32 v208, v93
	v_mov_b32_e32 v209, v89
	v_pk_mul_f32 v[208:209], v[208:209], v[208:209]
	v_mul_f32_e32 v199, 0x45800000, v154
	v_cndmask_b32_e32 v154, v154, v199, vcc
	v_mul_f32_e32 v154, v213, v154
	v_pk_mul_f32 v[200:201], v[108:109], v[154:155] op_sel_hi:[1,0]
	v_pk_mul_f32 v[202:203], v[110:111], v[154:155] op_sel_hi:[1,0]
	v_pk_mul_f32 v[206:207], v[106:107], v[154:155] op_sel_hi:[1,0]
	v_pk_mul_f32 v[202:203], v[142:143], v[202:203]
	v_pk_mul_f32 v[200:201], v[140:141], v[200:201]
	v_pk_mul_f32 v[206:207], v[138:139], v[206:207]
	v_cvt_pk_bf16_f32 v200, v200, v201
	v_cvt_pk_bf16_f32 v201, v202, v203
	v_mov_b32_e32 v211, v81
	v_cvt_pk_bf16_f32 v203, v206, v207
	v_mov_b32_e32 v206, v92
	v_mov_b32_e32 v207, v88
	v_pk_fma_f32 v[206:207], v[206:207], v[206:207], v[208:209]
	v_mov_b32_e32 v208, v94
	v_mov_b32_e32 v209, v90
	v_pk_fma_f32 v[206:207], v[208:209], v[208:209], v[206:207]
	v_mov_b32_e32 v208, v95
	v_mov_b32_e32 v209, v91
	v_pk_fma_f32 v[206:207], v[208:209], v[208:209], v[206:207]
	v_mov_b32_e32 v208, v84
	v_mov_b32_e32 v209, v80
	v_pk_mul_f32 v[210:211], v[210:211], v[210:211]
	v_add_f32_e32 v199, v206, v207
	v_pk_fma_f32 v[208:209], v[208:209], v[208:209], v[210:211]
	v_mov_b32_e32 v210, v86
	v_mov_b32_e32 v211, v82
	v_pk_fma_f32 v[208:209], v[210:211], v[210:211], v[208:209]
	v_mov_b32_e32 v210, v87
	v_mov_b32_e32 v211, v83
	v_pk_fma_f32 v[208:209], v[210:211], v[210:211], v[208:209]
	v_pk_mul_f32 v[204:205], v[104:105], v[154:155] op_sel_hi:[1,0]
	v_add_f32_e32 v199, v199, v208
	v_add_f32_e32 v199, v199, v209
	ds_bpermute_b32 v210, v197, v199
	v_pk_mul_f32 v[204:205], v[136:137], v[204:205]
	v_pk_mul_f32 v[206:207], v[96:97], v[154:155] op_sel_hi:[1,0]
	v_cvt_pk_bf16_f32 v202, v204, v205
	v_add_co_u32_e32 v204, vcc, s54, v170
	v_pk_mul_f32 v[208:209], v[98:99], v[154:155] op_sel_hi:[1,0]
	s_nop 0
	v_addc_co_u32_e32 v205, vcc, 0, v171, vcc
	global_store_dwordx4 v[204:205], v[200:203], off
	v_pk_mul_f32 v[208:209], v[130:131], v[208:209]
	v_pk_mul_f32 v[206:207], v[128:129], v[206:207]
	v_pk_mul_f32 v[200:201], v[100:101], v[154:155] op_sel_hi:[1,0]
	v_pk_mul_f32 v[202:203], v[102:103], v[154:155] op_sel_hi:[1,0]
	s_waitcnt lgkmcnt(0)
	v_add_f32_e32 v154, v199, v210
	ds_bpermute_b32 v199, v198, v154
	v_pk_mul_f32 v[202:203], v[134:135], v[202:203]
	v_pk_mul_f32 v[200:201], v[132:133], v[200:201]
	v_mov_b32_e32 v210, v69
	v_cvt_pk_bf16_f32 v200, v200, v201
	s_waitcnt lgkmcnt(0)
	v_add_f32_e32 v154, v154, v199
	v_mul_f32_e32 v154, v174, v154
	v_mul_f32_e32 v154, v174, v154
	v_fmamk_f32 v154, v154, 0x3c800000, v195
	v_mul_f32_e32 v199, 0x4b800000, v154
	v_cmp_gt_f32_e32 vcc, s71, v154
	v_cvt_pk_bf16_f32 v201, v202, v203
	v_cvt_pk_bf16_f32 v202, v206, v207
	v_cvt_pk_bf16_f32 v203, v208, v209
	global_store_dwordx4 v[204:205], v[200:203], off offset:64
	v_mov_b32_e32 v208, v77
	v_cndmask_b32_e32 v154, v154, v199, vcc
	v_rsq_f32_e32 v154, v154
	v_mov_b32_e32 v209, v73
	v_pk_mul_f32 v[208:209], v[208:209], v[208:209]
	v_mov_b32_e32 v211, v65
	v_mul_f32_e32 v199, 0x45800000, v154
	v_cndmask_b32_e32 v154, v154, v199, vcc
	v_mul_f32_e32 v154, v174, v154
	v_pk_mul_f32 v[200:201], v[92:93], v[154:155] op_sel_hi:[1,0]
	v_pk_mul_f32 v[202:203], v[94:95], v[154:155] op_sel_hi:[1,0]
	v_pk_mul_f32 v[206:207], v[90:91], v[154:155] op_sel_hi:[1,0]
	v_pk_mul_f32 v[202:203], v[142:143], v[202:203]
	v_pk_mul_f32 v[200:201], v[140:141], v[200:201]
	v_pk_mul_f32 v[206:207], v[138:139], v[206:207]
	v_cvt_pk_bf16_f32 v200, v200, v201
	v_cvt_pk_bf16_f32 v201, v202, v203
	v_pk_mul_f32 v[210:211], v[210:211], v[210:211]
	v_cvt_pk_bf16_f32 v203, v206, v207
	v_mov_b32_e32 v206, v76
	v_mov_b32_e32 v207, v72
	v_pk_fma_f32 v[206:207], v[206:207], v[206:207], v[208:209]
	v_mov_b32_e32 v208, v78
	v_mov_b32_e32 v209, v74
	v_pk_fma_f32 v[206:207], v[208:209], v[208:209], v[206:207]
	v_mov_b32_e32 v208, v79
	v_mov_b32_e32 v209, v75
	v_pk_fma_f32 v[206:207], v[208:209], v[208:209], v[206:207]
	v_mov_b32_e32 v208, v68
	v_mov_b32_e32 v209, v64
	v_pk_fma_f32 v[208:209], v[208:209], v[208:209], v[210:211]
	v_mov_b32_e32 v210, v70
	v_mov_b32_e32 v211, v66
	v_pk_fma_f32 v[208:209], v[210:211], v[210:211], v[208:209]
	v_mov_b32_e32 v210, v71
	v_mov_b32_e32 v211, v67
	v_pk_fma_f32 v[208:209], v[210:211], v[210:211], v[208:209]
	v_add_f32_e32 v174, v206, v207
	v_add_f32_e32 v174, v174, v208
	v_add_f32_e32 v174, v174, v209
	ds_bpermute_b32 v199, v197, v174
	v_pk_mul_f32 v[204:205], v[88:89], v[154:155] op_sel_hi:[1,0]
	v_pk_mul_f32 v[206:207], v[80:81], v[154:155] op_sel_hi:[1,0]
	v_pk_mul_f32 v[204:205], v[136:137], v[204:205]
	v_pk_mul_f32 v[208:209], v[82:83], v[154:155] op_sel_hi:[1,0]
	v_cvt_pk_bf16_f32 v202, v204, v205
	v_add_co_u32_e32 v204, vcc, s62, v170
	v_pk_mul_f32 v[208:209], v[130:131], v[208:209]
	s_nop 0
	v_addc_co_u32_e32 v205, vcc, 0, v171, vcc
	global_store_dwordx4 v[204:205], v[200:203], off
	v_pk_mul_f32 v[206:207], v[128:129], v[206:207]
	s_nop 0
	v_pk_mul_f32 v[200:201], v[84:85], v[154:155] op_sel_hi:[1,0]
	v_pk_mul_f32 v[202:203], v[86:87], v[154:155] op_sel_hi:[1,0]
	s_waitcnt lgkmcnt(0)
	v_add_f32_e32 v154, v174, v199
	ds_bpermute_b32 v174, v198, v154
	v_pk_mul_f32 v[200:201], v[132:133], v[200:201]
	v_pk_mul_f32 v[202:203], v[134:135], v[202:203]
	v_cvt_pk_bf16_f32 v200, v200, v201
	s_waitcnt lgkmcnt(0)
	v_add_f32_e32 v154, v154, v174
	v_mul_f32_e32 v154, v175, v154
	v_mul_f32_e32 v154, v175, v154
	v_fmamk_f32 v154, v154, 0x3c800000, v195
	v_mul_f32_e32 v174, 0x4b800000, v154
	v_cmp_gt_f32_e32 vcc, s71, v154
	v_cvt_pk_bf16_f32 v201, v202, v203
	v_cvt_pk_bf16_f32 v202, v206, v207
	v_cvt_pk_bf16_f32 v203, v208, v209
	global_store_dwordx4 v[204:205], v[200:203], off offset:64
	v_mov_b32_e32 v208, v53
	v_cndmask_b32_e32 v154, v154, v174, vcc
	v_rsq_f32_e32 v154, v154
	v_mov_b32_e32 v209, v49
	v_pk_mul_f32 v[208:209], v[208:209], v[208:209]
	v_mul_f32_e32 v174, 0x45800000, v154
	v_cndmask_b32_e32 v154, v154, v174, vcc
	v_mul_f32_e32 v154, v175, v154
	v_pk_mul_f32 v[200:201], v[78:79], v[154:155] op_sel_hi:[1,0]
	v_pk_mul_f32 v[204:205], v[74:75], v[154:155] op_sel_hi:[1,0]
	v_pk_mul_f32 v[202:203], v[142:143], v[200:201]
	v_pk_mul_f32 v[200:201], v[72:73], v[154:155] op_sel_hi:[1,0]
	v_pk_mul_f32 v[204:205], v[138:139], v[204:205]
	v_pk_mul_f32 v[206:207], v[136:137], v[200:201]
	v_cvt_pk_bf16_f32 v201, v202, v203
	v_cvt_pk_bf16_f32 v203, v204, v205
	v_mov_b32_e32 v204, v60
	v_cvt_pk_bf16_f32 v202, v206, v207
	v_mov_b32_e32 v206, v61
	v_mov_b32_e32 v207, v57
	v_mov_b32_e32 v205, v56
	v_pk_mul_f32 v[206:207], v[206:207], v[206:207]
	v_pk_mul_f32 v[174:175], v[76:77], v[154:155] op_sel_hi:[1,0]
	v_pk_fma_f32 v[204:205], v[204:205], v[204:205], v[206:207]
	v_mov_b32_e32 v206, v62
	v_mov_b32_e32 v207, v58
	v_pk_fma_f32 v[204:205], v[206:207], v[206:207], v[204:205]
	v_mov_b32_e32 v206, v63
	v_mov_b32_e32 v207, v59
	v_pk_fma_f32 v[204:205], v[206:207], v[206:207], v[204:205]
	v_mov_b32_e32 v206, v52
	v_mov_b32_e32 v207, v48
	v_pk_fma_f32 v[206:207], v[206:207], v[206:207], v[208:209]
	v_mov_b32_e32 v208, v54
	v_mov_b32_e32 v209, v50
	v_pk_fma_f32 v[206:207], v[208:209], v[208:209], v[206:207]
	v_mov_b32_e32 v208, v55
	v_mov_b32_e32 v209, v51
	v_pk_fma_f32 v[206:207], v[208:209], v[208:209], v[206:207]
	v_add_f32_e32 v199, v204, v205
	v_add_f32_e32 v199, v199, v206
	v_add_f32_e32 v199, v199, v207
	ds_bpermute_b32 v208, v197, v199
	v_pk_mul_f32 v[174:175], v[140:141], v[174:175]
	v_pk_mul_f32 v[204:205], v[64:65], v[154:155] op_sel_hi:[1,0]
	v_cvt_pk_bf16_f32 v200, v174, v175
	v_add_co_u32_e32 v174, vcc, s53, v170
	v_pk_mul_f32 v[206:207], v[66:67], v[154:155] op_sel_hi:[1,0]
	s_nop 0
	v_addc_co_u32_e32 v175, vcc, 0, v171, vcc
	global_store_dwordx4 v[174:175], v[200:203], off
	v_pk_mul_f32 v[206:207], v[130:131], v[206:207]
	v_pk_mul_f32 v[204:205], v[128:129], v[204:205]
	v_pk_mul_f32 v[200:201], v[68:69], v[154:155] op_sel_hi:[1,0]
	v_pk_mul_f32 v[202:203], v[70:71], v[154:155] op_sel_hi:[1,0]
	s_waitcnt lgkmcnt(0)
	v_add_f32_e32 v154, v199, v208
	ds_bpermute_b32 v199, v198, v154
	v_pk_mul_f32 v[202:203], v[134:135], v[202:203]
	v_pk_mul_f32 v[200:201], v[132:133], v[200:201]
	v_mov_b32_e32 v208, v37
	v_cvt_pk_bf16_f32 v200, v200, v201
	s_waitcnt lgkmcnt(0)
	v_add_f32_e32 v154, v154, v199
	v_mul_f32_e32 v154, v172, v154
	v_mul_f32_e32 v154, v172, v154
	v_fmamk_f32 v154, v154, 0x3c800000, v195
	v_mul_f32_e32 v199, 0x4b800000, v154
	v_cmp_gt_f32_e32 vcc, s71, v154
	v_cvt_pk_bf16_f32 v201, v202, v203
	v_cvt_pk_bf16_f32 v202, v204, v205
	v_cvt_pk_bf16_f32 v203, v206, v207
	global_store_dwordx4 v[174:175], v[200:203], off offset:64
	v_mov_b32_e32 v209, v33
	v_cndmask_b32_e32 v154, v154, v199, vcc
	v_rsq_f32_e32 v154, v154
	v_pk_mul_f32 v[208:209], v[208:209], v[208:209]
	v_mul_f32_e32 v174, 0x45800000, v154
	v_cndmask_b32_e32 v154, v154, v174, vcc
	v_mul_f32_e32 v154, v172, v154
	v_pk_mul_f32 v[200:201], v[62:63], v[154:155] op_sel_hi:[1,0]
	v_pk_mul_f32 v[204:205], v[58:59], v[154:155] op_sel_hi:[1,0]
	v_pk_mul_f32 v[202:203], v[142:143], v[200:201]
	v_pk_mul_f32 v[200:201], v[56:57], v[154:155] op_sel_hi:[1,0]
	v_pk_mul_f32 v[204:205], v[138:139], v[204:205]
	v_pk_mul_f32 v[206:207], v[136:137], v[200:201]
	v_cvt_pk_bf16_f32 v201, v202, v203
	v_cvt_pk_bf16_f32 v203, v204, v205
	v_mov_b32_e32 v204, v44
	v_cvt_pk_bf16_f32 v202, v206, v207
	v_mov_b32_e32 v206, v45
	v_mov_b32_e32 v207, v41
	v_mov_b32_e32 v205, v40
	v_pk_mul_f32 v[206:207], v[206:207], v[206:207]
	v_pk_mul_f32 v[174:175], v[60:61], v[154:155] op_sel_hi:[1,0]
	v_pk_fma_f32 v[204:205], v[204:205], v[204:205], v[206:207]
	v_mov_b32_e32 v206, v46
	v_mov_b32_e32 v207, v42
	v_pk_fma_f32 v[204:205], v[206:207], v[206:207], v[204:205]
	v_mov_b32_e32 v206, v47
	v_mov_b32_e32 v207, v43
	v_pk_fma_f32 v[204:205], v[206:207], v[206:207], v[204:205]
	v_mov_b32_e32 v206, v36
	v_mov_b32_e32 v207, v32
	v_pk_fma_f32 v[206:207], v[206:207], v[206:207], v[208:209]
	v_mov_b32_e32 v208, v38
	v_mov_b32_e32 v209, v34
	v_pk_fma_f32 v[206:207], v[208:209], v[208:209], v[206:207]
	v_mov_b32_e32 v208, v39
	v_mov_b32_e32 v209, v35
	v_pk_fma_f32 v[206:207], v[208:209], v[208:209], v[206:207]
	v_add_f32_e32 v172, v204, v205
	v_add_f32_e32 v172, v172, v206
	v_add_f32_e32 v172, v172, v207
	ds_bpermute_b32 v199, v197, v172
	v_pk_mul_f32 v[174:175], v[140:141], v[174:175]
	v_pk_mul_f32 v[204:205], v[48:49], v[154:155] op_sel_hi:[1,0]
	v_cvt_pk_bf16_f32 v200, v174, v175
	v_add_co_u32_e32 v174, vcc, s66, v170
	v_pk_mul_f32 v[206:207], v[50:51], v[154:155] op_sel_hi:[1,0]
	s_nop 0
	v_addc_co_u32_e32 v175, vcc, 0, v171, vcc
	global_store_dwordx4 v[174:175], v[200:203], off
	v_pk_mul_f32 v[206:207], v[130:131], v[206:207]
	v_pk_mul_f32 v[204:205], v[128:129], v[204:205]
	v_pk_mul_f32 v[200:201], v[52:53], v[154:155] op_sel_hi:[1,0]
	v_pk_mul_f32 v[202:203], v[54:55], v[154:155] op_sel_hi:[1,0]
	s_waitcnt lgkmcnt(0)
	v_add_f32_e32 v154, v172, v199
	ds_bpermute_b32 v172, v198, v154
	v_pk_mul_f32 v[202:203], v[134:135], v[202:203]
	v_pk_mul_f32 v[200:201], v[132:133], v[200:201]
	s_waitcnt lgkmcnt(0)
	v_add_f32_e32 v154, v154, v172
	v_mul_f32_e32 v154, v173, v154
	v_mul_f32_e32 v154, v173, v154
	v_fmamk_f32 v154, v154, 0x3c800000, v195
	v_mul_f32_e32 v172, 0x4b800000, v154
	v_cmp_gt_f32_e32 vcc, s71, v154
	v_cvt_pk_bf16_f32 v200, v200, v201
	v_cvt_pk_bf16_f32 v201, v202, v203
	v_cvt_pk_bf16_f32 v202, v204, v205
	v_cvt_pk_bf16_f32 v203, v206, v207
	global_store_dwordx4 v[174:175], v[200:203], off offset:64
	s_nop 0
	v_cndmask_b32_e32 v154, v154, v172, vcc
	v_rsq_f32_e32 v154, v154
	v_mov_b32_e32 v204, v29
	v_mov_b32_e32 v205, v25
	v_pk_mul_f32 v[204:205], v[204:205], v[204:205]
	v_mul_f32_e32 v172, 0x45800000, v154
	v_cndmask_b32_e32 v154, v154, v172, vcc
	v_mul_f32_e32 v154, v173, v154
	v_pk_mul_f32 v[172:173], v[44:45], v[154:155] op_sel_hi:[1,0]
	v_pk_mul_f32 v[174:175], v[46:47], v[154:155] op_sel_hi:[1,0]
	v_pk_mul_f32 v[202:203], v[42:43], v[154:155] op_sel_hi:[1,0]
	v_pk_mul_f32 v[174:175], v[142:143], v[174:175]
	v_pk_mul_f32 v[172:173], v[140:141], v[172:173]
	v_pk_mul_f32 v[202:203], v[138:139], v[202:203]
	v_cvt_pk_bf16_f32 v172, v172, v173
	v_cvt_pk_bf16_f32 v173, v174, v175
	v_mov_b32_e32 v206, v21
	v_cvt_pk_bf16_f32 v175, v202, v203
	v_mov_b32_e32 v202, v28
	v_mov_b32_e32 v203, v24
	v_pk_fma_f32 v[202:203], v[202:203], v[202:203], v[204:205]
	v_mov_b32_e32 v204, v30
	v_mov_b32_e32 v205, v26
	v_pk_fma_f32 v[202:203], v[204:205], v[204:205], v[202:203]
	v_mov_b32_e32 v204, v31
	v_mov_b32_e32 v205, v27
	v_mov_b32_e32 v207, v17
	v_pk_fma_f32 v[202:203], v[204:205], v[204:205], v[202:203]
	v_mov_b32_e32 v204, v20
	v_mov_b32_e32 v205, v16
	v_pk_mul_f32 v[206:207], v[206:207], v[206:207]
	v_add_f32_e32 v199, v202, v203
	v_pk_fma_f32 v[204:205], v[204:205], v[204:205], v[206:207]
	v_mov_b32_e32 v206, v22
	v_mov_b32_e32 v207, v18
	v_pk_fma_f32 v[204:205], v[206:207], v[206:207], v[204:205]
	v_mov_b32_e32 v206, v23
	v_mov_b32_e32 v207, v19
	v_pk_fma_f32 v[204:205], v[206:207], v[206:207], v[204:205]
	v_pk_mul_f32 v[200:201], v[40:41], v[154:155] op_sel_hi:[1,0]
	v_add_f32_e32 v199, v199, v204
	v_add_f32_e32 v199, v199, v205
	ds_bpermute_b32 v206, v197, v199
	v_pk_mul_f32 v[200:201], v[136:137], v[200:201]
	v_pk_mul_f32 v[202:203], v[32:33], v[154:155] op_sel_hi:[1,0]
	v_cvt_pk_bf16_f32 v174, v200, v201
	v_add_co_u32_e32 v200, vcc, s67, v170
	v_pk_mul_f32 v[204:205], v[34:35], v[154:155] op_sel_hi:[1,0]
	s_nop 0
	v_addc_co_u32_e32 v201, vcc, 0, v171, vcc
	global_store_dwordx4 v[200:201], v[172:175], off
	v_pk_mul_f32 v[204:205], v[130:131], v[204:205]
	v_pk_mul_f32 v[202:203], v[128:129], v[202:203]
	v_pk_mul_f32 v[172:173], v[36:37], v[154:155] op_sel_hi:[1,0]
	v_pk_mul_f32 v[174:175], v[38:39], v[154:155] op_sel_hi:[1,0]
	s_waitcnt lgkmcnt(0)
	v_add_f32_e32 v154, v199, v206
	ds_bpermute_b32 v199, v198, v154
	v_pk_mul_f32 v[174:175], v[134:135], v[174:175]
	v_pk_mul_f32 v[172:173], v[132:133], v[172:173]
	v_mov_b32_e32 v206, v5
	v_cvt_pk_bf16_f32 v172, v172, v173
	s_waitcnt lgkmcnt(0)
	v_add_f32_e32 v154, v154, v199
	v_mul_f32_e32 v154, v168, v154
	v_mul_f32_e32 v154, v168, v154
	v_fmamk_f32 v154, v154, 0x3c800000, v195
	v_cvt_pk_bf16_f32 v173, v174, v175
	v_mul_f32_e32 v174, 0x4b800000, v154
	v_cmp_gt_f32_e32 vcc, s71, v154
	v_cvt_pk_bf16_f32 v175, v204, v205
	v_mov_b32_e32 v204, v13
	v_mov_b32_e32 v205, v9
	v_cndmask_b32_e32 v154, v154, v174, vcc
	v_rsq_f32_e32 v154, v154
	v_cvt_pk_bf16_f32 v174, v202, v203
	global_store_dwordx4 v[200:201], v[172:175], off offset:64
	v_pk_mul_f32 v[204:205], v[204:205], v[204:205]
	v_mov_b32_e32 v207, v1
	v_mul_f32_e32 v172, 0x45800000, v154
	v_cndmask_b32_e32 v154, v154, v172, vcc
	v_mul_f32_e32 v154, v168, v154
	v_pk_mul_f32 v[172:173], v[28:29], v[154:155] op_sel_hi:[1,0]
	v_pk_mul_f32 v[174:175], v[30:31], v[154:155] op_sel_hi:[1,0]
	v_pk_mul_f32 v[202:203], v[26:27], v[154:155] op_sel_hi:[1,0]
	v_pk_mul_f32 v[174:175], v[142:143], v[174:175]
	v_pk_mul_f32 v[172:173], v[140:141], v[172:173]
	v_pk_mul_f32 v[202:203], v[138:139], v[202:203]
	v_cvt_pk_bf16_f32 v172, v172, v173
	v_cvt_pk_bf16_f32 v173, v174, v175
	v_pk_mul_f32 v[206:207], v[206:207], v[206:207]
	v_cvt_pk_bf16_f32 v175, v202, v203
	v_mov_b32_e32 v202, v12
	v_mov_b32_e32 v203, v8
	v_pk_fma_f32 v[202:203], v[202:203], v[202:203], v[204:205]
	v_mov_b32_e32 v204, v14
	v_mov_b32_e32 v205, v10
	v_pk_fma_f32 v[202:203], v[204:205], v[204:205], v[202:203]
	v_mov_b32_e32 v204, v15
	v_mov_b32_e32 v205, v11
	v_pk_fma_f32 v[202:203], v[204:205], v[204:205], v[202:203]
	v_mov_b32_e32 v204, v4
	v_mov_b32_e32 v205, v0
	v_pk_fma_f32 v[204:205], v[204:205], v[204:205], v[206:207]
	v_mov_b32_e32 v206, v6
	v_mov_b32_e32 v207, v2
	v_pk_fma_f32 v[204:205], v[206:207], v[206:207], v[204:205]
	v_mov_b32_e32 v206, v7
	v_mov_b32_e32 v207, v3
	v_pk_fma_f32 v[204:205], v[206:207], v[206:207], v[204:205]
	v_add_f32_e32 v168, v202, v203
	v_add_f32_e32 v168, v168, v204
	v_add_f32_e32 v168, v168, v205
	ds_bpermute_b32 v197, v197, v168
	v_pk_mul_f32 v[200:201], v[24:25], v[154:155] op_sel_hi:[1,0]
	v_pk_mul_f32 v[202:203], v[16:17], v[154:155] op_sel_hi:[1,0]
	v_pk_mul_f32 v[200:201], v[136:137], v[200:201]
	v_pk_mul_f32 v[204:205], v[18:19], v[154:155] op_sel_hi:[1,0]
	v_cvt_pk_bf16_f32 v174, v200, v201
	v_add_co_u32_e32 v200, vcc, s68, v170
	v_pk_mul_f32 v[202:203], v[128:129], v[202:203]
	s_nop 0
	v_addc_co_u32_e32 v201, vcc, 0, v171, vcc
	global_store_dwordx4 v[200:201], v[172:175], off
	s_nop 1
	v_pk_mul_f32 v[172:173], v[20:21], v[154:155] op_sel_hi:[1,0]
	v_pk_mul_f32 v[174:175], v[22:23], v[154:155] op_sel_hi:[1,0]
	s_waitcnt lgkmcnt(0)
	v_add_f32_e32 v154, v168, v197
	ds_bpermute_b32 v168, v198, v154
	v_pk_mul_f32 v[172:173], v[132:133], v[172:173]
	v_pk_mul_f32 v[174:175], v[134:135], v[174:175]
	v_cvt_pk_bf16_f32 v172, v172, v173
	v_pk_mul_f32 v[198:199], v[130:131], v[204:205]
	s_waitcnt lgkmcnt(0)
	v_add_f32_e32 v154, v154, v168
	v_mul_f32_e32 v154, v169, v154
	v_mul_f32_e32 v154, v169, v154
	v_fmamk_f32 v154, v154, 0x3c800000, v195
	v_mul_f32_e32 v168, 0x4b800000, v154
	v_cmp_gt_f32_e32 vcc, s71, v154
	v_cvt_pk_bf16_f32 v173, v174, v175
	v_cvt_pk_bf16_f32 v174, v202, v203
	v_cvt_pk_bf16_f32 v175, v198, v199
	global_store_dwordx4 v[200:201], v[172:175], off offset:64
	s_nop 0
	v_cndmask_b32_e32 v154, v154, v168, vcc
	v_rsq_f32_e32 v154, v154
	s_nop 0
	v_mul_f32_e32 v168, 0x45800000, v154
	v_cndmask_b32_e32 v154, v154, v168, vcc
	v_mul_f32_e32 v154, v169, v154
	v_pk_mul_f32 v[168:169], v[12:13], v[154:155] op_sel_hi:[1,0]
	v_pk_mul_f32 v[172:173], v[14:15], v[154:155] op_sel_hi:[1,0]
	v_pk_mul_f32 v[140:141], v[140:141], v[168:169]
	v_pk_mul_f32 v[142:143], v[142:143], v[172:173]
	v_pk_mul_f32 v[168:169], v[8:9], v[154:155] op_sel_hi:[1,0]
	v_pk_mul_f32 v[172:173], v[10:11], v[154:155] op_sel_hi:[1,0]
	s_nop 0
	v_pk_mul_f32 v[172:173], v[138:139], v[172:173]
	v_pk_mul_f32 v[138:139], v[136:137], v[168:169]
	v_cvt_pk_bf16_f32 v136, v140, v141
	v_add_co_u32_e32 v140, vcc, s69, v170
	v_cvt_pk_bf16_f32 v137, v142, v143
	v_cvt_pk_bf16_f32 v138, v138, v139
	v_cvt_pk_bf16_f32 v139, v172, v173
	s_nop 1
	v_addc_co_u32_e32 v141, vcc, 0, v171, vcc
	global_store_dwordx4 v[140:141], v[136:139], off
	s_nop 1
	v_pk_mul_f32 v[136:137], v[4:5], v[154:155] op_sel_hi:[1,0]
	v_pk_mul_f32 v[138:139], v[6:7], v[154:155] op_sel_hi:[1,0]
	v_pk_mul_f32 v[132:133], v[132:133], v[136:137]
	v_pk_mul_f32 v[134:135], v[134:135], v[138:139]
	v_pk_mul_f32 v[136:137], v[0:1], v[154:155] op_sel_hi:[1,0]
	v_pk_mul_f32 v[138:139], v[2:3], v[154:155] op_sel_hi:[1,0]
	s_nop 0
	v_pk_mul_f32 v[138:139], v[130:131], v[138:139]
	v_pk_mul_f32 v[130:131], v[128:129], v[136:137]
	v_cvt_pk_bf16_f32 v128, v132, v133
	v_cvt_pk_bf16_f32 v129, v134, v135
	s_nop 0
	v_cvt_pk_bf16_f32 v130, v130, v131
	v_cvt_pk_bf16_f32 v131, v138, v139
	global_store_dwordx4 v[140:141], v[128:131], off offset:64

.LBB0_1734:
	s_andn2_b64 vcc, exec, s[28:29]
	s_cbranch_vccnz .LBB0_1723
	v_lshl_add_u32 v128, s82, 10, v177
	ds_read2_b32 v[134:135], v128 offset1:16
	s_ashr_i32 s27, s26, 31
	s_lshl_b64 s[26:27], s[26:27], 8
	v_lshlrev_b32_e32 v154, 1, v144
	ds_read2_b32 v[132:133], v128 offset0:32 offset1:48
	ds_read2_b32 v[130:131], v128 offset0:128 offset1:144
	ds_read2_b32 v[128:129], v128 offset0:160 offset1:176
	s_waitcnt lgkmcnt(0)
	v_mul_f32_e32 v120, v120, v134
	v_mul_f32_e32 v124, v124, v134
	v_mul_f32_e32 v137, 0xbfb8aa3b, v120
	v_mul_f32_e32 v136, 0xbfb8aa3b, v124
	v_exp_f32_e32 v137, v137
	v_exp_f32_e32 v136, v136
	v_mul_f32_e32 v112, v112, v134
	v_mul_f32_e32 v116, v116, v134
	v_add_f32_e32 v137, 1.0, v137
	v_add_f32_e32 v136, 1.0, v136
	v_rcp_f32_e32 v137, v137
	v_rcp_f32_e32 v136, v136
	v_mul_f32_e32 v121, v121, v134
	v_mul_f32_e32 v117, v117, v134
	v_mul_f32_e32 v120, v120, v137
	v_mul_f32_e32 v124, v124, v136
	v_mul_f32_e32 v120, v112, v120
	v_mul_f32_e32 v112, v125, v134
	v_mul_f32_e32 v116, v116, v124
	v_mul_f32_e32 v124, 0xbfb8aa3b, v112
	v_exp_f32_e32 v124, v124
	v_mul_f32_e32 v125, 0xbfb8aa3b, v121
	v_exp_f32_e32 v125, v125
	v_mul_f32_e32 v113, v113, v134
	v_add_f32_e32 v124, 1.0, v124
	v_rcp_f32_e32 v124, v124
	v_add_f32_e32 v125, 1.0, v125
	v_rcp_f32_e32 v125, v125
	v_mul_f32_e32 v118, v118, v134
	v_mul_f32_e32 v112, v112, v124
	v_mul_f32_e32 v117, v117, v112
	v_mul_f32_e32 v112, v121, v125
	v_mul_f32_e32 v121, v113, v112
	v_mul_f32_e32 v112, v126, v134
	v_mul_f32_e32 v113, v122, v134
	v_mul_f32_e32 v122, 0xbfb8aa3b, v112
	v_exp_f32_e32 v122, v122
	v_mul_f32_e32 v124, 0xbfb8aa3b, v113
	v_exp_f32_e32 v124, v124
	v_mul_f32_e32 v114, v114, v134
	v_add_f32_e32 v122, 1.0, v122
	v_rcp_f32_e32 v122, v122
	v_add_f32_e32 v124, 1.0, v124
	v_rcp_f32_e32 v124, v124
	v_mul_f32_e32 v119, v119, v134
	v_mul_f32_e32 v112, v112, v122
	v_mul_f32_e32 v118, v118, v112
	v_mul_f32_e32 v112, v113, v124
	v_mul_f32_e32 v122, v114, v112
	v_mul_f32_e32 v112, v127, v134
	v_mul_f32_e32 v113, v123, v134
	v_mul_f32_e32 v114, 0xbfb8aa3b, v112
	v_exp_f32_e32 v114, v114
	v_mul_f32_e32 v123, 0xbfb8aa3b, v113
	v_exp_f32_e32 v123, v123
	v_mul_f32_e32 v115, v115, v134
	v_add_f32_e32 v114, 1.0, v114
	v_rcp_f32_e32 v114, v114
	v_add_f32_e32 v123, 1.0, v123
	v_rcp_f32_e32 v123, v123
	v_mul_f32_e32 v104, v104, v135
	v_mul_f32_e32 v112, v112, v114
	v_mul_f32_e32 v119, v119, v112
	v_mul_f32_e32 v112, v113, v123
	v_mul_f32_e32 v123, v115, v112
	v_lshl_add_u64 v[112:113], s[26:27], 0, v[156:157]
	v_cvt_pk_bf16_f32 v115, v118, v119
	v_mov_b64_e32 v[118:119], s[10:11]
	v_mad_u64_u32 v[118:119], s[26:27], v112, s72, v[118:119]
	s_lshl_b32 s26, s8, 7
	v_mad_i32_i24 v119, v113, s72, v119
	s_ashr_i32 s27, s26, 31
	v_lshl_add_u64 v[112:113], s[26:27], 1, v[118:119]
	s_lshl_b32 s8, s55, 1
	v_lshl_add_u64 v[112:113], v[112:113], 0, s[8:9]
	v_lshl_add_u64 v[112:113], v[112:113], 0, v[154:155]
	v_cvt_pk_bf16_f32 v114, v116, v117
	v_cvt_pk_bf16_f32 v116, v120, v121
	v_cvt_pk_bf16_f32 v117, v122, v123
	s_waitcnt vmcnt(0)
	global_store_dwordx4 v[112:113], v[114:117], off
	v_mul_f32_e32 v108, v108, v135
	v_mul_f32_e32 v96, v96, v135
	v_mul_f32_e32 v115, 0xbfb8aa3b, v104
	v_mul_f32_e32 v114, 0xbfb8aa3b, v108
	v_exp_f32_e32 v115, v115
	v_exp_f32_e32 v114, v114
	v_mul_f32_e32 v100, v100, v135
	v_mul_f32_e32 v105, v105, v135
	v_add_f32_e32 v115, 1.0, v115
	v_add_f32_e32 v114, 1.0, v114
	v_rcp_f32_e32 v115, v115
	v_rcp_f32_e32 v114, v114
	v_mul_f32_e32 v101, v101, v135
	v_mul_f32_e32 v97, v97, v135
	v_mul_f32_e32 v104, v104, v115
	v_mul_f32_e32 v108, v108, v114
	v_mul_f32_e32 v104, v96, v104
	v_mul_f32_e32 v96, v109, v135
	v_mul_f32_e32 v100, v100, v108
	v_mul_f32_e32 v108, 0xbfb8aa3b, v96
	v_exp_f32_e32 v108, v108
	v_mul_f32_e32 v109, 0xbfb8aa3b, v105
	v_exp_f32_e32 v109, v109
	v_mul_f32_e32 v102, v102, v135
	v_add_f32_e32 v108, 1.0, v108
	v_rcp_f32_e32 v108, v108
	v_add_f32_e32 v109, 1.0, v109
	v_rcp_f32_e32 v109, v109
	v_mul_f32_e32 v98, v98, v135
	v_mul_f32_e32 v96, v96, v108
	v_mul_f32_e32 v96, v101, v96
	v_mul_f32_e32 v101, v105, v109
	v_mul_f32_e32 v101, v97, v101
	v_mul_f32_e32 v97, v110, v135
	v_mul_f32_e32 v105, v106, v135
	v_mul_f32_e32 v106, 0xbfb8aa3b, v97
	v_exp_f32_e32 v106, v106
	v_mul_f32_e32 v108, 0xbfb8aa3b, v105
	v_exp_f32_e32 v108, v108
	v_mul_f32_e32 v103, v103, v135
	v_add_f32_e32 v106, 1.0, v106
	v_rcp_f32_e32 v106, v106
	v_add_f32_e32 v108, 1.0, v108
	v_rcp_f32_e32 v108, v108
	s_mov_b32 s8, 0x16000
	v_mul_f32_e32 v97, v97, v106
	v_mul_f32_e32 v97, v102, v97
	v_mul_f32_e32 v102, v105, v108
	v_mul_f32_e32 v102, v98, v102
	v_mul_f32_e32 v98, v111, v135
	v_mul_f32_e32 v105, v107, v135
	v_mul_f32_e32 v106, 0xbfb8aa3b, v98
	v_exp_f32_e32 v106, v106
	v_mul_f32_e32 v107, 0xbfb8aa3b, v105
	v_exp_f32_e32 v107, v107
	v_mul_f32_e32 v99, v99, v135
	v_add_f32_e32 v106, 1.0, v106
	v_rcp_f32_e32 v106, v106
	v_add_f32_e32 v107, 1.0, v107
	v_rcp_f32_e32 v107, v107
	v_cvt_pk_bf16_f32 v96, v100, v96
	v_mul_f32_e32 v98, v98, v106
	v_mul_f32_e32 v98, v103, v98
	v_mul_f32_e32 v103, v105, v107
	v_add_co_u32_e32 v100, vcc, s8, v112
	v_mul_f32_e32 v99, v99, v103
	v_cvt_pk_bf16_f32 v97, v97, v98
	v_cvt_pk_bf16_f32 v98, v104, v101
	s_nop 0
	v_addc_co_u32_e32 v101, vcc, 0, v113, vcc
	v_mul_f32_e32 v88, v88, v132
	v_cvt_pk_bf16_f32 v99, v102, v99
	global_store_dwordx4 v[100:101], v[96:99], off
	v_mul_f32_e32 v92, v92, v132
	v_mul_f32_e32 v80, v80, v132
	v_mul_f32_e32 v97, 0xbfb8aa3b, v88
	v_mul_f32_e32 v96, 0xbfb8aa3b, v92
	v_exp_f32_e32 v97, v97
	v_exp_f32_e32 v96, v96
	v_mul_f32_e32 v84, v84, v132
	v_mul_f32_e32 v89, v89, v132
	v_add_f32_e32 v97, 1.0, v97
	v_add_f32_e32 v96, 1.0, v96
	v_rcp_f32_e32 v97, v97
	v_rcp_f32_e32 v96, v96
	v_mul_f32_e32 v85, v85, v132
	v_mul_f32_e32 v81, v81, v132
	v_mul_f32_e32 v88, v88, v97
	v_mul_f32_e32 v92, v92, v96
	v_mul_f32_e32 v88, v80, v88
	v_mul_f32_e32 v80, v93, v132
	v_mul_f32_e32 v84, v84, v92
	v_mul_f32_e32 v92, 0xbfb8aa3b, v80
	v_exp_f32_e32 v92, v92
	v_mul_f32_e32 v93, 0xbfb8aa3b, v89
	v_exp_f32_e32 v93, v93
	v_mul_f32_e32 v86, v86, v132
	v_add_f32_e32 v92, 1.0, v92
	v_rcp_f32_e32 v92, v92
	v_add_f32_e32 v93, 1.0, v93
	v_rcp_f32_e32 v93, v93
	v_mul_f32_e32 v82, v82, v132
	v_mul_f32_e32 v80, v80, v92
	v_mul_f32_e32 v80, v85, v80
	v_mul_f32_e32 v85, v89, v93
	v_mul_f32_e32 v85, v81, v85
	v_mul_f32_e32 v81, v94, v132
	v_mul_f32_e32 v89, v90, v132
	v_mul_f32_e32 v90, 0xbfb8aa3b, v81
	v_exp_f32_e32 v90, v90
	v_mul_f32_e32 v92, 0xbfb8aa3b, v89
	v_exp_f32_e32 v92, v92
	v_mul_f32_e32 v87, v87, v132
	v_add_f32_e32 v90, 1.0, v90
	v_rcp_f32_e32 v90, v90
	v_add_f32_e32 v92, 1.0, v92
	v_rcp_f32_e32 v92, v92
	v_mul_f32_e32 v83, v83, v132
	v_mul_f32_e32 v81, v81, v90
	v_mul_f32_e32 v81, v86, v81
	v_mul_f32_e32 v86, v89, v92
	v_mul_f32_e32 v86, v82, v86
	v_mul_f32_e32 v82, v95, v132
	v_mul_f32_e32 v89, v91, v132
	v_mul_f32_e32 v90, 0xbfb8aa3b, v82
	v_exp_f32_e32 v90, v90
	v_mul_f32_e32 v91, 0xbfb8aa3b, v89
	v_exp_f32_e32 v91, v91
	v_cvt_pk_bf16_f32 v80, v84, v80
	v_add_f32_e32 v90, 1.0, v90
	v_rcp_f32_e32 v90, v90
	v_add_f32_e32 v91, 1.0, v91
	v_rcp_f32_e32 v91, v91
	v_add_co_u32_e32 v84, vcc, s73, v112
	v_mul_f32_e32 v82, v82, v90
	v_mul_f32_e32 v82, v87, v82
	v_mul_f32_e32 v87, v89, v91
	v_mul_f32_e32 v83, v83, v87
	v_cvt_pk_bf16_f32 v81, v81, v82
	v_cvt_pk_bf16_f32 v82, v88, v85
	v_addc_co_u32_e32 v85, vcc, 0, v113, vcc
	v_mul_f32_e32 v72, v72, v133
	v_cvt_pk_bf16_f32 v83, v86, v83
	global_store_dwordx4 v[84:85], v[80:83], off
	v_mul_f32_e32 v76, v76, v133
	v_mul_f32_e32 v64, v64, v133
	v_mul_f32_e32 v81, 0xbfb8aa3b, v72
	v_mul_f32_e32 v80, 0xbfb8aa3b, v76
	v_exp_f32_e32 v81, v81
	v_exp_f32_e32 v80, v80
	v_mul_f32_e32 v68, v68, v133
	v_mul_f32_e32 v73, v73, v133
	v_add_f32_e32 v81, 1.0, v81
	v_add_f32_e32 v80, 1.0, v80
	v_rcp_f32_e32 v81, v81
	v_rcp_f32_e32 v80, v80
	v_mul_f32_e32 v69, v69, v133
	v_mul_f32_e32 v65, v65, v133
	v_mul_f32_e32 v72, v72, v81
	v_mul_f32_e32 v76, v76, v80
	v_mul_f32_e32 v72, v64, v72
	v_mul_f32_e32 v64, v77, v133
	v_mul_f32_e32 v68, v68, v76
	v_mul_f32_e32 v76, 0xbfb8aa3b, v64
	v_exp_f32_e32 v76, v76
	v_mul_f32_e32 v77, 0xbfb8aa3b, v73
	v_exp_f32_e32 v77, v77
	v_mul_f32_e32 v70, v70, v133
	v_add_f32_e32 v76, 1.0, v76
	v_rcp_f32_e32 v76, v76
	v_add_f32_e32 v77, 1.0, v77
	v_rcp_f32_e32 v77, v77
	v_mul_f32_e32 v66, v66, v133
	v_mul_f32_e32 v64, v64, v76
	v_mul_f32_e32 v64, v69, v64
	v_mul_f32_e32 v69, v73, v77
	v_mul_f32_e32 v69, v65, v69
	v_mul_f32_e32 v65, v78, v133
	v_mul_f32_e32 v73, v74, v133
	v_mul_f32_e32 v74, 0xbfb8aa3b, v65
	v_exp_f32_e32 v74, v74
	v_mul_f32_e32 v76, 0xbfb8aa3b, v73
	v_exp_f32_e32 v76, v76
	v_mul_f32_e32 v71, v71, v133
	v_add_f32_e32 v74, 1.0, v74
	v_rcp_f32_e32 v74, v74
	v_add_f32_e32 v76, 1.0, v76
	v_rcp_f32_e32 v76, v76
	v_mul_f32_e32 v67, v67, v133
	v_mul_f32_e32 v65, v65, v74
	v_mul_f32_e32 v65, v70, v65
	v_mul_f32_e32 v70, v73, v76
	v_mul_f32_e32 v70, v66, v70
	v_mul_f32_e32 v66, v79, v133
	v_mul_f32_e32 v73, v75, v133
	v_mul_f32_e32 v74, 0xbfb8aa3b, v66
	v_exp_f32_e32 v74, v74
	v_mul_f32_e32 v75, 0xbfb8aa3b, v73
	v_exp_f32_e32 v75, v75
	v_cvt_pk_bf16_f32 v64, v68, v64
	v_add_f32_e32 v74, 1.0, v74
	v_rcp_f32_e32 v74, v74
	v_add_f32_e32 v75, 1.0, v75
	v_rcp_f32_e32 v75, v75
	v_add_co_u32_e32 v68, vcc, s69, v112
	v_mul_f32_e32 v66, v66, v74
	v_mul_f32_e32 v66, v71, v66
	v_mul_f32_e32 v71, v73, v75
	v_mul_f32_e32 v67, v67, v71
	v_cvt_pk_bf16_f32 v65, v65, v66
	v_cvt_pk_bf16_f32 v66, v72, v69
	v_addc_co_u32_e32 v69, vcc, 0, v113, vcc
	v_mul_f32_e32 v56, v56, v130
	v_cvt_pk_bf16_f32 v67, v70, v67
	global_store_dwordx4 v[68:69], v[64:67], off
	v_mul_f32_e32 v60, v60, v130
	v_mul_f32_e32 v48, v48, v130
	v_mul_f32_e32 v65, 0xbfb8aa3b, v56
	v_mul_f32_e32 v64, 0xbfb8aa3b, v60
	v_exp_f32_e32 v65, v65
	v_exp_f32_e32 v64, v64
	v_mul_f32_e32 v52, v52, v130
	v_mul_f32_e32 v57, v57, v130
	v_add_f32_e32 v65, 1.0, v65
	v_add_f32_e32 v64, 1.0, v64
	v_rcp_f32_e32 v65, v65
	v_rcp_f32_e32 v64, v64
	v_mul_f32_e32 v53, v53, v130
	v_mul_f32_e32 v49, v49, v130
	v_mul_f32_e32 v56, v56, v65
	v_mul_f32_e32 v60, v60, v64
	v_mul_f32_e32 v56, v48, v56
	v_mul_f32_e32 v48, v61, v130
	v_mul_f32_e32 v52, v52, v60
	v_mul_f32_e32 v60, 0xbfb8aa3b, v48
	v_exp_f32_e32 v60, v60
	v_mul_f32_e32 v61, 0xbfb8aa3b, v57
	v_exp_f32_e32 v61, v61
	v_mul_f32_e32 v54, v54, v130
	v_add_f32_e32 v60, 1.0, v60
	v_rcp_f32_e32 v60, v60
	v_add_f32_e32 v61, 1.0, v61
	v_rcp_f32_e32 v61, v61
	v_mul_f32_e32 v50, v50, v130
	v_mul_f32_e32 v48, v48, v60
	v_mul_f32_e32 v48, v53, v48
	v_mul_f32_e32 v53, v57, v61
	v_mul_f32_e32 v53, v49, v53
	v_mul_f32_e32 v49, v62, v130
	v_mul_f32_e32 v57, v58, v130
	v_mul_f32_e32 v58, 0xbfb8aa3b, v49
	v_exp_f32_e32 v58, v58
	v_mul_f32_e32 v60, 0xbfb8aa3b, v57
	v_exp_f32_e32 v60, v60
	v_mul_f32_e32 v55, v55, v130
	v_add_f32_e32 v58, 1.0, v58
	v_rcp_f32_e32 v58, v58
	v_add_f32_e32 v60, 1.0, v60
	v_rcp_f32_e32 v60, v60
	v_mul_f32_e32 v51, v51, v130
	v_mul_f32_e32 v49, v49, v58
	v_mul_f32_e32 v49, v54, v49
	v_mul_f32_e32 v54, v57, v60
	v_mul_f32_e32 v54, v50, v54
	v_mul_f32_e32 v50, v63, v130
	v_mul_f32_e32 v57, v59, v130
	v_mul_f32_e32 v58, 0xbfb8aa3b, v50
	v_exp_f32_e32 v58, v58
	v_mul_f32_e32 v59, 0xbfb8aa3b, v57
	v_exp_f32_e32 v59, v59
	v_cvt_pk_bf16_f32 v48, v52, v48
	v_add_f32_e32 v58, 1.0, v58
	v_rcp_f32_e32 v58, v58
	v_add_f32_e32 v59, 1.0, v59
	v_rcp_f32_e32 v59, v59
	v_add_co_u32_e32 v52, vcc, s74, v112
	v_mul_f32_e32 v50, v50, v58
	v_mul_f32_e32 v50, v55, v50
	v_mul_f32_e32 v55, v57, v59
	v_mul_f32_e32 v51, v51, v55
	v_cvt_pk_bf16_f32 v49, v49, v50
	v_cvt_pk_bf16_f32 v50, v56, v53
	v_addc_co_u32_e32 v53, vcc, 0, v113, vcc
	v_mul_f32_e32 v40, v40, v131
	v_cvt_pk_bf16_f32 v51, v54, v51
	global_store_dwordx4 v[52:53], v[48:51], off
	v_mul_f32_e32 v44, v44, v131
	v_mul_f32_e32 v32, v32, v131
	v_mul_f32_e32 v49, 0xbfb8aa3b, v40
	v_mul_f32_e32 v48, 0xbfb8aa3b, v44
	v_exp_f32_e32 v49, v49
	v_exp_f32_e32 v48, v48
	v_mul_f32_e32 v36, v36, v131
	v_mul_f32_e32 v41, v41, v131
	v_add_f32_e32 v49, 1.0, v49
	v_add_f32_e32 v48, 1.0, v48
	v_rcp_f32_e32 v49, v49
	v_rcp_f32_e32 v48, v48
	v_mul_f32_e32 v37, v37, v131
	v_mul_f32_e32 v33, v33, v131
	v_mul_f32_e32 v40, v40, v49
	v_mul_f32_e32 v44, v44, v48
	v_mul_f32_e32 v40, v32, v40
	v_mul_f32_e32 v32, v45, v131
	v_mul_f32_e32 v36, v36, v44
	v_mul_f32_e32 v44, 0xbfb8aa3b, v32
	v_exp_f32_e32 v44, v44
	v_mul_f32_e32 v45, 0xbfb8aa3b, v41
	v_exp_f32_e32 v45, v45
	v_mul_f32_e32 v38, v38, v131
	v_add_f32_e32 v44, 1.0, v44
	v_rcp_f32_e32 v44, v44
	v_add_f32_e32 v45, 1.0, v45
	v_rcp_f32_e32 v45, v45
	v_mul_f32_e32 v34, v34, v131
	v_mul_f32_e32 v32, v32, v44
	v_mul_f32_e32 v32, v37, v32
	v_mul_f32_e32 v37, v41, v45
	v_mul_f32_e32 v37, v33, v37
	v_mul_f32_e32 v33, v46, v131
	v_mul_f32_e32 v41, v42, v131
	v_mul_f32_e32 v42, 0xbfb8aa3b, v33
	v_exp_f32_e32 v42, v42
	v_mul_f32_e32 v44, 0xbfb8aa3b, v41
	v_exp_f32_e32 v44, v44
	v_mul_f32_e32 v39, v39, v131
	v_add_f32_e32 v42, 1.0, v42
	v_rcp_f32_e32 v42, v42
	v_add_f32_e32 v44, 1.0, v44
	v_rcp_f32_e32 v44, v44
	v_mul_f32_e32 v35, v35, v131
	v_mul_f32_e32 v33, v33, v42
	v_mul_f32_e32 v33, v38, v33
	v_mul_f32_e32 v38, v41, v44
	v_mul_f32_e32 v38, v34, v38
	v_mul_f32_e32 v34, v47, v131
	v_mul_f32_e32 v41, v43, v131
	v_mul_f32_e32 v42, 0xbfb8aa3b, v34
	v_exp_f32_e32 v42, v42
	v_mul_f32_e32 v43, 0xbfb8aa3b, v41
	v_exp_f32_e32 v43, v43
	v_cvt_pk_bf16_f32 v32, v36, v32
	v_add_f32_e32 v42, 1.0, v42
	v_rcp_f32_e32 v42, v42
	v_add_f32_e32 v43, 1.0, v43
	v_rcp_f32_e32 v43, v43
	v_add_co_u32_e32 v36, vcc, s75, v112
	v_mul_f32_e32 v34, v34, v42
	v_mul_f32_e32 v34, v39, v34
	v_mul_f32_e32 v39, v41, v43
	v_mul_f32_e32 v35, v35, v39
	v_cvt_pk_bf16_f32 v33, v33, v34
	v_cvt_pk_bf16_f32 v34, v40, v37
	v_addc_co_u32_e32 v37, vcc, 0, v113, vcc
	v_mul_f32_e32 v24, v24, v128
	v_cvt_pk_bf16_f32 v35, v38, v35
	global_store_dwordx4 v[36:37], v[32:35], off
	v_mul_f32_e32 v28, v28, v128
	v_mul_f32_e32 v16, v16, v128
	v_mul_f32_e32 v33, 0xbfb8aa3b, v24
	v_mul_f32_e32 v32, 0xbfb8aa3b, v28
	v_exp_f32_e32 v33, v33
	v_exp_f32_e32 v32, v32
	v_mul_f32_e32 v20, v20, v128
	v_mul_f32_e32 v25, v25, v128
	v_add_f32_e32 v33, 1.0, v33
	v_add_f32_e32 v32, 1.0, v32
	v_rcp_f32_e32 v33, v33
	v_rcp_f32_e32 v32, v32
	v_mul_f32_e32 v21, v21, v128
	v_mul_f32_e32 v17, v17, v128
	v_mul_f32_e32 v24, v24, v33
	v_mul_f32_e32 v28, v28, v32
	v_mul_f32_e32 v24, v16, v24
	v_mul_f32_e32 v16, v29, v128
	v_mul_f32_e32 v20, v20, v28
	v_mul_f32_e32 v28, 0xbfb8aa3b, v16
	v_exp_f32_e32 v28, v28
	v_mul_f32_e32 v29, 0xbfb8aa3b, v25
	v_exp_f32_e32 v29, v29
	v_mul_f32_e32 v22, v22, v128
	v_add_f32_e32 v28, 1.0, v28
	v_rcp_f32_e32 v28, v28
	v_add_f32_e32 v29, 1.0, v29
	v_rcp_f32_e32 v29, v29
	v_mul_f32_e32 v18, v18, v128
	v_mul_f32_e32 v16, v16, v28
	v_mul_f32_e32 v16, v21, v16
	v_mul_f32_e32 v21, v25, v29
	v_mul_f32_e32 v21, v17, v21
	v_mul_f32_e32 v17, v30, v128
	v_mul_f32_e32 v25, v26, v128
	v_mul_f32_e32 v26, 0xbfb8aa3b, v17
	v_exp_f32_e32 v26, v26
	v_mul_f32_e32 v28, 0xbfb8aa3b, v25
	v_exp_f32_e32 v28, v28
	v_mul_f32_e32 v23, v23, v128
	v_add_f32_e32 v26, 1.0, v26
	v_rcp_f32_e32 v26, v26
	v_add_f32_e32 v28, 1.0, v28
	v_rcp_f32_e32 v28, v28
	v_mul_f32_e32 v19, v19, v128
	v_mul_f32_e32 v17, v17, v26
	v_mul_f32_e32 v17, v22, v17
	v_mul_f32_e32 v22, v25, v28
	v_mul_f32_e32 v22, v18, v22
	v_mul_f32_e32 v18, v31, v128
	v_mul_f32_e32 v25, v27, v128
	v_mul_f32_e32 v26, 0xbfb8aa3b, v18
	v_exp_f32_e32 v26, v26
	v_mul_f32_e32 v27, 0xbfb8aa3b, v25
	v_exp_f32_e32 v27, v27
	v_cvt_pk_bf16_f32 v16, v20, v16
	v_add_f32_e32 v26, 1.0, v26
	v_rcp_f32_e32 v26, v26
	v_add_f32_e32 v27, 1.0, v27
	v_rcp_f32_e32 v27, v27
	v_add_co_u32_e32 v20, vcc, s80, v112
	v_mul_f32_e32 v18, v18, v26
	v_mul_f32_e32 v18, v23, v18
	v_mul_f32_e32 v23, v25, v27
	v_mul_f32_e32 v19, v19, v23
	v_cvt_pk_bf16_f32 v17, v17, v18
	v_cvt_pk_bf16_f32 v18, v24, v21
	v_addc_co_u32_e32 v21, vcc, 0, v113, vcc
	v_mul_f32_e32 v8, v8, v129
	v_cvt_pk_bf16_f32 v19, v22, v19
	global_store_dwordx4 v[20:21], v[16:19], off
	v_mul_f32_e32 v12, v12, v129
	v_mul_f32_e32 v0, v0, v129
	v_mul_f32_e32 v17, 0xbfb8aa3b, v8
	v_mul_f32_e32 v16, 0xbfb8aa3b, v12
	v_exp_f32_e32 v17, v17
	v_exp_f32_e32 v16, v16
	v_mul_f32_e32 v4, v4, v129
	v_mul_f32_e32 v9, v9, v129
	v_add_f32_e32 v17, 1.0, v17
	v_add_f32_e32 v16, 1.0, v16
	v_rcp_f32_e32 v17, v17
	v_rcp_f32_e32 v16, v16
	v_mul_f32_e32 v5, v5, v129
	v_mul_f32_e32 v1, v1, v129
	v_mul_f32_e32 v8, v8, v17
	v_mul_f32_e32 v12, v12, v16
	v_mul_f32_e32 v8, v0, v8
	v_mul_f32_e32 v0, v13, v129
	v_mul_f32_e32 v4, v4, v12
	v_mul_f32_e32 v12, 0xbfb8aa3b, v0
	v_exp_f32_e32 v12, v12
	v_mul_f32_e32 v13, 0xbfb8aa3b, v9
	v_exp_f32_e32 v13, v13
	v_mul_f32_e32 v6, v6, v129
	v_add_f32_e32 v12, 1.0, v12
	v_rcp_f32_e32 v12, v12
	v_add_f32_e32 v13, 1.0, v13
	v_rcp_f32_e32 v13, v13
	v_mul_f32_e32 v2, v2, v129
	v_mul_f32_e32 v0, v0, v12
	v_mul_f32_e32 v0, v5, v0
	v_mul_f32_e32 v5, v9, v13
	v_mul_f32_e32 v5, v1, v5
	v_mul_f32_e32 v1, v14, v129
	v_mul_f32_e32 v9, v10, v129
	v_mul_f32_e32 v10, 0xbfb8aa3b, v1
	v_exp_f32_e32 v10, v10
	v_mul_f32_e32 v12, 0xbfb8aa3b, v9
	v_exp_f32_e32 v12, v12
	v_mul_f32_e32 v7, v7, v129
	v_add_f32_e32 v10, 1.0, v10
	v_rcp_f32_e32 v10, v10
	v_add_f32_e32 v12, 1.0, v12
	v_rcp_f32_e32 v12, v12
	v_mul_f32_e32 v3, v3, v129
	v_mul_f32_e32 v1, v1, v10
	v_mul_f32_e32 v1, v6, v1
	v_mul_f32_e32 v6, v9, v12
	v_mul_f32_e32 v6, v2, v6
	v_mul_f32_e32 v2, v15, v129
	v_mul_f32_e32 v9, v11, v129
	v_mul_f32_e32 v10, 0xbfb8aa3b, v2
	v_exp_f32_e32 v10, v10
	v_mul_f32_e32 v11, 0xbfb8aa3b, v9
	v_exp_f32_e32 v11, v11
	v_cvt_pk_bf16_f32 v0, v4, v0
	v_add_f32_e32 v10, 1.0, v10
	v_rcp_f32_e32 v10, v10
	v_add_f32_e32 v11, 1.0, v11
	v_rcp_f32_e32 v11, v11
	v_add_co_u32_e32 v4, vcc, 0xf2000, v112
	v_mul_f32_e32 v2, v2, v10
	v_mul_f32_e32 v2, v7, v2
	v_mul_f32_e32 v7, v9, v11
	v_mul_f32_e32 v3, v3, v7
	v_cvt_pk_bf16_f32 v1, v1, v2
	v_cvt_pk_bf16_f32 v2, v8, v5
	v_addc_co_u32_e32 v5, vcc, 0, v113, vcc
	v_cvt_pk_bf16_f32 v3, v6, v3
	global_store_dwordx4 v[4:5], v[0:3], off
	s_branch .LBB0_1723

.LBB0_1899:
	s_ashr_i32 s13, s13, 3
	s_add_i32 s13, s14, s13
	s_ashr_i32 s14, s13, 31
	s_lshr_b32 s14, s14, 27
	s_add_i32 s14, s13, s14
	s_ashr_i32 s15, s14, 5
	s_lshl_b32 s15, s15, 3
	s_sub_i32 s16, 0x80, s15
	s_min_i32 s16, s16, 8
	s_abs_i32 s16, s16
	v_cvt_f32_u32_e32 v7, s16
	s_sub_i32 s17, 0, s16
	s_andn2_b32 s14, s14, 31
	s_sub_i32 s13, s13, s14
	v_rcp_iflag_f32_e32 v7, v7
	s_ashr_i32 s14, s13, 31
	s_abs_i32 s13, s13
	v_mul_f32_e32 v7, 0x4f7ffffe, v7
	v_cvt_u32_f32_e32 v7, v7
	s_nop 0
	v_readfirstlane_b32 s18, v7
	s_mul_i32 s17, s17, s18
	s_mul_hi_u32 s17, s18, s17
	s_add_i32 s18, s18, s17
	s_mul_hi_u32 s17, s13, s18
	s_mul_i32 s17, s17, s16
	s_sub_i32 s13, s13, s17
	s_sub_i32 s17, s13, s16
	s_cmp_ge_u32 s13, s16
	s_cselect_b32 s13, s17, s13
	s_sub_i32 s17, s13, s16
	s_cmp_ge_u32 s13, s16
	s_cselect_b32 s13, s17, s13
	s_xor_b32 s13, s13, s14
	s_sub_i32 s13, s13, s14
	s_add_i32 s14, s13, s15
	s_ashr_i32 s15, s14, 31
	s_lshl_b64 s[14:15], s[14:15], 14
	v_lshl_add_u64 v[26:27], v[2:3], 0, s[14:15]
	s_waitcnt vmcnt(0)
	global_load_dwordx4 v[8:11], v[26:27], off
	global_load_dwordx4 v[14:17], v[26:27], off offset:16
	global_load_dwordx4 v[18:21], v[26:27], off offset:32
	global_load_dwordx4 v[22:25], v[26:27], off offset:48
	s_waitcnt vmcnt(0) lgkmcnt(0)
	v_mov_b32_e32 v26, v9
	v_mov_b32_e32 v27, v10
	v_mov_b32_e32 v28, v15
	v_mov_b32_e32 v29, v16
	v_mov_b32_e32 v9, v11
	v_mov_b32_e32 v15, v17
	v_mov_b32_e32 v10, v19
	v_mov_b32_e32 v16, v21
	v_pk_add_f32 v[8:9], v[26:27], v[8:9]
	v_pk_add_f32 v[14:15], v[28:29], v[14:15]
	v_pk_add_f32 v[10:11], v[18:19], v[10:11]
	v_pk_add_f32 v[16:17], v[20:21], v[16:17]
	v_pk_add_f32 v[8:9], v[8:9], v[8:9] op_sel:[0,1] op_sel_hi:[1,0]
	v_pk_add_f32 v[14:15], v[14:15], v[14:15] op_sel:[0,1] op_sel_hi:[1,0]
	v_mov_b32_e32 v11, v24
	v_mov_b32_e32 v17, v25
	v_mov_b32_e32 v9, v22
	v_mov_b32_e32 v15, v23
	v_pk_add_f32 v[10:11], v[10:11], v[16:17]
	v_pk_add_f32 v[8:9], v[8:9], v[14:15]
	s_nop 0
	v_pk_add_f32 v[8:9], v[8:9], v[10:11]
	s_nop 0
	v_add_f32_e32 v7, v8, v9
	v_fmamk_f32 v7, v7, 0x3a800000, v6
	v_mul_f32_e32 v8, 0x4b800000, v7
	v_cmp_gt_f32_e32 vcc, s12, v7
	s_nop 1
	v_cndmask_b32_e32 v7, v7, v8, vcc
	v_rsq_f32_e32 v7, v7
	s_nop 0
	v_mul_f32_e32 v8, 0x45800000, v7
	v_cndmask_b32_e32 v7, v7, v8, vcc
	ds_write_b32 v1, v7
	s_branch .LBB0_1891

.LBB0_1915:
	ds_read_b128 v[148:151], v168
	ds_read_b128 v[152:155], v169
	ds_read_b128 v[156:159], v170
	ds_read_b128 v[160:163], v171
	s_add_u32 s22, s20, 0xfffc0080
	s_addc_u32 s23, s21, -1
	s_cmp_eq_u32 s67, 12
	s_cselect_b32 s25, s13, s23
	s_cselect_b32 s24, s63, s22
	s_cselect_b32 s23, s11, s66
	s_cselect_b32 s22, s64, s65
	s_mov_b32 m0, s9
	v_lshl_add_u64 v[164:165], s[20:21], 0, v[142:143]
	ds_read_b128 v[190:193], v166
	ds_read_b128 v[194:197], v166 offset:1024
	ds_read_b128 v[198:201], v166 offset:2048
	ds_read_b128 v[202:205], v166 offset:3072
	ds_read_b128 v[206:209], v166 offset:4096
	ds_read_b128 v[210:213], v166 offset:5120
	ds_read_b128 v[214:217], v166 offset:6144
	ds_read_b128 v[218:221], v166 offset:7168
	global_load_lds_dwordx4 v[164:165], off
	v_lshl_add_u64 v[164:165], s[20:21], 0, v[140:141]
	s_mov_b32 m0, s55
	s_nop 0
	global_load_lds_dwordx4 v[164:165], off
	s_waitcnt lgkmcnt(8)
	s_barrier
	s_waitcnt lgkmcnt(0)
	s_setprio 1
	s_waitcnt lgkmcnt(0)
	v_mfma_f32_16x16x32_bf16 v[124:127], v[148:151], v[190:193], v[124:127]
	v_mfma_f32_16x16x32_bf16 v[120:123], v[156:159], v[190:193], v[120:123]
	v_mfma_f32_16x16x32_bf16 v[112:115], v[148:151], v[198:201], v[112:115]
	v_mfma_f32_16x16x32_bf16 v[104:107], v[156:159], v[198:201], v[104:107]
	v_mfma_f32_16x16x32_bf16 v[96:99], v[148:151], v[206:209], v[96:99]
	v_mfma_f32_16x16x32_bf16 v[88:91], v[156:159], v[206:209], v[88:91]
	v_mfma_f32_16x16x32_bf16 v[80:83], v[148:151], v[214:217], v[80:83]
	v_mfma_f32_16x16x32_bf16 v[72:75], v[156:159], v[214:217], v[72:75]
	v_mfma_f32_16x16x32_bf16 v[124:127], v[152:155], v[194:197], v[124:127]
	v_mfma_f32_16x16x32_bf16 v[120:123], v[160:163], v[194:197], v[120:123]
	v_mfma_f32_16x16x32_bf16 v[112:115], v[152:155], v[202:205], v[112:115]
	v_mfma_f32_16x16x32_bf16 v[104:107], v[160:163], v[202:205], v[104:107]
	v_mfma_f32_16x16x32_bf16 v[96:99], v[152:155], v[210:213], v[96:99]
	v_mfma_f32_16x16x32_bf16 v[88:91], v[160:163], v[210:213], v[88:91]
	v_mfma_f32_16x16x32_bf16 v[80:83], v[152:155], v[218:221], v[80:83]
	v_mfma_f32_16x16x32_bf16 v[72:75], v[160:163], v[218:221], v[72:75]
	s_setprio 0
	s_barrier
	s_mov_b32 m0, s35
	v_lshl_add_u64 v[164:165], s[22:23], 0, v[130:131]
	ds_read_b128 v[222:225], v172
	ds_read_b128 v[226:229], v173
	ds_read_b128 v[230:233], v174
	ds_read_b128 v[234:237], v175
	global_load_lds_dwordx4 v[164:165], off
	v_lshl_add_u64 v[238:239], s[22:23], 0, v[134:135]
	s_mov_b32 m0, s36
	s_nop 0
	global_load_lds_dwordx4 v[238:239], off
	s_barrier
	s_waitcnt lgkmcnt(0)
	s_setprio 1
	s_waitcnt lgkmcnt(0)
	v_mfma_f32_16x16x32_bf16 v[116:119], v[222:225], v[190:193], v[116:119]
	v_mfma_f32_16x16x32_bf16 v[108:111], v[230:233], v[190:193], v[108:111]
	v_mfma_f32_16x16x32_bf16 v[100:103], v[222:225], v[198:201], v[100:103]
	v_mfma_f32_16x16x32_bf16 v[92:95], v[230:233], v[198:201], v[92:95]
	v_mfma_f32_16x16x32_bf16 v[84:87], v[222:225], v[206:209], v[84:87]
	v_mfma_f32_16x16x32_bf16 v[76:79], v[230:233], v[206:209], v[76:79]
	v_mfma_f32_16x16x32_bf16 v[68:71], v[222:225], v[214:217], v[68:71]
	v_mfma_f32_16x16x32_bf16 v[64:67], v[230:233], v[214:217], v[64:67]
	v_mfma_f32_16x16x32_bf16 v[116:119], v[226:229], v[194:197], v[116:119]
	v_mfma_f32_16x16x32_bf16 v[108:111], v[234:237], v[194:197], v[108:111]
	v_mfma_f32_16x16x32_bf16 v[100:103], v[226:229], v[202:205], v[100:103]
	v_mfma_f32_16x16x32_bf16 v[92:95], v[234:237], v[202:205], v[92:95]
	v_mfma_f32_16x16x32_bf16 v[84:87], v[226:229], v[210:213], v[84:87]
	v_mfma_f32_16x16x32_bf16 v[76:79], v[234:237], v[210:213], v[76:79]
	v_mfma_f32_16x16x32_bf16 v[68:71], v[226:229], v[218:221], v[68:71]
	v_mfma_f32_16x16x32_bf16 v[64:67], v[234:237], v[218:221], v[64:67]
	s_setprio 0
	s_mov_b32 m0, s31
	v_lshl_add_u64 v[240:241], s[24:25], 0, v[128:129]
	s_barrier
	ds_read_b128 v[190:193], v166 offset:16384
	ds_read_b128 v[194:197], v166 offset:17408
	ds_read_b128 v[198:201], v166 offset:18432
	ds_read_b128 v[202:205], v166 offset:19456
	ds_read_b128 v[206:209], v166 offset:20480
	ds_read_b128 v[210:213], v166 offset:21504
	ds_read_b128 v[214:217], v166 offset:22528
	ds_read_b128 v[218:221], v166 offset:23552
	global_load_lds_dwordx4 v[240:241], off
	v_lshl_add_u64 v[242:243], s[24:25], 0, v[132:133]
	s_mov_b32 m0, s37
	s_nop 0
	global_load_lds_dwordx4 v[242:243], off
	s_barrier
	s_waitcnt lgkmcnt(0)
	s_setprio 1
	s_waitcnt lgkmcnt(0)
	v_mfma_f32_16x16x32_bf16 v[60:63], v[148:151], v[190:193], v[60:63]
	v_mfma_f32_16x16x32_bf16 v[56:59], v[156:159], v[190:193], v[56:59]
	v_mfma_f32_16x16x32_bf16 v[48:51], v[148:151], v[198:201], v[48:51]
	v_mfma_f32_16x16x32_bf16 v[40:43], v[156:159], v[198:201], v[40:43]
	v_mfma_f32_16x16x32_bf16 v[32:35], v[148:151], v[206:209], v[32:35]
	v_mfma_f32_16x16x32_bf16 v[24:27], v[156:159], v[206:209], v[24:27]
	v_mfma_f32_16x16x32_bf16 v[16:19], v[148:151], v[214:217], v[16:19]
	v_mfma_f32_16x16x32_bf16 v[8:11], v[156:159], v[214:217], v[8:11]
	v_mfma_f32_16x16x32_bf16 v[60:63], v[152:155], v[194:197], v[60:63]
	v_mfma_f32_16x16x32_bf16 v[56:59], v[160:163], v[194:197], v[56:59]
	v_mfma_f32_16x16x32_bf16 v[48:51], v[152:155], v[202:205], v[48:51]
	v_mfma_f32_16x16x32_bf16 v[40:43], v[160:163], v[202:205], v[40:43]
	v_mfma_f32_16x16x32_bf16 v[32:35], v[152:155], v[210:213], v[32:35]
	v_mfma_f32_16x16x32_bf16 v[24:27], v[160:163], v[210:213], v[24:27]
	v_mfma_f32_16x16x32_bf16 v[16:19], v[152:155], v[218:221], v[16:19]
	v_mfma_f32_16x16x32_bf16 v[8:11], v[160:163], v[218:221], v[8:11]
	s_setprio 0
	s_barrier
	s_add_u32 s68, s22, 0x40000
	s_addc_u32 s69, s23, 0
	s_mov_b32 m0, s38
	v_lshl_add_u64 v[148:149], s[68:69], 0, v[130:131]
	global_load_lds_dwordx4 v[148:149], off
	v_lshl_add_u64 v[148:149], s[68:69], 0, v[134:135]
	s_mov_b32 m0, s39
	s_nop 0
	global_load_lds_dwordx4 v[148:149], off
	s_waitcnt vmcnt(6)
	s_barrier
	s_setprio 1
	v_mfma_f32_16x16x32_bf16 v[52:55], v[222:225], v[190:193], v[52:55]
	v_mfma_f32_16x16x32_bf16 v[44:47], v[230:233], v[190:193], v[44:47]
	v_mfma_f32_16x16x32_bf16 v[36:39], v[222:225], v[198:201], v[36:39]
	v_mfma_f32_16x16x32_bf16 v[28:31], v[230:233], v[198:201], v[28:31]
	v_mfma_f32_16x16x32_bf16 v[20:23], v[222:225], v[206:209], v[20:23]
	v_mfma_f32_16x16x32_bf16 v[12:15], v[230:233], v[206:209], v[12:15]
	v_mfma_f32_16x16x32_bf16 v[4:7], v[222:225], v[214:217], v[4:7]
	v_mfma_f32_16x16x32_bf16 v[0:3], v[230:233], v[214:217], v[0:3]
	v_mfma_f32_16x16x32_bf16 v[52:55], v[226:229], v[194:197], v[52:55]
	v_mfma_f32_16x16x32_bf16 v[44:47], v[234:237], v[194:197], v[44:47]
	v_mfma_f32_16x16x32_bf16 v[36:39], v[226:229], v[202:205], v[36:39]
	v_mfma_f32_16x16x32_bf16 v[28:31], v[234:237], v[202:205], v[28:31]
	v_mfma_f32_16x16x32_bf16 v[20:23], v[226:229], v[210:213], v[20:23]
	v_mfma_f32_16x16x32_bf16 v[12:15], v[234:237], v[210:213], v[12:15]
	v_mfma_f32_16x16x32_bf16 v[4:7], v[226:229], v[218:221], v[4:7]
	v_mfma_f32_16x16x32_bf16 v[0:3], v[234:237], v[218:221], v[0:3]
	s_setprio 0
	s_barrier
	ds_read_b128 v[148:151], v177
	ds_read_b128 v[152:155], v178
	ds_read_b128 v[156:159], v180
	ds_read_b128 v[160:163], v181
	s_add_u32 s24, s24, 0x40000
	s_addc_u32 s25, s25, 0
	s_mov_b32 m0, s40
	v_lshl_add_u64 v[222:223], s[24:25], 0, v[128:129]
	ds_read_b128 v[190:193], v166 offset:32768
	ds_read_b128 v[194:197], v166 offset:33792
	ds_read_b128 v[198:201], v166 offset:34816
	ds_read_b128 v[202:205], v166 offset:35840
	ds_read_b128 v[206:209], v166 offset:36864
	ds_read_b128 v[210:213], v166 offset:37888
	ds_read_b128 v[214:217], v166 offset:38912
	ds_read_b128 v[218:221], v166 offset:39936
	global_load_lds_dwordx4 v[222:223], off
	v_lshl_add_u64 v[222:223], s[24:25], 0, v[132:133]
	s_mov_b32 m0, s41
	s_nop 0
	global_load_lds_dwordx4 v[222:223], off
	s_waitcnt lgkmcnt(8)
	s_barrier
	s_waitcnt lgkmcnt(0)
	s_setprio 1
	s_waitcnt lgkmcnt(0)
	v_mfma_f32_16x16x32_bf16 v[124:127], v[148:151], v[190:193], v[124:127]
	v_mfma_f32_16x16x32_bf16 v[120:123], v[156:159], v[190:193], v[120:123]
	v_mfma_f32_16x16x32_bf16 v[112:115], v[148:151], v[198:201], v[112:115]
	v_mfma_f32_16x16x32_bf16 v[104:107], v[156:159], v[198:201], v[104:107]
	v_mfma_f32_16x16x32_bf16 v[96:99], v[148:151], v[206:209], v[96:99]
	v_mfma_f32_16x16x32_bf16 v[88:91], v[156:159], v[206:209], v[88:91]
	v_mfma_f32_16x16x32_bf16 v[80:83], v[148:151], v[214:217], v[80:83]
	v_mfma_f32_16x16x32_bf16 v[72:75], v[156:159], v[214:217], v[72:75]
	v_mfma_f32_16x16x32_bf16 v[124:127], v[152:155], v[194:197], v[124:127]
	v_mfma_f32_16x16x32_bf16 v[120:123], v[160:163], v[194:197], v[120:123]
	v_mfma_f32_16x16x32_bf16 v[112:115], v[152:155], v[202:205], v[112:115]
	v_mfma_f32_16x16x32_bf16 v[104:107], v[160:163], v[202:205], v[104:107]
	v_mfma_f32_16x16x32_bf16 v[96:99], v[152:155], v[210:213], v[96:99]
	v_mfma_f32_16x16x32_bf16 v[88:91], v[160:163], v[210:213], v[88:91]
	v_mfma_f32_16x16x32_bf16 v[80:83], v[152:155], v[218:221], v[80:83]
	v_mfma_f32_16x16x32_bf16 v[72:75], v[160:163], v[218:221], v[72:75]
	s_setprio 0
	s_barrier
	s_mov_b32 m0, s45
	v_lshl_add_u64 v[164:165], v[164:165], 0, s[4:5]
	ds_read_b128 v[222:225], v182
	ds_read_b128 v[226:229], v183
	ds_read_b128 v[230:233], v184
	ds_read_b128 v[234:237], v185
	global_load_lds_dwordx4 v[164:165], off
	v_lshl_add_u64 v[164:165], v[238:239], 0, s[4:5]
	s_mov_b32 m0, s46
	s_nop 0
	global_load_lds_dwordx4 v[164:165], off
	s_barrier
	s_waitcnt lgkmcnt(0)
	s_setprio 1
	s_waitcnt lgkmcnt(0)
	v_mfma_f32_16x16x32_bf16 v[116:119], v[222:225], v[190:193], v[116:119]
	v_mfma_f32_16x16x32_bf16 v[108:111], v[230:233], v[190:193], v[108:111]
	v_mfma_f32_16x16x32_bf16 v[100:103], v[222:225], v[198:201], v[100:103]
	v_mfma_f32_16x16x32_bf16 v[92:95], v[230:233], v[198:201], v[92:95]
	v_mfma_f32_16x16x32_bf16 v[84:87], v[222:225], v[206:209], v[84:87]
	v_mfma_f32_16x16x32_bf16 v[76:79], v[230:233], v[206:209], v[76:79]
	v_mfma_f32_16x16x32_bf16 v[68:71], v[222:225], v[214:217], v[68:71]
	v_mfma_f32_16x16x32_bf16 v[64:67], v[230:233], v[214:217], v[64:67]
	v_mfma_f32_16x16x32_bf16 v[116:119], v[226:229], v[194:197], v[116:119]
	v_mfma_f32_16x16x32_bf16 v[108:111], v[234:237], v[194:197], v[108:111]
	v_mfma_f32_16x16x32_bf16 v[100:103], v[226:229], v[202:205], v[100:103]
	v_mfma_f32_16x16x32_bf16 v[92:95], v[234:237], v[202:205], v[92:95]
	v_mfma_f32_16x16x32_bf16 v[84:87], v[226:229], v[210:213], v[84:87]
	v_mfma_f32_16x16x32_bf16 v[76:79], v[234:237], v[210:213], v[76:79]
	v_mfma_f32_16x16x32_bf16 v[68:71], v[226:229], v[218:221], v[68:71]
	v_mfma_f32_16x16x32_bf16 v[64:67], v[234:237], v[218:221], v[64:67]
	s_setprio 0
	s_mov_b32 m0, s47
	v_lshl_add_u64 v[164:165], v[240:241], 0, s[4:5]
	s_barrier
	ds_read_b128 v[190:193], v166 offset:49152
	ds_read_b128 v[194:197], v166 offset:50176
	ds_read_b128 v[198:201], v166 offset:51200
	ds_read_b128 v[202:205], v166 offset:52224
	ds_read_b128 v[206:209], v166 offset:53248
	ds_read_b128 v[210:213], v166 offset:54272
	ds_read_b128 v[214:217], v166 offset:55296
	ds_read_b128 v[218:221], v166 offset:56320
	global_load_lds_dwordx4 v[164:165], off
	v_lshl_add_u64 v[164:165], v[242:243], 0, s[4:5]
	s_mov_b32 m0, s48
	s_nop 0
	global_load_lds_dwordx4 v[164:165], off
	s_barrier
	s_waitcnt lgkmcnt(0)
	s_setprio 1
	s_waitcnt lgkmcnt(0)
	v_mfma_f32_16x16x32_bf16 v[60:63], v[148:151], v[190:193], v[60:63]
	v_mfma_f32_16x16x32_bf16 v[56:59], v[156:159], v[190:193], v[56:59]
	v_mfma_f32_16x16x32_bf16 v[48:51], v[148:151], v[198:201], v[48:51]
	v_mfma_f32_16x16x32_bf16 v[40:43], v[156:159], v[198:201], v[40:43]
	v_mfma_f32_16x16x32_bf16 v[32:35], v[148:151], v[206:209], v[32:35]
	v_mfma_f32_16x16x32_bf16 v[24:27], v[156:159], v[206:209], v[24:27]
	v_mfma_f32_16x16x32_bf16 v[16:19], v[148:151], v[214:217], v[16:19]
	v_mfma_f32_16x16x32_bf16 v[8:11], v[156:159], v[214:217], v[8:11]
	v_mfma_f32_16x16x32_bf16 v[60:63], v[152:155], v[194:197], v[60:63]
	v_mfma_f32_16x16x32_bf16 v[56:59], v[160:163], v[194:197], v[56:59]
	v_mfma_f32_16x16x32_bf16 v[48:51], v[152:155], v[202:205], v[48:51]
	v_mfma_f32_16x16x32_bf16 v[40:43], v[160:163], v[202:205], v[40:43]
	v_mfma_f32_16x16x32_bf16 v[32:35], v[152:155], v[210:213], v[32:35]
	v_mfma_f32_16x16x32_bf16 v[24:27], v[160:163], v[210:213], v[24:27]
	v_mfma_f32_16x16x32_bf16 v[16:19], v[152:155], v[218:221], v[16:19]
	v_mfma_f32_16x16x32_bf16 v[8:11], v[160:163], v[218:221], v[8:11]
	s_setprio 0
	s_barrier
	s_add_u32 s22, s22, 0x40080
	s_addc_u32 s23, s23, 0
	s_mov_b32 m0, s49
	v_lshl_add_u64 v[148:149], s[22:23], 0, v[130:131]
	global_load_lds_dwordx4 v[148:149], off
	v_lshl_add_u64 v[148:149], s[22:23], 0, v[134:135]
	s_mov_b32 m0, s52
	s_nop 0
	global_load_lds_dwordx4 v[148:149], off
	s_waitcnt vmcnt(6)
	s_barrier
	s_setprio 1
	v_mfma_f32_16x16x32_bf16 v[52:55], v[222:225], v[190:193], v[52:55]
	v_mfma_f32_16x16x32_bf16 v[44:47], v[230:233], v[190:193], v[44:47]
	v_mfma_f32_16x16x32_bf16 v[36:39], v[222:225], v[198:201], v[36:39]
	v_mfma_f32_16x16x32_bf16 v[28:31], v[230:233], v[198:201], v[28:31]
	v_mfma_f32_16x16x32_bf16 v[20:23], v[222:225], v[206:209], v[20:23]
	v_mfma_f32_16x16x32_bf16 v[12:15], v[230:233], v[206:209], v[12:15]
	v_mfma_f32_16x16x32_bf16 v[4:7], v[222:225], v[214:217], v[4:7]
	v_mfma_f32_16x16x32_bf16 v[0:3], v[230:233], v[214:217], v[0:3]
	v_mfma_f32_16x16x32_bf16 v[52:55], v[226:229], v[194:197], v[52:55]
	v_mfma_f32_16x16x32_bf16 v[44:47], v[234:237], v[194:197], v[44:47]
	v_mfma_f32_16x16x32_bf16 v[36:39], v[226:229], v[202:205], v[36:39]
	v_mfma_f32_16x16x32_bf16 v[28:31], v[234:237], v[202:205], v[28:31]
	v_mfma_f32_16x16x32_bf16 v[20:23], v[226:229], v[210:213], v[20:23]
	v_mfma_f32_16x16x32_bf16 v[12:15], v[234:237], v[210:213], v[12:15]
	v_mfma_f32_16x16x32_bf16 v[4:7], v[226:229], v[218:221], v[4:7]
	v_mfma_f32_16x16x32_bf16 v[0:3], v[234:237], v[218:221], v[0:3]
	s_setprio 0
	s_add_i32 s67, s67, 2
	s_add_u32 s65, s65, 0x100
	s_addc_u32 s66, s66, 0
	s_add_u32 s20, s20, 0x100
	s_addc_u32 s21, s21, 0
	s_cmp_gt_u32 s67, 13
	s_barrier
	s_cbranch_scc0 .LBB0_1915
	v_readlane_b32 s12, v253, 40
	s_cmp_lt_i32 s75, 3
	v_readlane_b32 s20, v253, 48
	v_readlane_b32 s21, v253, 49
	v_readlane_b32 s22, v253, 50
	v_readlane_b32 s23, v253, 51
	s_cselect_b32 s21, s23, s44
	s_cselect_b32 s20, s22, s43
	s_nop 0
	global_load_dwordx4 v[154:157], v186, s[20:21]
	global_load_dwordx4 v[192:195], v186, s[20:21] offset:16
	global_load_dwordx4 v[196:199], v186, s[20:21] offset:128
	global_load_dwordx4 v[200:203], v186, s[20:21] offset:144
	v_mov_b32_e32 v150, v125
	v_mov_b32_e32 v151, v121
	v_mov_b32_e32 v148, v124
	v_mov_b32_e32 v149, v120
	v_mov_b32_e32 v162, v117
	v_mov_b32_e32 v163, v109
	v_pk_mul_f32 v[150:151], v[150:151], v[150:151]
	v_mov_b32_e32 v152, v126
	v_mov_b32_e32 v153, v122
	v_mov_b32_e32 v160, v116
	v_mov_b32_e32 v161, v108
	v_pk_mul_f32 v[162:163], v[162:163], v[162:163]
	v_pk_fma_f32 v[148:149], v[148:149], v[148:149], v[150:151]
	v_and_b32_e32 v204, 64, v187
	v_mov_b32_e32 v158, v127
	v_mov_b32_e32 v159, v123
	v_mov_b32_e32 v164, v118
	v_mov_b32_e32 v165, v110
	v_pk_fma_f32 v[150:151], v[160:161], v[160:161], v[162:163]
	v_pk_fma_f32 v[148:149], v[152:153], v[152:153], v[148:149]
	v_xor_b32_e32 v189, 16, v187
	v_mov_b32_e32 v190, v119
	v_mov_b32_e32 v191, v111
	v_add_u32_e32 v204, 64, v204
	v_pk_fma_f32 v[150:151], v[164:165], v[164:165], v[150:151]
	v_pk_fma_f32 v[148:149], v[158:159], v[158:159], v[148:149]
	v_cmp_lt_i32_e32 vcc, v189, v204
	v_pk_fma_f32 v[150:151], v[190:191], v[190:191], v[150:151]
	v_add_f32_e32 v148, v148, v149
	v_cndmask_b32_e32 v189, v187, v189, vcc
	v_add_f32_e32 v148, v148, v150
	v_lshlrev_b32_e32 v189, 2, v189
	v_add_f32_e32 v148, v148, v151
	ds_bpermute_b32 v149, v189, v148
	v_xor_b32_e32 v205, 32, v187
	v_cmp_lt_i32_e32 vcc, v205, v204
	v_lshl_add_u32 v206, s62, 10, v167
	s_waitcnt vmcnt(0)
	s_waitcnt lgkmcnt(0)
	v_add_f32_e32 v148, v148, v149
	v_cndmask_b32_e32 v150, v187, v205, vcc
	v_lshlrev_b32_e32 v190, 2, v150
	ds_bpermute_b32 v149, v190, v148
	ds_read2_b32 v[204:205], v206 offset1:16
	ds_read2_b32 v[164:165], v206 offset0:32 offset1:48
	ds_read2_b32 v[162:163], v206 offset0:128 offset1:144
	ds_read2_b32 v[152:153], v206 offset0:160 offset1:176
	s_lshl_b32 s20, s75, 8
	v_readlane_b32 s18, v253, 46
	v_readlane_b32 s19, v253, 47
	s_waitcnt lgkmcnt(0)
	v_add_f32_e32 v148, v148, v149
	v_mul_f32_e32 v148, v204, v148
	v_mul_f32_e32 v148, v204, v148
	v_fmamk_f32 v148, v148, 0x3c800000, v188
	v_mul_f32_e32 v149, 0x4b800000, v148
	v_cmp_gt_f32_e32 vcc, s56, v148
	s_ashr_i32 s75, s74, 31
	s_ashr_i32 s21, s20, 31
	v_cndmask_b32_e32 v148, v148, v149, vcc
	v_rsq_f32_e32 v150, v148
	s_lshl_b64 s[18:19], s[74:75], 19
	v_lshl_add_u64 v[148:149], s[20:21], 1, v[138:139]
	v_lshl_add_u64 v[148:149], v[148:149], 0, s[18:19]
	v_mul_f32_e32 v151, 0x45800000, v150
	v_cndmask_b32_e32 v150, v150, v151, vcc
	v_mul_f32_e32 v204, v204, v150
	v_pk_mul_f32 v[206:207], v[124:125], v[204:205] op_sel_hi:[1,0]
	v_pk_mul_f32 v[208:209], v[126:127], v[204:205] op_sel_hi:[1,0]
	v_lshl_add_u64 v[148:149], v[148:149], 0, v[136:137]
	v_pk_mul_f32 v[210:211], v[120:121], v[204:205] op_sel_hi:[1,0]
	v_pk_mul_f32 v[122:123], v[122:123], v[204:205] op_sel_hi:[1,0]
	v_pk_mul_f32 v[116:117], v[116:117], v[204:205] op_sel_hi:[1,0]
	v_pk_mul_f32 v[108:109], v[108:109], v[204:205] op_sel_hi:[1,0]
	v_pk_mul_f32 v[110:111], v[110:111], v[204:205] op_sel_hi:[1,0]
	v_pk_mul_f32 v[118:119], v[118:119], v[204:205] op_sel_hi:[1,0]
	s_mov_b32 s74, s72
	s_mov_b32 s75, s10
	s_mov_b64 s[20:21], s[70:71]
	s_mov_b64 s[22:23], s[50:51]
	s_mov_b32 s62, s61
	s_waitcnt vmcnt(0)
	v_pk_mul_f32 v[160:161], v[154:155], s[8:9] op_sel_hi:[1,0]
	v_pk_mul_f32 v[158:159], v[156:157], s[8:9] op_sel_hi:[1,0]
	v_pk_mul_f32 v[156:157], v[192:193], s[8:9] op_sel_hi:[1,0]
	v_pk_mul_f32 v[192:193], v[160:161], v[206:207]
	v_pk_mul_f32 v[154:155], v[194:195], s[8:9] op_sel_hi:[1,0]
	v_pk_mul_f32 v[194:195], v[158:159], v[208:209]
	v_cvt_pk_bf16_f32 v192, v192, v193
	v_pk_mul_f32 v[150:151], v[196:197], s[8:9] op_sel_hi:[1,0]
	v_cvt_pk_bf16_f32 v193, v194, v195
	v_pk_mul_f32 v[122:123], v[154:155], v[122:123]
	v_pk_mul_f32 v[196:197], v[156:157], v[210:211]
	v_cvt_pk_bf16_f32 v195, v122, v123
	v_mov_b32_e32 v122, v112
	v_cvt_pk_bf16_f32 v194, v196, v197
	global_store_dwordx4 v[148:149], v[192:195], off
	v_mov_b32_e32 v123, v104
	v_pk_mul_f32 v[120:121], v[202:203], s[8:9] op_sel_hi:[1,0]
	v_mov_b32_e32 v192, v113
	v_mov_b32_e32 v193, v105
	v_pk_mul_f32 v[192:193], v[192:193], v[192:193]
	v_mov_b32_e32 v194, v101
	v_pk_fma_f32 v[122:123], v[122:123], v[122:123], v[192:193]
	v_mov_b32_e32 v192, v114
	v_mov_b32_e32 v193, v106
	v_pk_fma_f32 v[122:123], v[192:193], v[192:193], v[122:123]
	v_mov_b32_e32 v192, v115
	v_mov_b32_e32 v193, v107
	v_mov_b32_e32 v195, v93
	v_pk_fma_f32 v[122:123], v[192:193], v[192:193], v[122:123]
	v_mov_b32_e32 v192, v100
	v_mov_b32_e32 v193, v92
	v_pk_mul_f32 v[194:195], v[194:195], v[194:195]
	v_add_f32_e32 v122, v122, v123
	v_pk_fma_f32 v[192:193], v[192:193], v[192:193], v[194:195]
	v_mov_b32_e32 v194, v102
	v_mov_b32_e32 v195, v94
	v_pk_fma_f32 v[192:193], v[194:195], v[194:195], v[192:193]
	v_mov_b32_e32 v194, v103
	v_mov_b32_e32 v195, v95
	v_pk_fma_f32 v[192:193], v[194:195], v[194:195], v[192:193]
	v_pk_mul_f32 v[124:125], v[200:201], s[8:9] op_sel_hi:[1,0]
	v_add_f32_e32 v122, v122, v192
	v_add_f32_e32 v122, v122, v193
	ds_bpermute_b32 v123, v189, v122
	v_pk_mul_f32 v[116:117], v[150:151], v[116:117]
	v_pk_mul_f32 v[126:127], v[198:199], s[8:9] op_sel_hi:[1,0]
	v_readlane_b32 s13, v253, 41
	v_pk_mul_f32 v[118:119], v[126:127], v[118:119]
	s_waitcnt lgkmcnt(0)
	v_add_f32_e32 v191, v122, v123
	ds_bpermute_b32 v192, v190, v191
	v_pk_mul_f32 v[122:123], v[120:121], v[110:111]
	v_pk_mul_f32 v[110:111], v[124:125], v[108:109]
	v_cvt_pk_bf16_f32 v108, v116, v117
	v_cvt_pk_bf16_f32 v109, v118, v119
	s_waitcnt lgkmcnt(0)
	v_add_f32_e32 v116, v191, v192
	v_mul_f32_e32 v116, v205, v116
	v_mul_f32_e32 v116, v205, v116
	v_fmamk_f32 v116, v116, 0x3c800000, v188
	v_mul_f32_e32 v117, 0x4b800000, v116
	v_cmp_gt_f32_e32 vcc, s56, v116
	v_cvt_pk_bf16_f32 v110, v110, v111
	v_cvt_pk_bf16_f32 v111, v122, v123
	global_store_dwordx4 v[148:149], v[108:111], off offset:64
	v_readlane_b32 s14, v253, 42
	v_cndmask_b32_e32 v116, v116, v117, vcc
	v_rsq_f32_e32 v116, v116
	v_readlane_b32 s15, v253, 43
	v_readlane_b32 s16, v253, 44
	v_readlane_b32 s17, v253, 45
	v_mul_f32_e32 v108, 0x45800000, v116
	v_cndmask_b32_e32 v108, v116, v108, vcc
	v_mul_f32_e32 v108, v205, v108
	v_pk_mul_f32 v[110:111], v[112:113], v[108:109] op_sel_hi:[1,0]
	v_pk_mul_f32 v[104:105], v[104:105], v[108:109] op_sel_hi:[1,0]
	v_pk_mul_f32 v[110:111], v[160:161], v[110:111]
	v_pk_mul_f32 v[106:107], v[106:107], v[108:109] op_sel_hi:[1,0]
	v_pk_mul_f32 v[112:113], v[114:115], v[108:109] op_sel_hi:[1,0]
	v_pk_mul_f32 v[114:115], v[154:155], v[106:107]
	v_pk_mul_f32 v[106:107], v[156:157], v[104:105]
	v_cvt_pk_bf16_f32 v104, v110, v111
	v_add_co_u32_e32 v110, vcc, s54, v148
	v_cvt_pk_bf16_f32 v106, v106, v107
	v_cvt_pk_bf16_f32 v107, v114, v115
	v_pk_mul_f32 v[112:113], v[158:159], v[112:113]
	s_nop 0
	v_addc_co_u32_e32 v111, vcc, 0, v149, vcc
	v_cvt_pk_bf16_f32 v105, v112, v113
	global_store_dwordx4 v[110:111], v[104:107], off
	v_mov_b32_e32 v112, v85
	v_mov_b32_e32 v113, v77
	v_mov_b32_e32 v106, v97
	v_mov_b32_e32 v107, v89
	v_mov_b32_e32 v104, v96
	v_mov_b32_e32 v105, v88
	v_pk_mul_f32 v[106:107], v[106:107], v[106:107]
	v_pk_mul_f32 v[112:113], v[112:113], v[112:113]
	v_pk_fma_f32 v[104:105], v[104:105], v[104:105], v[106:107]
	v_mov_b32_e32 v106, v98
	v_mov_b32_e32 v107, v90
	v_pk_fma_f32 v[104:105], v[106:107], v[106:107], v[104:105]
	v_mov_b32_e32 v106, v99
	v_mov_b32_e32 v107, v91
	v_pk_fma_f32 v[104:105], v[106:107], v[106:107], v[104:105]
	v_mov_b32_e32 v106, v84
	v_mov_b32_e32 v107, v76
	v_pk_fma_f32 v[106:107], v[106:107], v[106:107], v[112:113]
	v_mov_b32_e32 v112, v86
	v_mov_b32_e32 v113, v78
	v_pk_fma_f32 v[106:107], v[112:113], v[112:113], v[106:107]
	v_mov_b32_e32 v112, v87
	v_mov_b32_e32 v113, v79
	v_pk_fma_f32 v[106:107], v[112:113], v[112:113], v[106:107]
	v_add_f32_e32 v104, v104, v105
	v_add_f32_e32 v104, v104, v106
	v_add_f32_e32 v104, v104, v107
	ds_bpermute_b32 v105, v189, v104
	v_pk_mul_f32 v[100:101], v[100:101], v[108:109] op_sel_hi:[1,0]
	v_pk_mul_f32 v[92:93], v[92:93], v[108:109] op_sel_hi:[1,0]
	v_pk_mul_f32 v[100:101], v[150:151], v[100:101]
	v_pk_mul_f32 v[94:95], v[94:95], v[108:109] op_sel_hi:[1,0]
	s_waitcnt lgkmcnt(0)
	v_add_f32_e32 v106, v104, v105
	ds_bpermute_b32 v107, v190, v106
	v_pk_mul_f32 v[104:105], v[120:121], v[94:95]
	v_pk_mul_f32 v[94:95], v[124:125], v[92:93]
	v_cvt_pk_bf16_f32 v92, v100, v101
	v_pk_mul_f32 v[102:103], v[102:103], v[108:109] op_sel_hi:[1,0]
	s_waitcnt lgkmcnt(0)
	v_add_f32_e32 v100, v106, v107
	v_mul_f32_e32 v100, v164, v100
	v_mul_f32_e32 v100, v164, v100
	v_fmamk_f32 v100, v100, 0x3c800000, v188
	v_mul_f32_e32 v101, 0x4b800000, v100
	v_cmp_gt_f32_e32 vcc, s56, v100
	v_pk_mul_f32 v[102:103], v[126:127], v[102:103]
	v_cvt_pk_bf16_f32 v94, v94, v95
	v_cvt_pk_bf16_f32 v95, v104, v105
	v_readlane_b32 s24, v253, 52
	v_cndmask_b32_e32 v100, v100, v101, vcc
	v_rsq_f32_e32 v100, v100
	v_cvt_pk_bf16_f32 v93, v102, v103
	global_store_dwordx4 v[110:111], v[92:95], off offset:64
	v_readlane_b32 s25, v253, 53
	v_readlane_b32 s26, v253, 54
	v_mul_f32_e32 v92, 0x45800000, v100
	v_cndmask_b32_e32 v92, v100, v92, vcc
	v_mul_f32_e32 v92, v164, v92
	v_pk_mul_f32 v[94:95], v[96:97], v[92:93] op_sel_hi:[1,0]
	v_pk_mul_f32 v[88:89], v[88:89], v[92:93] op_sel_hi:[1,0]
	v_pk_mul_f32 v[94:95], v[160:161], v[94:95]
	v_pk_mul_f32 v[90:91], v[90:91], v[92:93] op_sel_hi:[1,0]
	v_pk_mul_f32 v[96:97], v[98:99], v[92:93] op_sel_hi:[1,0]
	v_pk_mul_f32 v[98:99], v[154:155], v[90:91]
	v_pk_mul_f32 v[90:91], v[156:157], v[88:89]
	v_cvt_pk_bf16_f32 v88, v94, v95
	v_add_co_u32_e32 v94, vcc, s42, v148
	v_cvt_pk_bf16_f32 v90, v90, v91
	v_cvt_pk_bf16_f32 v91, v98, v99
	v_pk_mul_f32 v[96:97], v[158:159], v[96:97]
	s_nop 0
	v_addc_co_u32_e32 v95, vcc, 0, v149, vcc
	v_cvt_pk_bf16_f32 v89, v96, v97
	global_store_dwordx4 v[94:95], v[88:91], off
	v_mov_b32_e32 v96, v69
	v_mov_b32_e32 v97, v65
	v_mov_b32_e32 v90, v81
	v_mov_b32_e32 v91, v73
	v_mov_b32_e32 v88, v80
	v_mov_b32_e32 v89, v72
	v_pk_mul_f32 v[90:91], v[90:91], v[90:91]
	v_pk_mul_f32 v[96:97], v[96:97], v[96:97]
	v_pk_fma_f32 v[88:89], v[88:89], v[88:89], v[90:91]
	v_mov_b32_e32 v90, v82
	v_mov_b32_e32 v91, v74
	v_pk_fma_f32 v[88:89], v[90:91], v[90:91], v[88:89]
	v_mov_b32_e32 v90, v83
	v_mov_b32_e32 v91, v75
	v_pk_fma_f32 v[88:89], v[90:91], v[90:91], v[88:89]
	v_mov_b32_e32 v90, v68
	v_mov_b32_e32 v91, v64
	v_pk_fma_f32 v[90:91], v[90:91], v[90:91], v[96:97]
	v_mov_b32_e32 v96, v70
	v_mov_b32_e32 v97, v66
	v_pk_fma_f32 v[90:91], v[96:97], v[96:97], v[90:91]
	v_mov_b32_e32 v96, v71
	v_mov_b32_e32 v97, v67
	v_pk_fma_f32 v[90:91], v[96:97], v[96:97], v[90:91]
	v_add_f32_e32 v88, v88, v89
	v_add_f32_e32 v88, v88, v90
	v_add_f32_e32 v88, v88, v91
	ds_bpermute_b32 v89, v189, v88
	v_pk_mul_f32 v[84:85], v[84:85], v[92:93] op_sel_hi:[1,0]
	v_pk_mul_f32 v[76:77], v[76:77], v[92:93] op_sel_hi:[1,0]
	v_pk_mul_f32 v[84:85], v[150:151], v[84:85]
	v_pk_mul_f32 v[78:79], v[78:79], v[92:93] op_sel_hi:[1,0]
	s_waitcnt lgkmcnt(0)
	v_add_f32_e32 v90, v88, v89
	ds_bpermute_b32 v91, v190, v90
	v_pk_mul_f32 v[88:89], v[120:121], v[78:79]
	v_pk_mul_f32 v[78:79], v[124:125], v[76:77]
	v_cvt_pk_bf16_f32 v76, v84, v85
	v_pk_mul_f32 v[86:87], v[86:87], v[92:93] op_sel_hi:[1,0]
	s_waitcnt lgkmcnt(0)
	v_add_f32_e32 v84, v90, v91
	v_mul_f32_e32 v84, v165, v84
	v_mul_f32_e32 v84, v165, v84
	v_fmamk_f32 v84, v84, 0x3c800000, v188
	v_mul_f32_e32 v85, 0x4b800000, v84
	v_cmp_gt_f32_e32 vcc, s56, v84
	v_pk_mul_f32 v[86:87], v[126:127], v[86:87]
	v_cvt_pk_bf16_f32 v78, v78, v79
	v_cvt_pk_bf16_f32 v79, v88, v89
	v_readlane_b32 s27, v253, 55
	v_cndmask_b32_e32 v84, v84, v85, vcc
	v_rsq_f32_e32 v84, v84
	v_cvt_pk_bf16_f32 v77, v86, v87
	global_store_dwordx4 v[94:95], v[76:79], off offset:64
	s_nop 1
	v_mul_f32_e32 v76, 0x45800000, v84
	v_cndmask_b32_e32 v76, v84, v76, vcc
	v_mul_f32_e32 v76, v165, v76
	v_pk_mul_f32 v[78:79], v[80:81], v[76:77] op_sel_hi:[1,0]
	v_pk_mul_f32 v[72:73], v[72:73], v[76:77] op_sel_hi:[1,0]
	v_pk_mul_f32 v[78:79], v[160:161], v[78:79]
	v_pk_mul_f32 v[74:75], v[74:75], v[76:77] op_sel_hi:[1,0]
	v_pk_mul_f32 v[80:81], v[82:83], v[76:77] op_sel_hi:[1,0]
	v_pk_mul_f32 v[82:83], v[154:155], v[74:75]
	v_pk_mul_f32 v[74:75], v[156:157], v[72:73]
	v_cvt_pk_bf16_f32 v72, v78, v79
	v_add_co_u32_e32 v78, vcc, s53, v148
	v_cvt_pk_bf16_f32 v74, v74, v75
	v_cvt_pk_bf16_f32 v75, v82, v83
	v_pk_mul_f32 v[80:81], v[158:159], v[80:81]
	s_nop 0
	v_addc_co_u32_e32 v79, vcc, 0, v149, vcc
	v_cvt_pk_bf16_f32 v73, v80, v81
	global_store_dwordx4 v[78:79], v[72:75], off
	v_mov_b32_e32 v80, v53
	v_mov_b32_e32 v81, v45
	v_mov_b32_e32 v74, v61
	v_mov_b32_e32 v75, v57
	v_mov_b32_e32 v72, v60
	v_mov_b32_e32 v73, v56
	v_pk_mul_f32 v[74:75], v[74:75], v[74:75]
	v_pk_mul_f32 v[80:81], v[80:81], v[80:81]
	v_pk_fma_f32 v[72:73], v[72:73], v[72:73], v[74:75]
	v_mov_b32_e32 v74, v62
	v_mov_b32_e32 v75, v58
	v_pk_fma_f32 v[72:73], v[74:75], v[74:75], v[72:73]
	v_mov_b32_e32 v74, v63
	v_mov_b32_e32 v75, v59
	v_pk_fma_f32 v[72:73], v[74:75], v[74:75], v[72:73]
	v_mov_b32_e32 v74, v52
	v_mov_b32_e32 v75, v44
	v_pk_fma_f32 v[74:75], v[74:75], v[74:75], v[80:81]
	v_mov_b32_e32 v80, v54
	v_mov_b32_e32 v81, v46
	v_pk_fma_f32 v[74:75], v[80:81], v[80:81], v[74:75]
	v_mov_b32_e32 v80, v55
	v_mov_b32_e32 v81, v47
	v_pk_fma_f32 v[74:75], v[80:81], v[80:81], v[74:75]
	v_add_f32_e32 v72, v72, v73
	v_add_f32_e32 v72, v72, v74
	v_add_f32_e32 v72, v72, v75
	ds_bpermute_b32 v73, v189, v72
	v_pk_mul_f32 v[68:69], v[68:69], v[76:77] op_sel_hi:[1,0]
	v_pk_mul_f32 v[64:65], v[64:65], v[76:77] op_sel_hi:[1,0]
	v_pk_mul_f32 v[68:69], v[150:151], v[68:69]
	v_pk_mul_f32 v[66:67], v[66:67], v[76:77] op_sel_hi:[1,0]
	s_waitcnt lgkmcnt(0)
	v_add_f32_e32 v74, v72, v73
	ds_bpermute_b32 v75, v190, v74
	v_pk_mul_f32 v[72:73], v[120:121], v[66:67]
	v_pk_mul_f32 v[66:67], v[124:125], v[64:65]
	v_cvt_pk_bf16_f32 v64, v68, v69
	v_pk_mul_f32 v[70:71], v[70:71], v[76:77] op_sel_hi:[1,0]
	s_waitcnt lgkmcnt(0)
	v_add_f32_e32 v68, v74, v75
	v_mul_f32_e32 v68, v162, v68
	v_mul_f32_e32 v68, v162, v68
	v_fmamk_f32 v68, v68, 0x3c800000, v188
	v_mul_f32_e32 v69, 0x4b800000, v68
	v_cmp_gt_f32_e32 vcc, s56, v68
	v_pk_mul_f32 v[70:71], v[126:127], v[70:71]
	v_cvt_pk_bf16_f32 v66, v66, v67
	v_cvt_pk_bf16_f32 v67, v72, v73
	s_nop 0
	v_cndmask_b32_e32 v68, v68, v69, vcc
	v_rsq_f32_e32 v68, v68
	v_cvt_pk_bf16_f32 v65, v70, v71
	global_store_dwordx4 v[78:79], v[64:67], off offset:64
	s_nop 1
	v_mul_f32_e32 v64, 0x45800000, v68
	v_cndmask_b32_e32 v64, v68, v64, vcc
	v_mul_f32_e32 v64, v162, v64
	v_pk_mul_f32 v[60:61], v[60:61], v[64:65] op_sel_hi:[1,0]
	v_pk_mul_f32 v[56:57], v[56:57], v[64:65] op_sel_hi:[1,0]
	v_pk_mul_f32 v[60:61], v[160:161], v[60:61]
	v_pk_mul_f32 v[58:59], v[58:59], v[64:65] op_sel_hi:[1,0]
	v_pk_mul_f32 v[62:63], v[62:63], v[64:65] op_sel_hi:[1,0]
	v_pk_mul_f32 v[66:67], v[154:155], v[58:59]
	v_pk_mul_f32 v[58:59], v[156:157], v[56:57]
	v_cvt_pk_bf16_f32 v56, v60, v61
	v_add_co_u32_e32 v60, vcc, s57, v148
	v_cvt_pk_bf16_f32 v58, v58, v59
	v_cvt_pk_bf16_f32 v59, v66, v67
	v_pk_mul_f32 v[62:63], v[158:159], v[62:63]
	s_nop 0
	v_addc_co_u32_e32 v61, vcc, 0, v149, vcc
	v_cvt_pk_bf16_f32 v57, v62, v63
	global_store_dwordx4 v[60:61], v[56:59], off
	v_mov_b32_e32 v62, v37
	v_mov_b32_e32 v63, v29
	v_mov_b32_e32 v58, v49
	v_mov_b32_e32 v59, v41
	v_mov_b32_e32 v56, v48
	v_mov_b32_e32 v57, v40
	v_pk_mul_f32 v[58:59], v[58:59], v[58:59]
	v_pk_mul_f32 v[62:63], v[62:63], v[62:63]
	v_pk_fma_f32 v[56:57], v[56:57], v[56:57], v[58:59]
	v_mov_b32_e32 v58, v50
	v_mov_b32_e32 v59, v42
	v_pk_fma_f32 v[56:57], v[58:59], v[58:59], v[56:57]
	v_mov_b32_e32 v58, v51
	v_mov_b32_e32 v59, v43
	v_pk_fma_f32 v[56:57], v[58:59], v[58:59], v[56:57]
	v_mov_b32_e32 v58, v36
	v_mov_b32_e32 v59, v28
	v_pk_fma_f32 v[58:59], v[58:59], v[58:59], v[62:63]
	v_mov_b32_e32 v62, v38
	v_mov_b32_e32 v63, v30
	v_pk_fma_f32 v[58:59], v[62:63], v[62:63], v[58:59]
	v_mov_b32_e32 v62, v39
	v_mov_b32_e32 v63, v31
	v_pk_fma_f32 v[58:59], v[62:63], v[62:63], v[58:59]
	v_add_f32_e32 v56, v56, v57
	v_add_f32_e32 v56, v56, v58
	v_add_f32_e32 v56, v56, v59
	ds_bpermute_b32 v57, v189, v56
	v_pk_mul_f32 v[52:53], v[52:53], v[64:65] op_sel_hi:[1,0]
	v_pk_mul_f32 v[44:45], v[44:45], v[64:65] op_sel_hi:[1,0]
	v_pk_mul_f32 v[52:53], v[150:151], v[52:53]
	v_pk_mul_f32 v[46:47], v[46:47], v[64:65] op_sel_hi:[1,0]
	s_waitcnt lgkmcnt(0)
	v_add_f32_e32 v58, v56, v57
	ds_bpermute_b32 v59, v190, v58
	v_pk_mul_f32 v[56:57], v[120:121], v[46:47]
	v_pk_mul_f32 v[46:47], v[124:125], v[44:45]
	v_cvt_pk_bf16_f32 v44, v52, v53
	v_pk_mul_f32 v[54:55], v[54:55], v[64:65] op_sel_hi:[1,0]
	s_waitcnt lgkmcnt(0)
	v_add_f32_e32 v52, v58, v59
	v_mul_f32_e32 v52, v163, v52
	v_mul_f32_e32 v52, v163, v52
	v_fmamk_f32 v52, v52, 0x3c800000, v188
	v_mul_f32_e32 v53, 0x4b800000, v52
	v_cmp_gt_f32_e32 vcc, s56, v52
	v_pk_mul_f32 v[54:55], v[126:127], v[54:55]
	v_cvt_pk_bf16_f32 v46, v46, v47
	v_cvt_pk_bf16_f32 v47, v56, v57
	s_nop 0
	v_cndmask_b32_e32 v52, v52, v53, vcc
	v_rsq_f32_e32 v52, v52
	v_cvt_pk_bf16_f32 v45, v54, v55
	global_store_dwordx4 v[60:61], v[44:47], off offset:64
	s_nop 1
	v_mul_f32_e32 v44, 0x45800000, v52
	v_cndmask_b32_e32 v44, v52, v44, vcc
	v_mul_f32_e32 v44, v163, v44
	v_pk_mul_f32 v[46:47], v[48:49], v[44:45] op_sel_hi:[1,0]
	v_pk_mul_f32 v[40:41], v[40:41], v[44:45] op_sel_hi:[1,0]
	v_pk_mul_f32 v[46:47], v[160:161], v[46:47]
	v_pk_mul_f32 v[42:43], v[42:43], v[44:45] op_sel_hi:[1,0]
	v_pk_mul_f32 v[48:49], v[50:51], v[44:45] op_sel_hi:[1,0]
	v_pk_mul_f32 v[50:51], v[154:155], v[42:43]
	v_pk_mul_f32 v[42:43], v[156:157], v[40:41]
	v_cvt_pk_bf16_f32 v40, v46, v47
	v_add_co_u32_e32 v46, vcc, s58, v148
	v_cvt_pk_bf16_f32 v42, v42, v43
	v_cvt_pk_bf16_f32 v43, v50, v51
	v_pk_mul_f32 v[48:49], v[158:159], v[48:49]
	s_nop 0
	v_addc_co_u32_e32 v47, vcc, 0, v149, vcc
	v_cvt_pk_bf16_f32 v41, v48, v49
	global_store_dwordx4 v[46:47], v[40:43], off
	v_mov_b32_e32 v48, v21
	v_mov_b32_e32 v49, v13
	v_mov_b32_e32 v42, v33
	v_mov_b32_e32 v43, v25
	v_mov_b32_e32 v40, v32
	v_mov_b32_e32 v41, v24
	v_pk_mul_f32 v[42:43], v[42:43], v[42:43]
	v_pk_mul_f32 v[48:49], v[48:49], v[48:49]
	v_pk_fma_f32 v[40:41], v[40:41], v[40:41], v[42:43]
	v_mov_b32_e32 v42, v34
	v_mov_b32_e32 v43, v26
	v_pk_fma_f32 v[40:41], v[42:43], v[42:43], v[40:41]
	v_mov_b32_e32 v42, v35
	v_mov_b32_e32 v43, v27
	v_pk_fma_f32 v[40:41], v[42:43], v[42:43], v[40:41]
	v_mov_b32_e32 v42, v20
	v_mov_b32_e32 v43, v12
	v_pk_fma_f32 v[42:43], v[42:43], v[42:43], v[48:49]
	v_mov_b32_e32 v48, v22
	v_mov_b32_e32 v49, v14
	v_pk_fma_f32 v[42:43], v[48:49], v[48:49], v[42:43]
	v_mov_b32_e32 v48, v23
	v_mov_b32_e32 v49, v15
	v_pk_fma_f32 v[42:43], v[48:49], v[48:49], v[42:43]
	v_add_f32_e32 v40, v40, v41
	v_add_f32_e32 v40, v40, v42
	v_add_f32_e32 v40, v40, v43
	ds_bpermute_b32 v41, v189, v40
	v_pk_mul_f32 v[36:37], v[36:37], v[44:45] op_sel_hi:[1,0]
	v_pk_mul_f32 v[28:29], v[28:29], v[44:45] op_sel_hi:[1,0]
	v_pk_mul_f32 v[36:37], v[150:151], v[36:37]
	v_pk_mul_f32 v[30:31], v[30:31], v[44:45] op_sel_hi:[1,0]
	s_waitcnt lgkmcnt(0)
	v_add_f32_e32 v42, v40, v41
	ds_bpermute_b32 v43, v190, v42
	v_pk_mul_f32 v[40:41], v[120:121], v[30:31]
	v_pk_mul_f32 v[30:31], v[124:125], v[28:29]
	v_cvt_pk_bf16_f32 v28, v36, v37
	v_pk_mul_f32 v[38:39], v[38:39], v[44:45] op_sel_hi:[1,0]
	s_waitcnt lgkmcnt(0)
	v_add_f32_e32 v36, v42, v43
	v_mul_f32_e32 v36, v152, v36
	v_mul_f32_e32 v36, v152, v36
	v_fmamk_f32 v36, v36, 0x3c800000, v188
	v_mul_f32_e32 v37, 0x4b800000, v36
	v_cmp_gt_f32_e32 vcc, s56, v36
	v_pk_mul_f32 v[38:39], v[126:127], v[38:39]
	v_cvt_pk_bf16_f32 v30, v30, v31
	v_cvt_pk_bf16_f32 v31, v40, v41
	s_nop 0
	v_cndmask_b32_e32 v36, v36, v37, vcc
	v_rsq_f32_e32 v36, v36
	v_cvt_pk_bf16_f32 v29, v38, v39
	global_store_dwordx4 v[46:47], v[28:31], off offset:64
	s_nop 1
	v_mul_f32_e32 v28, 0x45800000, v36
	v_cndmask_b32_e32 v28, v36, v28, vcc
	v_mul_f32_e32 v28, v152, v28
	v_pk_mul_f32 v[30:31], v[32:33], v[28:29] op_sel_hi:[1,0]
	v_pk_mul_f32 v[24:25], v[24:25], v[28:29] op_sel_hi:[1,0]
	v_pk_mul_f32 v[30:31], v[160:161], v[30:31]
	v_pk_mul_f32 v[26:27], v[26:27], v[28:29] op_sel_hi:[1,0]
	v_pk_mul_f32 v[32:33], v[34:35], v[28:29] op_sel_hi:[1,0]
	v_pk_mul_f32 v[34:35], v[154:155], v[26:27]
	v_pk_mul_f32 v[26:27], v[156:157], v[24:25]
	v_cvt_pk_bf16_f32 v24, v30, v31
	v_add_co_u32_e32 v30, vcc, s59, v148
	v_cvt_pk_bf16_f32 v26, v26, v27
	v_cvt_pk_bf16_f32 v27, v34, v35
	v_pk_mul_f32 v[32:33], v[158:159], v[32:33]
	s_nop 0
	v_addc_co_u32_e32 v31, vcc, 0, v149, vcc
	v_cvt_pk_bf16_f32 v25, v32, v33
	global_store_dwordx4 v[30:31], v[24:27], off
	v_mov_b32_e32 v32, v5
	v_mov_b32_e32 v33, v1
	v_mov_b32_e32 v26, v17
	v_mov_b32_e32 v27, v9
	v_mov_b32_e32 v24, v16
	v_mov_b32_e32 v25, v8
	v_pk_mul_f32 v[26:27], v[26:27], v[26:27]
	v_pk_mul_f32 v[32:33], v[32:33], v[32:33]
	v_pk_fma_f32 v[24:25], v[24:25], v[24:25], v[26:27]
	v_mov_b32_e32 v26, v18
	v_mov_b32_e32 v27, v10
	v_pk_fma_f32 v[24:25], v[26:27], v[26:27], v[24:25]
	v_mov_b32_e32 v26, v19
	v_mov_b32_e32 v27, v11
	v_pk_fma_f32 v[24:25], v[26:27], v[26:27], v[24:25]
	v_mov_b32_e32 v26, v4
	v_mov_b32_e32 v27, v0
	v_pk_fma_f32 v[26:27], v[26:27], v[26:27], v[32:33]
	v_mov_b32_e32 v32, v6
	v_mov_b32_e32 v33, v2
	v_pk_fma_f32 v[26:27], v[32:33], v[32:33], v[26:27]
	v_mov_b32_e32 v32, v7
	v_mov_b32_e32 v33, v3
	v_pk_fma_f32 v[26:27], v[32:33], v[32:33], v[26:27]
	v_add_f32_e32 v24, v24, v25
	v_add_f32_e32 v24, v24, v26
	v_add_f32_e32 v24, v24, v27
	ds_bpermute_b32 v25, v189, v24
	v_pk_mul_f32 v[20:21], v[20:21], v[28:29] op_sel_hi:[1,0]
	v_pk_mul_f32 v[12:13], v[12:13], v[28:29] op_sel_hi:[1,0]
	v_pk_mul_f32 v[20:21], v[150:151], v[20:21]
	v_pk_mul_f32 v[14:15], v[14:15], v[28:29] op_sel_hi:[1,0]
	s_waitcnt lgkmcnt(0)
	v_add_f32_e32 v26, v24, v25
	ds_bpermute_b32 v27, v190, v26
	v_pk_mul_f32 v[24:25], v[120:121], v[14:15]
	v_pk_mul_f32 v[14:15], v[124:125], v[12:13]
	v_cvt_pk_bf16_f32 v12, v20, v21
	v_pk_mul_f32 v[22:23], v[22:23], v[28:29] op_sel_hi:[1,0]
	s_waitcnt lgkmcnt(0)
	v_add_f32_e32 v20, v26, v27
	v_mul_f32_e32 v20, v153, v20
	v_mul_f32_e32 v20, v153, v20
	v_fmamk_f32 v20, v20, 0x3c800000, v188
	v_mul_f32_e32 v21, 0x4b800000, v20
	v_cmp_gt_f32_e32 vcc, s56, v20
	v_pk_mul_f32 v[22:23], v[126:127], v[22:23]
	v_cvt_pk_bf16_f32 v14, v14, v15
	v_cvt_pk_bf16_f32 v15, v24, v25
	s_nop 0
	v_cndmask_b32_e32 v20, v20, v21, vcc
	v_rsq_f32_e32 v20, v20
	v_cvt_pk_bf16_f32 v13, v22, v23
	global_store_dwordx4 v[30:31], v[12:15], off offset:64
	s_nop 1
	v_mul_f32_e32 v12, 0x45800000, v20
	v_cndmask_b32_e32 v12, v20, v12, vcc
	v_mul_f32_e32 v12, v153, v12
	v_pk_mul_f32 v[14:15], v[16:17], v[12:13] op_sel_hi:[1,0]
	v_pk_mul_f32 v[8:9], v[8:9], v[12:13] op_sel_hi:[1,0]
	v_pk_mul_f32 v[14:15], v[160:161], v[14:15]
	v_pk_mul_f32 v[10:11], v[10:11], v[12:13] op_sel_hi:[1,0]
	v_pk_mul_f32 v[16:17], v[18:19], v[12:13] op_sel_hi:[1,0]
	v_pk_mul_f32 v[18:19], v[154:155], v[10:11]
	v_pk_mul_f32 v[10:11], v[156:157], v[8:9]
	v_cvt_pk_bf16_f32 v8, v14, v15
	v_add_co_u32_e32 v14, vcc, s60, v148
	v_pk_mul_f32 v[16:17], v[158:159], v[16:17]
	s_nop 0
	v_addc_co_u32_e32 v15, vcc, 0, v149, vcc
	v_cvt_pk_bf16_f32 v9, v16, v17
	v_pk_mul_f32 v[0:1], v[0:1], v[12:13] op_sel_hi:[1,0]
	v_pk_mul_f32 v[2:3], v[2:3], v[12:13] op_sel_hi:[1,0]
	v_cvt_pk_bf16_f32 v10, v10, v11
	v_cvt_pk_bf16_f32 v11, v18, v19
	global_store_dwordx4 v[14:15], v[8:11], off
	v_pk_mul_f32 v[4:5], v[4:5], v[12:13] op_sel_hi:[1,0]
	v_pk_mul_f32 v[6:7], v[6:7], v[12:13] op_sel_hi:[1,0]
	v_pk_mul_f32 v[8:9], v[120:121], v[2:3]
	v_pk_mul_f32 v[2:3], v[124:125], v[0:1]
	s_and_b64 vcc, exec, s[6:7]
	v_pk_mul_f32 v[6:7], v[126:127], v[6:7]
	v_pk_mul_f32 v[4:5], v[150:151], v[4:5]
	v_cvt_pk_bf16_f32 v1, v6, v7
	v_cvt_pk_bf16_f32 v2, v2, v3
	v_cvt_pk_bf16_f32 v3, v8, v9
	s_nop 0
	v_cvt_pk_bf16_f32 v0, v4, v5
	global_store_dwordx4 v[14:15], v[0:3], off offset:64
	s_cbranch_vccz .LBB0_1908
	s_waitcnt vmcnt(0)
	s_cmpk_gt_u32 s76, 0xff
	s_cbranch_scc1 .LBB0_1919
	s_barrier

.LBB0_2248:
	ds_read_b128 v[148:151], v156
	ds_read_b128 v[172:175], v157
	ds_read_b128 v[178:181], v158
	ds_read_b128 v[182:185], v159
	s_add_u32 s24, s22, 0xfffc0080
	s_addc_u32 s25, s23, -1
	s_cmp_eq_u32 s66, 12
	s_cselect_b32 s27, s15, s25
	s_cselect_b32 s26, s62, s24
	s_cselect_b32 s25, s13, s65
	s_cselect_b32 s24, s63, s64
	s_mov_b32 m0, s52
	v_lshl_add_u64 v[152:153], s[22:23], 0, v[142:143]
	ds_read_b128 v[186:189], v154
	ds_read_b128 v[190:193], v154 offset:1024
	ds_read_b128 v[194:197], v154 offset:2048
	ds_read_b128 v[198:201], v154 offset:3072
	ds_read_b128 v[202:205], v154 offset:4096
	ds_read_b128 v[206:209], v154 offset:5120
	ds_read_b128 v[210:213], v154 offset:6144
	ds_read_b128 v[214:217], v154 offset:7168
	global_load_lds_dwordx4 v[152:153], off
	v_lshl_add_u64 v[152:153], s[22:23], 0, v[140:141]
	s_mov_b32 m0, s53
	s_nop 0
	global_load_lds_dwordx4 v[152:153], off
	s_waitcnt lgkmcnt(8)
	s_barrier
	s_waitcnt lgkmcnt(0)
	s_setprio 1
	s_waitcnt lgkmcnt(0)
	v_mfma_f32_16x16x32_bf16 v[124:127], v[148:151], v[186:189], v[124:127]
	v_mfma_f32_16x16x32_bf16 v[120:123], v[178:181], v[186:189], v[120:123]
	v_mfma_f32_16x16x32_bf16 v[108:111], v[148:151], v[194:197], v[108:111]
	v_mfma_f32_16x16x32_bf16 v[104:107], v[178:181], v[194:197], v[104:107]
	v_mfma_f32_16x16x32_bf16 v[92:95], v[148:151], v[202:205], v[92:95]
	v_mfma_f32_16x16x32_bf16 v[88:91], v[178:181], v[202:205], v[88:91]
	v_mfma_f32_16x16x32_bf16 v[76:79], v[148:151], v[210:213], v[76:79]
	v_mfma_f32_16x16x32_bf16 v[72:75], v[178:181], v[210:213], v[72:75]
	v_mfma_f32_16x16x32_bf16 v[124:127], v[172:175], v[190:193], v[124:127]
	v_mfma_f32_16x16x32_bf16 v[120:123], v[182:185], v[190:193], v[120:123]
	v_mfma_f32_16x16x32_bf16 v[108:111], v[172:175], v[198:201], v[108:111]
	v_mfma_f32_16x16x32_bf16 v[104:107], v[182:185], v[198:201], v[104:107]
	v_mfma_f32_16x16x32_bf16 v[92:95], v[172:175], v[206:209], v[92:95]
	v_mfma_f32_16x16x32_bf16 v[88:91], v[182:185], v[206:209], v[88:91]
	v_mfma_f32_16x16x32_bf16 v[76:79], v[172:175], v[214:217], v[76:79]
	v_mfma_f32_16x16x32_bf16 v[72:75], v[182:185], v[214:217], v[72:75]
	s_setprio 0
	s_barrier
	s_mov_b32 m0, s38
	v_lshl_add_u64 v[152:153], s[24:25], 0, v[132:133]
	ds_read_b128 v[218:221], v160
	ds_read_b128 v[222:225], v161
	ds_read_b128 v[226:229], v162
	ds_read_b128 v[230:233], v163
	global_load_lds_dwordx4 v[152:153], off
	v_lshl_add_u64 v[234:235], s[24:25], 0, v[128:129]
	s_mov_b32 m0, s39
	s_nop 0
	global_load_lds_dwordx4 v[234:235], off
	s_barrier
	s_waitcnt lgkmcnt(0)
	s_setprio 1
	s_waitcnt lgkmcnt(0)
	v_mfma_f32_16x16x32_bf16 v[116:119], v[218:221], v[186:189], v[116:119]
	v_mfma_f32_16x16x32_bf16 v[112:115], v[226:229], v[186:189], v[112:115]
	v_mfma_f32_16x16x32_bf16 v[100:103], v[218:221], v[194:197], v[100:103]
	v_mfma_f32_16x16x32_bf16 v[96:99], v[226:229], v[194:197], v[96:99]
	v_mfma_f32_16x16x32_bf16 v[84:87], v[218:221], v[202:205], v[84:87]
	v_mfma_f32_16x16x32_bf16 v[80:83], v[226:229], v[202:205], v[80:83]
	v_mfma_f32_16x16x32_bf16 v[68:71], v[218:221], v[210:213], v[68:71]
	v_mfma_f32_16x16x32_bf16 v[64:67], v[226:229], v[210:213], v[64:67]
	v_mfma_f32_16x16x32_bf16 v[116:119], v[222:225], v[190:193], v[116:119]
	v_mfma_f32_16x16x32_bf16 v[112:115], v[230:233], v[190:193], v[112:115]
	v_mfma_f32_16x16x32_bf16 v[100:103], v[222:225], v[198:201], v[100:103]
	v_mfma_f32_16x16x32_bf16 v[96:99], v[230:233], v[198:201], v[96:99]
	v_mfma_f32_16x16x32_bf16 v[84:87], v[222:225], v[206:209], v[84:87]
	v_mfma_f32_16x16x32_bf16 v[80:83], v[230:233], v[206:209], v[80:83]
	v_mfma_f32_16x16x32_bf16 v[68:71], v[222:225], v[214:217], v[68:71]
	v_mfma_f32_16x16x32_bf16 v[64:67], v[230:233], v[214:217], v[64:67]
	s_setprio 0
	s_mov_b32 m0, s34
	v_lshl_add_u64 v[236:237], s[26:27], 0, v[134:135]
	s_barrier
	ds_read_b128 v[186:189], v154 offset:16384
	ds_read_b128 v[190:193], v154 offset:17408
	ds_read_b128 v[194:197], v154 offset:18432
	ds_read_b128 v[198:201], v154 offset:19456
	ds_read_b128 v[202:205], v154 offset:20480
	ds_read_b128 v[206:209], v154 offset:21504
	ds_read_b128 v[210:213], v154 offset:22528
	ds_read_b128 v[214:217], v154 offset:23552
	global_load_lds_dwordx4 v[236:237], off
	v_lshl_add_u64 v[238:239], s[26:27], 0, v[130:131]
	s_mov_b32 m0, s40
	s_nop 0
	global_load_lds_dwordx4 v[238:239], off
	s_barrier
	s_waitcnt lgkmcnt(0)
	s_setprio 1
	s_waitcnt lgkmcnt(0)
	v_mfma_f32_16x16x32_bf16 v[60:63], v[148:151], v[186:189], v[60:63]
	v_mfma_f32_16x16x32_bf16 v[56:59], v[178:181], v[186:189], v[56:59]
	v_mfma_f32_16x16x32_bf16 v[44:47], v[148:151], v[194:197], v[44:47]
	v_mfma_f32_16x16x32_bf16 v[40:43], v[178:181], v[194:197], v[40:43]
	v_mfma_f32_16x16x32_bf16 v[28:31], v[148:151], v[202:205], v[28:31]
	v_mfma_f32_16x16x32_bf16 v[24:27], v[178:181], v[202:205], v[24:27]
	v_mfma_f32_16x16x32_bf16 v[12:15], v[148:151], v[210:213], v[12:15]
	v_mfma_f32_16x16x32_bf16 v[8:11], v[178:181], v[210:213], v[8:11]
	v_mfma_f32_16x16x32_bf16 v[60:63], v[172:175], v[190:193], v[60:63]
	v_mfma_f32_16x16x32_bf16 v[56:59], v[182:185], v[190:193], v[56:59]
	v_mfma_f32_16x16x32_bf16 v[44:47], v[172:175], v[198:201], v[44:47]
	v_mfma_f32_16x16x32_bf16 v[40:43], v[182:185], v[198:201], v[40:43]
	v_mfma_f32_16x16x32_bf16 v[28:31], v[172:175], v[206:209], v[28:31]
	v_mfma_f32_16x16x32_bf16 v[24:27], v[182:185], v[206:209], v[24:27]
	v_mfma_f32_16x16x32_bf16 v[12:15], v[172:175], v[214:217], v[12:15]
	v_mfma_f32_16x16x32_bf16 v[8:11], v[182:185], v[214:217], v[8:11]
	s_setprio 0
	s_barrier
	s_add_u32 s68, s24, 0x40000
	s_addc_u32 s69, s25, 0
	s_mov_b32 m0, s41
	v_lshl_add_u64 v[148:149], s[68:69], 0, v[132:133]
	global_load_lds_dwordx4 v[148:149], off
	v_lshl_add_u64 v[148:149], s[68:69], 0, v[128:129]
	s_mov_b32 m0, s42
	s_nop 0
	global_load_lds_dwordx4 v[148:149], off
	s_waitcnt vmcnt(6)
	s_barrier
	s_setprio 1
	v_mfma_f32_16x16x32_bf16 v[52:55], v[218:221], v[186:189], v[52:55]
	v_mfma_f32_16x16x32_bf16 v[48:51], v[226:229], v[186:189], v[48:51]
	v_mfma_f32_16x16x32_bf16 v[36:39], v[218:221], v[194:197], v[36:39]
	v_mfma_f32_16x16x32_bf16 v[32:35], v[226:229], v[194:197], v[32:35]
	v_mfma_f32_16x16x32_bf16 v[20:23], v[218:221], v[202:205], v[20:23]
	v_mfma_f32_16x16x32_bf16 v[16:19], v[226:229], v[202:205], v[16:19]
	v_mfma_f32_16x16x32_bf16 v[4:7], v[218:221], v[210:213], v[4:7]
	v_mfma_f32_16x16x32_bf16 v[0:3], v[226:229], v[210:213], v[0:3]
	v_mfma_f32_16x16x32_bf16 v[52:55], v[222:225], v[190:193], v[52:55]
	v_mfma_f32_16x16x32_bf16 v[48:51], v[230:233], v[190:193], v[48:51]
	v_mfma_f32_16x16x32_bf16 v[36:39], v[222:225], v[198:201], v[36:39]
	v_mfma_f32_16x16x32_bf16 v[32:35], v[230:233], v[198:201], v[32:35]
	v_mfma_f32_16x16x32_bf16 v[20:23], v[222:225], v[206:209], v[20:23]
	v_mfma_f32_16x16x32_bf16 v[16:19], v[230:233], v[206:209], v[16:19]
	v_mfma_f32_16x16x32_bf16 v[4:7], v[222:225], v[214:217], v[4:7]
	v_mfma_f32_16x16x32_bf16 v[0:3], v[230:233], v[214:217], v[0:3]
	s_setprio 0
	s_barrier
	ds_read_b128 v[148:151], v164
	ds_read_b128 v[172:175], v165
	ds_read_b128 v[178:181], v166
	ds_read_b128 v[182:185], v167
	s_add_u32 s26, s26, 0x40000
	s_addc_u32 s27, s27, 0
	s_mov_b32 m0, s43
	v_lshl_add_u64 v[218:219], s[26:27], 0, v[134:135]
	ds_read_b128 v[186:189], v154 offset:32768
	ds_read_b128 v[190:193], v154 offset:33792
	ds_read_b128 v[194:197], v154 offset:34816
	ds_read_b128 v[198:201], v154 offset:35840
	ds_read_b128 v[202:205], v154 offset:36864
	ds_read_b128 v[206:209], v154 offset:37888
	ds_read_b128 v[210:213], v154 offset:38912
	ds_read_b128 v[214:217], v154 offset:39936
	global_load_lds_dwordx4 v[218:219], off
	v_lshl_add_u64 v[218:219], s[26:27], 0, v[130:131]
	s_mov_b32 m0, s44
	s_nop 0
	global_load_lds_dwordx4 v[218:219], off
	s_waitcnt lgkmcnt(8)
	s_barrier
	s_waitcnt lgkmcnt(0)
	s_setprio 1
	s_waitcnt lgkmcnt(0)
	v_mfma_f32_16x16x32_bf16 v[124:127], v[148:151], v[186:189], v[124:127]
	v_mfma_f32_16x16x32_bf16 v[120:123], v[178:181], v[186:189], v[120:123]
	v_mfma_f32_16x16x32_bf16 v[108:111], v[148:151], v[194:197], v[108:111]
	v_mfma_f32_16x16x32_bf16 v[104:107], v[178:181], v[194:197], v[104:107]
	v_mfma_f32_16x16x32_bf16 v[92:95], v[148:151], v[202:205], v[92:95]
	v_mfma_f32_16x16x32_bf16 v[88:91], v[178:181], v[202:205], v[88:91]
	v_mfma_f32_16x16x32_bf16 v[76:79], v[148:151], v[210:213], v[76:79]
	v_mfma_f32_16x16x32_bf16 v[72:75], v[178:181], v[210:213], v[72:75]
	v_mfma_f32_16x16x32_bf16 v[124:127], v[172:175], v[190:193], v[124:127]
	v_mfma_f32_16x16x32_bf16 v[120:123], v[182:185], v[190:193], v[120:123]
	v_mfma_f32_16x16x32_bf16 v[108:111], v[172:175], v[198:201], v[108:111]
	v_mfma_f32_16x16x32_bf16 v[104:107], v[182:185], v[198:201], v[104:107]
	v_mfma_f32_16x16x32_bf16 v[92:95], v[172:175], v[206:209], v[92:95]
	v_mfma_f32_16x16x32_bf16 v[88:91], v[182:185], v[206:209], v[88:91]
	v_mfma_f32_16x16x32_bf16 v[76:79], v[172:175], v[214:217], v[76:79]
	v_mfma_f32_16x16x32_bf16 v[72:75], v[182:185], v[214:217], v[72:75]
	s_setprio 0
	s_barrier
	s_mov_b32 m0, s46
	v_lshl_add_u64 v[152:153], v[152:153], 0, s[10:11]
	ds_read_b128 v[218:221], v168
	ds_read_b128 v[222:225], v169
	ds_read_b128 v[226:229], v170
	ds_read_b128 v[230:233], v171
	global_load_lds_dwordx4 v[152:153], off
	v_lshl_add_u64 v[152:153], v[234:235], 0, s[10:11]
	s_mov_b32 m0, s47
	s_nop 0
	global_load_lds_dwordx4 v[152:153], off
	s_barrier
	s_waitcnt lgkmcnt(0)
	s_setprio 1
	s_waitcnt lgkmcnt(0)
	v_mfma_f32_16x16x32_bf16 v[116:119], v[218:221], v[186:189], v[116:119]
	v_mfma_f32_16x16x32_bf16 v[112:115], v[226:229], v[186:189], v[112:115]
	v_mfma_f32_16x16x32_bf16 v[100:103], v[218:221], v[194:197], v[100:103]
	v_mfma_f32_16x16x32_bf16 v[96:99], v[226:229], v[194:197], v[96:99]
	v_mfma_f32_16x16x32_bf16 v[84:87], v[218:221], v[202:205], v[84:87]
	v_mfma_f32_16x16x32_bf16 v[80:83], v[226:229], v[202:205], v[80:83]
	v_mfma_f32_16x16x32_bf16 v[68:71], v[218:221], v[210:213], v[68:71]
	v_mfma_f32_16x16x32_bf16 v[64:67], v[226:229], v[210:213], v[64:67]
	v_mfma_f32_16x16x32_bf16 v[116:119], v[222:225], v[190:193], v[116:119]
	v_mfma_f32_16x16x32_bf16 v[112:115], v[230:233], v[190:193], v[112:115]
	v_mfma_f32_16x16x32_bf16 v[100:103], v[222:225], v[198:201], v[100:103]
	v_mfma_f32_16x16x32_bf16 v[96:99], v[230:233], v[198:201], v[96:99]
	v_mfma_f32_16x16x32_bf16 v[84:87], v[222:225], v[206:209], v[84:87]
	v_mfma_f32_16x16x32_bf16 v[80:83], v[230:233], v[206:209], v[80:83]
	v_mfma_f32_16x16x32_bf16 v[68:71], v[222:225], v[214:217], v[68:71]
	v_mfma_f32_16x16x32_bf16 v[64:67], v[230:233], v[214:217], v[64:67]
	s_setprio 0
	s_mov_b32 m0, s48
	v_lshl_add_u64 v[152:153], v[236:237], 0, s[10:11]
	s_barrier
	ds_read_b128 v[186:189], v154 offset:49152
	ds_read_b128 v[190:193], v154 offset:50176
	ds_read_b128 v[194:197], v154 offset:51200
	ds_read_b128 v[198:201], v154 offset:52224
	ds_read_b128 v[202:205], v154 offset:53248
	ds_read_b128 v[206:209], v154 offset:54272
	ds_read_b128 v[210:213], v154 offset:55296
	ds_read_b128 v[214:217], v154 offset:56320
	global_load_lds_dwordx4 v[152:153], off
	v_lshl_add_u64 v[152:153], v[238:239], 0, s[10:11]
	s_mov_b32 m0, s49
	s_nop 0
	global_load_lds_dwordx4 v[152:153], off
	s_barrier
	s_waitcnt lgkmcnt(0)
	s_setprio 1
	s_waitcnt lgkmcnt(0)
	v_mfma_f32_16x16x32_bf16 v[60:63], v[148:151], v[186:189], v[60:63]
	v_mfma_f32_16x16x32_bf16 v[56:59], v[178:181], v[186:189], v[56:59]
	v_mfma_f32_16x16x32_bf16 v[44:47], v[148:151], v[194:197], v[44:47]
	v_mfma_f32_16x16x32_bf16 v[40:43], v[178:181], v[194:197], v[40:43]
	v_mfma_f32_16x16x32_bf16 v[28:31], v[148:151], v[202:205], v[28:31]
	v_mfma_f32_16x16x32_bf16 v[24:27], v[178:181], v[202:205], v[24:27]
	v_mfma_f32_16x16x32_bf16 v[12:15], v[148:151], v[210:213], v[12:15]
	v_mfma_f32_16x16x32_bf16 v[8:11], v[178:181], v[210:213], v[8:11]
	v_mfma_f32_16x16x32_bf16 v[60:63], v[172:175], v[190:193], v[60:63]
	v_mfma_f32_16x16x32_bf16 v[56:59], v[182:185], v[190:193], v[56:59]
	v_mfma_f32_16x16x32_bf16 v[44:47], v[172:175], v[198:201], v[44:47]
	v_mfma_f32_16x16x32_bf16 v[40:43], v[182:185], v[198:201], v[40:43]
	v_mfma_f32_16x16x32_bf16 v[28:31], v[172:175], v[206:209], v[28:31]
	v_mfma_f32_16x16x32_bf16 v[24:27], v[182:185], v[206:209], v[24:27]
	v_mfma_f32_16x16x32_bf16 v[12:15], v[172:175], v[214:217], v[12:15]
	v_mfma_f32_16x16x32_bf16 v[8:11], v[182:185], v[214:217], v[8:11]
	s_setprio 0
	s_barrier
	s_add_u32 s24, s24, 0x40080
	s_addc_u32 s25, s25, 0
	s_mov_b32 m0, s50
	v_lshl_add_u64 v[148:149], s[24:25], 0, v[132:133]
	global_load_lds_dwordx4 v[148:149], off
	v_lshl_add_u64 v[148:149], s[24:25], 0, v[128:129]
	s_mov_b32 m0, s51
	s_nop 0
	global_load_lds_dwordx4 v[148:149], off
	s_waitcnt vmcnt(6)
	s_barrier
	s_setprio 1
	v_mfma_f32_16x16x32_bf16 v[52:55], v[218:221], v[186:189], v[52:55]
	v_mfma_f32_16x16x32_bf16 v[48:51], v[226:229], v[186:189], v[48:51]
	v_mfma_f32_16x16x32_bf16 v[36:39], v[218:221], v[194:197], v[36:39]
	v_mfma_f32_16x16x32_bf16 v[32:35], v[226:229], v[194:197], v[32:35]
	v_mfma_f32_16x16x32_bf16 v[20:23], v[218:221], v[202:205], v[20:23]
	v_mfma_f32_16x16x32_bf16 v[16:19], v[226:229], v[202:205], v[16:19]
	v_mfma_f32_16x16x32_bf16 v[4:7], v[218:221], v[210:213], v[4:7]
	v_mfma_f32_16x16x32_bf16 v[0:3], v[226:229], v[210:213], v[0:3]
	v_mfma_f32_16x16x32_bf16 v[52:55], v[222:225], v[190:193], v[52:55]
	v_mfma_f32_16x16x32_bf16 v[48:51], v[230:233], v[190:193], v[48:51]
	v_mfma_f32_16x16x32_bf16 v[36:39], v[222:225], v[198:201], v[36:39]
	v_mfma_f32_16x16x32_bf16 v[32:35], v[230:233], v[198:201], v[32:35]
	v_mfma_f32_16x16x32_bf16 v[20:23], v[222:225], v[206:209], v[20:23]
	v_mfma_f32_16x16x32_bf16 v[16:19], v[230:233], v[206:209], v[16:19]
	v_mfma_f32_16x16x32_bf16 v[4:7], v[222:225], v[214:217], v[4:7]
	v_mfma_f32_16x16x32_bf16 v[0:3], v[230:233], v[214:217], v[0:3]
	s_setprio 0
	s_add_i32 s66, s66, 2
	s_add_u32 s64, s64, 0x100
	s_addc_u32 s65, s65, 0
	s_add_u32 s22, s22, 0x100
	s_addc_u32 s23, s23, 0
	s_cmp_gt_u32 s66, 13
	s_barrier
	s_cbranch_scc0 .LBB0_2248
	v_lshl_add_u32 v148, s21, 10, v155
	ds_read2_b32 v[172:173], v148 offset1:16
	s_ashr_i32 s21, s20, 31
	s_lshl_b64 s[20:21], s[20:21], 8
	ds_read2_b32 v[152:153], v148 offset0:32 offset1:48
	ds_read2_b32 v[150:151], v148 offset0:128 offset1:144
	ds_read2_b32 v[148:149], v148 offset0:160 offset1:176
	s_mov_b64 s[22:23], s[18:19]
	s_waitcnt lgkmcnt(0)
	v_mul_f32_e32 v120, v120, v172
	v_mul_f32_e32 v124, v124, v172
	v_mul_f32_e32 v175, 0xbfb8aa3b, v120
	v_mul_f32_e32 v174, 0xbfb8aa3b, v124
	v_exp_f32_e32 v175, v175
	v_exp_f32_e32 v174, v174
	v_mul_f32_e32 v112, v112, v172
	v_mul_f32_e32 v116, v116, v172
	v_add_f32_e32 v175, 1.0, v175
	v_add_f32_e32 v174, 1.0, v174
	v_rcp_f32_e32 v175, v175
	v_rcp_f32_e32 v174, v174
	v_mul_f32_e32 v121, v121, v172
	v_mul_f32_e32 v117, v117, v172
	v_mul_f32_e32 v120, v120, v175
	v_mul_f32_e32 v124, v124, v174
	v_mul_f32_e32 v120, v112, v120
	v_mul_f32_e32 v112, v125, v172
	v_mul_f32_e32 v116, v116, v124
	v_mul_f32_e32 v124, 0xbfb8aa3b, v112
	v_exp_f32_e32 v124, v124
	v_mul_f32_e32 v125, 0xbfb8aa3b, v121
	v_exp_f32_e32 v125, v125
	v_mul_f32_e32 v113, v113, v172
	v_add_f32_e32 v124, 1.0, v124
	v_rcp_f32_e32 v124, v124
	v_add_f32_e32 v125, 1.0, v125
	v_rcp_f32_e32 v125, v125
	v_mul_f32_e32 v118, v118, v172
	v_mul_f32_e32 v112, v112, v124
	v_mul_f32_e32 v117, v117, v112
	v_mul_f32_e32 v112, v121, v125
	v_mul_f32_e32 v121, v113, v112
	v_mul_f32_e32 v112, v126, v172
	v_mul_f32_e32 v113, v122, v172
	v_mul_f32_e32 v122, 0xbfb8aa3b, v112
	v_exp_f32_e32 v122, v122
	v_mul_f32_e32 v124, 0xbfb8aa3b, v113
	v_exp_f32_e32 v124, v124
	v_mul_f32_e32 v114, v114, v172
	v_add_f32_e32 v122, 1.0, v122
	v_rcp_f32_e32 v122, v122
	v_add_f32_e32 v124, 1.0, v124
	v_rcp_f32_e32 v124, v124
	v_mul_f32_e32 v119, v119, v172
	v_mul_f32_e32 v112, v112, v122
	v_mul_f32_e32 v118, v118, v112
	v_mul_f32_e32 v112, v113, v124
	v_mul_f32_e32 v122, v114, v112
	v_mul_f32_e32 v112, v127, v172
	v_mul_f32_e32 v113, v123, v172
	v_mul_f32_e32 v114, 0xbfb8aa3b, v112
	v_exp_f32_e32 v114, v114
	v_mul_f32_e32 v123, 0xbfb8aa3b, v113
	v_exp_f32_e32 v123, v123
	v_mul_f32_e32 v115, v115, v172
	v_add_f32_e32 v114, 1.0, v114
	v_rcp_f32_e32 v114, v114
	v_add_f32_e32 v123, 1.0, v123
	v_rcp_f32_e32 v123, v123
	v_mul_f32_e32 v104, v104, v173
	v_mul_f32_e32 v112, v112, v114
	v_mul_f32_e32 v119, v119, v112
	v_mul_f32_e32 v112, v113, v123
	v_mul_f32_e32 v123, v115, v112
	v_lshl_add_u64 v[112:113], s[20:21], 0, v[138:139]
	v_cvt_pk_bf16_f32 v115, v118, v119
	v_mov_b64_e32 v[118:119], s[8:9]
	v_mad_u64_u32 v[118:119], s[20:21], v112, s54, v[118:119]
	s_lshl_b32 s20, s61, 7
	v_mad_i32_i24 v119, v113, s54, v119
	s_ashr_i32 s21, s20, 31
	v_lshl_add_u64 v[112:113], s[20:21], 1, v[118:119]
	v_lshl_add_u64 v[112:113], v[112:113], 0, s[4:5]
	v_lshl_add_u64 v[112:113], v[112:113], 0, v[136:137]
	v_cvt_pk_bf16_f32 v114, v116, v117
	v_cvt_pk_bf16_f32 v116, v120, v121
	v_cvt_pk_bf16_f32 v117, v122, v123
	s_waitcnt vmcnt(0)
	global_store_dwordx4 v[112:113], v[114:117], off
	v_mul_f32_e32 v108, v108, v173
	v_mul_f32_e32 v96, v96, v173
	v_mul_f32_e32 v115, 0xbfb8aa3b, v104
	v_mul_f32_e32 v114, 0xbfb8aa3b, v108
	v_exp_f32_e32 v115, v115
	v_exp_f32_e32 v114, v114
	v_mul_f32_e32 v100, v100, v173
	v_mul_f32_e32 v105, v105, v173
	v_add_f32_e32 v115, 1.0, v115
	v_add_f32_e32 v114, 1.0, v114
	v_rcp_f32_e32 v115, v115
	v_rcp_f32_e32 v114, v114
	v_mul_f32_e32 v101, v101, v173
	v_mul_f32_e32 v97, v97, v173
	v_mul_f32_e32 v104, v104, v115
	v_mul_f32_e32 v108, v108, v114
	v_mul_f32_e32 v104, v96, v104
	v_mul_f32_e32 v96, v109, v173
	v_mul_f32_e32 v100, v100, v108
	v_mul_f32_e32 v108, 0xbfb8aa3b, v96
	v_exp_f32_e32 v108, v108
	v_mul_f32_e32 v109, 0xbfb8aa3b, v105
	v_exp_f32_e32 v109, v109
	v_mul_f32_e32 v102, v102, v173
	v_add_f32_e32 v108, 1.0, v108
	v_rcp_f32_e32 v108, v108
	v_add_f32_e32 v109, 1.0, v109
	v_rcp_f32_e32 v109, v109
	v_mul_f32_e32 v98, v98, v173
	v_mul_f32_e32 v96, v96, v108
	v_mul_f32_e32 v96, v101, v96
	v_mul_f32_e32 v101, v105, v109
	v_mul_f32_e32 v101, v97, v101
	v_mul_f32_e32 v97, v110, v173
	v_mul_f32_e32 v105, v106, v173
	v_mul_f32_e32 v106, 0xbfb8aa3b, v97
	v_exp_f32_e32 v106, v106
	v_mul_f32_e32 v108, 0xbfb8aa3b, v105
	v_exp_f32_e32 v108, v108
	v_mul_f32_e32 v103, v103, v173
	v_add_f32_e32 v106, 1.0, v106
	v_rcp_f32_e32 v106, v106
	v_add_f32_e32 v108, 1.0, v108
	v_rcp_f32_e32 v108, v108
	v_mul_f32_e32 v99, v99, v173
	v_mul_f32_e32 v97, v97, v106
	v_mul_f32_e32 v97, v102, v97
	v_mul_f32_e32 v102, v105, v108
	v_mul_f32_e32 v102, v98, v102
	v_mul_f32_e32 v98, v111, v173
	v_mul_f32_e32 v105, v107, v173
	v_mul_f32_e32 v106, 0xbfb8aa3b, v98
	v_exp_f32_e32 v106, v106
	v_mul_f32_e32 v107, 0xbfb8aa3b, v105
	v_exp_f32_e32 v107, v107
	v_cvt_pk_bf16_f32 v96, v100, v96
	v_add_f32_e32 v106, 1.0, v106
	v_rcp_f32_e32 v106, v106
	v_add_f32_e32 v107, 1.0, v107
	v_rcp_f32_e32 v107, v107
	v_add_co_u32_e32 v100, vcc, s45, v112
	v_mul_f32_e32 v98, v98, v106
	v_mul_f32_e32 v98, v103, v98
	v_mul_f32_e32 v103, v105, v107
	v_mul_f32_e32 v99, v99, v103
	v_cvt_pk_bf16_f32 v97, v97, v98
	v_cvt_pk_bf16_f32 v98, v104, v101
	v_addc_co_u32_e32 v101, vcc, 0, v113, vcc
	v_mul_f32_e32 v88, v88, v152
	v_cvt_pk_bf16_f32 v99, v102, v99
	global_store_dwordx4 v[100:101], v[96:99], off
	v_mul_f32_e32 v92, v92, v152
	v_mul_f32_e32 v80, v80, v152
	v_mul_f32_e32 v97, 0xbfb8aa3b, v88
	v_mul_f32_e32 v96, 0xbfb8aa3b, v92
	v_exp_f32_e32 v97, v97
	v_exp_f32_e32 v96, v96
	v_mul_f32_e32 v84, v84, v152
	v_mul_f32_e32 v89, v89, v152
	v_add_f32_e32 v97, 1.0, v97
	v_add_f32_e32 v96, 1.0, v96
	v_rcp_f32_e32 v97, v97
	v_rcp_f32_e32 v96, v96
	v_mul_f32_e32 v85, v85, v152
	v_mul_f32_e32 v81, v81, v152
	v_mul_f32_e32 v88, v88, v97
	v_mul_f32_e32 v92, v92, v96
	v_mul_f32_e32 v88, v80, v88
	v_mul_f32_e32 v80, v93, v152
	v_mul_f32_e32 v84, v84, v92
	v_mul_f32_e32 v92, 0xbfb8aa3b, v80
	v_exp_f32_e32 v92, v92
	v_mul_f32_e32 v93, 0xbfb8aa3b, v89
	v_exp_f32_e32 v93, v93
	v_mul_f32_e32 v86, v86, v152
	v_add_f32_e32 v92, 1.0, v92
	v_rcp_f32_e32 v92, v92
	v_add_f32_e32 v93, 1.0, v93
	v_rcp_f32_e32 v93, v93
	v_mul_f32_e32 v82, v82, v152
	v_mul_f32_e32 v80, v80, v92
	v_mul_f32_e32 v80, v85, v80
	v_mul_f32_e32 v85, v89, v93
	v_mul_f32_e32 v85, v81, v85
	v_mul_f32_e32 v81, v94, v152
	v_mul_f32_e32 v89, v90, v152
	v_mul_f32_e32 v90, 0xbfb8aa3b, v81
	v_exp_f32_e32 v90, v90
	v_mul_f32_e32 v92, 0xbfb8aa3b, v89
	v_exp_f32_e32 v92, v92
	v_mul_f32_e32 v87, v87, v152
	v_add_f32_e32 v90, 1.0, v90
	v_rcp_f32_e32 v90, v90
	v_add_f32_e32 v92, 1.0, v92
	v_rcp_f32_e32 v92, v92
	v_mul_f32_e32 v83, v83, v152
	v_mul_f32_e32 v81, v81, v90
	v_mul_f32_e32 v81, v86, v81
	v_mul_f32_e32 v86, v89, v92
	v_mul_f32_e32 v86, v82, v86
	v_mul_f32_e32 v82, v95, v152
	v_mul_f32_e32 v89, v91, v152
	v_mul_f32_e32 v90, 0xbfb8aa3b, v82
	v_exp_f32_e32 v90, v90
	v_mul_f32_e32 v91, 0xbfb8aa3b, v89
	v_exp_f32_e32 v91, v91
	v_cvt_pk_bf16_f32 v80, v84, v80
	v_add_f32_e32 v90, 1.0, v90
	v_rcp_f32_e32 v90, v90
	v_add_f32_e32 v91, 1.0, v91
	v_rcp_f32_e32 v91, v91
	v_add_co_u32_e32 v84, vcc, s55, v112
	v_mul_f32_e32 v82, v82, v90
	v_mul_f32_e32 v82, v87, v82
	v_mul_f32_e32 v87, v89, v91
	v_mul_f32_e32 v83, v83, v87
	v_cvt_pk_bf16_f32 v81, v81, v82
	v_cvt_pk_bf16_f32 v82, v88, v85
	v_addc_co_u32_e32 v85, vcc, 0, v113, vcc
	v_mul_f32_e32 v72, v72, v153
	v_cvt_pk_bf16_f32 v83, v86, v83
	global_store_dwordx4 v[84:85], v[80:83], off
	v_mul_f32_e32 v76, v76, v153
	v_mul_f32_e32 v64, v64, v153
	v_mul_f32_e32 v81, 0xbfb8aa3b, v72
	v_mul_f32_e32 v80, 0xbfb8aa3b, v76
	v_exp_f32_e32 v81, v81
	v_exp_f32_e32 v80, v80
	v_mul_f32_e32 v68, v68, v153
	v_mul_f32_e32 v73, v73, v153
	v_add_f32_e32 v81, 1.0, v81
	v_add_f32_e32 v80, 1.0, v80
	v_rcp_f32_e32 v81, v81
	v_rcp_f32_e32 v80, v80
	v_mul_f32_e32 v69, v69, v153
	v_mul_f32_e32 v65, v65, v153
	v_mul_f32_e32 v72, v72, v81
	v_mul_f32_e32 v76, v76, v80
	v_mul_f32_e32 v72, v64, v72
	v_mul_f32_e32 v64, v77, v153
	v_mul_f32_e32 v68, v68, v76
	v_mul_f32_e32 v76, 0xbfb8aa3b, v64
	v_exp_f32_e32 v76, v76
	v_mul_f32_e32 v77, 0xbfb8aa3b, v73
	v_exp_f32_e32 v77, v77
	v_mul_f32_e32 v70, v70, v153
	v_add_f32_e32 v76, 1.0, v76
	v_rcp_f32_e32 v76, v76
	v_add_f32_e32 v77, 1.0, v77
	v_rcp_f32_e32 v77, v77
	v_mul_f32_e32 v66, v66, v153
	v_mul_f32_e32 v64, v64, v76
	v_mul_f32_e32 v64, v69, v64
	v_mul_f32_e32 v69, v73, v77
	v_mul_f32_e32 v69, v65, v69
	v_mul_f32_e32 v65, v78, v153
	v_mul_f32_e32 v73, v74, v153
	v_mul_f32_e32 v74, 0xbfb8aa3b, v65
	v_exp_f32_e32 v74, v74
	v_mul_f32_e32 v76, 0xbfb8aa3b, v73
	v_exp_f32_e32 v76, v76
	v_mul_f32_e32 v71, v71, v153
	v_add_f32_e32 v74, 1.0, v74
	v_rcp_f32_e32 v74, v74
	v_add_f32_e32 v76, 1.0, v76
	v_rcp_f32_e32 v76, v76
	v_mul_f32_e32 v67, v67, v153
	v_mul_f32_e32 v65, v65, v74
	v_mul_f32_e32 v65, v70, v65
	v_mul_f32_e32 v70, v73, v76
	v_mul_f32_e32 v70, v66, v70
	v_mul_f32_e32 v66, v79, v153
	v_mul_f32_e32 v73, v75, v153
	v_mul_f32_e32 v74, 0xbfb8aa3b, v66
	v_exp_f32_e32 v74, v74
	v_mul_f32_e32 v75, 0xbfb8aa3b, v73
	v_exp_f32_e32 v75, v75
	v_cvt_pk_bf16_f32 v64, v68, v64
	v_add_f32_e32 v74, 1.0, v74
	v_rcp_f32_e32 v74, v74
	v_add_f32_e32 v75, 1.0, v75
	v_rcp_f32_e32 v75, v75
	v_add_co_u32_e32 v68, vcc, s56, v112
	v_mul_f32_e32 v66, v66, v74
	v_mul_f32_e32 v66, v71, v66
	v_mul_f32_e32 v71, v73, v75
	v_mul_f32_e32 v67, v67, v71
	v_cvt_pk_bf16_f32 v65, v65, v66
	v_cvt_pk_bf16_f32 v66, v72, v69
	v_addc_co_u32_e32 v69, vcc, 0, v113, vcc
	v_mul_f32_e32 v56, v56, v150
	v_cvt_pk_bf16_f32 v67, v70, v67
	global_store_dwordx4 v[68:69], v[64:67], off
	v_mul_f32_e32 v60, v60, v150
	v_mul_f32_e32 v48, v48, v150
	v_mul_f32_e32 v65, 0xbfb8aa3b, v56
	v_mul_f32_e32 v64, 0xbfb8aa3b, v60
	v_exp_f32_e32 v65, v65
	v_exp_f32_e32 v64, v64
	v_mul_f32_e32 v52, v52, v150
	v_mul_f32_e32 v57, v57, v150
	v_add_f32_e32 v65, 1.0, v65
	v_add_f32_e32 v64, 1.0, v64
	v_rcp_f32_e32 v65, v65
	v_rcp_f32_e32 v64, v64
	v_mul_f32_e32 v53, v53, v150
	v_mul_f32_e32 v49, v49, v150
	v_mul_f32_e32 v56, v56, v65
	v_mul_f32_e32 v60, v60, v64
	v_mul_f32_e32 v56, v48, v56
	v_mul_f32_e32 v48, v61, v150
	v_mul_f32_e32 v52, v52, v60
	v_mul_f32_e32 v60, 0xbfb8aa3b, v48
	v_exp_f32_e32 v60, v60
	v_mul_f32_e32 v61, 0xbfb8aa3b, v57
	v_exp_f32_e32 v61, v61
	v_mul_f32_e32 v54, v54, v150
	v_add_f32_e32 v60, 1.0, v60
	v_rcp_f32_e32 v60, v60
	v_add_f32_e32 v61, 1.0, v61
	v_rcp_f32_e32 v61, v61
	v_mul_f32_e32 v50, v50, v150
	v_mul_f32_e32 v48, v48, v60
	v_mul_f32_e32 v48, v53, v48
	v_mul_f32_e32 v53, v57, v61
	v_mul_f32_e32 v53, v49, v53
	v_mul_f32_e32 v49, v62, v150
	v_mul_f32_e32 v57, v58, v150
	v_mul_f32_e32 v58, 0xbfb8aa3b, v49
	v_exp_f32_e32 v58, v58
	v_mul_f32_e32 v60, 0xbfb8aa3b, v57
	v_exp_f32_e32 v60, v60
	v_mul_f32_e32 v55, v55, v150
	v_add_f32_e32 v58, 1.0, v58
	v_rcp_f32_e32 v58, v58
	v_add_f32_e32 v60, 1.0, v60
	v_rcp_f32_e32 v60, v60
	v_mul_f32_e32 v51, v51, v150
	v_mul_f32_e32 v49, v49, v58
	v_mul_f32_e32 v49, v54, v49
	v_mul_f32_e32 v54, v57, v60
	v_mul_f32_e32 v54, v50, v54
	v_mul_f32_e32 v50, v63, v150
	v_mul_f32_e32 v57, v59, v150
	v_mul_f32_e32 v58, 0xbfb8aa3b, v50
	v_exp_f32_e32 v58, v58
	v_mul_f32_e32 v59, 0xbfb8aa3b, v57
	v_exp_f32_e32 v59, v59
	v_cvt_pk_bf16_f32 v48, v52, v48
	v_add_f32_e32 v58, 1.0, v58
	v_rcp_f32_e32 v58, v58
	v_add_f32_e32 v59, 1.0, v59
	v_rcp_f32_e32 v59, v59
	v_add_co_u32_e32 v52, vcc, s57, v112
	v_mul_f32_e32 v50, v50, v58
	v_mul_f32_e32 v50, v55, v50
	v_mul_f32_e32 v55, v57, v59
	v_mul_f32_e32 v51, v51, v55
	v_cvt_pk_bf16_f32 v49, v49, v50
	v_cvt_pk_bf16_f32 v50, v56, v53
	v_addc_co_u32_e32 v53, vcc, 0, v113, vcc
	v_mul_f32_e32 v40, v40, v151
	v_cvt_pk_bf16_f32 v51, v54, v51
	global_store_dwordx4 v[52:53], v[48:51], off
	v_mul_f32_e32 v44, v44, v151
	v_mul_f32_e32 v32, v32, v151
	v_mul_f32_e32 v49, 0xbfb8aa3b, v40
	v_mul_f32_e32 v48, 0xbfb8aa3b, v44
	v_exp_f32_e32 v49, v49
	v_exp_f32_e32 v48, v48
	v_mul_f32_e32 v36, v36, v151
	v_mul_f32_e32 v41, v41, v151
	v_add_f32_e32 v49, 1.0, v49
	v_add_f32_e32 v48, 1.0, v48
	v_rcp_f32_e32 v49, v49
	v_rcp_f32_e32 v48, v48
	v_mul_f32_e32 v37, v37, v151
	v_mul_f32_e32 v33, v33, v151
	v_mul_f32_e32 v40, v40, v49
	v_mul_f32_e32 v44, v44, v48
	v_mul_f32_e32 v40, v32, v40
	v_mul_f32_e32 v32, v45, v151
	v_mul_f32_e32 v36, v36, v44
	v_mul_f32_e32 v44, 0xbfb8aa3b, v32
	v_exp_f32_e32 v44, v44
	v_mul_f32_e32 v45, 0xbfb8aa3b, v41
	v_exp_f32_e32 v45, v45
	v_mul_f32_e32 v38, v38, v151
	v_add_f32_e32 v44, 1.0, v44
	v_rcp_f32_e32 v44, v44
	v_add_f32_e32 v45, 1.0, v45
	v_rcp_f32_e32 v45, v45
	v_mul_f32_e32 v34, v34, v151
	v_mul_f32_e32 v32, v32, v44
	v_mul_f32_e32 v32, v37, v32
	v_mul_f32_e32 v37, v41, v45
	v_mul_f32_e32 v37, v33, v37
	v_mul_f32_e32 v33, v46, v151
	v_mul_f32_e32 v41, v42, v151
	v_mul_f32_e32 v42, 0xbfb8aa3b, v33
	v_exp_f32_e32 v42, v42
	v_mul_f32_e32 v44, 0xbfb8aa3b, v41
	v_exp_f32_e32 v44, v44
	v_mul_f32_e32 v39, v39, v151
	v_add_f32_e32 v42, 1.0, v42
	v_rcp_f32_e32 v42, v42
	v_add_f32_e32 v44, 1.0, v44
	v_rcp_f32_e32 v44, v44
	v_mul_f32_e32 v35, v35, v151
	v_mul_f32_e32 v33, v33, v42
	v_mul_f32_e32 v33, v38, v33
	v_mul_f32_e32 v38, v41, v44
	v_mul_f32_e32 v38, v34, v38
	v_mul_f32_e32 v34, v47, v151
	v_mul_f32_e32 v41, v43, v151
	v_mul_f32_e32 v42, 0xbfb8aa3b, v34
	v_exp_f32_e32 v42, v42
	v_mul_f32_e32 v43, 0xbfb8aa3b, v41
	v_exp_f32_e32 v43, v43
	v_cvt_pk_bf16_f32 v32, v36, v32
	v_add_f32_e32 v42, 1.0, v42
	v_rcp_f32_e32 v42, v42
	v_add_f32_e32 v43, 1.0, v43
	v_rcp_f32_e32 v43, v43
	v_add_co_u32_e32 v36, vcc, s58, v112
	v_mul_f32_e32 v34, v34, v42
	v_mul_f32_e32 v34, v39, v34
	v_mul_f32_e32 v39, v41, v43
	v_mul_f32_e32 v35, v35, v39
	v_cvt_pk_bf16_f32 v33, v33, v34
	v_cvt_pk_bf16_f32 v34, v40, v37
	v_addc_co_u32_e32 v37, vcc, 0, v113, vcc
	v_mul_f32_e32 v24, v24, v148
	v_cvt_pk_bf16_f32 v35, v38, v35
	global_store_dwordx4 v[36:37], v[32:35], off
	v_mul_f32_e32 v28, v28, v148
	v_mul_f32_e32 v16, v16, v148
	v_mul_f32_e32 v33, 0xbfb8aa3b, v24
	v_mul_f32_e32 v32, 0xbfb8aa3b, v28
	v_exp_f32_e32 v33, v33
	v_exp_f32_e32 v32, v32
	v_mul_f32_e32 v20, v20, v148
	v_mul_f32_e32 v25, v25, v148
	v_add_f32_e32 v33, 1.0, v33
	v_add_f32_e32 v32, 1.0, v32
	v_rcp_f32_e32 v33, v33
	v_rcp_f32_e32 v32, v32
	v_mul_f32_e32 v21, v21, v148
	v_mul_f32_e32 v17, v17, v148
	v_mul_f32_e32 v24, v24, v33
	v_mul_f32_e32 v28, v28, v32
	v_mul_f32_e32 v24, v16, v24
	v_mul_f32_e32 v16, v29, v148
	v_mul_f32_e32 v20, v20, v28
	v_mul_f32_e32 v28, 0xbfb8aa3b, v16
	v_exp_f32_e32 v28, v28
	v_mul_f32_e32 v29, 0xbfb8aa3b, v25
	v_exp_f32_e32 v29, v29
	v_mul_f32_e32 v22, v22, v148
	v_add_f32_e32 v28, 1.0, v28
	v_rcp_f32_e32 v28, v28
	v_add_f32_e32 v29, 1.0, v29
	v_rcp_f32_e32 v29, v29
	v_mul_f32_e32 v18, v18, v148
	v_mul_f32_e32 v16, v16, v28
	v_mul_f32_e32 v16, v21, v16
	v_mul_f32_e32 v21, v25, v29
	v_mul_f32_e32 v21, v17, v21
	v_mul_f32_e32 v17, v30, v148
	v_mul_f32_e32 v25, v26, v148
	v_mul_f32_e32 v26, 0xbfb8aa3b, v17
	v_exp_f32_e32 v26, v26
	v_mul_f32_e32 v28, 0xbfb8aa3b, v25
	v_exp_f32_e32 v28, v28
	v_mul_f32_e32 v23, v23, v148
	v_add_f32_e32 v26, 1.0, v26
	v_rcp_f32_e32 v26, v26
	v_add_f32_e32 v28, 1.0, v28
	v_rcp_f32_e32 v28, v28
	v_mul_f32_e32 v19, v19, v148
	v_mul_f32_e32 v17, v17, v26
	v_mul_f32_e32 v17, v22, v17
	v_mul_f32_e32 v22, v25, v28
	v_mul_f32_e32 v22, v18, v22
	v_mul_f32_e32 v18, v31, v148
	v_mul_f32_e32 v25, v27, v148
	v_mul_f32_e32 v26, 0xbfb8aa3b, v18
	v_exp_f32_e32 v26, v26
	v_mul_f32_e32 v27, 0xbfb8aa3b, v25
	v_exp_f32_e32 v27, v27
	v_cvt_pk_bf16_f32 v16, v20, v16
	v_add_f32_e32 v26, 1.0, v26
	v_rcp_f32_e32 v26, v26
	v_add_f32_e32 v27, 1.0, v27
	v_rcp_f32_e32 v27, v27
	v_add_co_u32_e32 v20, vcc, s59, v112
	v_mul_f32_e32 v18, v18, v26
	v_mul_f32_e32 v18, v23, v18
	v_mul_f32_e32 v23, v25, v27
	v_mul_f32_e32 v19, v19, v23
	v_cvt_pk_bf16_f32 v17, v17, v18
	v_cvt_pk_bf16_f32 v18, v24, v21
	v_addc_co_u32_e32 v21, vcc, 0, v113, vcc
	v_mul_f32_e32 v8, v8, v149
	v_cvt_pk_bf16_f32 v19, v22, v19
	global_store_dwordx4 v[20:21], v[16:19], off
	v_mul_f32_e32 v12, v12, v149
	v_mul_f32_e32 v0, v0, v149
	v_mul_f32_e32 v17, 0xbfb8aa3b, v8
	v_mul_f32_e32 v16, 0xbfb8aa3b, v12
	v_exp_f32_e32 v17, v17
	v_exp_f32_e32 v16, v16
	v_mul_f32_e32 v4, v4, v149
	v_mul_f32_e32 v9, v9, v149
	v_add_f32_e32 v17, 1.0, v17
	v_add_f32_e32 v16, 1.0, v16
	v_rcp_f32_e32 v17, v17
	v_rcp_f32_e32 v16, v16
	v_mul_f32_e32 v5, v5, v149
	v_mul_f32_e32 v1, v1, v149
	v_mul_f32_e32 v8, v8, v17
	v_mul_f32_e32 v12, v12, v16
	v_mul_f32_e32 v8, v0, v8
	v_mul_f32_e32 v0, v13, v149
	v_mul_f32_e32 v4, v4, v12
	v_mul_f32_e32 v12, 0xbfb8aa3b, v0
	v_exp_f32_e32 v12, v12
	v_mul_f32_e32 v13, 0xbfb8aa3b, v9
	v_exp_f32_e32 v13, v13
	v_mul_f32_e32 v6, v6, v149
	v_add_f32_e32 v12, 1.0, v12
	v_rcp_f32_e32 v12, v12
	v_add_f32_e32 v13, 1.0, v13
	v_rcp_f32_e32 v13, v13
	v_mul_f32_e32 v2, v2, v149
	v_mul_f32_e32 v0, v0, v12
	v_mul_f32_e32 v0, v5, v0
	v_mul_f32_e32 v5, v9, v13
	v_mul_f32_e32 v5, v1, v5
	v_mul_f32_e32 v1, v14, v149
	v_mul_f32_e32 v9, v10, v149
	v_mul_f32_e32 v10, 0xbfb8aa3b, v1
	v_exp_f32_e32 v10, v10
	v_mul_f32_e32 v12, 0xbfb8aa3b, v9
	v_exp_f32_e32 v12, v12
	v_mul_f32_e32 v7, v7, v149
	v_add_f32_e32 v10, 1.0, v10
	v_rcp_f32_e32 v10, v10
	v_add_f32_e32 v12, 1.0, v12
	v_rcp_f32_e32 v12, v12
	v_cvt_pk_bf16_f32 v0, v4, v0
	v_mul_f32_e32 v1, v1, v10
	v_mul_f32_e32 v1, v6, v1
	v_mul_f32_e32 v6, v9, v12
	v_mul_f32_e32 v6, v2, v6
	v_mul_f32_e32 v2, v15, v149
	v_mul_f32_e32 v10, 0xbfb8aa3b, v2
	v_mul_f32_e32 v9, v11, v149
	v_exp_f32_e32 v10, v10
	v_mul_f32_e32 v11, 0xbfb8aa3b, v9
	v_exp_f32_e32 v11, v11
	v_add_co_u32_e32 v4, vcc, 0xf2000, v112
	v_add_f32_e32 v10, 1.0, v10
	v_rcp_f32_e32 v10, v10
	v_add_f32_e32 v11, 1.0, v11
	v_rcp_f32_e32 v11, v11
	v_mul_f32_e32 v3, v3, v149
	v_mul_f32_e32 v2, v2, v10
	v_mul_f32_e32 v2, v7, v2
	v_mul_f32_e32 v7, v9, v11
	v_cvt_pk_bf16_f32 v1, v1, v2
	v_cvt_pk_bf16_f32 v2, v8, v5
	v_addc_co_u32_e32 v5, vcc, 0, v113, vcc
	v_mul_f32_e32 v3, v3, v7
	s_and_b64 vcc, exec, s[6:7]
	s_mov_b32 s20, s14
	s_mov_b32 s61, s12
	s_mov_b64 s[24:25], s[16:17]
	s_mov_b32 s21, s60
	v_cvt_pk_bf16_f32 v3, v6, v3
	global_store_dwordx4 v[4:5], v[0:3], off
	s_cbranch_vccz .LBB0_2245
	s_waitcnt vmcnt(0)
	s_cmpk_gt_u32 s28, 0xff
	s_cbranch_scc1 .LBB0_2252
	s_barrier
